# 160 xor-16/32 ds_bpermute butterflies in GEMM epilogue row statistics replaced by v_permlane16/32_swap (bit-identical), on top of v29
# baseline (speedup 1.0000x reference)
.LBB0_1542:
	v_and_b32_e32 v129, 64, v207
	v_xor_b32_e32 v128, 16, v207
	v_add_u32_e32 v129, 64, v129
	v_cmp_lt_i32_e32 vcc, v128, v129
	s_ashr_i32 s35, s34, 31
	v_lshl_or_b32 v174, s16, 8, v195
	v_cndmask_b32_e32 v128, v207, v128, vcc
	s_lshl_b64 s[34:35], s[34:35], 8
	v_ashrrev_i32_e32 v175, 31, v174
	v_lshlrev_b32_e32 v209, 2, v128
	v_xor_b32_e32 v128, 32, v207
	v_lshl_add_u64 v[176:177], s[34:35], 0, v[166:167]
	v_cmp_lt_i32_e32 vcc, v128, v129
	v_lshlrev_b64 v[202:203], 1, v[174:175]
	v_lshl_add_u64 v[178:179], s[44:45], 0, v[202:203]
	v_cndmask_b32_e32 v128, v207, v128, vcc
	v_lshlrev_b64 v[214:215], 11, v[176:177]
	v_lshlrev_b32_e32 v208, 2, v128
	v_lshl_add_u64 v[128:129], v[178:179], 0, v[214:215]
	global_load_dwordx4 v[196:199], v[128:129], off
	global_load_dwordx4 v[152:155], v[128:129], off offset:256
	v_or_b32_e32 v188, 16, v176
	v_mov_b32_e32 v189, v177
	v_lshlrev_b64 v[190:191], 11, v[188:189]
	v_or_b32_e32 v184, 32, v176
	v_mov_b32_e32 v185, v177
	v_lshl_add_u64 v[128:129], v[178:179], 0, v[190:191]
	v_lshlrev_b64 v[186:187], 11, v[184:185]
	v_or_b32_e32 v180, 48, v176
	v_mov_b32_e32 v181, v177
	global_load_dwordx4 v[148:151], v[128:129], off
	global_load_dwordx4 v[144:147], v[128:129], off offset:256
	v_lshl_add_u64 v[128:129], v[178:179], 0, v[186:187]
	v_lshlrev_b64 v[182:183], 11, v[180:181]
	global_load_dwordx4 v[140:143], v[128:129], off
	global_load_dwordx4 v[136:139], v[128:129], off offset:256
	v_lshl_add_u64 v[128:129], v[178:179], 0, v[182:183]
	global_load_dwordx4 v[132:135], v[128:129], off
	s_nop 0
	global_load_dwordx4 v[128:131], v[128:129], off offset:256
	v_lshl_add_u64 v[214:215], s[44:45], 0, v[214:215]
	v_lshl_add_u64 v[202:203], v[214:215], 0, v[202:203]
	s_lshl_b32 s34, s16, 2
	s_ashr_i32 s35, s34, 31
	s_waitcnt vmcnt(0)
	v_lshlrev_b32_e32 v200, 16, v196
	v_and_b32_e32 v201, 0xffff0000, v196
	v_lshlrev_b32_e32 v196, 16, v197
	v_and_b32_e32 v197, 0xffff0000, v197
	v_pk_fma_f32 v[212:213], v[196:197], s[28:29], v[126:127] op_sel_hi:[1,0,1]
	v_pk_fma_f32 v[216:217], v[200:201], s[28:29], v[124:125] op_sel_hi:[1,0,1]
	v_mov_b32_e32 v127, v213
	v_pk_mov_b32 v[124:125], v[216:217], v[212:213] op_sel:[1,0]
	v_mov_b32_e32 v126, v216
	v_pk_add_f32 v[124:125], v[124:125], v[126:127]
	v_mul_f32_e32 v126, v216, v216
	v_lshlrev_b32_e32 v210, 16, v198
	v_and_b32_e32 v211, 0xffff0000, v198
	v_lshlrev_b32_e32 v198, 16, v199
	v_and_b32_e32 v199, 0xffff0000, v199
	v_pk_fma_f32 v[126:127], v[216:217], v[216:217], v[126:127] op_sel_hi:[1,1,0]
	v_pk_fma_f32 v[218:219], v[198:199], s[28:29], v[122:123] op_sel_hi:[1,0,1]
	v_mul_f32_e32 v126, v212, v212
	v_pk_fma_f32 v[220:221], v[210:211], s[28:29], v[120:121] op_sel_hi:[1,0,1]
	v_pk_fma_f32 v[196:197], v[212:213], v[212:213], v[126:127] op_sel_hi:[1,1,0]
	v_mul_f32_e32 v126, v220, v220
	v_cvt_pk_bf16_f32 v210, v216, v217
	v_cvt_pk_bf16_f32 v211, v212, v213
	v_cvt_pk_bf16_f32 v212, v220, v221
	v_cvt_pk_bf16_f32 v213, v218, v219
	v_pk_fma_f32 v[198:199], v[220:221], v[220:221], v[126:127] op_sel_hi:[1,1,0]
	v_mul_f32_e32 v126, v218, v218
	global_store_dwordx4 v[202:203], v[210:213], off
	v_pk_fma_f32 v[200:201], v[218:219], v[218:219], v[126:127] op_sel_hi:[1,1,0]
	v_add_f32_e32 v120, v220, v221
	v_lshlrev_b32_e32 v210, 16, v152
	v_and_b32_e32 v211, 0xffff0000, v152
	v_lshlrev_b32_e32 v152, 16, v153
	v_and_b32_e32 v153, 0xffff0000, v153
	v_lshlrev_b32_e32 v212, 16, v154
	v_and_b32_e32 v213, 0xffff0000, v154
	v_lshlrev_b32_e32 v154, 16, v155
	v_and_b32_e32 v155, 0xffff0000, v155
	v_pk_fma_f32 v[118:119], v[152:153], s[28:29], v[118:119] op_sel_hi:[1,0,1]
	v_pk_fma_f32 v[116:117], v[210:211], s[28:29], v[116:117] op_sel_hi:[1,0,1]
	v_pk_fma_f32 v[152:153], v[154:155], s[28:29], v[114:115] op_sel_hi:[1,0,1]
	v_pk_fma_f32 v[154:155], v[212:213], s[28:29], v[112:113] op_sel_hi:[1,0,1]
	v_mul_f32_e32 v121, v116, v116
	v_mul_f32_e32 v123, v117, v117
	v_mul_f32_e32 v210, v118, v118
	v_cvt_pk_bf16_f32 v112, v116, v117
	v_cvt_pk_bf16_f32 v113, v118, v119
	v_cvt_pk_bf16_f32 v114, v154, v155
	v_cvt_pk_bf16_f32 v115, v152, v153
	v_mov_b32_e32 v126, v116
	v_mov_b32_e32 v196, v117
	v_mov_b32_e32 v198, v118
	v_mov_b32_e32 v200, v119
	v_pk_add_f32 v[116:117], v[124:125], v[124:125] op_sel:[0,1] op_sel_hi:[1,0]
	v_add_f32_e32 v122, v218, v219
	v_mul_f32_e32 v165, v119, v119
	global_store_dwordx4 v[202:203], v[112:115], off offset:256
	v_mov_b32_e32 v117, v210
	v_pk_add_f32 v[116:117], v[116:117], v[164:165]
	v_pk_add_f32 v[112:113], v[126:127], v[196:197]
	v_pk_add_f32 v[114:115], v[198:199], v[200:201]
	v_mul_f32_e32 v211, v154, v154
	v_pk_add_f32 v[112:113], v[112:113], v[114:115]
	v_pk_add_f32 v[114:115], v[120:121], v[122:123]
	v_mul_f32_e32 v213, v155, v155
	v_mul_f32_e32 v215, v152, v152
	v_mul_f32_e32 v217, v153, v153
	v_pk_add_f32 v[114:115], v[114:115], v[116:117]
	v_mov_b32_e32 v210, v154
	v_mov_b32_e32 v212, v155
	v_mov_b32_e32 v214, v152
	v_mov_b32_e32 v216, v153
	v_pk_add_f32 v[112:113], v[112:113], v[114:115]
	v_pk_add_f32 v[114:115], v[210:211], v[212:213]
	v_pk_add_f32 v[116:117], v[214:215], v[216:217]
	s_nop 0
	v_pk_add_f32 v[114:115], v[114:115], v[116:117]
	s_nop 0
	v_pk_add_f32 v[112:113], v[114:115], v[112:113]
	s_waitcnt lgkmcnt(0)
	v_mov_b32_e32 v114, v112
	v_mov_b32_e32 v115, v113
	s_nop 1
	v_permlane16_swap_b32_e32 v114, v112
	v_permlane16_swap_b32_e32 v115, v113
	s_nop 0
	v_pk_add_f32 v[112:113], v[112:113], v[114:115]
	ds_bpermute_b32 v114, v208, v112
	ds_bpermute_b32 v115, v208, v113
	s_and_saveexec_b64 s[36:37], s[4:5]
	s_cbranch_execz .LBB0_1544
	s_waitcnt lgkmcnt(0)
	v_pk_add_f32 v[112:113], v[112:113], v[114:115]
	v_lshlrev_b64 v[114:115], 7, v[176:177]
	v_lshl_add_u64 v[114:115], s[74:75], 0, v[114:115]
	v_lshl_add_u64 v[114:115], s[34:35], 3, v[114:115]
	s_lshl_b32 s16, s76, 3
	v_lshl_add_u64 v[114:115], v[114:115], 0, s[16:17]
	global_store_dwordx2 v[114:115], v[112:113], off
.LBB0_1544:
	s_or_b64 exec, exec, s[36:37]
	v_lshlrev_b32_e32 v112, 16, v148
	v_and_b32_e32 v113, 0xffff0000, v148
	s_waitcnt lgkmcnt(1)
	v_lshlrev_b32_e32 v114, 16, v149
	s_waitcnt lgkmcnt(0)
	v_and_b32_e32 v115, 0xffff0000, v149
	v_pk_fma_f32 v[110:111], v[114:115], s[28:29], v[110:111] op_sel_hi:[1,0,1]
	v_pk_fma_f32 v[108:109], v[112:113], s[28:29], v[108:109] op_sel_hi:[1,0,1]
	v_lshlrev_b32_e32 v116, 16, v150
	v_and_b32_e32 v117, 0xffff0000, v150
	v_lshlrev_b32_e32 v118, 16, v151
	v_and_b32_e32 v119, 0xffff0000, v151
	v_pk_mov_b32 v[112:113], v[108:109], v[110:111] op_sel:[1,0]
	v_mov_b32_e32 v114, v108
	v_mov_b32_e32 v115, v111
	v_pk_add_f32 v[112:113], v[112:113], v[114:115]
	v_mul_f32_e32 v114, v108, v108
	v_pk_fma_f32 v[118:119], v[118:119], s[28:29], v[106:107] op_sel_hi:[1,0,1]
	v_pk_fma_f32 v[106:107], v[116:117], s[28:29], v[104:105] op_sel_hi:[1,0,1]
	v_pk_fma_f32 v[114:115], v[108:109], v[108:109], v[114:115] op_sel_hi:[1,1,0]
	v_mul_f32_e32 v104, v106, v106
	v_mul_f32_e32 v114, v110, v110
	v_pk_fma_f32 v[124:125], v[106:107], v[106:107], v[104:105] op_sel_hi:[1,1,0]
	v_mul_f32_e32 v104, v118, v118
	v_pk_fma_f32 v[120:121], v[110:111], v[110:111], v[114:115] op_sel_hi:[1,1,0]
	v_pk_fma_f32 v[126:127], v[118:119], v[118:119], v[104:105] op_sel_hi:[1,1,0]
	v_cvt_pk_bf16_f32 v105, v110, v111
	v_lshlrev_b32_e32 v110, 16, v145
	v_and_b32_e32 v111, 0xffff0000, v145
	v_cvt_pk_bf16_f32 v104, v108, v109
	v_lshlrev_b32_e32 v108, 16, v144
	v_and_b32_e32 v109, 0xffff0000, v144
	v_pk_fma_f32 v[102:103], v[110:111], s[28:29], v[102:103] op_sel_hi:[1,0,1]
	v_add_f32_e32 v116, v106, v107
	v_add_f32_e32 v122, v118, v119
	v_cvt_pk_bf16_f32 v106, v106, v107
	v_cvt_pk_bf16_f32 v107, v118, v119
	v_lshlrev_b32_e32 v118, 16, v146
	v_and_b32_e32 v119, 0xffff0000, v146
	v_lshlrev_b32_e32 v144, 16, v147
	v_and_b32_e32 v145, 0xffff0000, v147
	v_pk_fma_f32 v[100:101], v[108:109], s[28:29], v[100:101] op_sel_hi:[1,0,1]
	v_mul_f32_e32 v146, v102, v102
	v_pk_add_f32 v[112:113], v[112:113], v[112:113] op_sel:[0,1] op_sel_hi:[1,0]
	v_mul_f32_e32 v117, v100, v100
	v_mul_f32_e32 v123, v101, v101
	v_mul_f32_e32 v165, v103, v103
	v_pk_fma_f32 v[108:109], v[144:145], s[28:29], v[98:99] op_sel_hi:[1,0,1]
	v_pk_fma_f32 v[110:111], v[118:119], s[28:29], v[96:97] op_sel_hi:[1,0,1]
	v_mov_b32_e32 v114, v100
	v_mov_b32_e32 v120, v101
	v_mov_b32_e32 v124, v102
	v_mov_b32_e32 v126, v103
	v_mov_b32_e32 v113, v146
	v_mul_f32_e32 v97, v110, v110
	v_mul_f32_e32 v99, v111, v111
	v_mul_f32_e32 v119, v108, v108
	v_mul_f32_e32 v145, v109, v109
	v_pk_add_f32 v[114:115], v[114:115], v[120:121]
	v_pk_add_f32 v[120:121], v[124:125], v[126:127]
	v_pk_add_f32 v[116:117], v[116:117], v[122:123]
	v_pk_add_f32 v[112:113], v[112:113], v[164:165]
	v_mov_b32_e32 v96, v110
	v_mov_b32_e32 v98, v111
	v_mov_b32_e32 v118, v108
	v_mov_b32_e32 v144, v109
	v_pk_add_f32 v[114:115], v[114:115], v[120:121]
	v_pk_add_f32 v[112:113], v[116:117], v[112:113]
	v_pk_add_f32 v[96:97], v[96:97], v[98:99]
	v_pk_add_f32 v[98:99], v[118:119], v[144:145]
	v_pk_add_f32 v[112:113], v[114:115], v[112:113]
	v_pk_add_f32 v[96:97], v[96:97], v[98:99]
	v_cvt_pk_bf16_f32 v100, v100, v101
	v_pk_add_f32 v[96:97], v[96:97], v[112:113]
	v_lshl_add_u64 v[112:113], s[44:45], 0, v[190:191]
	v_lshl_add_u64 v[112:113], v[174:175], 1, v[112:113]
	v_cvt_pk_bf16_f32 v101, v102, v103
	v_cvt_pk_bf16_f32 v102, v110, v111
	s_waitcnt lgkmcnt(0)
	v_mov_b32_e32 v98, v96
	v_mov_b32_e32 v99, v97
	s_nop 1
	v_permlane16_swap_b32_e32 v98, v96
	v_permlane16_swap_b32_e32 v99, v97
	s_nop 0
	v_pk_add_f32 v[96:97], v[96:97], v[98:99]
	ds_bpermute_b32 v98, v208, v96
	ds_bpermute_b32 v99, v208, v97
	v_cvt_pk_bf16_f32 v103, v108, v109
	global_store_dwordx4 v[112:113], v[104:107], off
	global_store_dwordx4 v[112:113], v[100:103], off offset:256
	s_and_saveexec_b64 s[36:37], s[4:5]
	s_cbranch_execz .LBB0_1546
	s_waitcnt lgkmcnt(0)
	v_pk_add_f32 v[96:97], v[96:97], v[98:99]
	v_lshlrev_b64 v[98:99], 7, v[188:189]
	v_lshl_add_u64 v[98:99], s[74:75], 0, v[98:99]
	v_lshl_add_u64 v[98:99], s[34:35], 3, v[98:99]
	s_lshl_b32 s16, s76, 3
	v_lshl_add_u64 v[98:99], v[98:99], 0, s[16:17]
	global_store_dwordx2 v[98:99], v[96:97], off
.LBB0_1546:
	s_or_b64 exec, exec, s[36:37]
	v_lshlrev_b32_e32 v96, 16, v140
	v_and_b32_e32 v97, 0xffff0000, v140
	s_waitcnt lgkmcnt(1)
	v_lshlrev_b32_e32 v98, 16, v141
	s_waitcnt lgkmcnt(0)
	v_and_b32_e32 v99, 0xffff0000, v141
	v_pk_fma_f32 v[94:95], v[98:99], s[28:29], v[94:95] op_sel_hi:[1,0,1]
	v_pk_fma_f32 v[92:93], v[96:97], s[28:29], v[92:93] op_sel_hi:[1,0,1]
	v_lshlrev_b32_e32 v100, 16, v142
	v_and_b32_e32 v101, 0xffff0000, v142
	v_lshlrev_b32_e32 v102, 16, v143
	v_and_b32_e32 v103, 0xffff0000, v143
	v_pk_mov_b32 v[96:97], v[92:93], v[94:95] op_sel:[1,0]
	v_mov_b32_e32 v98, v92
	v_mov_b32_e32 v99, v95
	v_pk_add_f32 v[96:97], v[96:97], v[98:99]
	v_mul_f32_e32 v98, v92, v92
	v_pk_fma_f32 v[102:103], v[102:103], s[28:29], v[90:91] op_sel_hi:[1,0,1]
	v_pk_fma_f32 v[90:91], v[100:101], s[28:29], v[88:89] op_sel_hi:[1,0,1]
	v_pk_fma_f32 v[98:99], v[92:93], v[92:93], v[98:99] op_sel_hi:[1,1,0]
	v_mul_f32_e32 v88, v90, v90
	v_mul_f32_e32 v98, v94, v94
	v_pk_fma_f32 v[108:109], v[90:91], v[90:91], v[88:89] op_sel_hi:[1,1,0]
	v_mul_f32_e32 v88, v102, v102
	v_pk_fma_f32 v[104:105], v[94:95], v[94:95], v[98:99] op_sel_hi:[1,1,0]
	v_pk_fma_f32 v[110:111], v[102:103], v[102:103], v[88:89] op_sel_hi:[1,1,0]
	v_cvt_pk_bf16_f32 v89, v94, v95
	v_lshlrev_b32_e32 v94, 16, v137
	v_and_b32_e32 v95, 0xffff0000, v137
	v_cvt_pk_bf16_f32 v88, v92, v93
	v_lshlrev_b32_e32 v92, 16, v136
	v_and_b32_e32 v93, 0xffff0000, v136
	v_pk_fma_f32 v[86:87], v[94:95], s[28:29], v[86:87] op_sel_hi:[1,0,1]
	v_add_f32_e32 v100, v90, v91
	v_add_f32_e32 v106, v102, v103
	v_cvt_pk_bf16_f32 v90, v90, v91
	v_cvt_pk_bf16_f32 v91, v102, v103
	v_lshlrev_b32_e32 v102, 16, v138
	v_and_b32_e32 v103, 0xffff0000, v138
	v_lshlrev_b32_e32 v112, 16, v139
	v_and_b32_e32 v113, 0xffff0000, v139
	v_pk_fma_f32 v[84:85], v[92:93], s[28:29], v[84:85] op_sel_hi:[1,0,1]
	v_mul_f32_e32 v114, v86, v86
	v_pk_add_f32 v[96:97], v[96:97], v[96:97] op_sel:[0,1] op_sel_hi:[1,0]
	v_mul_f32_e32 v101, v84, v84
	v_mul_f32_e32 v107, v85, v85
	v_mul_f32_e32 v165, v87, v87
	v_pk_fma_f32 v[92:93], v[112:113], s[28:29], v[82:83] op_sel_hi:[1,0,1]
	v_pk_fma_f32 v[94:95], v[102:103], s[28:29], v[80:81] op_sel_hi:[1,0,1]
	v_mov_b32_e32 v98, v84
	v_mov_b32_e32 v104, v85
	v_mov_b32_e32 v108, v86
	v_mov_b32_e32 v110, v87
	v_mov_b32_e32 v97, v114
	v_mul_f32_e32 v81, v94, v94
	v_mul_f32_e32 v83, v95, v95
	v_mul_f32_e32 v103, v92, v92
	v_mul_f32_e32 v113, v93, v93
	v_pk_add_f32 v[98:99], v[98:99], v[104:105]
	v_pk_add_f32 v[104:105], v[108:109], v[110:111]
	v_pk_add_f32 v[100:101], v[100:101], v[106:107]
	v_pk_add_f32 v[96:97], v[96:97], v[164:165]
	v_mov_b32_e32 v80, v94
	v_mov_b32_e32 v82, v95
	v_mov_b32_e32 v102, v92
	v_mov_b32_e32 v112, v93
	v_pk_add_f32 v[98:99], v[98:99], v[104:105]
	v_pk_add_f32 v[96:97], v[100:101], v[96:97]
	v_pk_add_f32 v[80:81], v[80:81], v[82:83]
	v_pk_add_f32 v[82:83], v[102:103], v[112:113]
	v_pk_add_f32 v[96:97], v[98:99], v[96:97]
	v_pk_add_f32 v[80:81], v[80:81], v[82:83]
	v_cvt_pk_bf16_f32 v84, v84, v85
	v_pk_add_f32 v[80:81], v[80:81], v[96:97]
	v_lshl_add_u64 v[96:97], s[44:45], 0, v[186:187]
	v_lshl_add_u64 v[96:97], v[174:175], 1, v[96:97]
	v_cvt_pk_bf16_f32 v85, v86, v87
	v_cvt_pk_bf16_f32 v86, v94, v95
	s_waitcnt lgkmcnt(0)
	v_mov_b32_e32 v82, v80
	v_mov_b32_e32 v83, v81
	s_nop 1
	v_permlane16_swap_b32_e32 v82, v80
	v_permlane16_swap_b32_e32 v83, v81
	s_nop 0
	v_pk_add_f32 v[80:81], v[80:81], v[82:83]
	ds_bpermute_b32 v82, v208, v80
	ds_bpermute_b32 v83, v208, v81
	v_cvt_pk_bf16_f32 v87, v92, v93
	global_store_dwordx4 v[96:97], v[88:91], off
	global_store_dwordx4 v[96:97], v[84:87], off offset:256
	s_and_saveexec_b64 s[36:37], s[4:5]
	s_cbranch_execz .LBB0_1548
	s_waitcnt lgkmcnt(0)
	v_pk_add_f32 v[80:81], v[80:81], v[82:83]
	v_lshlrev_b64 v[82:83], 7, v[184:185]
	v_lshl_add_u64 v[82:83], s[74:75], 0, v[82:83]
	v_lshl_add_u64 v[82:83], s[34:35], 3, v[82:83]
	s_lshl_b32 s16, s76, 3
	v_lshl_add_u64 v[82:83], v[82:83], 0, s[16:17]
	global_store_dwordx2 v[82:83], v[80:81], off
.LBB0_1548:
	s_or_b64 exec, exec, s[36:37]
	v_lshlrev_b32_e32 v80, 16, v132
	v_and_b32_e32 v81, 0xffff0000, v132
	s_waitcnt lgkmcnt(1)
	v_lshlrev_b32_e32 v82, 16, v133
	s_waitcnt lgkmcnt(0)
	v_and_b32_e32 v83, 0xffff0000, v133
	v_pk_fma_f32 v[78:79], v[82:83], s[28:29], v[78:79] op_sel_hi:[1,0,1]
	v_pk_fma_f32 v[76:77], v[80:81], s[28:29], v[76:77] op_sel_hi:[1,0,1]
	v_lshlrev_b32_e32 v84, 16, v134
	v_and_b32_e32 v85, 0xffff0000, v134
	v_lshlrev_b32_e32 v86, 16, v135
	v_and_b32_e32 v87, 0xffff0000, v135
	v_pk_mov_b32 v[80:81], v[76:77], v[78:79] op_sel:[1,0]
	v_mov_b32_e32 v82, v76
	v_mov_b32_e32 v83, v79
	v_pk_add_f32 v[80:81], v[80:81], v[82:83]
	v_mul_f32_e32 v82, v76, v76
	v_pk_fma_f32 v[86:87], v[86:87], s[28:29], v[74:75] op_sel_hi:[1,0,1]
	v_pk_fma_f32 v[74:75], v[84:85], s[28:29], v[72:73] op_sel_hi:[1,0,1]
	v_pk_fma_f32 v[82:83], v[76:77], v[76:77], v[82:83] op_sel_hi:[1,1,0]
	v_mul_f32_e32 v72, v74, v74
	v_mul_f32_e32 v82, v78, v78
	v_pk_fma_f32 v[92:93], v[74:75], v[74:75], v[72:73] op_sel_hi:[1,1,0]
	v_mul_f32_e32 v72, v86, v86
	v_pk_fma_f32 v[88:89], v[78:79], v[78:79], v[82:83] op_sel_hi:[1,1,0]
	v_pk_fma_f32 v[94:95], v[86:87], v[86:87], v[72:73] op_sel_hi:[1,1,0]
	v_cvt_pk_bf16_f32 v73, v78, v79
	v_lshlrev_b32_e32 v78, 16, v129
	v_and_b32_e32 v79, 0xffff0000, v129
	v_cvt_pk_bf16_f32 v72, v76, v77
	v_lshlrev_b32_e32 v76, 16, v128
	v_and_b32_e32 v77, 0xffff0000, v128
	v_pk_fma_f32 v[70:71], v[78:79], s[28:29], v[70:71] op_sel_hi:[1,0,1]
	v_add_f32_e32 v84, v74, v75
	v_add_f32_e32 v90, v86, v87
	v_cvt_pk_bf16_f32 v74, v74, v75
	v_cvt_pk_bf16_f32 v75, v86, v87
	v_lshlrev_b32_e32 v86, 16, v130
	v_and_b32_e32 v87, 0xffff0000, v130
	v_lshlrev_b32_e32 v96, 16, v131
	v_and_b32_e32 v97, 0xffff0000, v131
	v_pk_fma_f32 v[68:69], v[76:77], s[28:29], v[68:69] op_sel_hi:[1,0,1]
	v_mul_f32_e32 v98, v70, v70
	v_pk_add_f32 v[80:81], v[80:81], v[80:81] op_sel:[0,1] op_sel_hi:[1,0]
	v_mul_f32_e32 v85, v68, v68
	v_mul_f32_e32 v91, v69, v69
	v_mul_f32_e32 v165, v71, v71
	v_pk_fma_f32 v[76:77], v[96:97], s[28:29], v[66:67] op_sel_hi:[1,0,1]
	v_pk_fma_f32 v[78:79], v[86:87], s[28:29], v[64:65] op_sel_hi:[1,0,1]
	v_mov_b32_e32 v82, v68
	v_mov_b32_e32 v88, v69
	v_mov_b32_e32 v92, v70
	v_mov_b32_e32 v94, v71
	v_mov_b32_e32 v81, v98
	v_mul_f32_e32 v65, v78, v78
	v_mul_f32_e32 v67, v79, v79
	v_mul_f32_e32 v87, v76, v76
	v_mul_f32_e32 v97, v77, v77
	v_pk_add_f32 v[82:83], v[82:83], v[88:89]
	v_pk_add_f32 v[88:89], v[92:93], v[94:95]
	v_pk_add_f32 v[84:85], v[84:85], v[90:91]
	v_pk_add_f32 v[80:81], v[80:81], v[164:165]
	v_mov_b32_e32 v64, v78
	v_mov_b32_e32 v66, v79
	v_mov_b32_e32 v86, v76
	v_mov_b32_e32 v96, v77
	v_pk_add_f32 v[82:83], v[82:83], v[88:89]
	v_pk_add_f32 v[80:81], v[84:85], v[80:81]
	v_pk_add_f32 v[64:65], v[64:65], v[66:67]
	v_pk_add_f32 v[66:67], v[86:87], v[96:97]
	v_pk_add_f32 v[80:81], v[82:83], v[80:81]
	v_pk_add_f32 v[64:65], v[64:65], v[66:67]
	v_cvt_pk_bf16_f32 v68, v68, v69
	v_pk_add_f32 v[64:65], v[64:65], v[80:81]
	v_lshl_add_u64 v[80:81], s[44:45], 0, v[182:183]
	v_lshl_add_u64 v[80:81], v[174:175], 1, v[80:81]
	v_cvt_pk_bf16_f32 v69, v70, v71
	v_cvt_pk_bf16_f32 v70, v78, v79
	s_waitcnt lgkmcnt(0)
	v_mov_b32_e32 v66, v64
	v_mov_b32_e32 v67, v65
	s_nop 1
	v_permlane16_swap_b32_e32 v66, v64
	v_permlane16_swap_b32_e32 v67, v65
	s_nop 0
	v_pk_add_f32 v[64:65], v[64:65], v[66:67]
	ds_bpermute_b32 v66, v208, v64
	ds_bpermute_b32 v67, v208, v65
	v_cvt_pk_bf16_f32 v71, v76, v77
	global_store_dwordx4 v[80:81], v[72:75], off
	global_store_dwordx4 v[80:81], v[68:71], off offset:256
	s_and_saveexec_b64 s[36:37], s[4:5]
	s_cbranch_execz .LBB0_1550
	s_waitcnt lgkmcnt(0)
	v_pk_add_f32 v[64:65], v[64:65], v[66:67]
	v_lshlrev_b64 v[66:67], 7, v[180:181]
	v_lshl_add_u64 v[66:67], s[74:75], 0, v[66:67]
	v_lshl_add_u64 v[66:67], s[34:35], 3, v[66:67]
	s_lshl_b32 s16, s76, 3
	v_lshl_add_u64 v[66:67], v[66:67], 0, s[16:17]
	global_store_dwordx2 v[66:67], v[64:65], off

.LBB0_1552:
	s_or_b64 exec, exec, s[36:37]
	s_waitcnt vmcnt(7)
	v_lshlrev_b32_e32 v48, 16, v84
	v_and_b32_e32 v49, 0xffff0000, v84
	s_waitcnt lgkmcnt(1)
	v_lshlrev_b32_e32 v50, 16, v85
	s_waitcnt lgkmcnt(0)
	v_and_b32_e32 v51, 0xffff0000, v85
	v_pk_fma_f32 v[46:47], v[50:51], s[28:29], v[46:47] op_sel_hi:[1,0,1]
	v_pk_fma_f32 v[44:45], v[48:49], s[28:29], v[44:45] op_sel_hi:[1,0,1]
	v_lshlrev_b32_e32 v52, 16, v86
	v_and_b32_e32 v53, 0xffff0000, v86
	v_lshlrev_b32_e32 v54, 16, v87
	v_and_b32_e32 v55, 0xffff0000, v87
	v_pk_mov_b32 v[48:49], v[44:45], v[46:47] op_sel:[1,0]
	v_mov_b32_e32 v50, v44
	v_mov_b32_e32 v51, v47
	v_pk_add_f32 v[48:49], v[48:49], v[50:51]
	v_mul_f32_e32 v50, v44, v44
	v_pk_fma_f32 v[54:55], v[54:55], s[28:29], v[42:43] op_sel_hi:[1,0,1]
	v_pk_fma_f32 v[42:43], v[52:53], s[28:29], v[40:41] op_sel_hi:[1,0,1]
	v_pk_fma_f32 v[50:51], v[44:45], v[44:45], v[50:51] op_sel_hi:[1,1,0]
	v_mul_f32_e32 v40, v42, v42
	v_mul_f32_e32 v50, v46, v46
	v_pk_fma_f32 v[60:61], v[42:43], v[42:43], v[40:41] op_sel_hi:[1,1,0]
	v_mul_f32_e32 v40, v54, v54
	v_pk_fma_f32 v[56:57], v[46:47], v[46:47], v[50:51] op_sel_hi:[1,1,0]
	v_pk_fma_f32 v[62:63], v[54:55], v[54:55], v[40:41] op_sel_hi:[1,1,0]
	v_cvt_pk_bf16_f32 v41, v46, v47
	s_waitcnt vmcnt(6)
	v_lshlrev_b32_e32 v46, 16, v81
	v_and_b32_e32 v47, 0xffff0000, v81
	v_cvt_pk_bf16_f32 v40, v44, v45
	v_lshlrev_b32_e32 v44, 16, v80
	v_and_b32_e32 v45, 0xffff0000, v80
	v_pk_fma_f32 v[38:39], v[46:47], s[28:29], v[38:39] op_sel_hi:[1,0,1]
	v_add_f32_e32 v52, v42, v43
	v_add_f32_e32 v58, v54, v55
	v_cvt_pk_bf16_f32 v42, v42, v43
	v_cvt_pk_bf16_f32 v43, v54, v55
	v_lshlrev_b32_e32 v54, 16, v82
	v_and_b32_e32 v55, 0xffff0000, v82
	v_lshlrev_b32_e32 v80, 16, v83
	v_and_b32_e32 v81, 0xffff0000, v83
	v_pk_fma_f32 v[36:37], v[44:45], s[28:29], v[36:37] op_sel_hi:[1,0,1]
	v_mul_f32_e32 v82, v38, v38
	v_pk_add_f32 v[48:49], v[48:49], v[48:49] op_sel:[0,1] op_sel_hi:[1,0]
	v_mul_f32_e32 v53, v36, v36
	v_mul_f32_e32 v59, v37, v37
	v_mul_f32_e32 v165, v39, v39
	v_pk_fma_f32 v[44:45], v[80:81], s[28:29], v[34:35] op_sel_hi:[1,0,1]
	v_pk_fma_f32 v[46:47], v[54:55], s[28:29], v[32:33] op_sel_hi:[1,0,1]
	v_mov_b32_e32 v50, v36
	v_mov_b32_e32 v56, v37
	v_mov_b32_e32 v60, v38
	v_mov_b32_e32 v62, v39
	v_mov_b32_e32 v49, v82
	v_mul_f32_e32 v33, v46, v46
	v_mul_f32_e32 v35, v47, v47
	v_mul_f32_e32 v55, v44, v44
	v_mul_f32_e32 v81, v45, v45
	v_pk_add_f32 v[50:51], v[50:51], v[56:57]
	v_pk_add_f32 v[56:57], v[60:61], v[62:63]
	v_pk_add_f32 v[52:53], v[52:53], v[58:59]
	v_pk_add_f32 v[48:49], v[48:49], v[164:165]
	v_mov_b32_e32 v32, v46
	v_mov_b32_e32 v34, v47
	v_mov_b32_e32 v54, v44
	v_mov_b32_e32 v80, v45
	v_pk_add_f32 v[50:51], v[50:51], v[56:57]
	v_pk_add_f32 v[48:49], v[52:53], v[48:49]
	v_pk_add_f32 v[32:33], v[32:33], v[34:35]
	v_pk_add_f32 v[34:35], v[54:55], v[80:81]
	v_pk_add_f32 v[48:49], v[50:51], v[48:49]
	v_pk_add_f32 v[32:33], v[32:33], v[34:35]
	v_cvt_pk_bf16_f32 v36, v36, v37
	v_pk_add_f32 v[32:33], v[32:33], v[48:49]
	v_lshl_add_u64 v[48:49], s[44:45], 0, v[98:99]
	v_lshl_add_u64 v[48:49], v[174:175], 1, v[48:49]
	v_cvt_pk_bf16_f32 v37, v38, v39
	v_cvt_pk_bf16_f32 v38, v46, v47
	s_waitcnt lgkmcnt(0)
	v_mov_b32_e32 v34, v32
	v_mov_b32_e32 v35, v33
	s_nop 1
	v_permlane16_swap_b32_e32 v34, v32
	v_permlane16_swap_b32_e32 v35, v33
	s_nop 0
	v_pk_add_f32 v[32:33], v[32:33], v[34:35]
	ds_bpermute_b32 v34, v208, v32
	ds_bpermute_b32 v35, v208, v33
	v_cvt_pk_bf16_f32 v39, v44, v45
	global_store_dwordx4 v[48:49], v[40:43], off
	global_store_dwordx4 v[48:49], v[36:39], off offset:256
	s_and_saveexec_b64 s[36:37], s[4:5]
	s_cbranch_execz .LBB0_1554
	s_waitcnt lgkmcnt(0)
	v_pk_add_f32 v[32:33], v[32:33], v[34:35]
	v_lshlrev_b64 v[34:35], 7, v[96:97]
	v_lshl_add_u64 v[34:35], s[74:75], 0, v[34:35]
	v_lshl_add_u64 v[34:35], s[34:35], 3, v[34:35]
	s_lshl_b32 s16, s76, 3
	v_lshl_add_u64 v[34:35], v[34:35], 0, s[16:17]
	global_store_dwordx2 v[34:35], v[32:33], off
.LBB0_1554:
	s_or_b64 exec, exec, s[36:37]
	s_waitcnt vmcnt(7)
	v_lshlrev_b32_e32 v32, 16, v76
	v_and_b32_e32 v33, 0xffff0000, v76
	s_waitcnt lgkmcnt(1)
	v_lshlrev_b32_e32 v34, 16, v77
	s_waitcnt lgkmcnt(0)
	v_and_b32_e32 v35, 0xffff0000, v77
	v_pk_fma_f32 v[30:31], v[34:35], s[28:29], v[30:31] op_sel_hi:[1,0,1]
	v_pk_fma_f32 v[28:29], v[32:33], s[28:29], v[28:29] op_sel_hi:[1,0,1]
	v_lshlrev_b32_e32 v36, 16, v78
	v_and_b32_e32 v37, 0xffff0000, v78
	v_lshlrev_b32_e32 v38, 16, v79
	v_and_b32_e32 v39, 0xffff0000, v79
	v_pk_mov_b32 v[32:33], v[28:29], v[30:31] op_sel:[1,0]
	v_mov_b32_e32 v34, v28
	v_mov_b32_e32 v35, v31
	v_pk_add_f32 v[32:33], v[32:33], v[34:35]
	v_mul_f32_e32 v34, v28, v28
	v_pk_fma_f32 v[38:39], v[38:39], s[28:29], v[26:27] op_sel_hi:[1,0,1]
	v_pk_fma_f32 v[26:27], v[36:37], s[28:29], v[24:25] op_sel_hi:[1,0,1]
	v_pk_fma_f32 v[34:35], v[28:29], v[28:29], v[34:35] op_sel_hi:[1,1,0]
	v_mul_f32_e32 v24, v26, v26
	v_mul_f32_e32 v34, v30, v30
	v_pk_fma_f32 v[44:45], v[26:27], v[26:27], v[24:25] op_sel_hi:[1,1,0]
	v_mul_f32_e32 v24, v38, v38
	v_pk_fma_f32 v[40:41], v[30:31], v[30:31], v[34:35] op_sel_hi:[1,1,0]
	v_pk_fma_f32 v[46:47], v[38:39], v[38:39], v[24:25] op_sel_hi:[1,1,0]
	v_cvt_pk_bf16_f32 v25, v30, v31
	s_waitcnt vmcnt(6)
	v_lshlrev_b32_e32 v30, 16, v73
	v_and_b32_e32 v31, 0xffff0000, v73
	v_cvt_pk_bf16_f32 v24, v28, v29
	v_lshlrev_b32_e32 v28, 16, v72
	v_and_b32_e32 v29, 0xffff0000, v72
	v_pk_fma_f32 v[22:23], v[30:31], s[28:29], v[22:23] op_sel_hi:[1,0,1]
	v_add_f32_e32 v36, v26, v27
	v_add_f32_e32 v42, v38, v39
	v_cvt_pk_bf16_f32 v26, v26, v27
	v_cvt_pk_bf16_f32 v27, v38, v39
	v_lshlrev_b32_e32 v38, 16, v74
	v_and_b32_e32 v39, 0xffff0000, v74
	v_lshlrev_b32_e32 v48, 16, v75
	v_and_b32_e32 v49, 0xffff0000, v75
	v_pk_fma_f32 v[20:21], v[28:29], s[28:29], v[20:21] op_sel_hi:[1,0,1]
	v_mul_f32_e32 v50, v22, v22
	v_pk_add_f32 v[32:33], v[32:33], v[32:33] op_sel:[0,1] op_sel_hi:[1,0]
	v_mul_f32_e32 v37, v20, v20
	v_mul_f32_e32 v43, v21, v21
	v_mul_f32_e32 v165, v23, v23
	v_pk_fma_f32 v[28:29], v[48:49], s[28:29], v[18:19] op_sel_hi:[1,0,1]
	v_pk_fma_f32 v[30:31], v[38:39], s[28:29], v[16:17] op_sel_hi:[1,0,1]
	v_mov_b32_e32 v34, v20
	v_mov_b32_e32 v40, v21
	v_mov_b32_e32 v44, v22
	v_mov_b32_e32 v46, v23
	v_mov_b32_e32 v33, v50
	v_mul_f32_e32 v17, v30, v30
	v_mul_f32_e32 v19, v31, v31
	v_mul_f32_e32 v39, v28, v28
	v_mul_f32_e32 v49, v29, v29
	v_pk_add_f32 v[34:35], v[34:35], v[40:41]
	v_pk_add_f32 v[40:41], v[44:45], v[46:47]
	v_pk_add_f32 v[36:37], v[36:37], v[42:43]
	v_pk_add_f32 v[32:33], v[32:33], v[164:165]
	v_mov_b32_e32 v16, v30
	v_mov_b32_e32 v18, v31
	v_mov_b32_e32 v38, v28
	v_mov_b32_e32 v48, v29
	v_pk_add_f32 v[34:35], v[34:35], v[40:41]
	v_pk_add_f32 v[32:33], v[36:37], v[32:33]
	v_pk_add_f32 v[16:17], v[16:17], v[18:19]
	v_pk_add_f32 v[18:19], v[38:39], v[48:49]
	v_pk_add_f32 v[32:33], v[34:35], v[32:33]
	v_pk_add_f32 v[16:17], v[16:17], v[18:19]
	v_cvt_pk_bf16_f32 v20, v20, v21
	v_pk_add_f32 v[16:17], v[16:17], v[32:33]
	v_lshl_add_u64 v[32:33], s[44:45], 0, v[94:95]
	v_lshl_add_u64 v[32:33], v[174:175], 1, v[32:33]
	v_cvt_pk_bf16_f32 v21, v22, v23
	v_cvt_pk_bf16_f32 v22, v30, v31
	s_waitcnt lgkmcnt(0)
	v_mov_b32_e32 v18, v16
	v_mov_b32_e32 v19, v17
	s_nop 1
	v_permlane16_swap_b32_e32 v18, v16
	v_permlane16_swap_b32_e32 v19, v17
	s_nop 0
	v_pk_add_f32 v[16:17], v[16:17], v[18:19]
	ds_bpermute_b32 v18, v208, v16
	ds_bpermute_b32 v19, v208, v17
	v_cvt_pk_bf16_f32 v23, v28, v29
	global_store_dwordx4 v[32:33], v[24:27], off
	global_store_dwordx4 v[32:33], v[20:23], off offset:256
	s_and_saveexec_b64 s[36:37], s[4:5]
	s_cbranch_execz .LBB0_1556
	s_waitcnt lgkmcnt(0)
	v_pk_add_f32 v[16:17], v[16:17], v[18:19]
	v_lshlrev_b64 v[18:19], 7, v[92:93]
	v_lshl_add_u64 v[18:19], s[74:75], 0, v[18:19]
	v_lshl_add_u64 v[18:19], s[34:35], 3, v[18:19]
	s_lshl_b32 s16, s76, 3
	v_lshl_add_u64 v[18:19], v[18:19], 0, s[16:17]
	global_store_dwordx2 v[18:19], v[16:17], off
.LBB0_1556:
	s_or_b64 exec, exec, s[36:37]
	s_waitcnt vmcnt(7)
	v_lshlrev_b32_e32 v16, 16, v68
	v_and_b32_e32 v17, 0xffff0000, v68
	s_waitcnt lgkmcnt(1)
	v_lshlrev_b32_e32 v18, 16, v69
	s_waitcnt lgkmcnt(0)
	v_and_b32_e32 v19, 0xffff0000, v69
	v_pk_fma_f32 v[14:15], v[18:19], s[28:29], v[14:15] op_sel_hi:[1,0,1]
	v_pk_fma_f32 v[12:13], v[16:17], s[28:29], v[12:13] op_sel_hi:[1,0,1]
	v_lshlrev_b32_e32 v20, 16, v70
	v_and_b32_e32 v21, 0xffff0000, v70
	v_lshlrev_b32_e32 v22, 16, v71
	v_and_b32_e32 v23, 0xffff0000, v71
	v_pk_mov_b32 v[16:17], v[12:13], v[14:15] op_sel:[1,0]
	v_mov_b32_e32 v18, v12
	v_mov_b32_e32 v19, v15
	v_pk_add_f32 v[16:17], v[16:17], v[18:19]
	v_mul_f32_e32 v18, v12, v12
	v_pk_fma_f32 v[22:23], v[22:23], s[28:29], v[10:11] op_sel_hi:[1,0,1]
	v_pk_fma_f32 v[10:11], v[20:21], s[28:29], v[8:9] op_sel_hi:[1,0,1]
	v_pk_fma_f32 v[18:19], v[12:13], v[12:13], v[18:19] op_sel_hi:[1,1,0]
	v_mul_f32_e32 v8, v10, v10
	v_mul_f32_e32 v18, v14, v14
	v_pk_fma_f32 v[28:29], v[10:11], v[10:11], v[8:9] op_sel_hi:[1,1,0]
	v_mul_f32_e32 v8, v22, v22
	v_pk_fma_f32 v[24:25], v[14:15], v[14:15], v[18:19] op_sel_hi:[1,1,0]
	v_pk_fma_f32 v[30:31], v[22:23], v[22:23], v[8:9] op_sel_hi:[1,1,0]
	v_cvt_pk_bf16_f32 v9, v14, v15
	s_waitcnt vmcnt(6)
	v_lshlrev_b32_e32 v14, 16, v65
	v_and_b32_e32 v15, 0xffff0000, v65
	v_cvt_pk_bf16_f32 v8, v12, v13
	v_lshlrev_b32_e32 v12, 16, v64
	v_and_b32_e32 v13, 0xffff0000, v64
	v_pk_fma_f32 v[6:7], v[14:15], s[28:29], v[6:7] op_sel_hi:[1,0,1]
	v_add_f32_e32 v20, v10, v11
	v_add_f32_e32 v26, v22, v23
	v_cvt_pk_bf16_f32 v10, v10, v11
	v_cvt_pk_bf16_f32 v11, v22, v23
	v_lshlrev_b32_e32 v22, 16, v66
	v_and_b32_e32 v23, 0xffff0000, v66
	v_lshlrev_b32_e32 v32, 16, v67
	v_and_b32_e32 v33, 0xffff0000, v67
	v_pk_fma_f32 v[4:5], v[12:13], s[28:29], v[4:5] op_sel_hi:[1,0,1]
	v_mul_f32_e32 v34, v6, v6
	v_pk_add_f32 v[16:17], v[16:17], v[16:17] op_sel:[0,1] op_sel_hi:[1,0]
	v_mul_f32_e32 v21, v4, v4
	v_mul_f32_e32 v27, v5, v5
	v_mul_f32_e32 v165, v7, v7
	v_pk_fma_f32 v[12:13], v[32:33], s[28:29], v[2:3] op_sel_hi:[1,0,1]
	v_pk_fma_f32 v[14:15], v[22:23], s[28:29], v[0:1] op_sel_hi:[1,0,1]
	v_mov_b32_e32 v18, v4
	v_mov_b32_e32 v24, v5
	v_mov_b32_e32 v28, v6
	v_mov_b32_e32 v30, v7
	v_mov_b32_e32 v17, v34
	v_mul_f32_e32 v1, v14, v14
	v_mul_f32_e32 v3, v15, v15
	v_mul_f32_e32 v23, v12, v12
	v_mul_f32_e32 v33, v13, v13
	v_pk_add_f32 v[18:19], v[18:19], v[24:25]
	v_pk_add_f32 v[24:25], v[28:29], v[30:31]
	v_pk_add_f32 v[20:21], v[20:21], v[26:27]
	v_pk_add_f32 v[16:17], v[16:17], v[164:165]
	v_mov_b32_e32 v0, v14
	v_mov_b32_e32 v2, v15
	v_mov_b32_e32 v22, v12
	v_mov_b32_e32 v32, v13
	v_pk_add_f32 v[18:19], v[18:19], v[24:25]
	v_pk_add_f32 v[16:17], v[20:21], v[16:17]
	v_pk_add_f32 v[0:1], v[0:1], v[2:3]
	v_pk_add_f32 v[2:3], v[22:23], v[32:33]
	v_pk_add_f32 v[16:17], v[18:19], v[16:17]
	v_pk_add_f32 v[0:1], v[0:1], v[2:3]
	v_cvt_pk_bf16_f32 v4, v4, v5
	v_pk_add_f32 v[0:1], v[0:1], v[16:17]
	v_lshl_add_u64 v[16:17], s[44:45], 0, v[90:91]
	v_lshl_add_u64 v[16:17], v[174:175], 1, v[16:17]
	v_cvt_pk_bf16_f32 v5, v6, v7
	v_cvt_pk_bf16_f32 v6, v14, v15
	s_waitcnt lgkmcnt(0)
	v_mov_b32_e32 v2, v0
	v_mov_b32_e32 v3, v1
	s_nop 1
	v_permlane16_swap_b32_e32 v2, v0
	v_permlane16_swap_b32_e32 v3, v1
	s_nop 0
	v_pk_add_f32 v[0:1], v[0:1], v[2:3]
	ds_bpermute_b32 v2, v208, v0
	ds_bpermute_b32 v3, v208, v1
	v_cvt_pk_bf16_f32 v7, v12, v13
	global_store_dwordx4 v[16:17], v[8:11], off
	global_store_dwordx4 v[16:17], v[4:7], off offset:256
	s_and_saveexec_b64 s[36:37], s[4:5]
	s_cbranch_execz .LBB0_1558
	s_waitcnt lgkmcnt(0)
	v_pk_add_f32 v[0:1], v[0:1], v[2:3]
	v_lshlrev_b64 v[2:3], 7, v[88:89]
	v_lshl_add_u64 v[2:3], s[74:75], 0, v[2:3]
	v_lshl_add_u64 v[2:3], s[34:35], 3, v[2:3]
	s_lshl_b32 s16, s76, 3
	v_lshl_add_u64 v[2:3], v[2:3], 0, s[16:17]
	global_store_dwordx2 v[2:3], v[0:1], off

; DI void row_stats(const f32x2v* st, size_t row, int fq, float& mu, float& rstd) {
;     const f32x4 a = *(const f32x4*)(st + row * 16 + 4 * fq), b = *(const f32x4*)(st + row * 16 + 4 * fq + 2);
;     float s1 = (a[0] + a[2]) + (b[0] + b[2]), s2 = (a[1] + a[3]) + (b[1] + b[3]);
;     s1 += __shfl_xor(s1, 16); s1 += __shfl_xor(s1, 32); s2 += __shfl_xor(s2, 16); s2 += __shfl_xor(s2, 32);
;     mu = s1 * (1.0f / 1024.0f); const float var = fmaxf(s2 * (1.0f / 1024.0f) - mu * mu, 0.f); rstd = rsqrtf(var + LN_EPS);
.LBB0_1642:
	v_and_b32_e32 v161, 64, v205
	v_xor_b32_e32 v160, 16, v205
	v_add_u32_e32 v161, 64, v161
	v_cmp_lt_i32_e32 vcc, v160, v161
	s_ashr_i32 s31, s30, 31
	s_lshl_b64 s[0:1], s[30:31], 8
	v_cndmask_b32_e32 v160, v205, v160, vcc
	v_lshl_or_b32 v76, s95, 8, v193
	v_lshlrev_b32_e32 v215, 2, v160
	v_xor_b32_e32 v160, 32, v205
	v_lshl_add_u64 v[206:207], s[0:1], 0, v[176:177]
	v_ashrrev_i32_e32 v77, 31, v76
	v_cmp_lt_i32_e32 vcc, v160, v161
	v_lshlrev_b64 v[76:77], 2, v[76:77]
	v_lshlrev_b64 v[162:163], 7, v[206:207]
	v_cndmask_b32_e32 v160, v205, v160, vcc
	v_lshl_add_u64 v[80:81], s[56:57], 0, v[76:77]
	v_lshl_add_u64 v[104:105], s[16:17], 0, v[76:77]
	v_lshlrev_b32_e32 v211, 2, v160
	v_lshl_add_u64 v[160:161], v[178:179], 0, v[162:163]
	global_load_dwordx4 v[88:91], v[80:81], off offset:16
	global_load_dwordx4 v[112:115], v[80:81], off
	global_load_dwordx4 v[92:95], v[104:105], off offset:16
	global_load_dwordx4 v[116:119], v[104:105], off
	global_load_dwordx4 v[76:79], v[80:81], off offset:528
	global_load_dwordx4 v[100:103], v[80:81], off offset:512
	s_nop 0
	global_load_dwordx4 v[80:83], v[104:105], off offset:528
	s_nop 0
	global_load_dwordx4 v[104:107], v[104:105], off offset:512
	s_nop 0
	global_load_dwordx4 v[164:167], v[160:161], off offset:16
	global_load_dwordx4 v[216:219], v[160:161], off
	s_mov_b64 s[0:1], 0x4000
	s_mov_b64 s[30:31], 0x5000
	s_waitcnt vmcnt(0)
	v_mov_b32_e32 v187, v164
	v_mov_b32_e32 v186, v216
	v_mov_b32_e32 v190, v218
	v_mov_b32_e32 v191, v166
	v_pk_add_f32 v[186:187], v[186:187], v[190:191]
	v_add_f32_e32 v164, v217, v219
	v_add_f32_e32 v166, v165, v167
	v_mov_b32_e32 v165, v186
	v_mov_b32_e32 v167, v187
	v_pk_add_f32 v[164:165], v[164:165], v[166:167]
	s_waitcnt lgkmcnt(0)
	v_mov_b32_e32 v167, v165
	v_mov_b32_e32 v166, v164
	s_nop 1
	v_permlane16_swap_b32_e32 v167, v165
	v_permlane16_swap_b32_e32 v166, v164
	s_nop 0
	v_pk_add_f32 v[164:165], v[164:165], v[166:167]
	s_waitcnt lgkmcnt(0)
	v_mov_b32_e32 v167, v165
	v_mov_b32_e32 v166, v164
	s_nop 1
	v_permlane32_swap_b32_e32 v167, v165
	v_permlane32_swap_b32_e32 v166, v164
	s_nop 0
	v_pk_add_f32 v[164:165], v[164:165], v[166:167]
	s_nop 0
	v_pk_mul_f32 v[216:217], v[164:165], s[26:27] op_sel_hi:[1,0]
	s_nop 0
	v_fma_f32 v164, -v217, v217, v216
	v_max_f32_e32 v164, 0, v164
	v_add_f32_e32 v164, 0x3727c5ac, v164
	v_cmp_gt_f32_e32 vcc, s91, v164
	v_mul_f32_e32 v165, 0x4b800000, v164
	v_pk_fma_f32 v[156:157], v[112:113], v[216:217], v[156:157] op_sel:[0,1,0] neg_lo:[1,0,0] neg_hi:[1,0,0]
	v_cndmask_b32_e32 v164, v164, v165, vcc
	v_rsq_f32_e32 v164, v164
	v_pk_fma_f32 v[152:153], v[100:101], v[216:217], v[152:153] op_sel:[0,1,0] neg_lo:[1,0,0] neg_hi:[1,0,0]
	v_pk_fma_f32 v[154:155], v[102:103], v[216:217], v[154:155] op_sel:[0,1,0] neg_lo:[1,0,0] neg_hi:[1,0,0]
	v_pk_fma_f32 v[148:149], v[88:89], v[216:217], v[148:149] op_sel:[0,1,0] neg_lo:[1,0,0] neg_hi:[1,0,0]
	v_mul_f32_e32 v165, 0x45800000, v164
	v_cndmask_b32_e32 v218, v164, v165, vcc
	v_or_b32_e32 v164, 0x800, v162
	v_mov_b32_e32 v165, v163
	v_lshl_add_u64 v[186:187], v[178:179], 0, v[164:165]
	global_load_dwordx4 v[164:167], v[186:187], off offset:16
	global_load_dwordx4 v[220:223], v[186:187], off
	v_pk_fma_f32 v[156:157], v[156:157], v[218:219], v[116:117] op_sel_hi:[1,0,1]
	v_pk_fma_f32 v[152:153], v[152:153], v[218:219], v[104:105] op_sel_hi:[1,0,1]
	v_pk_fma_f32 v[154:155], v[154:155], v[218:219], v[106:107] op_sel_hi:[1,0,1]
	v_pk_fma_f32 v[148:149], v[148:149], v[218:219], v[92:93] op_sel_hi:[1,0,1]
	v_pk_fma_f32 v[144:145], v[76:77], v[216:217], v[144:145] op_sel:[0,1,0] neg_lo:[1,0,0] neg_hi:[1,0,0]
	v_pk_fma_f32 v[146:147], v[78:79], v[216:217], v[146:147] op_sel:[0,1,0] neg_lo:[1,0,0] neg_hi:[1,0,0]
	v_pk_fma_f32 v[144:145], v[144:145], v[218:219], v[80:81] op_sel_hi:[1,0,1]
	v_pk_fma_f32 v[146:147], v[146:147], v[218:219], v[82:83] op_sel_hi:[1,0,1]
	s_waitcnt vmcnt(1)
	v_mov_b32_e32 v187, v164
	s_waitcnt vmcnt(0)
	v_mov_b32_e32 v186, v220
	v_mov_b32_e32 v190, v222
	v_mov_b32_e32 v191, v166
	v_pk_add_f32 v[186:187], v[186:187], v[190:191]
	v_add_f32_e32 v164, v221, v223
	v_add_f32_e32 v166, v165, v167
	v_mov_b32_e32 v165, v186
	v_mov_b32_e32 v167, v187
	v_pk_add_f32 v[164:165], v[164:165], v[166:167]
	s_waitcnt lgkmcnt(0)
	v_mov_b32_e32 v167, v165
	v_mov_b32_e32 v166, v164
	s_nop 1
	v_permlane16_swap_b32_e32 v167, v165
	v_permlane16_swap_b32_e32 v166, v164
	s_nop 0
	v_pk_add_f32 v[164:165], v[164:165], v[166:167]
	s_waitcnt lgkmcnt(0)
	v_mov_b32_e32 v167, v165
	v_mov_b32_e32 v166, v164
	s_nop 1
	v_permlane32_swap_b32_e32 v167, v165
	v_permlane32_swap_b32_e32 v166, v164
	s_nop 0
	v_pk_add_f32 v[164:165], v[164:165], v[166:167]
	s_nop 0
	v_pk_mul_f32 v[212:213], v[164:165], s[26:27] op_sel_hi:[1,0]
	s_nop 0
	v_fma_f32 v164, -v213, v213, v212
	v_max_f32_e32 v164, 0, v164
	v_add_f32_e32 v164, 0x3727c5ac, v164
	v_cmp_gt_f32_e32 vcc, s91, v164
	v_mul_f32_e32 v165, 0x4b800000, v164
	v_pk_fma_f32 v[140:141], v[112:113], v[212:213], v[140:141] op_sel:[0,1,0] neg_lo:[1,0,0] neg_hi:[1,0,0]
	v_cndmask_b32_e32 v164, v164, v165, vcc
	v_rsq_f32_e32 v164, v164
	v_pk_fma_f32 v[136:137], v[100:101], v[212:213], v[136:137] op_sel:[0,1,0] neg_lo:[1,0,0] neg_hi:[1,0,0]
	v_pk_fma_f32 v[138:139], v[102:103], v[212:213], v[138:139] op_sel:[0,1,0] neg_lo:[1,0,0] neg_hi:[1,0,0]
	v_pk_fma_f32 v[132:133], v[88:89], v[212:213], v[132:133] op_sel:[0,1,0] neg_lo:[1,0,0] neg_hi:[1,0,0]
	v_mul_f32_e32 v165, 0x45800000, v164
	v_cndmask_b32_e32 v214, v164, v165, vcc
	v_or_b32_e32 v164, 0x1000, v162
	v_mov_b32_e32 v165, v163
	v_lshl_add_u64 v[186:187], v[178:179], 0, v[164:165]
	global_load_dwordx4 v[164:167], v[186:187], off offset:16
	global_load_dwordx4 v[220:223], v[186:187], off
	v_or_b32_e32 v162, 0x1800, v162
	v_pk_fma_f32 v[140:141], v[140:141], v[214:215], v[116:117] op_sel_hi:[1,0,1]
	v_pk_fma_f32 v[136:137], v[136:137], v[214:215], v[104:105] op_sel_hi:[1,0,1]
	v_pk_fma_f32 v[138:139], v[138:139], v[214:215], v[106:107] op_sel_hi:[1,0,1]
	v_pk_fma_f32 v[132:133], v[132:133], v[214:215], v[92:93] op_sel_hi:[1,0,1]
	v_pk_fma_f32 v[128:129], v[76:77], v[212:213], v[128:129] op_sel:[0,1,0] neg_lo:[1,0,0] neg_hi:[1,0,0]
	v_pk_fma_f32 v[130:131], v[78:79], v[212:213], v[130:131] op_sel:[0,1,0] neg_lo:[1,0,0] neg_hi:[1,0,0]
	v_pk_fma_f32 v[128:129], v[128:129], v[214:215], v[80:81] op_sel_hi:[1,0,1]
	v_pk_fma_f32 v[130:131], v[130:131], v[214:215], v[82:83] op_sel_hi:[1,0,1]
	s_waitcnt vmcnt(1)
; DI void row_stats(const f32x2v* st, size_t row, int fq, float& mu, float& rstd) {
;     const f32x4 a = *(const f32x4*)(st + row * 16 + 4 * fq), b = *(const f32x4*)(st + row * 16 + 4 * fq + 2);
;     float s1 = (a[0] + a[2]) + (b[0] + b[2]), s2 = (a[1] + a[3]) + (b[1] + b[3]);
;     s1 += __shfl_xor(s1, 16); s1 += __shfl_xor(s1, 32); s2 += __shfl_xor(s2, 16); s2 += __shfl_xor(s2, 32);
;     mu = s1 * (1.0f / 1024.0f); const float var = fmaxf(s2 * (1.0f / 1024.0f) - mu * mu, 0.f); rstd = rsqrtf(var + LN_EPS);
	v_mov_b32_e32 v187, v164
	s_waitcnt vmcnt(0)
	v_mov_b32_e32 v186, v220
	v_mov_b32_e32 v190, v222
	v_mov_b32_e32 v191, v166
	v_pk_add_f32 v[186:187], v[186:187], v[190:191]
	v_add_f32_e32 v164, v221, v223
	v_add_f32_e32 v166, v165, v167
	v_mov_b32_e32 v165, v186
	v_mov_b32_e32 v167, v187
	v_pk_add_f32 v[164:165], v[164:165], v[166:167]
	v_lshl_add_u64 v[190:191], v[160:161], 0, s[0:1]
	s_movk_i32 s0, 0x4000
	s_waitcnt lgkmcnt(0)
	v_mov_b32_e32 v167, v165
	v_mov_b32_e32 v166, v164
	s_nop 1
	v_permlane16_swap_b32_e32 v167, v165
	v_permlane16_swap_b32_e32 v166, v164
	s_nop 0
	v_pk_add_f32 v[164:165], v[164:165], v[166:167]
	s_waitcnt lgkmcnt(0)
	v_mov_b32_e32 v167, v165
	v_mov_b32_e32 v166, v164
	s_nop 1
	v_permlane32_swap_b32_e32 v167, v165
	v_permlane32_swap_b32_e32 v166, v164
	s_nop 0
	v_pk_add_f32 v[164:165], v[164:165], v[166:167]
	s_nop 0
	v_pk_mul_f32 v[202:203], v[164:165], s[26:27] op_sel_hi:[1,0]
	v_lshl_add_u64 v[166:167], v[178:179], 0, v[162:163]
	v_fma_f32 v164, -v203, v203, v202
	v_max_f32_e32 v164, 0, v164
	v_add_f32_e32 v164, 0x3727c5ac, v164
	v_cmp_gt_f32_e32 vcc, s91, v164
	v_mul_f32_e32 v165, 0x4b800000, v164
	v_pk_fma_f32 v[124:125], v[112:113], v[202:203], v[124:125] op_sel:[0,1,0] neg_lo:[1,0,0] neg_hi:[1,0,0]
	v_cndmask_b32_e32 v164, v164, v165, vcc
	v_rsq_f32_e32 v164, v164
	v_pk_fma_f32 v[120:121], v[100:101], v[202:203], v[120:121] op_sel:[0,1,0] neg_lo:[1,0,0] neg_hi:[1,0,0]
	v_pk_fma_f32 v[122:123], v[102:103], v[202:203], v[122:123] op_sel:[0,1,0] neg_lo:[1,0,0] neg_hi:[1,0,0]
	v_pk_fma_f32 v[108:109], v[88:89], v[202:203], v[108:109] op_sel:[0,1,0] neg_lo:[1,0,0] neg_hi:[1,0,0]
	v_mul_f32_e32 v165, 0x45800000, v164
	v_cndmask_b32_e32 v204, v164, v165, vcc
	global_load_dwordx4 v[162:165], v[166:167], off offset:16
	global_load_dwordx4 v[220:223], v[166:167], off
	v_pk_fma_f32 v[124:125], v[124:125], v[204:205], v[116:117] op_sel_hi:[1,0,1]
	v_pk_fma_f32 v[120:121], v[120:121], v[204:205], v[104:105] op_sel_hi:[1,0,1]
	v_pk_fma_f32 v[122:123], v[122:123], v[204:205], v[106:107] op_sel_hi:[1,0,1]
	v_pk_fma_f32 v[108:109], v[108:109], v[204:205], v[92:93] op_sel_hi:[1,0,1]
	v_pk_fma_f32 v[96:97], v[76:77], v[202:203], v[96:97] op_sel:[0,1,0] neg_lo:[1,0,0] neg_hi:[1,0,0]
	v_pk_fma_f32 v[98:99], v[78:79], v[202:203], v[98:99] op_sel:[0,1,0] neg_lo:[1,0,0] neg_hi:[1,0,0]
	v_pk_fma_f32 v[96:97], v[96:97], v[204:205], v[80:81] op_sel_hi:[1,0,1]
	v_pk_fma_f32 v[98:99], v[98:99], v[204:205], v[82:83] op_sel_hi:[1,0,1]
	s_waitcnt vmcnt(1)
	v_mov_b32_e32 v167, v162
	s_waitcnt vmcnt(0)
	v_mov_b32_e32 v166, v220
	v_mov_b32_e32 v186, v222
	v_mov_b32_e32 v187, v164
	v_pk_add_f32 v[166:167], v[166:167], v[186:187]
	v_add_f32_e32 v162, v221, v223
	v_add_f32_e32 v164, v163, v165
	v_mov_b32_e32 v163, v166
	v_mov_b32_e32 v165, v167
	v_pk_add_f32 v[162:163], v[162:163], v[164:165]
	s_waitcnt lgkmcnt(0)
	v_mov_b32_e32 v165, v163
	v_mov_b32_e32 v164, v162
	s_nop 1
	v_permlane16_swap_b32_e32 v165, v163
	v_permlane16_swap_b32_e32 v164, v162
	s_nop 0
	v_pk_add_f32 v[162:163], v[162:163], v[164:165]
	s_waitcnt lgkmcnt(0)
	v_mov_b32_e32 v165, v163
	v_mov_b32_e32 v164, v162
	s_nop 1
	v_permlane32_swap_b32_e32 v165, v163
	v_permlane32_swap_b32_e32 v164, v162
	s_nop 0
	v_pk_add_f32 v[162:163], v[162:163], v[164:165]
	s_nop 0
	v_pk_mul_f32 v[186:187], v[162:163], s[26:27] op_sel_hi:[1,0]
	s_nop 0
	v_fma_f32 v162, -v187, v187, v186
	v_max_f32_e32 v162, 0, v162
	v_add_f32_e32 v162, 0x3727c5ac, v162
	v_cmp_gt_f32_e32 vcc, s91, v162
	v_mul_f32_e32 v163, 0x4b800000, v162
	v_pk_fma_f32 v[84:85], v[112:113], v[186:187], v[84:85] op_sel:[0,1,0] neg_lo:[1,0,0] neg_hi:[1,0,0]
	v_cndmask_b32_e32 v162, v162, v163, vcc
	v_rsq_f32_e32 v162, v162
	v_pk_fma_f32 v[72:73], v[100:101], v[186:187], v[72:73] op_sel:[0,1,0] neg_lo:[1,0,0] neg_hi:[1,0,0]
	v_pk_fma_f32 v[74:75], v[102:103], v[186:187], v[74:75] op_sel:[0,1,0] neg_lo:[1,0,0] neg_hi:[1,0,0]
	v_pk_fma_f32 v[68:69], v[88:89], v[186:187], v[68:69] op_sel:[0,1,0] neg_lo:[1,0,0] neg_hi:[1,0,0]
	v_mul_f32_e32 v163, 0x45800000, v162
	v_cndmask_b32_e32 v188, v162, v163, vcc
	v_add_co_u32_e32 v208, vcc, s0, v160
	s_movk_i32 s0, 0x5000
	s_nop 0
	v_addc_co_u32_e32 v209, vcc, 0, v161, vcc
	v_add_co_u32_e32 v162, vcc, s0, v160
	s_mov_b64 s[0:1], 0x4800
	s_nop 0
	v_addc_co_u32_e32 v163, vcc, 0, v161, vcc
	global_load_dwordx4 v[164:167], v[162:163], off offset:-4096
	global_load_dwordx4 v[220:223], v[190:191], off offset:16
	v_pk_fma_f32 v[84:85], v[84:85], v[188:189], v[116:117] op_sel_hi:[1,0,1]
	v_pk_fma_f32 v[72:73], v[72:73], v[188:189], v[104:105] op_sel_hi:[1,0,1]
	v_pk_fma_f32 v[74:75], v[74:75], v[188:189], v[106:107] op_sel_hi:[1,0,1]
	v_pk_fma_f32 v[68:69], v[68:69], v[188:189], v[92:93] op_sel_hi:[1,0,1]
	v_pk_fma_f32 v[64:65], v[76:77], v[186:187], v[64:65] op_sel:[0,1,0] neg_lo:[1,0,0] neg_hi:[1,0,0]
	v_pk_fma_f32 v[66:67], v[78:79], v[186:187], v[66:67] op_sel:[0,1,0] neg_lo:[1,0,0] neg_hi:[1,0,0]
	v_pk_fma_f32 v[64:65], v[64:65], v[188:189], v[80:81] op_sel_hi:[1,0,1]
	v_pk_fma_f32 v[66:67], v[66:67], v[188:189], v[82:83] op_sel_hi:[1,0,1]
	s_waitcnt vmcnt(1)
	v_mov_b32_e32 v190, v164
	s_waitcnt vmcnt(0)
	v_mov_b32_e32 v191, v220
	v_mov_b32_e32 v198, v166
	v_mov_b32_e32 v199, v222
	v_pk_add_f32 v[190:191], v[190:191], v[198:199]
	v_add_f32_e32 v164, v165, v167
	v_add_f32_e32 v166, v221, v223
	v_mov_b32_e32 v165, v190
	v_mov_b32_e32 v167, v191
	v_pk_add_f32 v[164:165], v[164:165], v[166:167]
	v_lshl_add_u64 v[190:191], v[160:161], 0, s[0:1]
	s_waitcnt lgkmcnt(0)
	v_mov_b32_e32 v167, v165
	v_mov_b32_e32 v166, v164
	s_nop 1
	v_permlane16_swap_b32_e32 v167, v165
	v_permlane16_swap_b32_e32 v166, v164
	s_nop 0
	v_pk_add_f32 v[164:165], v[164:165], v[166:167]
	s_waitcnt lgkmcnt(0)
; DI void row_stats(const f32x2v* st, size_t row, int fq, float& mu, float& rstd) {
;     const f32x4 a = *(const f32x4*)(st + row * 16 + 4 * fq), b = *(const f32x4*)(st + row * 16 + 4 * fq + 2);
;     float s1 = (a[0] + a[2]) + (b[0] + b[2]), s2 = (a[1] + a[3]) + (b[1] + b[3]);
;     s1 += __shfl_xor(s1, 16); s1 += __shfl_xor(s1, 32); s2 += __shfl_xor(s2, 16); s2 += __shfl_xor(s2, 32);
;     mu = s1 * (1.0f / 1024.0f); const float var = fmaxf(s2 * (1.0f / 1024.0f) - mu * mu, 0.f); rstd = rsqrtf(var + LN_EPS);
	v_mov_b32_e32 v167, v165
	v_mov_b32_e32 v166, v164
	s_nop 1
	v_permlane32_swap_b32_e32 v167, v165
	v_permlane32_swap_b32_e32 v166, v164
	s_nop 0
	v_pk_add_f32 v[164:165], v[164:165], v[166:167]
	s_nop 0
	v_pk_mul_f32 v[198:199], v[164:165], s[26:27] op_sel_hi:[1,0]
	s_nop 0
	v_fma_f32 v164, -v199, v199, v198
	v_max_f32_e32 v164, 0, v164
	v_add_f32_e32 v164, 0x3727c5ac, v164
	v_cmp_gt_f32_e32 vcc, s91, v164
	v_mul_f32_e32 v165, 0x4b800000, v164
	v_pk_fma_f32 v[60:61], v[112:113], v[198:199], v[60:61] op_sel:[0,1,0] neg_lo:[1,0,0] neg_hi:[1,0,0]
	v_cndmask_b32_e32 v164, v164, v165, vcc
	v_rsq_f32_e32 v164, v164
	v_pk_fma_f32 v[56:57], v[100:101], v[198:199], v[56:57] op_sel:[0,1,0] neg_lo:[1,0,0] neg_hi:[1,0,0]
	v_pk_fma_f32 v[58:59], v[102:103], v[198:199], v[58:59] op_sel:[0,1,0] neg_lo:[1,0,0] neg_hi:[1,0,0]
	v_pk_fma_f32 v[52:53], v[88:89], v[198:199], v[52:53] op_sel:[0,1,0] neg_lo:[1,0,0] neg_hi:[1,0,0]
	v_mul_f32_e32 v165, 0x45800000, v164
	v_cndmask_b32_e32 v200, v164, v165, vcc
	global_load_dwordx4 v[164:167], v[208:209], off offset:2048
	global_load_dwordx4 v[220:223], v[190:191], off offset:16
	v_pk_fma_f32 v[60:61], v[60:61], v[200:201], v[116:117] op_sel_hi:[1,0,1]
	v_pk_fma_f32 v[56:57], v[56:57], v[200:201], v[104:105] op_sel_hi:[1,0,1]
	v_pk_fma_f32 v[58:59], v[58:59], v[200:201], v[106:107] op_sel_hi:[1,0,1]
	v_pk_fma_f32 v[52:53], v[52:53], v[200:201], v[92:93] op_sel_hi:[1,0,1]
	v_pk_fma_f32 v[48:49], v[76:77], v[198:199], v[48:49] op_sel:[0,1,0] neg_lo:[1,0,0] neg_hi:[1,0,0]
	v_pk_fma_f32 v[50:51], v[78:79], v[198:199], v[50:51] op_sel:[0,1,0] neg_lo:[1,0,0] neg_hi:[1,0,0]
	v_pk_fma_f32 v[48:49], v[48:49], v[200:201], v[80:81] op_sel_hi:[1,0,1]
	v_pk_fma_f32 v[50:51], v[50:51], v[200:201], v[82:83] op_sel_hi:[1,0,1]
	s_waitcnt vmcnt(1)
	v_mov_b32_e32 v190, v164
	s_waitcnt vmcnt(0)
	v_mov_b32_e32 v191, v220
	v_mov_b32_e32 v208, v166
	v_mov_b32_e32 v209, v222
	v_pk_add_f32 v[190:191], v[190:191], v[208:209]
	v_add_f32_e32 v164, v165, v167
	v_add_f32_e32 v166, v221, v223
	v_mov_b32_e32 v165, v190
	v_mov_b32_e32 v167, v191
	v_pk_add_f32 v[164:165], v[164:165], v[166:167]
	v_lshl_add_u64 v[208:209], v[160:161], 0, s[30:31]
	s_mov_b64 s[30:31], 0x5800
	s_waitcnt lgkmcnt(0)
	v_mov_b32_e32 v167, v165
	v_mov_b32_e32 v166, v164
	s_nop 1
	v_permlane16_swap_b32_e32 v167, v165
	v_permlane16_swap_b32_e32 v166, v164
	s_nop 0
	v_pk_add_f32 v[164:165], v[164:165], v[166:167]
	s_waitcnt lgkmcnt(0)
	v_mov_b32_e32 v167, v165
	v_mov_b32_e32 v166, v164
	s_nop 1
	v_permlane32_swap_b32_e32 v167, v165
	v_permlane32_swap_b32_e32 v166, v164
	s_nop 0
	v_pk_add_f32 v[164:165], v[164:165], v[166:167]
	s_nop 0
	v_pk_mul_f32 v[190:191], v[164:165], s[26:27] op_sel_hi:[1,0]
	s_nop 0
	v_fma_f32 v164, -v191, v191, v190
	v_max_f32_e32 v164, 0, v164
	v_add_f32_e32 v164, 0x3727c5ac, v164
	v_cmp_gt_f32_e32 vcc, s91, v164
	v_mul_f32_e32 v165, 0x4b800000, v164
	v_pk_fma_f32 v[44:45], v[112:113], v[190:191], v[44:45] op_sel:[0,1,0] neg_lo:[1,0,0] neg_hi:[1,0,0]
	v_cndmask_b32_e32 v164, v164, v165, vcc
	v_rsq_f32_e32 v164, v164
	v_pk_fma_f32 v[40:41], v[100:101], v[190:191], v[40:41] op_sel:[0,1,0] neg_lo:[1,0,0] neg_hi:[1,0,0]
	v_pk_fma_f32 v[42:43], v[102:103], v[190:191], v[42:43] op_sel:[0,1,0] neg_lo:[1,0,0] neg_hi:[1,0,0]
	v_pk_fma_f32 v[36:37], v[88:89], v[190:191], v[36:37] op_sel:[0,1,0] neg_lo:[1,0,0] neg_hi:[1,0,0]
	v_mul_f32_e32 v165, 0x45800000, v164
	v_cndmask_b32_e32 v196, v164, v165, vcc
	global_load_dwordx4 v[164:167], v[162:163], off
	global_load_dwordx4 v[220:223], v[208:209], off offset:16
	v_pk_fma_f32 v[44:45], v[44:45], v[196:197], v[116:117] op_sel_hi:[1,0,1]
	v_pk_fma_f32 v[40:41], v[40:41], v[196:197], v[104:105] op_sel_hi:[1,0,1]
	v_pk_fma_f32 v[42:43], v[42:43], v[196:197], v[106:107] op_sel_hi:[1,0,1]
	v_pk_fma_f32 v[36:37], v[36:37], v[196:197], v[92:93] op_sel_hi:[1,0,1]
	v_pk_fma_f32 v[32:33], v[76:77], v[190:191], v[32:33] op_sel:[0,1,0] neg_lo:[1,0,0] neg_hi:[1,0,0]
	v_pk_fma_f32 v[34:35], v[78:79], v[190:191], v[34:35] op_sel:[0,1,0] neg_lo:[1,0,0] neg_hi:[1,0,0]
	v_pk_fma_f32 v[32:33], v[32:33], v[196:197], v[80:81] op_sel_hi:[1,0,1]
	v_pk_fma_f32 v[34:35], v[34:35], v[196:197], v[82:83] op_sel_hi:[1,0,1]
	s_waitcnt vmcnt(1)
	v_mov_b32_e32 v208, v164
	s_waitcnt vmcnt(0)
	v_mov_b32_e32 v209, v220
	v_mov_b32_e32 v224, v166
	v_mov_b32_e32 v225, v222
	v_pk_add_f32 v[208:209], v[208:209], v[224:225]
	v_add_f32_e32 v164, v165, v167
	v_add_f32_e32 v166, v221, v223
	v_mov_b32_e32 v165, v208
	v_mov_b32_e32 v167, v209
	v_pk_add_f32 v[164:165], v[164:165], v[166:167]
	s_waitcnt lgkmcnt(0)
	v_mov_b32_e32 v167, v165
	v_mov_b32_e32 v166, v164
	s_nop 1
	v_permlane16_swap_b32_e32 v167, v165
	v_permlane16_swap_b32_e32 v166, v164
	s_nop 0
	v_pk_add_f32 v[164:165], v[164:165], v[166:167]
	s_waitcnt lgkmcnt(0)
; DI void row_stats(const f32x2v* st, size_t row, int fq, float& mu, float& rstd) {
;     const f32x4 a = *(const f32x4*)(st + row * 16 + 4 * fq), b = *(const f32x4*)(st + row * 16 + 4 * fq + 2);
;     float s1 = (a[0] + a[2]) + (b[0] + b[2]), s2 = (a[1] + a[3]) + (b[1] + b[3]);
;     s1 += __shfl_xor(s1, 16); s1 += __shfl_xor(s1, 32); s2 += __shfl_xor(s2, 16); s2 += __shfl_xor(s2, 32);
;     mu = s1 * (1.0f / 1024.0f); const float var = fmaxf(s2 * (1.0f / 1024.0f) - mu * mu, 0.f); rstd = rsqrtf(var + LN_EPS);
	v_mov_b32_e32 v167, v165
	v_mov_b32_e32 v166, v164
	s_nop 1
	v_permlane32_swap_b32_e32 v167, v165
	v_permlane32_swap_b32_e32 v166, v164
	s_nop 0
	v_pk_add_f32 v[164:165], v[164:165], v[166:167]
	s_nop 0
	v_pk_mul_f32 v[208:209], v[164:165], s[26:27] op_sel_hi:[1,0]
	s_nop 0
	v_fma_f32 v164, -v209, v209, v208
	v_max_f32_e32 v164, 0, v164
	v_add_f32_e32 v164, 0x3727c5ac, v164
	v_cmp_gt_f32_e32 vcc, s91, v164
	v_mul_f32_e32 v165, 0x4b800000, v164
	v_pk_fma_f32 v[28:29], v[112:113], v[208:209], v[28:29] op_sel:[0,1,0] neg_lo:[1,0,0] neg_hi:[1,0,0]
	v_cndmask_b32_e32 v164, v164, v165, vcc
	v_rsq_f32_e32 v164, v164
	v_pk_fma_f32 v[24:25], v[100:101], v[208:209], v[24:25] op_sel:[0,1,0] neg_lo:[1,0,0] neg_hi:[1,0,0]
	v_pk_fma_f32 v[26:27], v[102:103], v[208:209], v[26:27] op_sel:[0,1,0] neg_lo:[1,0,0] neg_hi:[1,0,0]
	v_pk_fma_f32 v[20:21], v[88:89], v[208:209], v[20:21] op_sel:[0,1,0] neg_lo:[1,0,0] neg_hi:[1,0,0]
	v_mul_f32_e32 v165, 0x45800000, v164
	v_cndmask_b32_e32 v210, v164, v165, vcc
	v_lshl_add_u64 v[164:165], v[160:161], 0, s[30:31]
	global_load_dwordx4 v[160:163], v[162:163], off offset:2048
	s_nop 0
	global_load_dwordx4 v[164:167], v[164:165], off offset:16
	v_pk_fma_f32 v[28:29], v[28:29], v[210:211], v[116:117] op_sel_hi:[1,0,1]
	v_pk_fma_f32 v[24:25], v[24:25], v[210:211], v[104:105] op_sel_hi:[1,0,1]
	v_pk_fma_f32 v[26:27], v[26:27], v[210:211], v[106:107] op_sel_hi:[1,0,1]
	v_pk_fma_f32 v[20:21], v[20:21], v[210:211], v[92:93] op_sel_hi:[1,0,1]
	v_pk_fma_f32 v[16:17], v[76:77], v[208:209], v[16:17] op_sel:[0,1,0] neg_lo:[1,0,0] neg_hi:[1,0,0]
	v_pk_fma_f32 v[18:19], v[78:79], v[208:209], v[18:19] op_sel:[0,1,0] neg_lo:[1,0,0] neg_hi:[1,0,0]
	v_pk_fma_f32 v[16:17], v[16:17], v[210:211], v[80:81] op_sel_hi:[1,0,1]
	v_pk_fma_f32 v[18:19], v[18:19], v[210:211], v[82:83] op_sel_hi:[1,0,1]
	s_mov_b64 s[30:31], -1
	s_waitcnt vmcnt(1)
	v_mov_b32_e32 v220, v160
	s_waitcnt vmcnt(0)
	v_mov_b32_e32 v221, v164
	v_mov_b32_e32 v222, v162
	v_mov_b32_e32 v223, v166
	v_pk_add_f32 v[220:221], v[220:221], v[222:223]
	v_add_f32_e32 v160, v161, v163
	v_add_f32_e32 v162, v165, v167
	v_mov_b32_e32 v161, v220
	v_mov_b32_e32 v163, v221
	v_pk_add_f32 v[160:161], v[160:161], v[162:163]
	v_lshl_or_b32 v164, s95, 7, v193
	v_ashrrev_i32_e32 v165, 31, v164
	s_waitcnt lgkmcnt(0)
	v_mov_b32_e32 v163, v161
	v_mov_b32_e32 v162, v160
	s_nop 1
	v_permlane16_swap_b32_e32 v163, v161
	v_permlane16_swap_b32_e32 v162, v160
	s_nop 0
	v_pk_add_f32 v[160:161], v[160:161], v[162:163]
	s_waitcnt lgkmcnt(0)
	v_mov_b32_e32 v163, v161
	v_mov_b32_e32 v162, v160
	s_nop 1
	v_permlane32_swap_b32_e32 v163, v161
	v_permlane32_swap_b32_e32 v162, v160
	s_nop 0
	v_pk_add_f32 v[160:161], v[160:161], v[162:163]
	s_nop 0
	v_pk_mul_f32 v[160:161], v[160:161], s[26:27] op_sel_hi:[1,0]
	s_nop 0
	v_fma_f32 v162, -v161, v161, v160
	v_max_f32_e32 v162, 0, v162
	v_add_f32_e32 v162, 0x3727c5ac, v162
	v_cmp_gt_f32_e32 vcc, s91, v162
	v_mul_f32_e32 v163, 0x4b800000, v162
	v_pk_fma_f32 v[12:13], v[112:113], v[160:161], v[12:13] op_sel:[0,1,0] neg_lo:[1,0,0] neg_hi:[1,0,0]
	v_cndmask_b32_e32 v162, v162, v163, vcc
	v_rsq_f32_e32 v162, v162
	v_pk_fma_f32 v[8:9], v[100:101], v[160:161], v[8:9] op_sel:[0,1,0] neg_lo:[1,0,0] neg_hi:[1,0,0]
	v_pk_fma_f32 v[10:11], v[102:103], v[160:161], v[10:11] op_sel:[0,1,0] neg_lo:[1,0,0] neg_hi:[1,0,0]
	v_pk_fma_f32 v[4:5], v[88:89], v[160:161], v[4:5] op_sel:[0,1,0] neg_lo:[1,0,0] neg_hi:[1,0,0]
	v_mul_f32_e32 v163, 0x45800000, v162
	v_cndmask_b32_e32 v162, v162, v163, vcc
	v_mul_f32_e32 v163, 0xbfb8aa3b, v156
	v_exp_f32_e32 v163, v163
	v_pk_fma_f32 v[0:1], v[76:77], v[160:161], v[0:1] op_sel:[0,1,0] neg_lo:[1,0,0] neg_hi:[1,0,0]
	v_pk_fma_f32 v[2:3], v[78:79], v[160:161], v[2:3] op_sel:[0,1,0] neg_lo:[1,0,0] neg_hi:[1,0,0]
	v_add_f32_e32 v163, 1.0, v163
	v_rcp_f32_e32 v166, v163
	v_mul_f32_e32 v163, 0xbfb8aa3b, v157
	v_exp_f32_e32 v163, v163
	s_nop 0
	v_add_f32_e32 v163, 1.0, v163
	v_rcp_f32_e32 v167, v163
	v_pk_fma_f32 v[12:13], v[12:13], v[162:163], v[116:117] op_sel_hi:[1,0,1]
	v_pk_fma_f32 v[8:9], v[8:9], v[162:163], v[104:105] op_sel_hi:[1,0,1]
	v_pk_fma_f32 v[10:11], v[10:11], v[162:163], v[106:107] op_sel_hi:[1,0,1]
	v_pk_mul_f32 v[156:157], v[156:157], v[166:167]
	v_pk_fma_f32 v[4:5], v[4:5], v[162:163], v[92:93] op_sel_hi:[1,0,1]
	v_pk_mul_f32 v[152:153], v[152:153], v[156:157]
	v_pk_fma_f32 v[156:157], v[114:115], v[216:217], v[158:159] op_sel:[0,1,0] neg_lo:[1,0,0] neg_hi:[1,0,0]
	v_pk_fma_f32 v[0:1], v[0:1], v[162:163], v[80:81] op_sel_hi:[1,0,1]
	v_pk_fma_f32 v[156:157], v[156:157], v[218:219], v[118:119] op_sel_hi:[1,0,1]
	v_pk_fma_f32 v[2:3], v[2:3], v[162:163], v[82:83] op_sel_hi:[1,0,1]
	v_mul_f32_e32 v158, 0xbfb8aa3b, v156
	v_mul_f32_e32 v159, 0xbfb8aa3b, v157
	v_exp_f32_e32 v158, v158
	v_exp_f32_e32 v159, v159
	v_add_f32_e32 v158, 1.0, v158
	v_add_f32_e32 v159, 1.0, v159
	v_rcp_f32_e32 v158, v158
	v_rcp_f32_e32 v159, v159
	s_nop 0
	v_pk_mul_f32 v[156:157], v[156:157], v[158:159]
	s_nop 0
	v_pk_mul_f32 v[154:155], v[154:155], v[156:157]
	v_mul_f32_e32 v156, 0xbfb8aa3b, v148
	v_mul_f32_e32 v157, 0xbfb8aa3b, v149
	v_exp_f32_e32 v156, v156
	v_exp_f32_e32 v157, v157
	v_add_f32_e32 v156, 1.0, v156
	v_add_f32_e32 v157, 1.0, v157
	v_rcp_f32_e32 v156, v156
	v_rcp_f32_e32 v157, v157
	s_nop 0
	v_pk_mul_f32 v[148:149], v[148:149], v[156:157]
	s_nop 0
	v_pk_mul_f32 v[144:145], v[144:145], v[148:149]
	v_pk_fma_f32 v[148:149], v[90:91], v[216:217], v[150:151] op_sel:[0,1,0] neg_lo:[1,0,0] neg_hi:[1,0,0]
	s_nop 0
	v_pk_fma_f32 v[148:149], v[148:149], v[218:219], v[94:95] op_sel_hi:[1,0,1]
	s_nop 0
	v_mul_f32_e32 v150, 0xbfb8aa3b, v148
	v_mul_f32_e32 v151, 0xbfb8aa3b, v149
	v_exp_f32_e32 v150, v150
	v_exp_f32_e32 v151, v151
	v_add_f32_e32 v150, 1.0, v150
	v_add_f32_e32 v151, 1.0, v151
	v_rcp_f32_e32 v150, v150
	v_rcp_f32_e32 v151, v151
	s_nop 0
	v_pk_mul_f32 v[148:149], v[148:149], v[150:151]
	s_nop 0
	v_pk_mul_f32 v[150:151], v[146:147], v[148:149]
	v_cvt_pk_bf16_f32 v148, v144, v145
	v_mov_b64_e32 v[144:145], s[52:53]
	v_mad_u64_u32 v[144:145], s[0:1], v206, s92, v[144:145]
	v_cvt_pk_bf16_f32 v149, v150, v151
	v_mov_b32_e32 v150, v145
	v_mad_u64_u32 v[150:151], s[0:1], v207, s92, v[150:151]
	v_mov_b32_e32 v145, v150
	v_cvt_pk_bf16_f32 v146, v152, v153
	v_cvt_pk_bf16_f32 v147, v154, v155
	v_lshl_add_u64 v[144:145], v[164:165], 1, v[144:145]
	global_store_dwordx4 v[144:145], v[146:149], off
	s_mov_b32 s0, 0x16000
	s_nop 0
	v_mul_f32_e32 v146, 0xbfb8aa3b, v140
	v_mul_f32_e32 v147, 0xbfb8aa3b, v141
	v_exp_f32_e32 v146, v146
	v_exp_f32_e32 v147, v147
	v_add_f32_e32 v146, 1.0, v146
	v_add_f32_e32 v147, 1.0, v147
	v_rcp_f32_e32 v146, v146
	v_rcp_f32_e32 v147, v147
	s_nop 0
	v_pk_mul_f32 v[140:141], v[140:141], v[146:147]
	s_nop 0
	v_pk_mul_f32 v[136:137], v[136:137], v[140:141]
	v_pk_fma_f32 v[140:141], v[114:115], v[212:213], v[142:143] op_sel:[0,1,0] neg_lo:[1,0,0] neg_hi:[1,0,0]
	s_nop 0
	v_pk_fma_f32 v[140:141], v[140:141], v[214:215], v[118:119] op_sel_hi:[1,0,1]
	s_nop 0
	v_mul_f32_e32 v142, 0xbfb8aa3b, v140
	v_mul_f32_e32 v143, 0xbfb8aa3b, v141
	v_exp_f32_e32 v142, v142
	v_exp_f32_e32 v143, v143
	v_add_f32_e32 v142, 1.0, v142
	v_add_f32_e32 v143, 1.0, v143
	v_rcp_f32_e32 v142, v142
	v_rcp_f32_e32 v143, v143
	s_nop 0
	v_pk_mul_f32 v[140:141], v[140:141], v[142:143]
	s_nop 0
	v_pk_mul_f32 v[138:139], v[138:139], v[140:141]
	v_mul_f32_e32 v140, 0xbfb8aa3b, v132
	v_mul_f32_e32 v141, 0xbfb8aa3b, v133
	v_exp_f32_e32 v140, v140
	v_exp_f32_e32 v141, v141
	v_add_f32_e32 v140, 1.0, v140
	v_add_f32_e32 v141, 1.0, v141
	v_rcp_f32_e32 v140, v140
	v_rcp_f32_e32 v141, v141
	s_nop 0
	v_pk_mul_f32 v[132:133], v[132:133], v[140:141]
	s_nop 0
	v_pk_mul_f32 v[132:133], v[128:129], v[132:133]
	v_pk_fma_f32 v[128:129], v[90:91], v[212:213], v[134:135] op_sel:[0,1,0] neg_lo:[1,0,0] neg_hi:[1,0,0]
	s_nop 0
	v_pk_fma_f32 v[128:129], v[128:129], v[214:215], v[94:95] op_sel_hi:[1,0,1]
	s_nop 0
	v_mul_f32_e32 v134, 0xbfb8aa3b, v128
	v_mul_f32_e32 v135, 0xbfb8aa3b, v129
	v_exp_f32_e32 v134, v134
	v_exp_f32_e32 v135, v135
	v_add_f32_e32 v134, 1.0, v134
	v_add_f32_e32 v135, 1.0, v135
	v_rcp_f32_e32 v134, v134
	v_rcp_f32_e32 v135, v135
	s_nop 0
	v_pk_mul_f32 v[128:129], v[128:129], v[134:135]
	s_nop 0
	v_pk_mul_f32 v[134:135], v[130:131], v[128:129]
	v_cvt_pk_bf16_f32 v130, v132, v133
	v_add_co_u32_e32 v132, vcc, s0, v144
	v_cvt_pk_bf16_f32 v128, v136, v137
	v_cvt_pk_bf16_f32 v129, v138, v139
	v_cvt_pk_bf16_f32 v131, v134, v135
	v_addc_co_u32_e32 v133, vcc, 0, v145, vcc
	global_store_dwordx4 v[132:133], v[128:131], off
	s_mov_b32 s0, 0x2c000
	s_nop 0
	v_mul_f32_e32 v128, 0xbfb8aa3b, v124
	v_mul_f32_e32 v129, 0xbfb8aa3b, v125
	v_exp_f32_e32 v128, v128
	v_exp_f32_e32 v129, v129
	v_add_f32_e32 v128, 1.0, v128
	v_add_f32_e32 v129, 1.0, v129
	v_rcp_f32_e32 v128, v128
	v_rcp_f32_e32 v129, v129
	s_nop 0
	v_pk_mul_f32 v[124:125], v[124:125], v[128:129]
	s_nop 0
	v_pk_mul_f32 v[120:121], v[120:121], v[124:125]
	v_pk_fma_f32 v[124:125], v[114:115], v[202:203], v[126:127] op_sel:[0,1,0] neg_lo:[1,0,0] neg_hi:[1,0,0]
	s_nop 0
	v_pk_fma_f32 v[124:125], v[124:125], v[204:205], v[118:119] op_sel_hi:[1,0,1]
	s_nop 0
	v_mul_f32_e32 v126, 0xbfb8aa3b, v124
	v_mul_f32_e32 v127, 0xbfb8aa3b, v125
	v_exp_f32_e32 v126, v126
	v_exp_f32_e32 v127, v127
	v_add_f32_e32 v126, 1.0, v126
	v_add_f32_e32 v127, 1.0, v127
	v_rcp_f32_e32 v126, v126
	v_rcp_f32_e32 v127, v127
	s_nop 0
	v_pk_mul_f32 v[124:125], v[124:125], v[126:127]
	s_nop 0
	v_pk_mul_f32 v[122:123], v[122:123], v[124:125]
	v_mul_f32_e32 v124, 0xbfb8aa3b, v108
	v_mul_f32_e32 v125, 0xbfb8aa3b, v109
	v_exp_f32_e32 v124, v124
	v_exp_f32_e32 v125, v125
	v_add_f32_e32 v124, 1.0, v124
	v_add_f32_e32 v125, 1.0, v125
	v_rcp_f32_e32 v124, v124
	v_rcp_f32_e32 v125, v125
	s_nop 0
	v_pk_mul_f32 v[108:109], v[108:109], v[124:125]
	s_nop 0
	v_pk_mul_f32 v[108:109], v[96:97], v[108:109]
	v_pk_fma_f32 v[96:97], v[90:91], v[202:203], v[110:111] op_sel:[0,1,0] neg_lo:[1,0,0] neg_hi:[1,0,0]
	s_nop 0
	v_pk_fma_f32 v[96:97], v[96:97], v[204:205], v[94:95] op_sel_hi:[1,0,1]
	s_nop 0
	v_mul_f32_e32 v110, 0xbfb8aa3b, v96
	v_mul_f32_e32 v111, 0xbfb8aa3b, v97
	v_exp_f32_e32 v110, v110
	v_exp_f32_e32 v111, v111
	v_add_f32_e32 v110, 1.0, v110
	v_add_f32_e32 v111, 1.0, v111
	v_rcp_f32_e32 v110, v110
	v_rcp_f32_e32 v111, v111
	s_nop 0
	v_pk_mul_f32 v[96:97], v[96:97], v[110:111]
	s_nop 0
	v_pk_mul_f32 v[110:111], v[98:99], v[96:97]
	v_cvt_pk_bf16_f32 v98, v108, v109
	v_add_co_u32_e32 v108, vcc, s0, v144
	v_cvt_pk_bf16_f32 v96, v120, v121
	v_cvt_pk_bf16_f32 v97, v122, v123
	v_cvt_pk_bf16_f32 v99, v110, v111
	v_addc_co_u32_e32 v109, vcc, 0, v145, vcc
	global_store_dwordx4 v[108:109], v[96:99], off
	s_mov_b32 s0, 0x42000
	s_nop 0
	v_mul_f32_e32 v96, 0xbfb8aa3b, v84
	v_mul_f32_e32 v97, 0xbfb8aa3b, v85
	v_exp_f32_e32 v96, v96
	v_exp_f32_e32 v97, v97
	v_add_f32_e32 v96, 1.0, v96
	v_add_f32_e32 v97, 1.0, v97
	v_rcp_f32_e32 v96, v96
	v_rcp_f32_e32 v97, v97
	s_nop 0
	v_pk_mul_f32 v[84:85], v[84:85], v[96:97]
	s_nop 0
	v_pk_mul_f32 v[72:73], v[72:73], v[84:85]
	v_pk_fma_f32 v[84:85], v[114:115], v[186:187], v[86:87] op_sel:[0,1,0] neg_lo:[1,0,0] neg_hi:[1,0,0]
	s_nop 0
	v_pk_fma_f32 v[84:85], v[84:85], v[188:189], v[118:119] op_sel_hi:[1,0,1]
	s_nop 0
	v_mul_f32_e32 v86, 0xbfb8aa3b, v84
	v_mul_f32_e32 v87, 0xbfb8aa3b, v85
	v_exp_f32_e32 v86, v86
	v_exp_f32_e32 v87, v87
	v_add_f32_e32 v86, 1.0, v86
	v_add_f32_e32 v87, 1.0, v87
	v_rcp_f32_e32 v86, v86
	v_rcp_f32_e32 v87, v87
	s_nop 0
	v_pk_mul_f32 v[84:85], v[84:85], v[86:87]
	s_nop 0
	v_pk_mul_f32 v[74:75], v[74:75], v[84:85]
	v_mul_f32_e32 v84, 0xbfb8aa3b, v68
	v_mul_f32_e32 v85, 0xbfb8aa3b, v69
	v_exp_f32_e32 v84, v84
	v_exp_f32_e32 v85, v85
	v_add_f32_e32 v84, 1.0, v84
	v_add_f32_e32 v85, 1.0, v85
	v_rcp_f32_e32 v84, v84
	v_rcp_f32_e32 v85, v85
	s_nop 0
	v_pk_mul_f32 v[68:69], v[68:69], v[84:85]
	s_nop 0
	v_pk_mul_f32 v[68:69], v[64:65], v[68:69]
	v_pk_fma_f32 v[64:65], v[90:91], v[186:187], v[70:71] op_sel:[0,1,0] neg_lo:[1,0,0] neg_hi:[1,0,0]
	s_nop 0
	v_pk_fma_f32 v[64:65], v[64:65], v[188:189], v[94:95] op_sel_hi:[1,0,1]
	s_nop 0
	v_mul_f32_e32 v70, 0xbfb8aa3b, v64
	v_mul_f32_e32 v71, 0xbfb8aa3b, v65
	v_exp_f32_e32 v70, v70
	v_exp_f32_e32 v71, v71
	v_add_f32_e32 v70, 1.0, v70
	v_add_f32_e32 v71, 1.0, v71
	v_rcp_f32_e32 v70, v70
	v_rcp_f32_e32 v71, v71
	s_nop 0
	v_pk_mul_f32 v[64:65], v[64:65], v[70:71]
	s_nop 0
	v_pk_mul_f32 v[70:71], v[66:67], v[64:65]
	v_cvt_pk_bf16_f32 v66, v68, v69
	v_add_co_u32_e32 v68, vcc, s0, v144
	v_cvt_pk_bf16_f32 v64, v72, v73
	v_cvt_pk_bf16_f32 v65, v74, v75
	v_cvt_pk_bf16_f32 v67, v70, v71
	v_addc_co_u32_e32 v69, vcc, 0, v145, vcc
	global_store_dwordx4 v[68:69], v[64:67], off
	s_mov_b32 s0, 0xb0000
	s_nop 0
	v_mul_f32_e32 v64, 0xbfb8aa3b, v60
	v_mul_f32_e32 v65, 0xbfb8aa3b, v61
	v_exp_f32_e32 v64, v64
	v_exp_f32_e32 v65, v65
	v_add_f32_e32 v64, 1.0, v64
	v_add_f32_e32 v65, 1.0, v65
	v_rcp_f32_e32 v64, v64
	v_rcp_f32_e32 v65, v65
	s_nop 0
	v_pk_mul_f32 v[60:61], v[60:61], v[64:65]
	s_nop 0
	v_pk_mul_f32 v[56:57], v[56:57], v[60:61]
	v_pk_fma_f32 v[60:61], v[114:115], v[198:199], v[62:63] op_sel:[0,1,0] neg_lo:[1,0,0] neg_hi:[1,0,0]
	s_nop 0
	v_pk_fma_f32 v[60:61], v[60:61], v[200:201], v[118:119] op_sel_hi:[1,0,1]
	s_nop 0
	v_mul_f32_e32 v62, 0xbfb8aa3b, v60
	v_mul_f32_e32 v63, 0xbfb8aa3b, v61
	v_exp_f32_e32 v62, v62
	v_exp_f32_e32 v63, v63
	v_add_f32_e32 v62, 1.0, v62
	v_add_f32_e32 v63, 1.0, v63
	v_rcp_f32_e32 v62, v62
	v_rcp_f32_e32 v63, v63
	s_nop 0
	v_pk_mul_f32 v[60:61], v[60:61], v[62:63]
	s_nop 0
	v_pk_mul_f32 v[58:59], v[58:59], v[60:61]
	v_mul_f32_e32 v60, 0xbfb8aa3b, v52
	v_mul_f32_e32 v61, 0xbfb8aa3b, v53
	v_exp_f32_e32 v60, v60
	v_exp_f32_e32 v61, v61
	v_add_f32_e32 v60, 1.0, v60
	v_add_f32_e32 v61, 1.0, v61
	v_rcp_f32_e32 v60, v60
	v_rcp_f32_e32 v61, v61
	s_nop 0
	v_pk_mul_f32 v[52:53], v[52:53], v[60:61]
	s_nop 0
	v_pk_mul_f32 v[52:53], v[48:49], v[52:53]
	v_pk_fma_f32 v[48:49], v[90:91], v[198:199], v[54:55] op_sel:[0,1,0] neg_lo:[1,0,0] neg_hi:[1,0,0]
	s_nop 0
	v_pk_fma_f32 v[48:49], v[48:49], v[200:201], v[94:95] op_sel_hi:[1,0,1]
	s_nop 0
	v_mul_f32_e32 v54, 0xbfb8aa3b, v48
	v_mul_f32_e32 v55, 0xbfb8aa3b, v49
	v_exp_f32_e32 v54, v54
	v_exp_f32_e32 v55, v55
	v_add_f32_e32 v54, 1.0, v54
	v_add_f32_e32 v55, 1.0, v55
	v_rcp_f32_e32 v54, v54
	v_rcp_f32_e32 v55, v55
	s_nop 0
	v_pk_mul_f32 v[48:49], v[48:49], v[54:55]
	s_nop 0
	v_pk_mul_f32 v[54:55], v[50:51], v[48:49]
	v_cvt_pk_bf16_f32 v50, v52, v53
	v_add_co_u32_e32 v52, vcc, s0, v144
	v_cvt_pk_bf16_f32 v48, v56, v57
	v_cvt_pk_bf16_f32 v49, v58, v59
	v_cvt_pk_bf16_f32 v51, v54, v55
	v_addc_co_u32_e32 v53, vcc, 0, v145, vcc
	global_store_dwordx4 v[52:53], v[48:51], off
	s_mov_b32 s0, 0xc6000
	s_nop 0
	v_mul_f32_e32 v48, 0xbfb8aa3b, v44
	v_mul_f32_e32 v49, 0xbfb8aa3b, v45
	v_exp_f32_e32 v48, v48
	v_exp_f32_e32 v49, v49
	v_add_f32_e32 v48, 1.0, v48
	v_add_f32_e32 v49, 1.0, v49
	v_rcp_f32_e32 v48, v48
	v_rcp_f32_e32 v49, v49
	s_nop 0
	v_pk_mul_f32 v[44:45], v[44:45], v[48:49]
	s_nop 0
	v_pk_mul_f32 v[40:41], v[40:41], v[44:45]
	v_pk_fma_f32 v[44:45], v[114:115], v[190:191], v[46:47] op_sel:[0,1,0] neg_lo:[1,0,0] neg_hi:[1,0,0]
	s_nop 0
	v_pk_fma_f32 v[44:45], v[44:45], v[196:197], v[118:119] op_sel_hi:[1,0,1]
	s_nop 0
	v_mul_f32_e32 v46, 0xbfb8aa3b, v44
	v_mul_f32_e32 v47, 0xbfb8aa3b, v45
	v_exp_f32_e32 v46, v46
	v_exp_f32_e32 v47, v47
	v_add_f32_e32 v46, 1.0, v46
	v_add_f32_e32 v47, 1.0, v47
	v_rcp_f32_e32 v46, v46
	v_rcp_f32_e32 v47, v47
	s_nop 0
	v_pk_mul_f32 v[44:45], v[44:45], v[46:47]
	s_nop 0
	v_pk_mul_f32 v[42:43], v[42:43], v[44:45]
	v_mul_f32_e32 v44, 0xbfb8aa3b, v36
	v_mul_f32_e32 v45, 0xbfb8aa3b, v37
	v_exp_f32_e32 v44, v44
	v_exp_f32_e32 v45, v45
	v_add_f32_e32 v44, 1.0, v44
	v_add_f32_e32 v45, 1.0, v45
	v_rcp_f32_e32 v44, v44
	v_rcp_f32_e32 v45, v45
	s_nop 0
	v_pk_mul_f32 v[36:37], v[36:37], v[44:45]
	s_nop 0
	v_pk_mul_f32 v[36:37], v[32:33], v[36:37]
	v_pk_fma_f32 v[32:33], v[90:91], v[190:191], v[38:39] op_sel:[0,1,0] neg_lo:[1,0,0] neg_hi:[1,0,0]
	s_nop 0
	v_pk_fma_f32 v[32:33], v[32:33], v[196:197], v[94:95] op_sel_hi:[1,0,1]
	s_nop 0
	v_mul_f32_e32 v38, 0xbfb8aa3b, v32
	v_mul_f32_e32 v39, 0xbfb8aa3b, v33
	v_exp_f32_e32 v38, v38
	v_exp_f32_e32 v39, v39
	v_add_f32_e32 v38, 1.0, v38
	v_add_f32_e32 v39, 1.0, v39
	v_rcp_f32_e32 v38, v38
	v_rcp_f32_e32 v39, v39
	s_nop 0
	v_pk_mul_f32 v[32:33], v[32:33], v[38:39]
	s_nop 0
	v_pk_mul_f32 v[38:39], v[34:35], v[32:33]
	v_cvt_pk_bf16_f32 v34, v36, v37
	v_add_co_u32_e32 v36, vcc, s0, v144
	v_cvt_pk_bf16_f32 v32, v40, v41
	v_cvt_pk_bf16_f32 v33, v42, v43
	v_cvt_pk_bf16_f32 v35, v38, v39
	v_addc_co_u32_e32 v37, vcc, 0, v145, vcc
	global_store_dwordx4 v[36:37], v[32:35], off
	s_mov_b32 s0, 0xdc000
	s_nop 0
	v_mul_f32_e32 v32, 0xbfb8aa3b, v28
	v_mul_f32_e32 v33, 0xbfb8aa3b, v29
	v_exp_f32_e32 v32, v32
	v_exp_f32_e32 v33, v33
	v_add_f32_e32 v32, 1.0, v32
	v_add_f32_e32 v33, 1.0, v33
	v_rcp_f32_e32 v32, v32
	v_rcp_f32_e32 v33, v33
	s_nop 0
	v_pk_mul_f32 v[28:29], v[28:29], v[32:33]
	s_nop 0
	v_pk_mul_f32 v[24:25], v[24:25], v[28:29]
	v_pk_fma_f32 v[28:29], v[114:115], v[208:209], v[30:31] op_sel:[0,1,0] neg_lo:[1,0,0] neg_hi:[1,0,0]
	s_nop 0
	v_pk_fma_f32 v[28:29], v[28:29], v[210:211], v[118:119] op_sel_hi:[1,0,1]
	s_nop 0
	v_mul_f32_e32 v30, 0xbfb8aa3b, v28
	v_mul_f32_e32 v31, 0xbfb8aa3b, v29
	v_exp_f32_e32 v30, v30
	v_exp_f32_e32 v31, v31
	v_add_f32_e32 v30, 1.0, v30
	v_add_f32_e32 v31, 1.0, v31
	v_rcp_f32_e32 v30, v30
	v_rcp_f32_e32 v31, v31
	s_nop 0
	v_pk_mul_f32 v[28:29], v[28:29], v[30:31]
	s_nop 0
	v_pk_mul_f32 v[26:27], v[26:27], v[28:29]
	v_mul_f32_e32 v28, 0xbfb8aa3b, v20
	v_mul_f32_e32 v29, 0xbfb8aa3b, v21
	v_exp_f32_e32 v28, v28
	v_exp_f32_e32 v29, v29
	v_add_f32_e32 v28, 1.0, v28
	v_add_f32_e32 v29, 1.0, v29
	v_rcp_f32_e32 v28, v28
	v_rcp_f32_e32 v29, v29
	s_nop 0
	v_pk_mul_f32 v[20:21], v[20:21], v[28:29]
	s_nop 0
	v_pk_mul_f32 v[20:21], v[16:17], v[20:21]
	v_pk_fma_f32 v[16:17], v[90:91], v[208:209], v[22:23] op_sel:[0,1,0] neg_lo:[1,0,0] neg_hi:[1,0,0]
	s_nop 0
	v_pk_fma_f32 v[16:17], v[16:17], v[210:211], v[94:95] op_sel_hi:[1,0,1]
	s_nop 0
	v_mul_f32_e32 v22, 0xbfb8aa3b, v16
	v_mul_f32_e32 v23, 0xbfb8aa3b, v17
	v_exp_f32_e32 v22, v22
	v_exp_f32_e32 v23, v23
	v_add_f32_e32 v22, 1.0, v22
	v_add_f32_e32 v23, 1.0, v23
	v_rcp_f32_e32 v22, v22
	v_rcp_f32_e32 v23, v23
	s_nop 0
	v_pk_mul_f32 v[16:17], v[16:17], v[22:23]
	s_nop 0
	v_pk_mul_f32 v[22:23], v[18:19], v[16:17]
	v_cvt_pk_bf16_f32 v18, v20, v21
	v_add_co_u32_e32 v20, vcc, s0, v144
	v_cvt_pk_bf16_f32 v16, v24, v25
	v_cvt_pk_bf16_f32 v17, v26, v27
	v_cvt_pk_bf16_f32 v19, v22, v23
	v_addc_co_u32_e32 v21, vcc, 0, v145, vcc
	global_store_dwordx4 v[20:21], v[16:19], off
	s_nop 1
	v_mul_f32_e32 v16, 0xbfb8aa3b, v12
	v_mul_f32_e32 v17, 0xbfb8aa3b, v13
	v_exp_f32_e32 v16, v16
	v_exp_f32_e32 v17, v17
	v_add_f32_e32 v16, 1.0, v16
	v_add_f32_e32 v17, 1.0, v17
	v_rcp_f32_e32 v16, v16
	v_rcp_f32_e32 v17, v17
	s_nop 0
	v_pk_mul_f32 v[12:13], v[12:13], v[16:17]
	s_nop 0
	v_pk_mul_f32 v[8:9], v[8:9], v[12:13]
	v_pk_fma_f32 v[12:13], v[114:115], v[160:161], v[14:15] op_sel:[0,1,0] neg_lo:[1,0,0] neg_hi:[1,0,0]
	s_nop 0
	v_pk_fma_f32 v[12:13], v[12:13], v[162:163], v[118:119] op_sel_hi:[1,0,1]
	s_nop 0
	v_mul_f32_e32 v14, 0xbfb8aa3b, v12
	v_mul_f32_e32 v15, 0xbfb8aa3b, v13
	v_exp_f32_e32 v14, v14
	v_exp_f32_e32 v15, v15
	v_add_f32_e32 v14, 1.0, v14
	v_add_f32_e32 v15, 1.0, v15
	v_rcp_f32_e32 v14, v14
	v_rcp_f32_e32 v15, v15
	s_nop 0
	v_pk_mul_f32 v[12:13], v[12:13], v[14:15]
	s_nop 0
	v_pk_mul_f32 v[10:11], v[10:11], v[12:13]
	v_mul_f32_e32 v12, 0xbfb8aa3b, v4
	v_mul_f32_e32 v13, 0xbfb8aa3b, v5
	v_exp_f32_e32 v12, v12
	v_exp_f32_e32 v13, v13
	v_add_f32_e32 v12, 1.0, v12
	v_add_f32_e32 v13, 1.0, v13
	v_rcp_f32_e32 v12, v12
	v_rcp_f32_e32 v13, v13
	s_nop 0
	v_pk_mul_f32 v[4:5], v[4:5], v[12:13]
	s_nop 0
	v_pk_mul_f32 v[4:5], v[0:1], v[4:5]
	v_pk_fma_f32 v[0:1], v[90:91], v[160:161], v[6:7] op_sel:[0,1,0] neg_lo:[1,0,0] neg_hi:[1,0,0]
	s_nop 0
	v_pk_fma_f32 v[0:1], v[0:1], v[162:163], v[94:95] op_sel_hi:[1,0,1]
	s_nop 0
	v_mul_f32_e32 v6, 0xbfb8aa3b, v0
	v_mul_f32_e32 v7, 0xbfb8aa3b, v1
	v_exp_f32_e32 v6, v6
	v_exp_f32_e32 v7, v7
	v_add_f32_e32 v6, 1.0, v6
	v_add_f32_e32 v7, 1.0, v7
	v_rcp_f32_e32 v6, v6
	v_rcp_f32_e32 v7, v7
	s_nop 0
	v_pk_mul_f32 v[0:1], v[0:1], v[6:7]
	s_nop 0
	v_pk_mul_f32 v[6:7], v[2:3], v[0:1]
	v_cvt_pk_bf16_f32 v2, v4, v5
	v_add_co_u32_e32 v4, vcc, 0xf2000, v144
	v_cvt_pk_bf16_f32 v0, v8, v9
	s_nop 0
	v_addc_co_u32_e32 v5, vcc, 0, v145, vcc
	v_cvt_pk_bf16_f32 v1, v10, v11
	v_cvt_pk_bf16_f32 v3, v6, v7
	s_and_b64 vcc, exec, s[4:5]
	global_store_dwordx4 v[4:5], v[0:3], off
	s_cbranch_vccnz .LBB0_1626
	s_andn2_b64 vcc, exec, s[14:15]
	s_cbranch_vccnz .LBB0_1625
	s_barrier
	s_branch .LBB0_1625

; DI void row_stats(const f32x2v* st, size_t row, int fq, float& mu, float& rstd) {
;     const f32x4 a = *(const f32x4*)(st + row * 16 + 4 * fq), b = *(const f32x4*)(st + row * 16 + 4 * fq + 2);
;     float s1 = (a[0] + a[2]) + (b[0] + b[2]), s2 = (a[1] + a[3]) + (b[1] + b[3]);
;     s1 += __shfl_xor(s1, 16); s1 += __shfl_xor(s1, 32); s2 += __shfl_xor(s2, 16); s2 += __shfl_xor(s2, 32);
;     mu = s1 * (1.0f / 1024.0f); const float var = fmaxf(s2 * (1.0f / 1024.0f) - mu * mu, 0.f); rstd = rsqrtf(var + LN_EPS);
; }
; DI void unpack8(const u32x4& p, f32x4& a, f32x4& b) { a[0] = bflo(p.x); a[1] = bfhi(p.x); a[2] = bflo(p.y); a[3] = bfhi(p.y); b[0] = bflo(p.z); b[1] = bfhi(p.z); b[2] = bflo(p.w); b[3] = bfhi(p.w); }
.LBB0_1757:
	v_and_b32_e32 v117, 64, v243
	v_xor_b32_e32 v116, 16, v243
	v_add_u32_e32 v117, 64, v117
	s_ashr_i32 s37, s36, 31
	v_cmp_lt_i32_e32 vcc, v116, v117
	s_lshl_b64 s[36:37], s[36:37], 8
	v_lshl_add_u64 v[182:183], s[36:37], 0, v[166:167]
	v_cndmask_b32_e32 v116, v243, v116, vcc
	v_lshlrev_b32_e32 v245, 2, v116
	v_xor_b32_e32 v116, 32, v243
	v_cmp_lt_i32_e32 vcc, v116, v117
	v_lshlrev_b64 v[208:209], 7, v[182:183]
	v_lshl_add_u64 v[124:125], v[168:169], 0, v[208:209]
	v_cndmask_b32_e32 v116, v243, v116, vcc
	v_lshlrev_b32_e32 v244, 2, v116
	global_load_dwordx4 v[116:119], v[124:125], off offset:16
	s_nop 0
	global_load_dwordx4 v[124:127], v[124:125], off
	v_lshl_or_b32 v176, s16, 8, v195
	v_ashrrev_i32_e32 v177, 31, v176
	v_lshlrev_b64 v[234:235], 1, v[176:177]
	v_or_b32_e32 v128, 16, v182
	v_mov_b32_e32 v129, v183
	v_lshl_add_u64 v[184:185], s[44:45], 0, v[234:235]
	v_lshlrev_b64 v[236:237], 11, v[182:183]
	v_lshlrev_b64 v[206:207], 7, v[128:129]
	v_lshlrev_b64 v[210:211], 11, v[128:129]
	v_or_b32_e32 v128, 32, v182
	v_lshlrev_b64 v[198:199], 7, v[128:129]
	v_or_b32_e32 v188, 48, v182
	v_mov_b32_e32 v189, v183
	v_lshlrev_b64 v[200:201], 11, v[128:129]
	v_lshlrev_b64 v[186:187], 7, v[188:189]
	v_lshlrev_b64 v[188:189], 11, v[188:189]
	s_lshl_b32 s36, s16, 2
	s_ashr_i32 s37, s36, 31
	s_waitcnt vmcnt(0)
	v_pk_add_f32 v[116:117], v[116:117], v[118:119]
	v_pk_add_f32 v[124:125], v[124:125], v[126:127]
	s_nop 0
	v_pk_add_f32 v[116:117], v[124:125], v[116:117]
	v_lshl_add_u64 v[124:125], v[168:169], 0, v[206:207]
	s_waitcnt lgkmcnt(0)
	v_mov_b32_e32 v118, v116
	v_mov_b32_e32 v119, v117
	s_nop 1
	v_permlane16_swap_b32_e32 v118, v116
	v_permlane16_swap_b32_e32 v119, v117
	s_nop 0
	v_pk_add_f32 v[116:117], v[116:117], v[118:119]
	s_waitcnt lgkmcnt(0)
	v_mov_b32_e32 v118, v116
	v_mov_b32_e32 v119, v117
	s_nop 1
	v_permlane32_swap_b32_e32 v118, v116
	v_permlane32_swap_b32_e32 v119, v117
	s_nop 0
	v_pk_add_f32 v[116:117], v[116:117], v[118:119]
	s_nop 0
	v_pk_mul_f32 v[218:219], v[116:117], s[28:29] op_sel_hi:[1,0]
	s_nop 0
	v_fma_f32 v116, -v218, v218, v219
	v_max_f32_e32 v116, 0, v116
	v_add_f32_e32 v116, 0x3727c5ac, v116
	v_cmp_gt_f32_e32 vcc, s91, v116
	v_mul_f32_e32 v117, 0x4b800000, v116
	s_nop 0
	v_cndmask_b32_e32 v116, v116, v117, vcc
	v_rsq_f32_e32 v116, v116
	s_nop 0
	v_mul_f32_e32 v117, 0x45800000, v116
	v_cndmask_b32_e32 v216, v116, v117, vcc
	v_lshl_add_u64 v[116:117], v[184:185], 0, v[236:237]
	global_load_dwordx4 v[178:181], v[116:117], off
	global_load_dwordx4 v[152:155], v[116:117], off offset:256
	s_nop 0
	global_load_dwordx4 v[116:119], v[124:125], off offset:16
	s_nop 0
	global_load_dwordx4 v[124:127], v[124:125], off
	s_waitcnt vmcnt(3)
	v_lshlrev_b32_e32 v217, 16, v179
	s_waitcnt vmcnt(1)
	v_pk_add_f32 v[116:117], v[116:117], v[118:119]
	s_waitcnt vmcnt(0)
	v_pk_add_f32 v[124:125], v[124:125], v[126:127]
	v_and_b32_e32 v219, 0xffff0000, v179
	v_pk_add_f32 v[116:117], v[124:125], v[116:117]
	ds_bpermute_b32 v118, v245, v116
	ds_bpermute_b32 v119, v245, v117
	v_lshl_add_u64 v[124:125], v[168:169], 0, v[198:199]
	v_lshlrev_b32_e32 v165, 16, v178
	v_and_b32_e32 v178, 0xffff0000, v178
	v_lshlrev_b32_e32 v228, 16, v180
	s_waitcnt lgkmcnt(0)
	v_pk_add_f32 v[212:213], v[116:117], v[118:119]
	v_lshl_add_u64 v[116:117], v[184:185], 0, v[210:211]
	global_load_dwordx4 v[148:151], v[116:117], off
	global_load_dwordx4 v[136:139], v[116:117], off offset:256
	s_nop 0
	global_load_dwordx4 v[116:119], v[124:125], off offset:16
	s_nop 0
	global_load_dwordx4 v[124:127], v[124:125], off
	v_and_b32_e32 v238, 0xffff0000, v180
	v_lshlrev_b32_e32 v254, 16, v181
	v_and_b32_e32 v239, 0xffff0000, v181
	v_sub_f32_e32 v181, v219, v218
	v_sub_f32_e32 v180, v217, v218
	v_sub_f32_e32 v179, v178, v218
	v_sub_f32_e32 v178, v165, v218
	v_pk_mul_f32 v[220:221], v[180:181], v[216:217] op_sel_hi:[1,0]
	v_lshlrev_b64 v[180:181], 2, v[176:177]
	v_pk_mul_f32 v[222:223], v[178:179], v[216:217] op_sel_hi:[1,0]
	v_lshl_add_u64 v[178:179], s[50:51], 0, v[180:181]
	v_lshl_add_u64 v[180:181], s[60:61], 0, v[180:181]
	v_sub_f32_e32 v239, v239, v218
	v_lshlrev_b32_e32 v165, 16, v154
	ds_bpermute_b32 v214, v244, v212
	ds_bpermute_b32 v215, v244, v213
	s_waitcnt vmcnt(1)
	v_pk_add_f32 v[116:117], v[116:117], v[118:119]
	s_waitcnt vmcnt(0)
	v_pk_add_f32 v[124:125], v[124:125], v[126:127]
	s_nop 0
	v_pk_add_f32 v[116:117], v[124:125], v[116:117]
	ds_bpermute_b32 v118, v245, v116
	ds_bpermute_b32 v119, v245, v117
	v_lshl_add_u64 v[124:125], v[168:169], 0, v[186:187]
	s_waitcnt lgkmcnt(0)
	v_pk_add_f32 v[202:203], v[116:117], v[118:119]
	v_lshl_add_u64 v[116:117], v[184:185], 0, v[200:201]
	global_load_dwordx4 v[132:135], v[116:117], off
	global_load_dwordx4 v[128:131], v[116:117], off offset:256
	s_nop 0
	global_load_dwordx4 v[116:119], v[124:125], off offset:16
	s_nop 0
	global_load_dwordx4 v[124:127], v[124:125], off
	ds_bpermute_b32 v204, v244, v202
	ds_bpermute_b32 v205, v244, v203
	s_waitcnt vmcnt(1)
	v_pk_add_f32 v[116:117], v[116:117], v[118:119]
	s_waitcnt vmcnt(0)
	v_pk_add_f32 v[124:125], v[124:125], v[126:127]
	s_nop 0
	v_pk_add_f32 v[116:117], v[124:125], v[116:117]
	ds_bpermute_b32 v118, v245, v116
	ds_bpermute_b32 v119, v245, v117
	s_waitcnt lgkmcnt(0)
	v_pk_add_f32 v[190:191], v[116:117], v[118:119]
	v_lshl_add_u64 v[116:117], v[184:185], 0, v[188:189]
	global_load_dwordx4 v[124:127], v[116:117], off
	s_nop 0
	global_load_dwordx4 v[116:119], v[116:117], off offset:256
	s_nop 0
	global_load_dwordx4 v[230:233], v[178:179], off offset:16
	global_load_dwordx4 v[224:227], v[178:179], off
	global_load_dwordx4 v[246:249], v[180:181], off offset:16
	global_load_dwordx4 v[250:253], v[180:181], off
	ds_bpermute_b32 v196, v244, v190
	ds_bpermute_b32 v197, v244, v191
	s_waitcnt vmcnt(0)
	v_pk_fma_f32 v[220:221], v[220:221], v[226:227], v[252:253]
	s_nop 0
	v_pk_fma_f32 v[146:147], v[220:221], s[30:31], v[146:147] op_sel_hi:[1,0,1]
	v_pk_fma_f32 v[222:223], v[222:223], v[224:225], v[250:251]
	v_mul_f32_e32 v217, v146, v146
	v_sub_f32_e32 v225, v238, v218
	v_sub_f32_e32 v224, v228, v218
	v_sub_f32_e32 v238, v254, v218
	v_pk_mul_f32 v[238:239], v[238:239], v[216:217] op_sel_hi:[1,0]
	v_pk_mul_f32 v[224:225], v[224:225], v[216:217] op_sel_hi:[1,0]
	v_pk_fma_f32 v[144:145], v[222:223], s[30:31], v[144:145] op_sel_hi:[1,0,1]
	v_pk_fma_f32 v[224:225], v[224:225], v[230:231], v[246:247]
	v_pk_fma_f32 v[230:231], v[238:239], v[232:233], v[248:249]
	v_pk_fma_f32 v[232:233], v[224:225], s[30:31], v[140:141] op_sel_hi:[1,0,1]
	v_pk_fma_f32 v[230:231], v[230:231], s[30:31], v[142:143] op_sel_hi:[1,0,1]
	v_add_f32_e32 v220, v144, v145
	v_mul_f32_e32 v140, v230, v230
	v_mul_f32_e32 v227, v144, v144
	v_mul_f32_e32 v229, v145, v145
	v_pk_fma_f32 v[224:225], v[230:231], v[230:231], v[140:141] op_sel_hi:[1,1,0]
	v_cvt_pk_bf16_f32 v140, v144, v145
	v_lshl_add_u64 v[144:145], s[44:45], 0, v[236:237]
	v_cvt_pk_bf16_f32 v141, v146, v147
	v_cvt_pk_bf16_f32 v142, v232, v233
	v_cvt_pk_bf16_f32 v143, v230, v231
	v_lshl_add_u64 v[234:235], v[144:145], 0, v[234:235]
	global_store_dwordx4 v[234:235], v[140:143], off
	v_add_f32_e32 v222, v146, v147
	v_mul_f32_e32 v219, v147, v147
	v_lshlrev_b32_e32 v140, 16, v152
	v_and_b32_e32 v141, 0xffff0000, v152
	v_lshlrev_b32_e32 v142, 16, v153
	v_and_b32_e32 v143, 0xffff0000, v153
	v_sub_f32_e32 v141, v141, v218
	v_sub_f32_e32 v140, v140, v218
	v_sub_f32_e32 v143, v143, v218
	v_sub_f32_e32 v142, v142, v218
	v_and_b32_e32 v224, 0xffff0000, v154
	v_lshlrev_b32_e32 v226, 16, v155
	v_and_b32_e32 v228, 0xffff0000, v155
	v_pk_mul_f32 v[246:247], v[142:143], v[216:217] op_sel_hi:[1,0]
	v_pk_mul_f32 v[248:249], v[140:141], v[216:217] op_sel_hi:[1,0]
	global_load_dwordx4 v[140:143], v[178:179], off offset:528
	global_load_dwordx4 v[152:155], v[178:179], off offset:512
	global_load_dwordx4 v[144:147], v[180:181], off offset:528
	global_load_dwordx4 v[236:239], v[180:181], off offset:512
	v_mul_f32_e32 v221, v232, v232
	v_mul_f32_e32 v223, v233, v233
	s_waitcnt vmcnt(0)
	v_pk_fma_f32 v[152:153], v[248:249], v[152:153], v[236:237]
	v_pk_fma_f32 v[154:155], v[246:247], v[154:155], v[238:239]
	v_sub_f32_e32 v247, v224, v218
	v_sub_f32_e32 v246, v165, v218
	v_sub_f32_e32 v249, v228, v218
	v_sub_f32_e32 v248, v226, v218
	v_pk_mul_f32 v[248:249], v[248:249], v[216:217] op_sel_hi:[1,0]
	v_pk_mul_f32 v[246:247], v[246:247], v[216:217] op_sel_hi:[1,0]
	v_pk_fma_f32 v[142:143], v[248:249], v[142:143], v[146:147]
	v_pk_fma_f32 v[140:141], v[246:247], v[140:141], v[144:145]
	v_pk_fma_f32 v[122:123], v[154:155], s[30:31], v[122:123] op_sel_hi:[1,0,1]
	v_pk_fma_f32 v[236:237], v[152:153], s[30:31], v[120:121] op_sel_hi:[1,0,1]
	v_pk_fma_f32 v[142:143], v[142:143], s[30:31], v[114:115] op_sel_hi:[1,0,1]
	v_pk_fma_f32 v[140:141], v[140:141], s[30:31], v[112:113] op_sel_hi:[1,0,1]
	v_cvt_pk_bf16_f32 v112, v236, v237
	v_cvt_pk_bf16_f32 v113, v122, v123
	v_cvt_pk_bf16_f32 v114, v140, v141
	v_cvt_pk_bf16_f32 v115, v142, v143
	v_mov_b32_e32 v226, v232
	v_mov_b32_e32 v228, v233
	v_mov_b32_e32 v216, v230
	v_mov_b32_e32 v218, v231
	global_store_dwordx4 v[234:235], v[112:115], off offset:256
	v_mov_b32_e32 v165, v225
	v_mul_f32_e32 v155, v236, v236
	v_pk_add_f32 v[112:113], v[226:227], v[228:229]
	v_pk_add_f32 v[114:115], v[216:217], v[218:219]
	v_mul_f32_e32 v239, v237, v237
	v_pk_add_f32 v[112:113], v[112:113], v[114:115]
	v_pk_add_f32 v[114:115], v[220:221], v[222:223]
	v_mul_f32_e32 v121, v122, v122
	v_mul_f32_e32 v153, v123, v123
	v_pk_add_f32 v[114:115], v[114:115], v[164:165]
	v_mov_b32_e32 v154, v236
	v_mov_b32_e32 v238, v237
	v_mov_b32_e32 v120, v122
	v_mov_b32_e32 v152, v123
	v_pk_add_f32 v[112:113], v[112:113], v[114:115]
	v_pk_add_f32 v[114:115], v[154:155], v[238:239]
	v_pk_add_f32 v[120:121], v[120:121], v[152:153]
	v_mul_f32_e32 v145, v140, v140
	v_mul_f32_e32 v147, v141, v141
	v_mul_f32_e32 v247, v142, v142
	v_mul_f32_e32 v249, v143, v143
	v_pk_add_f32 v[114:115], v[114:115], v[120:121]
	v_mov_b32_e32 v144, v140
	v_mov_b32_e32 v146, v141
	v_mov_b32_e32 v246, v142
	v_mov_b32_e32 v248, v143
	v_pk_add_f32 v[112:113], v[112:113], v[114:115]
	v_pk_add_f32 v[114:115], v[144:145], v[146:147]
	v_pk_add_f32 v[120:121], v[246:247], v[248:249]
	s_nop 0
	v_pk_add_f32 v[114:115], v[114:115], v[120:121]
	s_nop 0
	v_pk_add_f32 v[112:113], v[112:113], v[114:115]
	s_waitcnt lgkmcnt(0)
	v_mov_b32_e32 v114, v112
	v_mov_b32_e32 v115, v113
	s_nop 1
	v_permlane16_swap_b32_e32 v114, v112
	v_permlane16_swap_b32_e32 v115, v113
	s_nop 0
	v_pk_add_f32 v[112:113], v[112:113], v[114:115]
	ds_bpermute_b32 v114, v244, v112
	ds_bpermute_b32 v115, v244, v113
	s_and_saveexec_b64 s[38:39], s[4:5]
	s_cbranch_execz .LBB0_1759
	v_lshl_add_u64 v[120:121], s[76:77], 0, v[208:209]
	v_lshl_add_u64 v[120:121], s[36:37], 3, v[120:121]
	s_lshl_b32 s16, s71, 3
	v_lshl_add_u64 v[120:121], v[120:121], 0, s[16:17]
	s_waitcnt lgkmcnt(0)
	v_pk_add_f32 v[112:113], v[112:113], v[114:115]
	global_store_dwordx2 v[120:121], v[112:113], off
; DI void row_stats(const f32x2v* st, size_t row, int fq, float& mu, float& rstd) {
;     ...
;     mu = s1 * (1.0f / 1024.0f); const float var = fmaxf(s2 * (1.0f / 1024.0f) - mu * mu, 0.f); rstd = rsqrtf(var + LN_EPS);
.LBB0_1759:
	s_or_b64 exec, exec, s[38:39]
	s_waitcnt lgkmcnt(0)
	global_load_dwordx4 v[112:115], v[180:181], off
	global_load_dwordx4 v[120:123], v[178:179], off
	global_load_dwordx4 v[140:143], v[178:179], off offset:16
	global_load_dwordx4 v[144:147], v[180:181], off offset:16
	v_pk_add_f32 v[152:153], v[212:213], v[214:215]
	v_lshlrev_b32_e32 v212, 16, v150
	v_and_b32_e32 v209, 0xffff0000, v150
	v_lshlrev_b32_e32 v213, 16, v151
	v_and_b32_e32 v214, 0xffff0000, v151
	v_pk_mul_f32 v[150:151], v[152:153], s[28:29] op_sel_hi:[1,0]
	v_lshlrev_b32_e32 v154, 16, v148
	v_fma_f32 v151, -v150, v150, v151
	v_max_f32_e32 v151, 0, v151
	v_lshlrev_b32_e32 v165, 16, v149
	v_add_f32_e32 v151, 0x3727c5ac, v151
	v_sub_f32_e32 v152, v154, v150
	v_sub_f32_e32 v154, v165, v150
	v_mul_f32_e32 v165, 0x4b800000, v151
	v_cmp_gt_f32_e32 vcc, s91, v151
	v_and_b32_e32 v155, 0xffff0000, v148
	v_and_b32_e32 v208, 0xffff0000, v149
	v_cndmask_b32_e32 v151, v151, v165, vcc
	v_rsq_f32_e32 v151, v151
	v_lshl_add_u64 v[148:149], s[44:45], 0, v[210:211]
	v_sub_f32_e32 v153, v155, v150
	v_sub_f32_e32 v155, v208, v150
	v_mul_f32_e32 v165, 0x45800000, v151
	v_sub_f32_e32 v209, v209, v150
	v_sub_f32_e32 v208, v212, v150
	v_sub_f32_e32 v211, v214, v150
	v_sub_f32_e32 v210, v213, v150
	v_cndmask_b32_e32 v212, v151, v165, vcc
	v_pk_mul_f32 v[154:155], v[154:155], v[212:213] op_sel_hi:[1,0]
	v_pk_mul_f32 v[152:153], v[152:153], v[212:213] op_sel_hi:[1,0]
	v_pk_mul_f32 v[210:211], v[210:211], v[212:213] op_sel_hi:[1,0]
	v_pk_mul_f32 v[208:209], v[208:209], v[212:213] op_sel_hi:[1,0]
	v_lshl_add_u64 v[148:149], v[176:177], 1, v[148:149]
	v_lshlrev_b32_e32 v151, 16, v136
	v_and_b32_e32 v136, 0xffff0000, v136
	v_lshlrev_b32_e32 v165, 16, v139
	s_waitcnt vmcnt(2)
	v_pk_fma_f32 v[112:113], v[152:153], v[120:121], v[112:113]
	v_pk_fma_f32 v[114:115], v[154:155], v[122:123], v[114:115]
	s_waitcnt vmcnt(0)
	v_pk_fma_f32 v[120:121], v[208:209], v[140:141], v[144:145]
	v_pk_fma_f32 v[122:123], v[210:211], v[142:143], v[146:147]
	v_pk_fma_f32 v[140:141], v[114:115], s[30:31], v[110:111] op_sel_hi:[1,0,1]
	v_pk_fma_f32 v[142:143], v[112:113], s[30:31], v[108:109] op_sel_hi:[1,0,1]
	v_pk_fma_f32 v[144:145], v[122:123], s[30:31], v[106:107] op_sel_hi:[1,0,1]
	v_pk_fma_f32 v[146:147], v[120:121], s[30:31], v[104:105] op_sel_hi:[1,0,1]
	v_cvt_pk_bf16_f32 v104, v142, v143
	v_cvt_pk_bf16_f32 v105, v140, v141
	v_cvt_pk_bf16_f32 v106, v146, v147
	v_cvt_pk_bf16_f32 v107, v144, v145
	global_store_dwordx4 v[148:149], v[104:107], off
	global_load_dwordx4 v[104:107], v[180:181], off offset:512
	s_nop 0
	global_load_dwordx4 v[108:111], v[178:179], off offset:512
	global_load_dwordx4 v[112:115], v[178:179], off offset:528
	global_load_dwordx4 v[120:123], v[180:181], off offset:528
	v_lshlrev_b32_e32 v152, 16, v137
	v_and_b32_e32 v153, 0xffff0000, v137
	v_lshlrev_b32_e32 v154, 16, v138
	v_and_b32_e32 v155, 0xffff0000, v138
	v_and_b32_e32 v208, 0xffff0000, v139
	v_sub_f32_e32 v137, v136, v150
	v_sub_f32_e32 v136, v151, v150
	v_sub_f32_e32 v139, v153, v150
	v_sub_f32_e32 v138, v152, v150
	v_sub_f32_e32 v153, v155, v150
	v_sub_f32_e32 v152, v154, v150
	v_sub_f32_e32 v151, v208, v150
	v_sub_f32_e32 v150, v165, v150
	v_pk_mul_f32 v[138:139], v[138:139], v[212:213] op_sel_hi:[1,0]
	v_pk_mul_f32 v[136:137], v[136:137], v[212:213] op_sel_hi:[1,0]
	v_pk_mul_f32 v[150:151], v[150:151], v[212:213] op_sel_hi:[1,0]
	v_pk_mul_f32 v[152:153], v[152:153], v[212:213] op_sel_hi:[1,0]
	v_mul_f32_e32 v214, v144, v144
	v_add_f32_e32 v154, v142, v143
	v_add_f32_e32 v208, v140, v141
	v_mul_f32_e32 v211, v142, v142
	v_mul_f32_e32 v143, v143, v143
	v_mul_f32_e32 v213, v140, v140
	v_mul_f32_e32 v141, v141, v141
	v_mul_f32_e32 v155, v146, v146
	v_mul_f32_e32 v209, v147, v147
	v_mov_b32_e32 v210, v146
	v_mov_b32_e32 v142, v147
	v_mov_b32_e32 v212, v144
	v_mov_b32_e32 v140, v145
	v_pk_fma_f32 v[144:145], v[144:145], v[144:145], v[214:215] op_sel_hi:[1,1,0]
	v_pk_add_f32 v[142:143], v[210:211], v[142:143]
	v_pk_add_f32 v[140:141], v[212:213], v[140:141]
	v_pk_add_f32 v[146:147], v[154:155], v[208:209]
	v_mov_b32_e32 v165, v145
	v_pk_add_f32 v[140:141], v[142:143], v[140:141]
	v_pk_add_f32 v[142:143], v[146:147], v[164:165]
	s_waitcnt vmcnt(2)
	v_pk_fma_f32 v[104:105], v[136:137], v[108:109], v[104:105]
	v_pk_fma_f32 v[106:107], v[138:139], v[110:111], v[106:107]
	s_waitcnt vmcnt(0)
	v_pk_fma_f32 v[108:109], v[152:153], v[112:113], v[120:121]
	v_pk_fma_f32 v[110:111], v[150:151], v[114:115], v[122:123]
	v_pk_fma_f32 v[102:103], v[106:107], s[30:31], v[102:103] op_sel_hi:[1,0,1]
	v_pk_fma_f32 v[100:101], v[104:105], s[30:31], v[100:101] op_sel_hi:[1,0,1]
	v_pk_fma_f32 v[104:105], v[110:111], s[30:31], v[98:99] op_sel_hi:[1,0,1]
	v_pk_fma_f32 v[106:107], v[108:109], s[30:31], v[96:97] op_sel_hi:[1,0,1]
	v_mul_f32_e32 v97, v100, v100
	v_mul_f32_e32 v99, v101, v101
	v_mul_f32_e32 v109, v102, v102
	v_mul_f32_e32 v111, v103, v103
	v_mov_b32_e32 v96, v100
	v_mov_b32_e32 v98, v101
	v_mov_b32_e32 v108, v102
	v_mov_b32_e32 v110, v103
	v_mul_f32_e32 v113, v106, v106
	v_mul_f32_e32 v115, v107, v107
	v_mul_f32_e32 v121, v104, v104
	v_mul_f32_e32 v123, v105, v105
	v_mov_b32_e32 v112, v106
	v_mov_b32_e32 v114, v107
	v_mov_b32_e32 v120, v104
	v_mov_b32_e32 v122, v105
	v_pk_add_f32 v[96:97], v[96:97], v[98:99]
	v_pk_add_f32 v[98:99], v[108:109], v[110:111]
	v_pk_add_f32 v[140:141], v[140:141], v[142:143]
	v_pk_add_f32 v[108:109], v[112:113], v[114:115]
	v_pk_add_f32 v[110:111], v[120:121], v[122:123]
	v_pk_add_f32 v[96:97], v[96:97], v[98:99]
	v_pk_add_f32 v[98:99], v[108:109], v[110:111]
	v_pk_add_f32 v[96:97], v[140:141], v[96:97]
	v_cvt_pk_bf16_f32 v100, v100, v101
	v_pk_add_f32 v[96:97], v[96:97], v[98:99]
	v_cvt_pk_bf16_f32 v101, v102, v103
	v_cvt_pk_bf16_f32 v102, v106, v107
	v_cvt_pk_bf16_f32 v103, v104, v105
	global_store_dwordx4 v[148:149], v[100:103], off offset:256
	s_waitcnt lgkmcnt(0)
	v_mov_b32_e32 v98, v96
	v_mov_b32_e32 v99, v97
	s_nop 1
	v_permlane16_swap_b32_e32 v98, v96
	v_permlane16_swap_b32_e32 v99, v97
	s_nop 0
	v_pk_add_f32 v[96:97], v[96:97], v[98:99]
	ds_bpermute_b32 v98, v244, v96
	ds_bpermute_b32 v99, v244, v97
	s_and_saveexec_b64 s[38:39], s[4:5]
	s_cbranch_execz .LBB0_1761
	v_lshl_add_u64 v[100:101], s[76:77], 0, v[206:207]
	v_lshl_add_u64 v[100:101], s[36:37], 3, v[100:101]
	s_lshl_b32 s16, s71, 3
	v_lshl_add_u64 v[100:101], v[100:101], 0, s[16:17]
	s_waitcnt lgkmcnt(0)
	v_pk_add_f32 v[96:97], v[96:97], v[98:99]
	global_store_dwordx2 v[100:101], v[96:97], off
; DI void row_stats(const f32x2v* st, size_t row, int fq, float& mu, float& rstd) {
;     ...
;     mu = s1 * (1.0f / 1024.0f); const float var = fmaxf(s2 * (1.0f / 1024.0f) - mu * mu, 0.f); rstd = rsqrtf(var + LN_EPS);
.LBB0_1761:
	s_or_b64 exec, exec, s[38:39]
	s_waitcnt lgkmcnt(0)
	global_load_dwordx4 v[96:99], v[180:181], off
	global_load_dwordx4 v[100:103], v[178:179], off
	global_load_dwordx4 v[104:107], v[178:179], off offset:16
	global_load_dwordx4 v[108:111], v[180:181], off offset:16
	v_pk_add_f32 v[112:113], v[202:203], v[204:205]
	v_lshlrev_b32_e32 v120, 16, v132
	v_pk_mul_f32 v[112:113], v[112:113], s[28:29] op_sel_hi:[1,0]
	v_and_b32_e32 v121, 0xffff0000, v132
	v_fma_f32 v113, -v112, v112, v113
	v_max_f32_e32 v113, 0, v113
	v_add_f32_e32 v113, 0x3727c5ac, v113
	v_mul_f32_e32 v136, 0x4b800000, v113
	v_cmp_gt_f32_e32 vcc, s91, v113
	v_lshlrev_b32_e32 v122, 16, v133
	v_and_b32_e32 v123, 0xffff0000, v133
	v_cndmask_b32_e32 v113, v113, v136, vcc
	v_rsq_f32_e32 v113, v113
	v_lshlrev_b32_e32 v132, 16, v134
	v_and_b32_e32 v133, 0xffff0000, v134
	v_lshlrev_b32_e32 v134, 16, v135
	v_and_b32_e32 v135, 0xffff0000, v135
	v_mul_f32_e32 v136, 0x45800000, v113
	v_sub_f32_e32 v121, v121, v112
	v_sub_f32_e32 v120, v120, v112
	v_sub_f32_e32 v123, v123, v112
	v_sub_f32_e32 v122, v122, v112
	v_sub_f32_e32 v133, v133, v112
	v_sub_f32_e32 v132, v132, v112
	v_sub_f32_e32 v135, v135, v112
	v_sub_f32_e32 v134, v134, v112
	v_cndmask_b32_e32 v136, v113, v136, vcc
	v_pk_mul_f32 v[122:123], v[122:123], v[136:137] op_sel_hi:[1,0]
	v_pk_mul_f32 v[120:121], v[120:121], v[136:137] op_sel_hi:[1,0]
	v_pk_mul_f32 v[134:135], v[134:135], v[136:137] op_sel_hi:[1,0]
	v_pk_mul_f32 v[132:133], v[132:133], v[136:137] op_sel_hi:[1,0]
	v_lshl_add_u64 v[114:115], s[44:45], 0, v[200:201]
	v_lshl_add_u64 v[114:115], v[176:177], 1, v[114:115]
	v_lshlrev_b32_e32 v113, 16, v128
	s_waitcnt vmcnt(2)
	v_pk_fma_f32 v[96:97], v[120:121], v[100:101], v[96:97]
	v_pk_fma_f32 v[98:99], v[122:123], v[102:103], v[98:99]
	s_waitcnt vmcnt(0)
	v_pk_fma_f32 v[100:101], v[132:133], v[104:105], v[108:109]
	v_pk_fma_f32 v[102:103], v[134:135], v[106:107], v[110:111]
	v_pk_fma_f32 v[104:105], v[98:99], s[30:31], v[94:95] op_sel_hi:[1,0,1]
	v_pk_fma_f32 v[106:107], v[96:97], s[30:31], v[92:93] op_sel_hi:[1,0,1]
	v_pk_fma_f32 v[108:109], v[102:103], s[30:31], v[90:91] op_sel_hi:[1,0,1]
	v_pk_fma_f32 v[110:111], v[100:101], s[30:31], v[88:89] op_sel_hi:[1,0,1]
	v_cvt_pk_bf16_f32 v88, v106, v107
	v_cvt_pk_bf16_f32 v89, v104, v105
	v_cvt_pk_bf16_f32 v90, v110, v111
	v_cvt_pk_bf16_f32 v91, v108, v109
	global_store_dwordx4 v[114:115], v[88:91], off
	global_load_dwordx4 v[88:91], v[180:181], off offset:512
	s_nop 0
	global_load_dwordx4 v[92:95], v[178:179], off offset:512
	global_load_dwordx4 v[96:99], v[178:179], off offset:528
	global_load_dwordx4 v[100:103], v[180:181], off offset:528
	v_and_b32_e32 v120, 0xffff0000, v128
	v_lshlrev_b32_e32 v122, 16, v129
	v_and_b32_e32 v123, 0xffff0000, v129
	v_lshlrev_b32_e32 v128, 16, v130
	v_and_b32_e32 v129, 0xffff0000, v130
	v_lshlrev_b32_e32 v130, 16, v131
	v_and_b32_e32 v131, 0xffff0000, v131
	v_sub_f32_e32 v121, v120, v112
	v_sub_f32_e32 v120, v113, v112
	v_sub_f32_e32 v123, v123, v112
	v_sub_f32_e32 v122, v122, v112
	v_sub_f32_e32 v129, v129, v112
	v_sub_f32_e32 v128, v128, v112
	v_sub_f32_e32 v113, v131, v112
	v_sub_f32_e32 v112, v130, v112
	v_pk_mul_f32 v[122:123], v[122:123], v[136:137] op_sel_hi:[1,0]
	v_pk_mul_f32 v[120:121], v[120:121], v[136:137] op_sel_hi:[1,0]
	v_pk_mul_f32 v[112:113], v[112:113], v[136:137] op_sel_hi:[1,0]
	v_pk_mul_f32 v[128:129], v[128:129], v[136:137] op_sel_hi:[1,0]
	v_mul_f32_e32 v138, v108, v108
	v_add_f32_e32 v130, v106, v107
	v_add_f32_e32 v132, v104, v105
	v_mul_f32_e32 v135, v106, v106
	v_mul_f32_e32 v107, v107, v107
	v_mul_f32_e32 v137, v104, v104
	v_mul_f32_e32 v105, v105, v105
	v_mul_f32_e32 v131, v110, v110
	v_mul_f32_e32 v133, v111, v111
	v_mov_b32_e32 v134, v110
	v_mov_b32_e32 v106, v111
	v_mov_b32_e32 v136, v108
	v_mov_b32_e32 v104, v109
	v_pk_fma_f32 v[108:109], v[108:109], v[108:109], v[138:139] op_sel_hi:[1,1,0]
	v_pk_add_f32 v[106:107], v[134:135], v[106:107]
	v_pk_add_f32 v[104:105], v[136:137], v[104:105]
	v_pk_add_f32 v[110:111], v[130:131], v[132:133]
	v_mov_b32_e32 v165, v109
	v_pk_add_f32 v[104:105], v[106:107], v[104:105]
	v_pk_add_f32 v[106:107], v[110:111], v[164:165]
	s_waitcnt vmcnt(2)
	v_pk_fma_f32 v[88:89], v[120:121], v[92:93], v[88:89]
	v_pk_fma_f32 v[90:91], v[122:123], v[94:95], v[90:91]
	s_waitcnt vmcnt(0)
	v_pk_fma_f32 v[92:93], v[128:129], v[96:97], v[100:101]
	v_pk_fma_f32 v[94:95], v[112:113], v[98:99], v[102:103]
	v_pk_fma_f32 v[86:87], v[90:91], s[30:31], v[86:87] op_sel_hi:[1,0,1]
	v_pk_fma_f32 v[84:85], v[88:89], s[30:31], v[84:85] op_sel_hi:[1,0,1]
	v_pk_fma_f32 v[88:89], v[94:95], s[30:31], v[82:83] op_sel_hi:[1,0,1]
	v_pk_fma_f32 v[90:91], v[92:93], s[30:31], v[80:81] op_sel_hi:[1,0,1]
	v_mul_f32_e32 v81, v84, v84
	v_mul_f32_e32 v83, v85, v85
	v_mul_f32_e32 v93, v86, v86
	v_mul_f32_e32 v95, v87, v87
	v_mov_b32_e32 v80, v84
	v_mov_b32_e32 v82, v85
	v_mov_b32_e32 v92, v86
	v_mov_b32_e32 v94, v87
	v_mul_f32_e32 v97, v90, v90
	v_mul_f32_e32 v99, v91, v91
	v_mul_f32_e32 v101, v88, v88
	v_mul_f32_e32 v103, v89, v89
	v_mov_b32_e32 v96, v90
	v_mov_b32_e32 v98, v91
	v_mov_b32_e32 v100, v88
	v_mov_b32_e32 v102, v89
	v_pk_add_f32 v[80:81], v[80:81], v[82:83]
	v_pk_add_f32 v[82:83], v[92:93], v[94:95]
	v_pk_add_f32 v[104:105], v[104:105], v[106:107]
	v_pk_add_f32 v[92:93], v[96:97], v[98:99]
	v_pk_add_f32 v[94:95], v[100:101], v[102:103]
	v_pk_add_f32 v[80:81], v[80:81], v[82:83]
	v_pk_add_f32 v[82:83], v[92:93], v[94:95]
	v_pk_add_f32 v[80:81], v[104:105], v[80:81]
	v_cvt_pk_bf16_f32 v84, v84, v85
	v_pk_add_f32 v[80:81], v[80:81], v[82:83]
	v_cvt_pk_bf16_f32 v85, v86, v87
	v_cvt_pk_bf16_f32 v86, v90, v91
	v_cvt_pk_bf16_f32 v87, v88, v89
	global_store_dwordx4 v[114:115], v[84:87], off offset:256
	s_waitcnt lgkmcnt(0)
	v_mov_b32_e32 v82, v80
	v_mov_b32_e32 v83, v81
	s_nop 1
	v_permlane16_swap_b32_e32 v82, v80
	v_permlane16_swap_b32_e32 v83, v81
	s_nop 0
	v_pk_add_f32 v[80:81], v[80:81], v[82:83]
	ds_bpermute_b32 v82, v244, v80
	ds_bpermute_b32 v83, v244, v81
	s_and_saveexec_b64 s[38:39], s[4:5]
	s_cbranch_execz .LBB0_1763
	v_lshl_add_u64 v[84:85], s[76:77], 0, v[198:199]
	v_lshl_add_u64 v[84:85], s[36:37], 3, v[84:85]
	s_lshl_b32 s16, s71, 3
	v_lshl_add_u64 v[84:85], v[84:85], 0, s[16:17]
	s_waitcnt lgkmcnt(0)
	v_pk_add_f32 v[80:81], v[80:81], v[82:83]
	global_store_dwordx2 v[84:85], v[80:81], off
; DI void row_stats(const f32x2v* st, size_t row, int fq, float& mu, float& rstd) {
;     ...
;     mu = s1 * (1.0f / 1024.0f); const float var = fmaxf(s2 * (1.0f / 1024.0f) - mu * mu, 0.f); rstd = rsqrtf(var + LN_EPS);
.LBB0_1763:
	s_or_b64 exec, exec, s[38:39]
	s_waitcnt lgkmcnt(0)
	global_load_dwordx4 v[80:83], v[180:181], off
	global_load_dwordx4 v[84:87], v[178:179], off
	global_load_dwordx4 v[88:91], v[178:179], off offset:16
	global_load_dwordx4 v[92:95], v[180:181], off offset:16
	v_pk_add_f32 v[96:97], v[190:191], v[196:197]
	v_lshlrev_b32_e32 v100, 16, v124
	v_pk_mul_f32 v[96:97], v[96:97], s[28:29] op_sel_hi:[1,0]
	v_and_b32_e32 v101, 0xffff0000, v124
	v_fma_f32 v97, -v96, v96, v97
	v_max_f32_e32 v97, 0, v97
	v_add_f32_e32 v97, 0x3727c5ac, v97
	v_mul_f32_e32 v108, 0x4b800000, v97
	v_cmp_gt_f32_e32 vcc, s91, v97
	v_lshlrev_b32_e32 v102, 16, v125
	v_and_b32_e32 v103, 0xffff0000, v125
	v_cndmask_b32_e32 v97, v97, v108, vcc
	v_rsq_f32_e32 v97, v97
	v_lshlrev_b32_e32 v104, 16, v126
	v_and_b32_e32 v105, 0xffff0000, v126
	v_lshlrev_b32_e32 v106, 16, v127
	v_and_b32_e32 v107, 0xffff0000, v127
	v_mul_f32_e32 v108, 0x45800000, v97
	v_sub_f32_e32 v101, v101, v96
	v_sub_f32_e32 v100, v100, v96
	v_sub_f32_e32 v103, v103, v96
	v_sub_f32_e32 v102, v102, v96
	v_sub_f32_e32 v105, v105, v96
	v_sub_f32_e32 v104, v104, v96
	v_sub_f32_e32 v107, v107, v96
	v_sub_f32_e32 v106, v106, v96
	v_cndmask_b32_e32 v108, v97, v108, vcc
	v_pk_mul_f32 v[102:103], v[102:103], v[108:109] op_sel_hi:[1,0]
	v_pk_mul_f32 v[100:101], v[100:101], v[108:109] op_sel_hi:[1,0]
	v_pk_mul_f32 v[106:107], v[106:107], v[108:109] op_sel_hi:[1,0]
	v_pk_mul_f32 v[104:105], v[104:105], v[108:109] op_sel_hi:[1,0]
	v_lshl_add_u64 v[98:99], s[44:45], 0, v[188:189]
	v_lshl_add_u64 v[98:99], v[176:177], 1, v[98:99]
	v_lshlrev_b32_e32 v97, 16, v116
	s_waitcnt vmcnt(2)
	v_pk_fma_f32 v[80:81], v[100:101], v[84:85], v[80:81]
	v_pk_fma_f32 v[82:83], v[102:103], v[86:87], v[82:83]
	s_waitcnt vmcnt(0)
	v_pk_fma_f32 v[84:85], v[104:105], v[88:89], v[92:93]
	v_pk_fma_f32 v[86:87], v[106:107], v[90:91], v[94:95]
	v_pk_fma_f32 v[88:89], v[82:83], s[30:31], v[78:79] op_sel_hi:[1,0,1]
	v_pk_fma_f32 v[90:91], v[80:81], s[30:31], v[76:77] op_sel_hi:[1,0,1]
	v_pk_fma_f32 v[92:93], v[86:87], s[30:31], v[74:75] op_sel_hi:[1,0,1]
	v_pk_fma_f32 v[94:95], v[84:85], s[30:31], v[72:73] op_sel_hi:[1,0,1]
	v_cvt_pk_bf16_f32 v72, v90, v91
	v_cvt_pk_bf16_f32 v73, v88, v89
	v_cvt_pk_bf16_f32 v74, v94, v95
	v_cvt_pk_bf16_f32 v75, v92, v93
	global_store_dwordx4 v[98:99], v[72:75], off
	global_load_dwordx4 v[72:75], v[180:181], off offset:512
	s_nop 0
	global_load_dwordx4 v[76:79], v[178:179], off offset:512
	global_load_dwordx4 v[80:83], v[178:179], off offset:528
	global_load_dwordx4 v[84:87], v[180:181], off offset:528
	v_and_b32_e32 v100, 0xffff0000, v116
	v_lshlrev_b32_e32 v102, 16, v117
	v_and_b32_e32 v103, 0xffff0000, v117
	v_lshlrev_b32_e32 v104, 16, v118
	v_and_b32_e32 v105, 0xffff0000, v118
	v_lshlrev_b32_e32 v106, 16, v119
	v_and_b32_e32 v107, 0xffff0000, v119
	v_sub_f32_e32 v101, v100, v96
	v_sub_f32_e32 v100, v97, v96
	v_sub_f32_e32 v103, v103, v96
	v_sub_f32_e32 v102, v102, v96
	v_sub_f32_e32 v105, v105, v96
	v_sub_f32_e32 v104, v104, v96
	v_sub_f32_e32 v97, v107, v96
	v_sub_f32_e32 v96, v106, v96
	v_pk_mul_f32 v[102:103], v[102:103], v[108:109] op_sel_hi:[1,0]
	v_pk_mul_f32 v[100:101], v[100:101], v[108:109] op_sel_hi:[1,0]
	v_pk_mul_f32 v[96:97], v[96:97], v[108:109] op_sel_hi:[1,0]
	v_pk_mul_f32 v[104:105], v[104:105], v[108:109] op_sel_hi:[1,0]
	v_mul_f32_e32 v114, v92, v92
	v_add_f32_e32 v106, v90, v91
	v_add_f32_e32 v108, v88, v89
	v_mul_f32_e32 v111, v90, v90
	v_mul_f32_e32 v91, v91, v91
	v_mul_f32_e32 v113, v88, v88
	v_mul_f32_e32 v89, v89, v89
	v_mul_f32_e32 v107, v94, v94
	v_mul_f32_e32 v109, v95, v95
	v_mov_b32_e32 v110, v94
	v_mov_b32_e32 v90, v95
	v_mov_b32_e32 v112, v92
	v_mov_b32_e32 v88, v93
	v_pk_fma_f32 v[92:93], v[92:93], v[92:93], v[114:115] op_sel_hi:[1,1,0]
	v_pk_add_f32 v[90:91], v[110:111], v[90:91]
	v_pk_add_f32 v[88:89], v[112:113], v[88:89]
	v_pk_add_f32 v[94:95], v[106:107], v[108:109]
	v_mov_b32_e32 v165, v93
	v_pk_add_f32 v[88:89], v[90:91], v[88:89]
	v_pk_add_f32 v[90:91], v[94:95], v[164:165]
	s_waitcnt vmcnt(2)
	v_pk_fma_f32 v[72:73], v[100:101], v[76:77], v[72:73]
	v_pk_fma_f32 v[74:75], v[102:103], v[78:79], v[74:75]
	s_waitcnt vmcnt(0)
	v_pk_fma_f32 v[76:77], v[104:105], v[80:81], v[84:85]
	v_pk_fma_f32 v[78:79], v[96:97], v[82:83], v[86:87]
	v_pk_fma_f32 v[70:71], v[74:75], s[30:31], v[70:71] op_sel_hi:[1,0,1]
	v_pk_fma_f32 v[68:69], v[72:73], s[30:31], v[68:69] op_sel_hi:[1,0,1]
	v_pk_fma_f32 v[72:73], v[78:79], s[30:31], v[66:67] op_sel_hi:[1,0,1]
	v_pk_fma_f32 v[74:75], v[76:77], s[30:31], v[64:65] op_sel_hi:[1,0,1]
	v_mul_f32_e32 v65, v68, v68
	v_mul_f32_e32 v67, v69, v69
	v_mul_f32_e32 v77, v70, v70
	v_mul_f32_e32 v79, v71, v71
	v_mov_b32_e32 v64, v68
	v_mov_b32_e32 v66, v69
	v_mov_b32_e32 v76, v70
	v_mov_b32_e32 v78, v71
	v_mul_f32_e32 v81, v74, v74
	v_mul_f32_e32 v83, v75, v75
	v_mul_f32_e32 v85, v72, v72
	v_mul_f32_e32 v87, v73, v73
	v_mov_b32_e32 v80, v74
	v_mov_b32_e32 v82, v75
	v_mov_b32_e32 v84, v72
	v_mov_b32_e32 v86, v73
	v_pk_add_f32 v[64:65], v[64:65], v[66:67]
	v_pk_add_f32 v[66:67], v[76:77], v[78:79]
	v_pk_add_f32 v[88:89], v[88:89], v[90:91]
	v_pk_add_f32 v[76:77], v[80:81], v[82:83]
	v_pk_add_f32 v[78:79], v[84:85], v[86:87]
	v_pk_add_f32 v[64:65], v[64:65], v[66:67]
	v_pk_add_f32 v[66:67], v[76:77], v[78:79]
	v_pk_add_f32 v[64:65], v[88:89], v[64:65]
	v_cvt_pk_bf16_f32 v68, v68, v69
	v_pk_add_f32 v[64:65], v[64:65], v[66:67]
	v_cvt_pk_bf16_f32 v69, v70, v71
	v_cvt_pk_bf16_f32 v70, v74, v75
	v_cvt_pk_bf16_f32 v71, v72, v73
	global_store_dwordx4 v[98:99], v[68:71], off offset:256
	s_waitcnt lgkmcnt(0)
	v_mov_b32_e32 v66, v64
	v_mov_b32_e32 v67, v65
	s_nop 1
	v_permlane16_swap_b32_e32 v66, v64
	v_permlane16_swap_b32_e32 v67, v65
	s_nop 0
	v_pk_add_f32 v[64:65], v[64:65], v[66:67]
	ds_bpermute_b32 v66, v244, v64
	ds_bpermute_b32 v67, v244, v65
	s_and_saveexec_b64 s[38:39], s[4:5]
	s_cbranch_execz .LBB0_1765
	v_lshl_add_u64 v[68:69], s[76:77], 0, v[186:187]
	v_lshl_add_u64 v[68:69], s[36:37], 3, v[68:69]
	s_lshl_b32 s16, s71, 3
	v_lshl_add_u64 v[68:69], v[68:69], 0, s[16:17]
	s_waitcnt lgkmcnt(0)
	v_pk_add_f32 v[64:65], v[64:65], v[66:67]
	global_store_dwordx2 v[68:69], v[64:65], off
; DI void row_stats(const f32x2v* st, size_t row, int fq, float& mu, float& rstd) {
;     const f32x4 a = *(const f32x4*)(st + row * 16 + 4 * fq), b = *(const f32x4*)(st + row * 16 + 4 * fq + 2);
;     float s1 = (a[0] + a[2]) + (b[0] + b[2]), s2 = (a[1] + a[3]) + (b[1] + b[3]);
;     s1 += __shfl_xor(s1, 16); s1 += __shfl_xor(s1, 32); s2 += __shfl_xor(s2, 16); s2 += __shfl_xor(s2, 32);
;     mu = s1 * (1.0f / 1024.0f); const float var = fmaxf(s2 * (1.0f / 1024.0f) - mu * mu, 0.f); rstd = rsqrtf(var + LN_EPS);
; }
; DI void unpack8(const u32x4& p, f32x4& a, f32x4& b) { a[0] = bflo(p.x); a[1] = bfhi(p.x); a[2] = bflo(p.y); a[3] = bfhi(p.y); b[0] = bflo(p.z); b[1] = bfhi(p.z); b[2] = bflo(p.w); b[3] = bfhi(p.w); }
.LBB0_1765:
	s_or_b64 exec, exec, s[38:39]
	v_lshl_add_u64 v[72:73], v[182:183], 0, s[22:23]
	v_lshlrev_b64 v[122:123], 7, v[72:73]
	v_lshl_add_u64 v[68:69], v[168:169], 0, v[122:123]
	s_waitcnt lgkmcnt(0)
	global_load_dwordx4 v[64:67], v[68:69], off offset:16
	s_nop 0
	global_load_dwordx4 v[68:71], v[68:69], off
	s_mov_b64 s[38:39], 0x90
	v_lshlrev_b64 v[138:139], 11, v[72:73]
	v_lshl_add_u64 v[72:73], v[182:183], 0, s[38:39]
	v_lshlrev_b64 v[120:121], 7, v[72:73]
	s_mov_b64 s[38:39], 0xa0
	v_lshlrev_b64 v[124:125], 11, v[72:73]
	v_lshl_add_u64 v[72:73], v[182:183], 0, s[38:39]
	v_lshlrev_b64 v[112:113], 7, v[72:73]
	s_mov_b64 s[38:39], 0xb0
	v_lshl_add_u64 v[96:97], v[182:183], 0, s[38:39]
	v_lshlrev_b64 v[114:115], 11, v[72:73]
	v_lshlrev_b64 v[104:105], 7, v[96:97]
	v_lshlrev_b64 v[106:107], 11, v[96:97]
	s_waitcnt vmcnt(1)
	v_pk_add_f32 v[64:65], v[64:65], v[66:67]
	s_waitcnt vmcnt(0)
	v_pk_add_f32 v[68:69], v[68:69], v[70:71]
	s_nop 0
	v_pk_add_f32 v[64:65], v[68:69], v[64:65]
	v_lshl_add_u64 v[68:69], v[168:169], 0, v[120:121]
	s_waitcnt lgkmcnt(0)
	v_mov_b32_e32 v66, v64
	v_mov_b32_e32 v67, v65
	s_nop 1
	v_permlane16_swap_b32_e32 v66, v64
	v_permlane16_swap_b32_e32 v67, v65
	s_nop 0
	v_pk_add_f32 v[64:65], v[64:65], v[66:67]
	s_waitcnt lgkmcnt(0)
	v_mov_b32_e32 v66, v64
	v_mov_b32_e32 v67, v65
	s_nop 1
	v_permlane32_swap_b32_e32 v66, v64
	v_permlane32_swap_b32_e32 v67, v65
	s_nop 0
	v_pk_add_f32 v[64:65], v[64:65], v[66:67]
	s_nop 0
	v_pk_mul_f32 v[132:133], v[64:65], s[28:29] op_sel_hi:[1,0]
	s_nop 0
	v_fma_f32 v64, -v132, v132, v133
	v_max_f32_e32 v64, 0, v64
	v_add_f32_e32 v64, 0x3727c5ac, v64
	v_cmp_gt_f32_e32 vcc, s91, v64
	v_mul_f32_e32 v65, 0x4b800000, v64
	s_nop 0
	v_cndmask_b32_e32 v64, v64, v65, vcc
	v_rsq_f32_e32 v64, v64
	s_nop 0
	v_mul_f32_e32 v65, 0x45800000, v64
	v_cndmask_b32_e32 v130, v64, v65, vcc
	v_lshl_add_u64 v[64:65], v[184:185], 0, v[138:139]
	global_load_dwordx4 v[92:95], v[64:65], off
	global_load_dwordx4 v[88:91], v[64:65], off offset:256
	s_nop 0
	global_load_dwordx4 v[64:67], v[68:69], off offset:16
	s_nop 0
	global_load_dwordx4 v[68:71], v[68:69], off
	s_waitcnt vmcnt(3)
	v_lshlrev_b32_e32 v96, 16, v92
	s_waitcnt vmcnt(1)
	v_pk_add_f32 v[64:65], v[64:65], v[66:67]
	s_waitcnt vmcnt(0)
	v_pk_add_f32 v[68:69], v[68:69], v[70:71]
	v_and_b32_e32 v92, 0xffff0000, v92
	v_pk_add_f32 v[64:65], v[68:69], v[64:65]
	ds_bpermute_b32 v66, v245, v64
	ds_bpermute_b32 v67, v245, v65
	v_lshl_add_u64 v[68:69], v[168:169], 0, v[112:113]
	v_lshlrev_b32_e32 v97, 16, v93
	v_and_b32_e32 v98, 0xffff0000, v93
	v_lshlrev_b32_e32 v144, 16, v94
	s_waitcnt lgkmcnt(0)
	v_pk_add_f32 v[126:127], v[64:65], v[66:67]
	v_lshl_add_u64 v[64:65], v[184:185], 0, v[124:125]
	global_load_dwordx4 v[84:87], v[64:65], off
	global_load_dwordx4 v[80:83], v[64:65], off offset:256
	s_nop 0
	global_load_dwordx4 v[64:67], v[68:69], off offset:16
	s_nop 0
	global_load_dwordx4 v[68:71], v[68:69], off
	v_and_b32_e32 v145, 0xffff0000, v94
	v_lshlrev_b32_e32 v146, 16, v95
	v_and_b32_e32 v147, 0xffff0000, v95
	v_sub_f32_e32 v93, v92, v132
	v_sub_f32_e32 v92, v96, v132
	v_sub_f32_e32 v95, v98, v132
	v_sub_f32_e32 v94, v97, v132
	v_pk_mul_f32 v[134:135], v[94:95], v[130:131] op_sel_hi:[1,0]
	v_pk_mul_f32 v[136:137], v[92:93], v[130:131] op_sel_hi:[1,0]
	ds_bpermute_b32 v128, v244, v126
	ds_bpermute_b32 v129, v244, v127
	s_waitcnt vmcnt(1)
	v_pk_add_f32 v[64:65], v[64:65], v[66:67]
	s_waitcnt vmcnt(0)
	v_pk_add_f32 v[68:69], v[68:69], v[70:71]
	s_nop 0
	v_pk_add_f32 v[64:65], v[68:69], v[64:65]
	ds_bpermute_b32 v66, v245, v64
	ds_bpermute_b32 v67, v245, v65
	v_lshl_add_u64 v[68:69], v[168:169], 0, v[104:105]
	s_waitcnt lgkmcnt(0)
	v_pk_add_f32 v[116:117], v[64:65], v[66:67]
	v_lshl_add_u64 v[64:65], v[184:185], 0, v[114:115]
	global_load_dwordx4 v[76:79], v[64:65], off
	global_load_dwordx4 v[72:75], v[64:65], off offset:256
	s_nop 0
	global_load_dwordx4 v[64:67], v[68:69], off offset:16
	s_nop 0
	global_load_dwordx4 v[68:71], v[68:69], off
	ds_bpermute_b32 v118, v244, v116
	ds_bpermute_b32 v119, v244, v117
	s_waitcnt vmcnt(1)
	v_pk_add_f32 v[64:65], v[64:65], v[66:67]
	s_waitcnt vmcnt(0)
	v_pk_add_f32 v[68:69], v[68:69], v[70:71]
	s_nop 0
	v_pk_add_f32 v[64:65], v[68:69], v[64:65]
	ds_bpermute_b32 v66, v245, v64
	ds_bpermute_b32 v67, v245, v65
	s_waitcnt lgkmcnt(0)
	v_pk_add_f32 v[108:109], v[64:65], v[66:67]
	v_lshl_add_u64 v[64:65], v[184:185], 0, v[106:107]
	global_load_dwordx4 v[68:71], v[64:65], off
	s_nop 0
	global_load_dwordx4 v[64:67], v[64:65], off offset:256
	s_nop 0
	global_load_dwordx4 v[92:95], v[178:179], off offset:16
	global_load_dwordx4 v[100:103], v[178:179], off
	global_load_dwordx4 v[96:99], v[180:181], off offset:16
	global_load_dwordx4 v[140:143], v[180:181], off
	ds_bpermute_b32 v110, v244, v108
	ds_bpermute_b32 v111, v244, v109
	s_waitcnt vmcnt(0)
	v_pk_fma_f32 v[102:103], v[134:135], v[102:103], v[142:143]
	s_nop 0
	v_pk_fma_f32 v[62:63], v[102:103], s[30:31], v[62:63] op_sel_hi:[1,0,1]
	v_sub_f32_e32 v143, v147, v132
	v_mul_f32_e32 v131, v62, v62
	v_sub_f32_e32 v142, v146, v132
	v_pk_fma_f32 v[100:101], v[136:137], v[100:101], v[140:141]
	v_sub_f32_e32 v141, v145, v132
	v_sub_f32_e32 v140, v144, v132
	v_pk_mul_f32 v[142:143], v[142:143], v[130:131] op_sel_hi:[1,0]
	v_pk_mul_f32 v[140:141], v[140:141], v[130:131] op_sel_hi:[1,0]
	v_pk_fma_f32 v[94:95], v[142:143], v[94:95], v[98:99]
	v_pk_fma_f32 v[92:93], v[140:141], v[92:93], v[96:97]
	v_pk_fma_f32 v[94:95], v[94:95], s[30:31], v[58:59] op_sel_hi:[1,0,1]
	v_pk_fma_f32 v[60:61], v[100:101], s[30:31], v[60:61] op_sel_hi:[1,0,1]
	v_pk_fma_f32 v[96:97], v[92:93], s[30:31], v[56:57] op_sel_hi:[1,0,1]
	v_mul_f32_e32 v56, v94, v94
	v_add_f32_e32 v100, v60, v61
	v_mul_f32_e32 v135, v60, v60
	v_mul_f32_e32 v137, v61, v61
	v_pk_fma_f32 v[92:93], v[94:95], v[94:95], v[56:57] op_sel_hi:[1,1,0]
	v_cvt_pk_bf16_f32 v56, v60, v61
	v_lshl_add_u64 v[60:61], s[44:45], 0, v[138:139]
	v_cvt_pk_bf16_f32 v57, v62, v63
	v_cvt_pk_bf16_f32 v58, v96, v97
	v_cvt_pk_bf16_f32 v59, v94, v95
	v_lshl_add_u64 v[98:99], v[176:177], 1, v[60:61]
	global_store_dwordx4 v[98:99], v[56:59], off
	v_add_f32_e32 v102, v62, v63
	v_mul_f32_e32 v133, v63, v63
	v_lshlrev_b32_e32 v56, 16, v88
	v_and_b32_e32 v57, 0xffff0000, v88
	v_lshlrev_b32_e32 v58, 16, v89
	v_and_b32_e32 v59, 0xffff0000, v89
	v_sub_f32_e32 v57, v57, v132
	v_sub_f32_e32 v56, v56, v132
	v_sub_f32_e32 v59, v59, v132
	v_sub_f32_e32 v58, v58, v132
	v_lshlrev_b32_e32 v92, 16, v90
	v_and_b32_e32 v134, 0xffff0000, v90
	v_lshlrev_b32_e32 v136, 16, v91
	v_and_b32_e32 v146, 0xffff0000, v91
	v_pk_mul_f32 v[142:143], v[58:59], v[130:131] op_sel_hi:[1,0]
	v_pk_mul_f32 v[144:145], v[56:57], v[130:131] op_sel_hi:[1,0]
	global_load_dwordx4 v[56:59], v[178:179], off offset:528
	global_load_dwordx4 v[88:91], v[178:179], off offset:512
	global_load_dwordx4 v[60:63], v[180:181], off offset:528
	global_load_dwordx4 v[138:141], v[180:181], off offset:512
	v_mul_f32_e32 v101, v96, v96
	v_mul_f32_e32 v103, v97, v97
	v_mov_b32_e32 v165, v93
	s_waitcnt vmcnt(0)
	v_pk_fma_f32 v[88:89], v[144:145], v[88:89], v[138:139]
	v_pk_fma_f32 v[90:91], v[142:143], v[90:91], v[140:141]
	v_sub_f32_e32 v143, v134, v132
	v_sub_f32_e32 v142, v92, v132
	v_sub_f32_e32 v145, v146, v132
	v_sub_f32_e32 v144, v136, v132
	v_pk_mul_f32 v[144:145], v[144:145], v[130:131] op_sel_hi:[1,0]
	v_pk_mul_f32 v[142:143], v[142:143], v[130:131] op_sel_hi:[1,0]
	v_pk_fma_f32 v[54:55], v[90:91], s[30:31], v[54:55] op_sel_hi:[1,0,1]
	v_pk_fma_f32 v[60:61], v[142:143], v[56:57], v[60:61]
	v_pk_fma_f32 v[56:57], v[144:145], v[58:59], v[62:63]
	v_pk_fma_f32 v[90:91], v[88:89], s[30:31], v[52:53] op_sel_hi:[1,0,1]
	v_pk_fma_f32 v[56:57], v[56:57], s[30:31], v[50:51] op_sel_hi:[1,0,1]
	v_pk_fma_f32 v[62:63], v[60:61], s[30:31], v[48:49] op_sel_hi:[1,0,1]
	v_cvt_pk_bf16_f32 v58, v90, v91
	v_cvt_pk_bf16_f32 v59, v54, v55
	v_cvt_pk_bf16_f32 v60, v62, v63
	v_cvt_pk_bf16_f32 v61, v56, v57
	v_mov_b32_e32 v134, v96
	v_mov_b32_e32 v136, v97
	v_mov_b32_e32 v130, v94
	v_mov_b32_e32 v132, v95
	global_store_dwordx4 v[98:99], v[58:61], off offset:256
	v_mul_f32_e32 v139, v90, v90
	v_mul_f32_e32 v141, v91, v91
	v_pk_add_f32 v[58:59], v[134:135], v[136:137]
	v_pk_add_f32 v[60:61], v[130:131], v[132:133]
	v_mul_f32_e32 v53, v54, v54
	v_pk_add_f32 v[58:59], v[58:59], v[60:61]
	v_pk_add_f32 v[60:61], v[100:101], v[102:103]
	v_mul_f32_e32 v89, v55, v55
	v_pk_add_f32 v[60:61], v[60:61], v[164:165]
	v_mov_b32_e32 v138, v90
	v_mov_b32_e32 v140, v91
	v_mov_b32_e32 v52, v54
	v_mov_b32_e32 v88, v55
	v_mul_f32_e32 v143, v62, v62
	v_mul_f32_e32 v145, v63, v63
	v_mul_f32_e32 v49, v56, v56
	v_mul_f32_e32 v51, v57, v57
	v_pk_add_f32 v[58:59], v[58:59], v[60:61]
	v_pk_add_f32 v[60:61], v[138:139], v[140:141]
	v_pk_add_f32 v[52:53], v[52:53], v[88:89]
	v_mov_b32_e32 v142, v62
	v_mov_b32_e32 v144, v63
	v_mov_b32_e32 v48, v56
	v_mov_b32_e32 v50, v57
	v_pk_add_f32 v[52:53], v[60:61], v[52:53]
	v_pk_add_f32 v[54:55], v[142:143], v[144:145]
	v_pk_add_f32 v[48:49], v[48:49], v[50:51]
	v_pk_add_f32 v[52:53], v[58:59], v[52:53]
	v_pk_add_f32 v[48:49], v[54:55], v[48:49]
	s_nop 0
	v_pk_add_f32 v[48:49], v[52:53], v[48:49]
	s_waitcnt lgkmcnt(0)
	v_mov_b32_e32 v50, v48
	v_mov_b32_e32 v51, v49
	s_nop 1
	v_permlane16_swap_b32_e32 v50, v48
	v_permlane16_swap_b32_e32 v51, v49
	s_nop 0
	v_pk_add_f32 v[48:49], v[48:49], v[50:51]
	ds_bpermute_b32 v50, v244, v48
	ds_bpermute_b32 v51, v244, v49
	s_and_saveexec_b64 s[38:39], s[4:5]
	s_cbranch_execz .LBB0_1767
	v_lshl_add_u64 v[52:53], s[76:77], 0, v[122:123]
	v_lshl_add_u64 v[52:53], s[36:37], 3, v[52:53]
	s_lshl_b32 s16, s71, 3
	v_lshl_add_u64 v[52:53], v[52:53], 0, s[16:17]
	s_waitcnt lgkmcnt(0)
	v_pk_add_f32 v[48:49], v[48:49], v[50:51]
	global_store_dwordx2 v[52:53], v[48:49], off
; DI void row_stats(const f32x2v* st, size_t row, int fq, float& mu, float& rstd) {
;     ...
;     mu = s1 * (1.0f / 1024.0f); const float var = fmaxf(s2 * (1.0f / 1024.0f) - mu * mu, 0.f); rstd = rsqrtf(var + LN_EPS);
.LBB0_1767:
	s_or_b64 exec, exec, s[38:39]
	s_waitcnt lgkmcnt(0)
	global_load_dwordx4 v[48:51], v[180:181], off
	global_load_dwordx4 v[52:55], v[178:179], off
	global_load_dwordx4 v[56:59], v[178:179], off offset:16
	global_load_dwordx4 v[60:63], v[180:181], off offset:16
	v_pk_add_f32 v[88:89], v[126:127], v[128:129]
	v_lshlrev_b32_e32 v94, 16, v86
	v_and_b32_e32 v95, 0xffff0000, v86
	v_lshlrev_b32_e32 v96, 16, v87
	v_and_b32_e32 v97, 0xffff0000, v87
	v_pk_mul_f32 v[86:87], v[88:89], s[28:29] op_sel_hi:[1,0]
	v_lshlrev_b32_e32 v90, 16, v84
	v_fma_f32 v87, -v86, v86, v87
	v_max_f32_e32 v87, 0, v87
	v_lshlrev_b32_e32 v92, 16, v85
	v_add_f32_e32 v87, 0x3727c5ac, v87
	v_sub_f32_e32 v88, v90, v86
	v_sub_f32_e32 v90, v92, v86
	v_mul_f32_e32 v92, 0x4b800000, v87
	v_cmp_gt_f32_e32 vcc, s91, v87
	v_and_b32_e32 v91, 0xffff0000, v84
	v_and_b32_e32 v93, 0xffff0000, v85
	v_cndmask_b32_e32 v87, v87, v92, vcc
	v_rsq_f32_e32 v87, v87
	v_sub_f32_e32 v92, v94, v86
	v_sub_f32_e32 v94, v96, v86
	v_sub_f32_e32 v89, v91, v86
	v_mul_f32_e32 v96, 0x45800000, v87
	v_sub_f32_e32 v91, v93, v86
	v_sub_f32_e32 v93, v95, v86
	v_sub_f32_e32 v95, v97, v86
	v_cndmask_b32_e32 v96, v87, v96, vcc
	v_pk_mul_f32 v[90:91], v[90:91], v[96:97] op_sel_hi:[1,0]
	v_pk_mul_f32 v[88:89], v[88:89], v[96:97] op_sel_hi:[1,0]
	v_pk_mul_f32 v[94:95], v[94:95], v[96:97] op_sel_hi:[1,0]
	v_pk_mul_f32 v[92:93], v[92:93], v[96:97] op_sel_hi:[1,0]
	v_lshl_add_u64 v[84:85], s[44:45], 0, v[124:125]
	v_lshl_add_u64 v[84:85], v[176:177], 1, v[84:85]
	v_lshlrev_b32_e32 v87, 16, v80
	v_and_b32_e32 v80, 0xffff0000, v80
	s_waitcnt vmcnt(2)
	v_pk_fma_f32 v[48:49], v[88:89], v[52:53], v[48:49]
	v_pk_fma_f32 v[50:51], v[90:91], v[54:55], v[50:51]
	s_waitcnt vmcnt(0)
	v_pk_fma_f32 v[52:53], v[92:93], v[56:57], v[60:61]
	v_pk_fma_f32 v[54:55], v[94:95], v[58:59], v[62:63]
	v_pk_fma_f32 v[56:57], v[50:51], s[30:31], v[46:47] op_sel_hi:[1,0,1]
	v_pk_fma_f32 v[58:59], v[48:49], s[30:31], v[44:45] op_sel_hi:[1,0,1]
	v_pk_fma_f32 v[60:61], v[54:55], s[30:31], v[42:43] op_sel_hi:[1,0,1]
	v_pk_fma_f32 v[62:63], v[52:53], s[30:31], v[40:41] op_sel_hi:[1,0,1]
	v_cvt_pk_bf16_f32 v40, v58, v59
	v_cvt_pk_bf16_f32 v41, v56, v57
	v_cvt_pk_bf16_f32 v42, v62, v63
	v_cvt_pk_bf16_f32 v43, v60, v61
	global_store_dwordx4 v[84:85], v[40:43], off
	global_load_dwordx4 v[40:43], v[180:181], off offset:512
	s_nop 0
	global_load_dwordx4 v[44:47], v[178:179], off offset:512
	global_load_dwordx4 v[48:51], v[178:179], off offset:528
	global_load_dwordx4 v[52:55], v[180:181], off offset:528
	v_lshlrev_b32_e32 v88, 16, v81
	v_and_b32_e32 v89, 0xffff0000, v81
	v_lshlrev_b32_e32 v90, 16, v82
	v_and_b32_e32 v91, 0xffff0000, v82
	v_lshlrev_b32_e32 v92, 16, v83
	v_and_b32_e32 v93, 0xffff0000, v83
	v_sub_f32_e32 v81, v80, v86
	v_sub_f32_e32 v80, v87, v86
	v_sub_f32_e32 v83, v89, v86
	v_sub_f32_e32 v82, v88, v86
	v_sub_f32_e32 v89, v91, v86
	v_sub_f32_e32 v88, v90, v86
	v_sub_f32_e32 v87, v93, v86
	v_sub_f32_e32 v86, v92, v86
	v_pk_mul_f32 v[82:83], v[82:83], v[96:97] op_sel_hi:[1,0]
	v_pk_mul_f32 v[80:81], v[80:81], v[96:97] op_sel_hi:[1,0]
	v_pk_mul_f32 v[86:87], v[86:87], v[96:97] op_sel_hi:[1,0]
	v_pk_mul_f32 v[88:89], v[88:89], v[96:97] op_sel_hi:[1,0]
	v_mul_f32_e32 v98, v60, v60
	v_add_f32_e32 v90, v58, v59
	v_add_f32_e32 v92, v56, v57
	v_mul_f32_e32 v95, v58, v58
	v_mul_f32_e32 v59, v59, v59
	v_mul_f32_e32 v97, v56, v56
	v_mul_f32_e32 v57, v57, v57
	v_mul_f32_e32 v91, v62, v62
	v_mul_f32_e32 v93, v63, v63
	v_mov_b32_e32 v94, v62
	v_mov_b32_e32 v58, v63
	v_mov_b32_e32 v96, v60
	v_mov_b32_e32 v56, v61
	v_pk_fma_f32 v[60:61], v[60:61], v[60:61], v[98:99] op_sel_hi:[1,1,0]
	v_pk_add_f32 v[58:59], v[94:95], v[58:59]
	v_pk_add_f32 v[56:57], v[96:97], v[56:57]
	v_pk_add_f32 v[62:63], v[90:91], v[92:93]
	v_mov_b32_e32 v165, v61
	v_pk_add_f32 v[56:57], v[58:59], v[56:57]
	v_pk_add_f32 v[58:59], v[62:63], v[164:165]
	s_waitcnt vmcnt(2)
	v_pk_fma_f32 v[40:41], v[80:81], v[44:45], v[40:41]
	v_pk_fma_f32 v[42:43], v[82:83], v[46:47], v[42:43]
	s_waitcnt vmcnt(0)
	v_pk_fma_f32 v[44:45], v[88:89], v[48:49], v[52:53]
	v_pk_fma_f32 v[46:47], v[86:87], v[50:51], v[54:55]
	v_pk_fma_f32 v[38:39], v[42:43], s[30:31], v[38:39] op_sel_hi:[1,0,1]
	v_pk_fma_f32 v[36:37], v[40:41], s[30:31], v[36:37] op_sel_hi:[1,0,1]
	v_pk_fma_f32 v[40:41], v[46:47], s[30:31], v[34:35] op_sel_hi:[1,0,1]
	v_pk_fma_f32 v[42:43], v[44:45], s[30:31], v[32:33] op_sel_hi:[1,0,1]
	v_mul_f32_e32 v33, v36, v36
	v_mul_f32_e32 v35, v37, v37
	v_mul_f32_e32 v45, v38, v38
	v_mul_f32_e32 v47, v39, v39
	v_mov_b32_e32 v32, v36
	v_mov_b32_e32 v34, v37
	v_mov_b32_e32 v44, v38
	v_mov_b32_e32 v46, v39
	v_mul_f32_e32 v49, v42, v42
	v_mul_f32_e32 v51, v43, v43
	v_mul_f32_e32 v53, v40, v40
	v_mul_f32_e32 v55, v41, v41
	v_mov_b32_e32 v48, v42
	v_mov_b32_e32 v50, v43
	v_mov_b32_e32 v52, v40
	v_mov_b32_e32 v54, v41
	v_pk_add_f32 v[32:33], v[32:33], v[34:35]
	v_pk_add_f32 v[34:35], v[44:45], v[46:47]
	v_pk_add_f32 v[56:57], v[56:57], v[58:59]
	v_pk_add_f32 v[44:45], v[48:49], v[50:51]
	v_pk_add_f32 v[46:47], v[52:53], v[54:55]
	v_pk_add_f32 v[32:33], v[32:33], v[34:35]
	v_pk_add_f32 v[34:35], v[44:45], v[46:47]
	v_pk_add_f32 v[32:33], v[56:57], v[32:33]
	v_cvt_pk_bf16_f32 v36, v36, v37
	v_pk_add_f32 v[32:33], v[32:33], v[34:35]
	v_cvt_pk_bf16_f32 v37, v38, v39
	v_cvt_pk_bf16_f32 v38, v42, v43
	v_cvt_pk_bf16_f32 v39, v40, v41
	global_store_dwordx4 v[84:85], v[36:39], off offset:256
	s_waitcnt lgkmcnt(0)
	v_mov_b32_e32 v34, v32
	v_mov_b32_e32 v35, v33
	s_nop 1
	v_permlane16_swap_b32_e32 v34, v32
	v_permlane16_swap_b32_e32 v35, v33
	s_nop 0
	v_pk_add_f32 v[32:33], v[32:33], v[34:35]
	ds_bpermute_b32 v34, v244, v32
	ds_bpermute_b32 v35, v244, v33
	s_and_saveexec_b64 s[38:39], s[4:5]
	s_cbranch_execz .LBB0_1769
	v_lshl_add_u64 v[36:37], s[76:77], 0, v[120:121]
	v_lshl_add_u64 v[36:37], s[36:37], 3, v[36:37]
	s_lshl_b32 s16, s71, 3
	v_lshl_add_u64 v[36:37], v[36:37], 0, s[16:17]
	s_waitcnt lgkmcnt(0)
	v_pk_add_f32 v[32:33], v[32:33], v[34:35]
	global_store_dwordx2 v[36:37], v[32:33], off
; DI void row_stats(const f32x2v* st, size_t row, int fq, float& mu, float& rstd) {
;     ...
;     mu = s1 * (1.0f / 1024.0f); const float var = fmaxf(s2 * (1.0f / 1024.0f) - mu * mu, 0.f); rstd = rsqrtf(var + LN_EPS);
.LBB0_1769:
	s_or_b64 exec, exec, s[38:39]
	s_waitcnt lgkmcnt(0)
	global_load_dwordx4 v[32:35], v[180:181], off
	global_load_dwordx4 v[36:39], v[178:179], off
	global_load_dwordx4 v[40:43], v[178:179], off offset:16
	global_load_dwordx4 v[44:47], v[180:181], off offset:16
	v_pk_add_f32 v[48:49], v[116:117], v[118:119]
	v_lshlrev_b32_e32 v52, 16, v76
	v_pk_mul_f32 v[48:49], v[48:49], s[28:29] op_sel_hi:[1,0]
	v_and_b32_e32 v53, 0xffff0000, v76
	v_fma_f32 v49, -v48, v48, v49
	v_max_f32_e32 v49, 0, v49
	v_add_f32_e32 v49, 0x3727c5ac, v49
	v_mul_f32_e32 v60, 0x4b800000, v49
	v_cmp_gt_f32_e32 vcc, s91, v49
	v_lshlrev_b32_e32 v54, 16, v77
	v_and_b32_e32 v55, 0xffff0000, v77
	v_cndmask_b32_e32 v49, v49, v60, vcc
	v_rsq_f32_e32 v49, v49
	v_lshlrev_b32_e32 v56, 16, v78
	v_and_b32_e32 v57, 0xffff0000, v78
	v_lshlrev_b32_e32 v58, 16, v79
	v_and_b32_e32 v59, 0xffff0000, v79
	v_mul_f32_e32 v60, 0x45800000, v49
	v_sub_f32_e32 v53, v53, v48
	v_sub_f32_e32 v52, v52, v48
	v_sub_f32_e32 v55, v55, v48
	v_sub_f32_e32 v54, v54, v48
	v_sub_f32_e32 v57, v57, v48
	v_sub_f32_e32 v56, v56, v48
	v_sub_f32_e32 v59, v59, v48
	v_sub_f32_e32 v58, v58, v48
	v_cndmask_b32_e32 v60, v49, v60, vcc
	v_pk_mul_f32 v[54:55], v[54:55], v[60:61] op_sel_hi:[1,0]
	v_pk_mul_f32 v[52:53], v[52:53], v[60:61] op_sel_hi:[1,0]
	v_pk_mul_f32 v[58:59], v[58:59], v[60:61] op_sel_hi:[1,0]
	v_pk_mul_f32 v[56:57], v[56:57], v[60:61] op_sel_hi:[1,0]
	v_lshl_add_u64 v[50:51], s[44:45], 0, v[114:115]
	v_lshl_add_u64 v[50:51], v[176:177], 1, v[50:51]
	v_lshlrev_b32_e32 v49, 16, v72
	s_waitcnt vmcnt(2)
	v_pk_fma_f32 v[32:33], v[52:53], v[36:37], v[32:33]
	v_pk_fma_f32 v[34:35], v[54:55], v[38:39], v[34:35]
	s_waitcnt vmcnt(0)
	v_pk_fma_f32 v[36:37], v[56:57], v[40:41], v[44:45]
	v_pk_fma_f32 v[38:39], v[58:59], v[42:43], v[46:47]
	v_pk_fma_f32 v[40:41], v[34:35], s[30:31], v[30:31] op_sel_hi:[1,0,1]
	v_pk_fma_f32 v[42:43], v[32:33], s[30:31], v[28:29] op_sel_hi:[1,0,1]
	v_pk_fma_f32 v[44:45], v[38:39], s[30:31], v[26:27] op_sel_hi:[1,0,1]
	v_pk_fma_f32 v[46:47], v[36:37], s[30:31], v[24:25] op_sel_hi:[1,0,1]
	v_cvt_pk_bf16_f32 v24, v42, v43
	v_cvt_pk_bf16_f32 v25, v40, v41
	v_cvt_pk_bf16_f32 v26, v46, v47
	v_cvt_pk_bf16_f32 v27, v44, v45
	global_store_dwordx4 v[50:51], v[24:27], off
	global_load_dwordx4 v[24:27], v[180:181], off offset:512
	s_nop 0
	global_load_dwordx4 v[28:31], v[178:179], off offset:512
	global_load_dwordx4 v[32:35], v[178:179], off offset:528
	global_load_dwordx4 v[36:39], v[180:181], off offset:528
	v_and_b32_e32 v52, 0xffff0000, v72
	v_lshlrev_b32_e32 v54, 16, v73
	v_and_b32_e32 v55, 0xffff0000, v73
	v_lshlrev_b32_e32 v56, 16, v74
	v_and_b32_e32 v57, 0xffff0000, v74
	v_lshlrev_b32_e32 v58, 16, v75
	v_and_b32_e32 v59, 0xffff0000, v75
	v_sub_f32_e32 v53, v52, v48
	v_sub_f32_e32 v52, v49, v48
	v_sub_f32_e32 v55, v55, v48
	v_sub_f32_e32 v54, v54, v48
	v_sub_f32_e32 v57, v57, v48
	v_sub_f32_e32 v56, v56, v48
	v_sub_f32_e32 v49, v59, v48
	v_sub_f32_e32 v48, v58, v48
	v_pk_mul_f32 v[54:55], v[54:55], v[60:61] op_sel_hi:[1,0]
	v_pk_mul_f32 v[52:53], v[52:53], v[60:61] op_sel_hi:[1,0]
	v_pk_mul_f32 v[48:49], v[48:49], v[60:61] op_sel_hi:[1,0]
	v_pk_mul_f32 v[56:57], v[56:57], v[60:61] op_sel_hi:[1,0]
	v_mul_f32_e32 v74, v44, v44
	v_add_f32_e32 v58, v42, v43
	v_add_f32_e32 v60, v40, v41
	v_mul_f32_e32 v63, v42, v42
	v_mul_f32_e32 v43, v43, v43
	v_mul_f32_e32 v73, v40, v40
	v_mul_f32_e32 v41, v41, v41
	v_mul_f32_e32 v59, v46, v46
	v_mul_f32_e32 v61, v47, v47
	v_mov_b32_e32 v62, v46
	v_mov_b32_e32 v42, v47
	v_mov_b32_e32 v72, v44
	v_mov_b32_e32 v40, v45
	v_pk_fma_f32 v[44:45], v[44:45], v[44:45], v[74:75] op_sel_hi:[1,1,0]
	v_pk_add_f32 v[42:43], v[62:63], v[42:43]
	v_pk_add_f32 v[40:41], v[72:73], v[40:41]
	v_pk_add_f32 v[46:47], v[58:59], v[60:61]
	v_mov_b32_e32 v165, v45
	v_pk_add_f32 v[40:41], v[42:43], v[40:41]
	v_pk_add_f32 v[42:43], v[46:47], v[164:165]
	s_waitcnt vmcnt(2)
	v_pk_fma_f32 v[24:25], v[52:53], v[28:29], v[24:25]
	v_pk_fma_f32 v[26:27], v[54:55], v[30:31], v[26:27]
	s_waitcnt vmcnt(0)
	v_pk_fma_f32 v[28:29], v[56:57], v[32:33], v[36:37]
	v_pk_fma_f32 v[30:31], v[48:49], v[34:35], v[38:39]
	v_pk_fma_f32 v[22:23], v[26:27], s[30:31], v[22:23] op_sel_hi:[1,0,1]
	v_pk_fma_f32 v[20:21], v[24:25], s[30:31], v[20:21] op_sel_hi:[1,0,1]
	v_pk_fma_f32 v[24:25], v[30:31], s[30:31], v[18:19] op_sel_hi:[1,0,1]
	v_pk_fma_f32 v[26:27], v[28:29], s[30:31], v[16:17] op_sel_hi:[1,0,1]
	v_mul_f32_e32 v17, v20, v20
	v_mul_f32_e32 v19, v21, v21
	v_mul_f32_e32 v29, v22, v22
	v_mul_f32_e32 v31, v23, v23
	v_mov_b32_e32 v16, v20
	v_mov_b32_e32 v18, v21
	v_mov_b32_e32 v28, v22
	v_mov_b32_e32 v30, v23
	v_mul_f32_e32 v33, v26, v26
	v_mul_f32_e32 v35, v27, v27
	v_mul_f32_e32 v37, v24, v24
	v_mul_f32_e32 v39, v25, v25
	v_mov_b32_e32 v32, v26
	v_mov_b32_e32 v34, v27
	v_mov_b32_e32 v36, v24
	v_mov_b32_e32 v38, v25
	v_pk_add_f32 v[16:17], v[16:17], v[18:19]
	v_pk_add_f32 v[18:19], v[28:29], v[30:31]
	v_pk_add_f32 v[40:41], v[40:41], v[42:43]
	v_pk_add_f32 v[28:29], v[32:33], v[34:35]
	v_pk_add_f32 v[30:31], v[36:37], v[38:39]
	v_pk_add_f32 v[16:17], v[16:17], v[18:19]
	v_pk_add_f32 v[18:19], v[28:29], v[30:31]
	v_pk_add_f32 v[16:17], v[40:41], v[16:17]
	v_cvt_pk_bf16_f32 v20, v20, v21
	v_pk_add_f32 v[16:17], v[16:17], v[18:19]
	v_cvt_pk_bf16_f32 v21, v22, v23
	v_cvt_pk_bf16_f32 v22, v26, v27
	v_cvt_pk_bf16_f32 v23, v24, v25
	global_store_dwordx4 v[50:51], v[20:23], off offset:256
	s_waitcnt lgkmcnt(0)
	v_mov_b32_e32 v18, v16
	v_mov_b32_e32 v19, v17
	s_nop 1
	v_permlane16_swap_b32_e32 v18, v16
	v_permlane16_swap_b32_e32 v19, v17
	s_nop 0
	v_pk_add_f32 v[16:17], v[16:17], v[18:19]
	ds_bpermute_b32 v18, v244, v16
	ds_bpermute_b32 v19, v244, v17
	s_and_saveexec_b64 s[38:39], s[4:5]
	s_cbranch_execz .LBB0_1771
	v_lshl_add_u64 v[20:21], s[76:77], 0, v[112:113]
	v_lshl_add_u64 v[20:21], s[36:37], 3, v[20:21]
	s_lshl_b32 s16, s71, 3
	v_lshl_add_u64 v[20:21], v[20:21], 0, s[16:17]
	s_waitcnt lgkmcnt(0)
	v_pk_add_f32 v[16:17], v[16:17], v[18:19]
	global_store_dwordx2 v[20:21], v[16:17], off
; DI void row_stats(const f32x2v* st, size_t row, int fq, float& mu, float& rstd) {
;     ...
;     mu = s1 * (1.0f / 1024.0f); const float var = fmaxf(s2 * (1.0f / 1024.0f) - mu * mu, 0.f); rstd = rsqrtf(var + LN_EPS);
.LBB0_1771:
	s_or_b64 exec, exec, s[38:39]
	s_waitcnt lgkmcnt(0)
	global_load_dwordx4 v[16:19], v[180:181], off
	global_load_dwordx4 v[20:23], v[178:179], off
	global_load_dwordx4 v[24:27], v[178:179], off offset:16
	global_load_dwordx4 v[28:31], v[180:181], off offset:16
	v_pk_add_f32 v[32:33], v[108:109], v[110:111]
	v_lshlrev_b32_e32 v36, 16, v68
	v_pk_mul_f32 v[32:33], v[32:33], s[28:29] op_sel_hi:[1,0]
	v_and_b32_e32 v37, 0xffff0000, v68
	v_fma_f32 v33, -v32, v32, v33
	v_max_f32_e32 v33, 0, v33
	v_add_f32_e32 v33, 0x3727c5ac, v33
	v_mul_f32_e32 v44, 0x4b800000, v33
	v_cmp_gt_f32_e32 vcc, s91, v33
	v_lshlrev_b32_e32 v38, 16, v69
	v_and_b32_e32 v39, 0xffff0000, v69
	v_cndmask_b32_e32 v33, v33, v44, vcc
	v_rsq_f32_e32 v33, v33
	v_lshlrev_b32_e32 v40, 16, v70
	v_and_b32_e32 v41, 0xffff0000, v70
	v_lshlrev_b32_e32 v42, 16, v71
	v_and_b32_e32 v43, 0xffff0000, v71
	v_mul_f32_e32 v44, 0x45800000, v33
	v_sub_f32_e32 v37, v37, v32
	v_sub_f32_e32 v36, v36, v32
	v_sub_f32_e32 v39, v39, v32
	v_sub_f32_e32 v38, v38, v32
	v_sub_f32_e32 v41, v41, v32
	v_sub_f32_e32 v40, v40, v32
	v_sub_f32_e32 v43, v43, v32
	v_sub_f32_e32 v42, v42, v32
	v_cndmask_b32_e32 v44, v33, v44, vcc
	v_pk_mul_f32 v[38:39], v[38:39], v[44:45] op_sel_hi:[1,0]
	v_pk_mul_f32 v[36:37], v[36:37], v[44:45] op_sel_hi:[1,0]
	v_pk_mul_f32 v[42:43], v[42:43], v[44:45] op_sel_hi:[1,0]
	v_pk_mul_f32 v[40:41], v[40:41], v[44:45] op_sel_hi:[1,0]
	v_lshl_add_u64 v[34:35], s[44:45], 0, v[106:107]
	v_lshl_add_u64 v[34:35], v[176:177], 1, v[34:35]
	v_lshlrev_b32_e32 v33, 16, v64
	s_waitcnt vmcnt(2)
	v_pk_fma_f32 v[16:17], v[36:37], v[20:21], v[16:17]
	v_pk_fma_f32 v[18:19], v[38:39], v[22:23], v[18:19]
	s_waitcnt vmcnt(0)
	v_pk_fma_f32 v[20:21], v[40:41], v[24:25], v[28:29]
	v_pk_fma_f32 v[22:23], v[42:43], v[26:27], v[30:31]
	v_pk_fma_f32 v[24:25], v[18:19], s[30:31], v[14:15] op_sel_hi:[1,0,1]
	v_pk_fma_f32 v[26:27], v[16:17], s[30:31], v[12:13] op_sel_hi:[1,0,1]
	v_pk_fma_f32 v[28:29], v[22:23], s[30:31], v[10:11] op_sel_hi:[1,0,1]
	v_pk_fma_f32 v[30:31], v[20:21], s[30:31], v[8:9] op_sel_hi:[1,0,1]
	v_cvt_pk_bf16_f32 v8, v26, v27
	v_cvt_pk_bf16_f32 v9, v24, v25
	v_cvt_pk_bf16_f32 v10, v30, v31
	v_cvt_pk_bf16_f32 v11, v28, v29
	global_store_dwordx4 v[34:35], v[8:11], off
	global_load_dwordx4 v[8:11], v[180:181], off offset:512
	s_nop 0
	global_load_dwordx4 v[12:15], v[178:179], off offset:512
	global_load_dwordx4 v[16:19], v[178:179], off offset:528
	global_load_dwordx4 v[20:23], v[180:181], off offset:528
	v_and_b32_e32 v36, 0xffff0000, v64
	v_lshlrev_b32_e32 v38, 16, v65
	v_and_b32_e32 v39, 0xffff0000, v65
	v_lshlrev_b32_e32 v40, 16, v66
	v_and_b32_e32 v41, 0xffff0000, v66
	v_lshlrev_b32_e32 v42, 16, v67
	v_and_b32_e32 v43, 0xffff0000, v67
	v_sub_f32_e32 v37, v36, v32
	v_sub_f32_e32 v36, v33, v32
	v_sub_f32_e32 v39, v39, v32
	v_sub_f32_e32 v38, v38, v32
	v_sub_f32_e32 v41, v41, v32
	v_sub_f32_e32 v40, v40, v32
	v_sub_f32_e32 v33, v43, v32
	v_sub_f32_e32 v32, v42, v32
	v_pk_mul_f32 v[38:39], v[38:39], v[44:45] op_sel_hi:[1,0]
	v_pk_mul_f32 v[36:37], v[36:37], v[44:45] op_sel_hi:[1,0]
	v_pk_mul_f32 v[32:33], v[32:33], v[44:45] op_sel_hi:[1,0]
	v_pk_mul_f32 v[40:41], v[40:41], v[44:45] op_sel_hi:[1,0]
	v_mul_f32_e32 v50, v28, v28
	v_add_f32_e32 v42, v26, v27
	v_add_f32_e32 v44, v24, v25
	v_mul_f32_e32 v47, v26, v26
	v_mul_f32_e32 v27, v27, v27
	v_mul_f32_e32 v49, v24, v24
	v_mul_f32_e32 v25, v25, v25
	v_mul_f32_e32 v43, v30, v30
	v_mul_f32_e32 v45, v31, v31
	v_mov_b32_e32 v46, v30
	v_mov_b32_e32 v26, v31
	v_mov_b32_e32 v48, v28
	v_mov_b32_e32 v24, v29
	v_pk_fma_f32 v[28:29], v[28:29], v[28:29], v[50:51] op_sel_hi:[1,1,0]
	v_pk_add_f32 v[26:27], v[46:47], v[26:27]
	v_pk_add_f32 v[24:25], v[48:49], v[24:25]
	v_pk_add_f32 v[30:31], v[42:43], v[44:45]
	v_mov_b32_e32 v165, v29
	v_pk_add_f32 v[24:25], v[26:27], v[24:25]
	v_pk_add_f32 v[26:27], v[30:31], v[164:165]
	s_waitcnt vmcnt(2)
	v_pk_fma_f32 v[8:9], v[36:37], v[12:13], v[8:9]
	v_pk_fma_f32 v[10:11], v[38:39], v[14:15], v[10:11]
	s_waitcnt vmcnt(0)
	v_pk_fma_f32 v[12:13], v[40:41], v[16:17], v[20:21]
	v_pk_fma_f32 v[14:15], v[32:33], v[18:19], v[22:23]
	v_pk_fma_f32 v[6:7], v[10:11], s[30:31], v[6:7] op_sel_hi:[1,0,1]
	v_pk_fma_f32 v[4:5], v[8:9], s[30:31], v[4:5] op_sel_hi:[1,0,1]
	v_pk_fma_f32 v[8:9], v[14:15], s[30:31], v[2:3] op_sel_hi:[1,0,1]
	v_pk_fma_f32 v[10:11], v[12:13], s[30:31], v[0:1] op_sel_hi:[1,0,1]
	v_mul_f32_e32 v1, v4, v4
	v_mul_f32_e32 v3, v5, v5
	v_mul_f32_e32 v13, v6, v6
	v_mul_f32_e32 v15, v7, v7
	v_mov_b32_e32 v0, v4
	v_mov_b32_e32 v2, v5
	v_mov_b32_e32 v12, v6
	v_mov_b32_e32 v14, v7
	v_mul_f32_e32 v17, v10, v10
	v_mul_f32_e32 v19, v11, v11
	v_mul_f32_e32 v21, v8, v8
	v_mul_f32_e32 v23, v9, v9
	v_mov_b32_e32 v16, v10
	v_mov_b32_e32 v18, v11
	v_mov_b32_e32 v20, v8
	v_mov_b32_e32 v22, v9
	v_pk_add_f32 v[0:1], v[0:1], v[2:3]
	v_pk_add_f32 v[2:3], v[12:13], v[14:15]
	v_pk_add_f32 v[24:25], v[24:25], v[26:27]
	v_pk_add_f32 v[12:13], v[16:17], v[18:19]
	v_pk_add_f32 v[14:15], v[20:21], v[22:23]
	v_pk_add_f32 v[0:1], v[0:1], v[2:3]
	v_pk_add_f32 v[2:3], v[12:13], v[14:15]
	v_pk_add_f32 v[0:1], v[24:25], v[0:1]
	v_cvt_pk_bf16_f32 v4, v4, v5
	v_pk_add_f32 v[0:1], v[0:1], v[2:3]
	v_cvt_pk_bf16_f32 v5, v6, v7
	v_cvt_pk_bf16_f32 v6, v10, v11
	v_cvt_pk_bf16_f32 v7, v8, v9
	global_store_dwordx4 v[34:35], v[4:7], off offset:256
	s_waitcnt lgkmcnt(0)
	v_mov_b32_e32 v2, v0
	v_mov_b32_e32 v3, v1
	s_nop 1
	v_permlane16_swap_b32_e32 v2, v0
	v_permlane16_swap_b32_e32 v3, v1
	s_nop 0
	v_pk_add_f32 v[0:1], v[0:1], v[2:3]
	ds_bpermute_b32 v2, v244, v0
	ds_bpermute_b32 v3, v244, v1
	s_and_saveexec_b64 s[38:39], s[4:5]
	s_cbranch_execz .LBB0_1773
	v_lshl_add_u64 v[4:5], s[76:77], 0, v[104:105]
	v_lshl_add_u64 v[4:5], s[36:37], 3, v[4:5]
	s_lshl_b32 s16, s71, 3
	v_lshl_add_u64 v[4:5], v[4:5], 0, s[16:17]
	s_waitcnt lgkmcnt(0)
	v_pk_add_f32 v[0:1], v[0:1], v[2:3]
	global_store_dwordx2 v[4:5], v[0:1], off

; DI void row_stats(const f32x2v* st, size_t row, int fq, float& mu, float& rstd) {
;     const f32x4 a = *(const f32x4*)(st + row * 16 + 4 * fq), b = *(const f32x4*)(st + row * 16 + 4 * fq + 2);
;     float s1 = (a[0] + a[2]) + (b[0] + b[2]), s2 = (a[1] + a[3]) + (b[1] + b[3]);
;     s1 += __shfl_xor(s1, 16); s1 += __shfl_xor(s1, 32); s2 += __shfl_xor(s2, 16); s2 += __shfl_xor(s2, 32);
;     mu = s1 * (1.0f / 1024.0f); const float var = fmaxf(s2 * (1.0f / 1024.0f) - mu * mu, 0.f); rstd = rsqrtf(var + LN_EPS);
.LBB0_1857:
	v_and_b32_e32 v121, 64, v241
	v_xor_b32_e32 v120, 16, v241
	v_add_u32_e32 v121, 64, v121
	v_cmp_lt_i32_e32 vcc, v120, v121
	s_ashr_i32 s35, s34, 31
	s_lshl_b64 s[34:35], s[34:35], 8
	v_cndmask_b32_e32 v120, v241, v120, vcc
	v_lshlrev_b32_e32 v242, 2, v120
	v_xor_b32_e32 v120, 32, v241
	v_cmp_lt_i32_e32 vcc, v120, v121
	v_lshl_add_u64 v[224:225], s[34:35], 0, v[204:205]
	v_lshl_or_b32 v222, s94, 8, v195
	v_cndmask_b32_e32 v120, v241, v120, vcc
	v_lshlrev_b32_e32 v243, 2, v120
	v_lshlrev_b64 v[120:121], 7, v[224:225]
	v_lshl_add_u64 v[124:125], v[206:207], 0, v[120:121]
	global_load_dwordx4 v[120:123], v[124:125], off offset:16
	s_nop 0
	global_load_dwordx4 v[124:127], v[124:125], off
	v_ashrrev_i32_e32 v223, 31, v222
	v_or_b32_e32 v226, 16, v224
	v_mov_b32_e32 v227, v225
	v_lshlrev_b64 v[172:173], 2, v[222:223]
	v_lshl_add_u64 v[214:215], s[62:63], 0, v[172:173]
	v_lshl_add_u64 v[216:217], s[64:65], 0, v[172:173]
	v_lshl_add_u64 v[218:219], s[16:17], 0, v[172:173]
	v_lshl_add_u64 v[220:221], s[20:21], 0, v[172:173]
	s_mov_b64 s[34:35], 0x90
	s_waitcnt vmcnt(0)
	v_mov_b32_e32 v137, v120
	v_mov_b32_e32 v136, v124
	v_mov_b32_e32 v138, v126
	v_mov_b32_e32 v139, v122
	v_pk_add_f32 v[136:137], v[136:137], v[138:139]
	v_add_f32_e32 v120, v125, v127
	v_add_f32_e32 v122, v121, v123
	v_mov_b32_e32 v121, v136
	v_mov_b32_e32 v123, v137
	v_pk_add_f32 v[120:121], v[120:121], v[122:123]
	s_waitcnt lgkmcnt(0)
	v_mov_b32_e32 v123, v121
	v_mov_b32_e32 v122, v120
	s_nop 1
	v_permlane16_swap_b32_e32 v123, v121
	v_permlane16_swap_b32_e32 v122, v120
	s_nop 0
	v_pk_add_f32 v[120:121], v[120:121], v[122:123]
	s_waitcnt lgkmcnt(0)
	v_mov_b32_e32 v123, v121
	v_mov_b32_e32 v122, v120
	s_nop 1
	v_permlane32_swap_b32_e32 v123, v121
	v_permlane32_swap_b32_e32 v122, v120
	s_nop 0
	v_pk_add_f32 v[120:121], v[120:121], v[122:123]
	s_nop 0
	v_pk_mul_f32 v[234:235], v[120:121], s[28:29] op_sel_hi:[1,0]
	s_nop 0
	v_fma_f32 v120, -v235, v235, v234
	v_max_f32_e32 v120, 0, v120
	v_add_f32_e32 v120, 0x3727c5ac, v120
	v_cmp_gt_f32_e32 vcc, s91, v120
	v_mul_f32_e32 v121, 0x4b800000, v120
	s_nop 0
	v_cndmask_b32_e32 v120, v120, v121, vcc
	v_rsq_f32_e32 v120, v120
	s_nop 0
	v_mul_f32_e32 v121, 0x45800000, v120
	v_cndmask_b32_e32 v236, v120, v121, vcc
	v_lshlrev_b64 v[120:121], 10, v[224:225]
	v_lshl_add_u64 v[120:121], v[120:121], 0, v[222:223]
	v_lshlrev_b64 v[238:239], 1, v[120:121]
	v_lshl_add_u64 v[120:121], s[48:49], 0, v[238:239]
	global_load_dwordx4 v[156:159], v[120:121], off
	v_lshl_add_u64 v[120:121], s[44:45], 0, v[238:239]
	global_load_dwordx4 v[152:155], v[120:121], off
	v_or_b32_e32 v120, 0x100, v238
	v_mov_b32_e32 v121, v239
	v_lshl_add_u64 v[122:123], s[48:49], 0, v[120:121]
	v_lshl_add_u64 v[120:121], s[44:45], 0, v[120:121]
	global_load_dwordx4 v[144:147], v[120:121], off
	v_lshlrev_b64 v[120:121], 7, v[226:227]
	v_lshl_add_u64 v[124:125], v[206:207], 0, v[120:121]
	global_load_dwordx4 v[148:151], v[122:123], off
	s_nop 0
	global_load_dwordx4 v[120:123], v[124:125], off offset:16
	s_nop 0
	global_load_dwordx4 v[124:127], v[124:125], off
	s_waitcnt vmcnt(1)
	v_mov_b32_e32 v137, v120
	s_waitcnt vmcnt(0)
	v_mov_b32_e32 v136, v124
	v_mov_b32_e32 v138, v126
	v_mov_b32_e32 v139, v122
	v_pk_add_f32 v[136:137], v[136:137], v[138:139]
	v_add_f32_e32 v120, v125, v127
	v_add_f32_e32 v122, v121, v123
	v_mov_b32_e32 v121, v136
	v_mov_b32_e32 v123, v137
	v_pk_add_f32 v[120:121], v[120:121], v[122:123]
	s_waitcnt lgkmcnt(0)
	v_mov_b32_e32 v123, v121
	v_mov_b32_e32 v122, v120
	s_nop 1
	v_permlane16_swap_b32_e32 v123, v121
	v_permlane16_swap_b32_e32 v122, v120
	s_nop 0
	v_pk_add_f32 v[120:121], v[120:121], v[122:123]
	s_waitcnt lgkmcnt(0)
	v_mov_b32_e32 v123, v121
	v_mov_b32_e32 v122, v120
	s_nop 1
	v_permlane32_swap_b32_e32 v123, v121
	v_permlane32_swap_b32_e32 v122, v120
	s_nop 0
	v_pk_add_f32 v[120:121], v[120:121], v[122:123]
	s_nop 0
	v_pk_mul_f32 v[228:229], v[120:121], s[28:29] op_sel_hi:[1,0]
	s_nop 0
	v_fma_f32 v120, -v229, v229, v228
	v_max_f32_e32 v120, 0, v120
	v_add_f32_e32 v120, 0x3727c5ac, v120
	v_cmp_gt_f32_e32 vcc, s91, v120
	v_mul_f32_e32 v121, 0x4b800000, v120
	s_nop 0
	v_cndmask_b32_e32 v120, v120, v121, vcc
	v_rsq_f32_e32 v120, v120
	s_nop 0
	v_mul_f32_e32 v121, 0x45800000, v120
	v_cndmask_b32_e32 v230, v120, v121, vcc
	v_lshlrev_b64 v[120:121], 10, v[226:227]
	v_lshl_add_u64 v[120:121], v[120:121], 0, v[222:223]
	v_lshlrev_b64 v[232:233], 1, v[120:121]
	v_lshl_add_u64 v[120:121], s[48:49], 0, v[232:233]
	global_load_dwordx4 v[140:143], v[120:121], off
	v_lshl_add_u64 v[120:121], s[44:45], 0, v[232:233]
	global_load_dwordx4 v[136:139], v[120:121], off
	v_or_b32_e32 v120, 0x100, v232
	v_mov_b32_e32 v121, v233
	v_lshl_add_u64 v[122:123], s[48:49], 0, v[120:121]
	v_lshl_add_u64 v[120:121], s[44:45], 0, v[120:121]
	global_load_dwordx4 v[124:127], v[122:123], off
	s_nop 0
	global_load_dwordx4 v[120:123], v[120:121], off
	s_nop 0
	global_load_dwordx4 v[160:163], v[214:215], off offset:16
	global_load_dwordx4 v[176:179], v[214:215], off
	global_load_dwordx4 v[164:167], v[216:217], off offset:16
	global_load_dwordx4 v[180:183], v[216:217], off
	global_load_dwordx4 v[168:171], v[218:219], off offset:16
	global_load_dwordx4 v[184:187], v[218:219], off
	global_load_dwordx4 v[172:175], v[220:221], off offset:16
	global_load_dwordx4 v[188:191], v[220:221], off
	s_waitcnt vmcnt(3)
	v_fma_f32 v128, -v235, v168, v128
	s_waitcnt vmcnt(2)
	v_fma_f32 v134, -v235, v186, v134
	v_fma_f32 v135, -v235, v187, v135
	s_waitcnt vmcnt(0)
	v_fma_f32 v134, v236, v134, v190
	v_fmac_f32_e32 v191, v236, v135
	v_mul_f32_e32 v134, 0xbfb8aa3b, v134
	v_mul_f32_e32 v135, 0xbfb8aa3b, v191
	v_exp_f32_e32 v134, v134
	v_exp_f32_e32 v135, v135
	v_fma_f32 v129, -v235, v169, v129
	v_fma_f32 v128, v236, v128, v172
	v_fma_f32 v129, v236, v129, v173
	v_mul_f32_e32 v128, 0xbfb8aa3b, v128
	v_mul_f32_e32 v129, 0xbfb8aa3b, v129
	v_fma_f32 v132, -v235, v184, v132
	v_fma_f32 v133, -v235, v185, v133
	v_add_f32_e32 v134, 1.0, v134
	v_add_f32_e32 v135, 1.0, v135
	v_exp_f32_e32 v128, v128
	v_exp_f32_e32 v129, v129
	v_fma_f32 v132, v236, v132, v188
	v_fma_f32 v133, v236, v133, v189
	v_lshlrev_b32_e32 v188, 16, v152
	v_and_b32_e32 v189, 0xffff0000, v152
	v_rcp_f32_e32 v134, v134
	v_rcp_f32_e32 v135, v135
	v_lshlrev_b32_e32 v152, 16, v153
	v_and_b32_e32 v153, 0xffff0000, v153
	v_pk_add_f32 v[152:153], v[152:153], v[234:235] op_sel:[0,1] neg_lo:[0,1] neg_hi:[0,1]
	v_lshlrev_b32_e32 v184, 16, v156
	v_pk_mul_f32 v[152:153], v[152:153], v[236:237] op_sel_hi:[1,0]
	v_and_b32_e32 v185, 0xffff0000, v156
	v_lshlrev_b32_e32 v156, 16, v157
	v_and_b32_e32 v157, 0xffff0000, v157
	v_pk_fma_f32 v[152:153], v[152:153], v[178:179], v[182:183]
	v_add_f32_e32 v128, 1.0, v128
	v_add_f32_e32 v129, 1.0, v129
	v_pk_fma_f32 v[134:135], v[134:135], v[156:157], v[152:153]
	v_rcp_f32_e32 v128, v128
	v_rcp_f32_e32 v129, v129
	v_lshlrev_b32_e32 v156, 16, v154
	v_and_b32_e32 v157, 0xffff0000, v154
	v_pk_add_f32 v[156:157], v[156:157], v[234:235] op_sel:[0,1] neg_lo:[0,1] neg_hi:[0,1]
	v_lshlrev_b32_e32 v152, 16, v158
	v_pk_mul_f32 v[156:157], v[156:157], v[236:237] op_sel_hi:[1,0]
	v_and_b32_e32 v153, 0xffff0000, v158
	v_pk_fma_f32 v[156:157], v[156:157], v[160:161], v[164:165]
	v_mul_f32_e32 v132, 0xbfb8aa3b, v132
	v_pk_fma_f32 v[152:153], v[128:129], v[152:153], v[156:157]
	v_fma_f32 v128, -v235, v170, v130
	v_fma_f32 v129, -v235, v171, v131
	v_fma_f32 v128, v236, v128, v174
	v_fmac_f32_e32 v175, v236, v129
	v_mul_f32_e32 v128, 0xbfb8aa3b, v128
	v_mul_f32_e32 v129, 0xbfb8aa3b, v175
	v_mul_f32_e32 v133, 0xbfb8aa3b, v133
	v_exp_f32_e32 v128, v128
	v_exp_f32_e32 v129, v129
	v_exp_f32_e32 v132, v132
	v_exp_f32_e32 v133, v133
	v_add_f32_e32 v128, 1.0, v128
	v_add_f32_e32 v129, 1.0, v129
	v_add_f32_e32 v132, 1.0, v132
	v_add_f32_e32 v133, 1.0, v133
	v_rcp_f32_e32 v128, v128
	v_rcp_f32_e32 v129, v129
	v_lshlrev_b32_e32 v154, 16, v155
	v_and_b32_e32 v155, 0xffff0000, v155
	v_rcp_f32_e32 v132, v132
	v_rcp_f32_e32 v133, v133
	v_pk_add_f32 v[154:155], v[154:155], v[234:235] op_sel:[0,1] neg_lo:[0,1] neg_hi:[0,1]
	v_pk_add_f32 v[188:189], v[188:189], v[234:235] op_sel:[0,1] neg_lo:[0,1] neg_hi:[0,1]
	v_pk_mul_f32 v[154:155], v[154:155], v[236:237] op_sel_hi:[1,0]
	v_pk_mul_f32 v[188:189], v[188:189], v[236:237] op_sel_hi:[1,0]
	v_lshlrev_b32_e32 v130, 16, v159
	v_and_b32_e32 v131, 0xffff0000, v159
	v_pk_fma_f32 v[154:155], v[154:155], v[162:163], v[166:167]
	v_pk_fma_f32 v[176:177], v[188:189], v[176:177], v[180:181]
	v_pk_fma_f32 v[154:155], v[128:129], v[130:131], v[154:155]
	v_cvt_pk_bf16_f32 v130, v152, v153
	v_or_b32_e32 v152, 0x80, v222
	v_pk_fma_f32 v[132:133], v[132:133], v[184:185], v[176:177]
	v_ashrrev_i32_e32 v153, 31, v152
	v_cvt_pk_bf16_f32 v128, v132, v133
	v_cvt_pk_bf16_f32 v129, v134, v135
	v_cvt_pk_bf16_f32 v131, v154, v155
	v_lshl_add_u64 v[132:133], s[52:53], 0, v[238:239]
	v_lshlrev_b64 v[152:153], 2, v[152:153]
	global_store_dwordx4 v[132:133], v[128:131], off
	v_lshl_add_u64 v[160:161], s[16:17], 0, v[152:153]
	global_load_dwordx4 v[128:131], v[214:215], off offset:528
	global_load_dwordx4 v[156:159], v[214:215], off offset:512
	global_load_dwordx4 v[132:135], v[216:217], off offset:528
	global_load_dwordx4 v[164:167], v[216:217], off offset:512
	global_load_dwordx4 v[168:171], v[160:161], off
	v_lshl_add_u64 v[162:163], s[20:21], 0, v[152:153]
	global_load_dwordx4 v[152:155], v[162:163], off offset:16
	global_load_dwordx4 v[172:175], v[162:163], off
	v_or_b32_e32 v176, 32, v224
	v_mov_b32_e32 v177, v225
	s_waitcnt vmcnt(2)
	v_fma_f32 v118, -v235, v170, v118
	v_fma_f32 v119, -v235, v171, v119
	s_waitcnt vmcnt(0)
	v_fma_f32 v118, v236, v118, v174
	v_fmac_f32_e32 v175, v236, v119
	v_mul_f32_e32 v118, 0xbfb8aa3b, v118
	v_mul_f32_e32 v119, 0xbfb8aa3b, v175
	v_fma_f32 v116, -v235, v168, v116
	v_fma_f32 v117, -v235, v169, v117
	v_exp_f32_e32 v118, v118
	v_exp_f32_e32 v119, v119
	v_fma_f32 v116, v236, v116, v172
	v_fma_f32 v117, v236, v117, v173
	v_mul_f32_e32 v116, 0xbfb8aa3b, v116
	v_mul_f32_e32 v117, 0xbfb8aa3b, v117
	v_exp_f32_e32 v116, v116
	v_exp_f32_e32 v117, v117
	v_add_f32_e32 v118, 1.0, v118
	v_add_f32_e32 v119, 1.0, v119
	v_lshlrev_b32_e32 v172, 16, v144
	v_and_b32_e32 v173, 0xffff0000, v144
	v_rcp_f32_e32 v118, v118
	v_rcp_f32_e32 v119, v119
	v_lshlrev_b32_e32 v144, 16, v145
	v_and_b32_e32 v145, 0xffff0000, v145
	v_pk_add_f32 v[144:145], v[144:145], v[234:235] op_sel:[0,1] neg_lo:[0,1] neg_hi:[0,1]
	v_add_f32_e32 v116, 1.0, v116
	v_add_f32_e32 v117, 1.0, v117
	v_pk_mul_f32 v[144:145], v[144:145], v[236:237] op_sel_hi:[1,0]
	v_rcp_f32_e32 v116, v116
	v_rcp_f32_e32 v117, v117
	v_lshlrev_b32_e32 v168, 16, v148
	v_and_b32_e32 v169, 0xffff0000, v148
	v_lshlrev_b32_e32 v148, 16, v149
	v_and_b32_e32 v149, 0xffff0000, v149
	v_pk_fma_f32 v[144:145], v[144:145], v[158:159], v[166:167]
	v_pk_add_f32 v[172:173], v[172:173], v[234:235] op_sel:[0,1] neg_lo:[0,1] neg_hi:[0,1]
	v_pk_fma_f32 v[118:119], v[118:119], v[148:149], v[144:145]
	v_or_b32_e32 v144, 0x84, v222
	v_pk_mul_f32 v[172:173], v[172:173], v[236:237] op_sel_hi:[1,0]
	v_ashrrev_i32_e32 v145, 31, v144
	v_pk_fma_f32 v[156:157], v[172:173], v[156:157], v[164:165]
	v_lshl_add_u64 v[164:165], v[144:145], 2, s[16:17]
	v_pk_fma_f32 v[116:117], v[116:117], v[168:169], v[156:157]
	global_load_dwordx4 v[156:159], v[164:165], off
	v_lshlrev_b32_e32 v148, 16, v146
	v_and_b32_e32 v149, 0xffff0000, v146
	v_pk_add_f32 v[148:149], v[148:149], v[234:235] op_sel:[0,1] neg_lo:[0,1] neg_hi:[0,1]
	v_lshlrev_b32_e32 v144, 16, v150
	v_pk_mul_f32 v[148:149], v[148:149], v[236:237] op_sel_hi:[1,0]
	v_and_b32_e32 v145, 0xffff0000, v150
	v_pk_fma_f32 v[128:129], v[148:149], v[128:129], v[132:133]
	v_lshlrev_b32_e32 v132, 16, v147
	v_and_b32_e32 v133, 0xffff0000, v147
	v_pk_add_f32 v[132:133], v[132:133], v[234:235] op_sel:[0,1] neg_lo:[0,1] neg_hi:[0,1]
	v_lshlrev_b64 v[166:167], 1, v[222:223]
	v_pk_mul_f32 v[132:133], v[132:133], v[236:237] op_sel_hi:[1,0]
	v_or_b32_e32 v168, 48, v224
	v_pk_fma_f32 v[130:131], v[132:133], v[130:131], v[134:135]
	v_mov_b32_e32 v169, v225
	s_waitcnt vmcnt(0)
	v_fma_f32 v112, -v235, v156, v112
	v_fma_f32 v113, -v235, v157, v113
	v_fma_f32 v112, v236, v112, v152
	v_fma_f32 v113, v236, v113, v153
	v_mul_f32_e32 v112, 0xbfb8aa3b, v112
	v_mul_f32_e32 v113, 0xbfb8aa3b, v113
	v_exp_f32_e32 v112, v112
	v_exp_f32_e32 v113, v113
	v_add_f32_e32 v112, 1.0, v112
	v_add_f32_e32 v113, 1.0, v113
	v_rcp_f32_e32 v112, v112
	v_rcp_f32_e32 v113, v113
	s_nop 0
	v_pk_fma_f32 v[128:129], v[112:113], v[144:145], v[128:129]
	v_fma_f32 v112, -v235, v158, v114
	v_fma_f32 v113, -v235, v159, v115
	v_fma_f32 v112, v236, v112, v154
	v_fmac_f32_e32 v155, v236, v113
	v_mul_f32_e32 v112, 0xbfb8aa3b, v112
	v_mul_f32_e32 v113, 0xbfb8aa3b, v155
	v_exp_f32_e32 v112, v112
	v_exp_f32_e32 v113, v113
	v_lshlrev_b32_e32 v114, 16, v151
	v_and_b32_e32 v115, 0xffff0000, v151
	v_add_f32_e32 v112, 1.0, v112
	v_add_f32_e32 v113, 1.0, v113
	v_rcp_f32_e32 v112, v112
	v_rcp_f32_e32 v113, v113
	s_nop 0
	v_pk_fma_f32 v[130:131], v[112:113], v[114:115], v[130:131]
	v_cvt_pk_bf16_f32 v112, v116, v117
	v_lshlrev_b64 v[116:117], 11, v[224:225]
	v_lshl_add_u64 v[116:117], s[52:53], 0, v[116:117]
	v_cvt_pk_bf16_f32 v113, v118, v119
	v_cvt_pk_bf16_f32 v114, v128, v129
	v_cvt_pk_bf16_f32 v115, v130, v131
	v_lshl_add_u64 v[116:117], v[116:117], 0, v[166:167]
	global_store_dwordx4 v[116:117], v[112:115], off offset:256
	global_load_dwordx4 v[112:115], v[214:215], off offset:16
	s_nop 0
	global_load_dwordx4 v[144:147], v[214:215], off
	global_load_dwordx4 v[116:119], v[216:217], off offset:16
	global_load_dwordx4 v[148:151], v[216:217], off
	global_load_dwordx4 v[128:131], v[218:219], off offset:16
	global_load_dwordx4 v[152:155], v[218:219], off
	global_load_dwordx4 v[132:135], v[220:221], off offset:16
	global_load_dwordx4 v[156:159], v[220:221], off
	s_waitcnt vmcnt(3)
	v_fma_f32 v104, -v229, v128, v104
	v_fma_f32 v105, -v229, v129, v105
	s_waitcnt vmcnt(1)
	v_fma_f32 v104, v230, v104, v132
	v_fma_f32 v105, v230, v105, v133
	v_mul_f32_e32 v104, 0xbfb8aa3b, v104
	v_mul_f32_e32 v105, 0xbfb8aa3b, v105
	v_exp_f32_e32 v104, v104
	v_exp_f32_e32 v105, v105
	v_lshlrev_b32_e32 v132, 16, v138
	v_and_b32_e32 v133, 0xffff0000, v138
	v_add_f32_e32 v104, 1.0, v104
	v_add_f32_e32 v105, 1.0, v105
	v_rcp_f32_e32 v104, v104
	v_rcp_f32_e32 v105, v105
	v_pk_add_f32 v[132:133], v[132:133], v[228:229] op_sel:[0,1] neg_lo:[0,1] neg_hi:[0,1]
	v_lshlrev_b32_e32 v128, 16, v142
	v_pk_mul_f32 v[132:133], v[132:133], v[230:231] op_sel_hi:[1,0]
	v_and_b32_e32 v129, 0xffff0000, v142
	v_pk_fma_f32 v[112:113], v[132:133], v[112:113], v[116:117]
	v_fma_f32 v108, -v229, v152, v108
	v_fma_f32 v109, -v229, v153, v109
	v_fma_f32 v110, -v229, v154, v110
	v_fma_f32 v111, -v229, v155, v111
	v_pk_fma_f32 v[112:113], v[104:105], v[128:129], v[112:113]
	v_fma_f32 v104, -v229, v130, v106
	v_fma_f32 v105, -v229, v131, v107
	s_waitcnt vmcnt(0)
	v_fma_f32 v108, v230, v108, v156
	v_fma_f32 v109, v230, v109, v157
	v_fma_f32 v110, v230, v110, v158
	v_fmac_f32_e32 v159, v230, v111
	v_fma_f32 v104, v230, v104, v134
	v_fmac_f32_e32 v135, v230, v105
	v_mul_f32_e32 v108, 0xbfb8aa3b, v108
	v_mul_f32_e32 v109, 0xbfb8aa3b, v109
	v_mul_f32_e32 v110, 0xbfb8aa3b, v110
	v_mul_f32_e32 v111, 0xbfb8aa3b, v159
	v_mul_f32_e32 v104, 0xbfb8aa3b, v104
	v_mul_f32_e32 v105, 0xbfb8aa3b, v135
	v_exp_f32_e32 v108, v108
	v_exp_f32_e32 v109, v109
	v_exp_f32_e32 v110, v110
	v_exp_f32_e32 v111, v111
	v_exp_f32_e32 v104, v104
	v_exp_f32_e32 v105, v105
	v_add_f32_e32 v108, 1.0, v108
	v_add_f32_e32 v109, 1.0, v109
	v_add_f32_e32 v110, 1.0, v110
	v_add_f32_e32 v111, 1.0, v111
	v_add_f32_e32 v104, 1.0, v104
	v_add_f32_e32 v105, 1.0, v105
	v_rcp_f32_e32 v108, v108
	v_rcp_f32_e32 v109, v109
	v_lshlrev_b32_e32 v156, 16, v136
	v_and_b32_e32 v157, 0xffff0000, v136
	v_rcp_f32_e32 v110, v110
	v_rcp_f32_e32 v111, v111
	v_lshlrev_b32_e32 v136, 16, v137
	v_and_b32_e32 v137, 0xffff0000, v137
	v_rcp_f32_e32 v104, v104
	v_rcp_f32_e32 v105, v105
	v_lshlrev_b32_e32 v116, 16, v139
	v_and_b32_e32 v117, 0xffff0000, v139
	v_pk_add_f32 v[156:157], v[156:157], v[228:229] op_sel:[0,1] neg_lo:[0,1] neg_hi:[0,1]
	v_pk_add_f32 v[136:137], v[136:137], v[228:229] op_sel:[0,1] neg_lo:[0,1] neg_hi:[0,1]
	v_pk_add_f32 v[116:117], v[116:117], v[228:229] op_sel:[0,1] neg_lo:[0,1] neg_hi:[0,1]
	v_pk_mul_f32 v[156:157], v[156:157], v[230:231] op_sel_hi:[1,0]
	v_pk_mul_f32 v[136:137], v[136:137], v[230:231] op_sel_hi:[1,0]
	v_pk_mul_f32 v[116:117], v[116:117], v[230:231] op_sel_hi:[1,0]
	v_lshlrev_b32_e32 v152, 16, v140
	v_and_b32_e32 v153, 0xffff0000, v140
	v_pk_fma_f32 v[144:145], v[156:157], v[144:145], v[148:149]
	v_lshlrev_b32_e32 v140, 16, v141
	v_and_b32_e32 v141, 0xffff0000, v141
	v_pk_fma_f32 v[136:137], v[136:137], v[146:147], v[150:151]
	v_lshlrev_b32_e32 v106, 16, v143
	v_and_b32_e32 v107, 0xffff0000, v143
	v_pk_fma_f32 v[114:115], v[116:117], v[114:115], v[118:119]
	v_pk_fma_f32 v[108:109], v[108:109], v[152:153], v[144:145]
	v_pk_fma_f32 v[110:111], v[110:111], v[140:141], v[136:137]
	v_pk_fma_f32 v[114:115], v[104:105], v[106:107], v[114:115]
	v_cvt_pk_bf16_f32 v104, v108, v109
	v_cvt_pk_bf16_f32 v105, v110, v111
	v_cvt_pk_bf16_f32 v106, v112, v113
	v_cvt_pk_bf16_f32 v107, v114, v115
	v_lshl_add_u64 v[108:109], s[52:53], 0, v[232:233]
	global_store_dwordx4 v[108:109], v[104:107], off
	global_load_dwordx4 v[104:107], v[214:215], off offset:528
	s_nop 0
	global_load_dwordx4 v[116:119], v[214:215], off offset:512
	global_load_dwordx4 v[108:111], v[216:217], off offset:528
	global_load_dwordx4 v[128:131], v[216:217], off offset:512
	global_load_dwordx4 v[132:135], v[160:161], off
	global_load_dwordx4 v[112:115], v[162:163], off offset:16
	global_load_dwordx4 v[136:139], v[162:163], off
	s_waitcnt vmcnt(2)
; DI void row_stats(const f32x2v* st, size_t row, int fq, float& mu, float& rstd) {
;     const f32x4 a = *(const f32x4*)(st + row * 16 + 4 * fq), b = *(const f32x4*)(st + row * 16 + 4 * fq + 2);
;     float s1 = (a[0] + a[2]) + (b[0] + b[2]), s2 = (a[1] + a[3]) + (b[1] + b[3]);
;     s1 += __shfl_xor(s1, 16); s1 += __shfl_xor(s1, 32); s2 += __shfl_xor(s2, 16); s2 += __shfl_xor(s2, 32);
;     mu = s1 * (1.0f / 1024.0f); const float var = fmaxf(s2 * (1.0f / 1024.0f) - mu * mu, 0.f); rstd = rsqrtf(var + LN_EPS);
	v_fma_f32 v100, -v229, v132, v100
	v_fma_f32 v101, -v229, v133, v101
	s_waitcnt vmcnt(0)
	v_fma_f32 v100, v230, v100, v136
	v_fma_f32 v101, v230, v101, v137
	v_fma_f32 v102, -v229, v134, v102
	v_fma_f32 v103, -v229, v135, v103
	v_mul_f32_e32 v100, 0xbfb8aa3b, v100
	v_mul_f32_e32 v101, 0xbfb8aa3b, v101
	v_fma_f32 v102, v230, v102, v138
	v_fmac_f32_e32 v139, v230, v103
	v_exp_f32_e32 v100, v100
	v_exp_f32_e32 v101, v101
	v_mul_f32_e32 v102, 0xbfb8aa3b, v102
	v_mul_f32_e32 v103, 0xbfb8aa3b, v139
	v_exp_f32_e32 v102, v102
	v_exp_f32_e32 v103, v103
	v_add_f32_e32 v100, 1.0, v100
	v_add_f32_e32 v101, 1.0, v101
	v_rcp_f32_e32 v100, v100
	v_rcp_f32_e32 v101, v101
	v_lshlrev_b32_e32 v136, 16, v120
	v_and_b32_e32 v137, 0xffff0000, v120
	v_add_f32_e32 v102, 1.0, v102
	v_add_f32_e32 v103, 1.0, v103
	v_pk_add_f32 v[136:137], v[136:137], v[228:229] op_sel:[0,1] neg_lo:[0,1] neg_hi:[0,1]
	v_rcp_f32_e32 v102, v102
	v_rcp_f32_e32 v103, v103
	v_lshlrev_b32_e32 v120, 16, v121
	v_and_b32_e32 v121, 0xffff0000, v121
	v_pk_mul_f32 v[136:137], v[136:137], v[230:231] op_sel_hi:[1,0]
	v_pk_add_f32 v[120:121], v[120:121], v[228:229] op_sel:[0,1] neg_lo:[0,1] neg_hi:[0,1]
	v_lshlrev_b32_e32 v132, 16, v124
	v_and_b32_e32 v133, 0xffff0000, v124
	v_pk_fma_f32 v[116:117], v[136:137], v[116:117], v[128:129]
	v_pk_mul_f32 v[120:121], v[120:121], v[230:231] op_sel_hi:[1,0]
	v_pk_fma_f32 v[100:101], v[100:101], v[132:133], v[116:117]
	v_lshlrev_b32_e32 v116, 16, v125
	v_and_b32_e32 v117, 0xffff0000, v125
	v_pk_fma_f32 v[118:119], v[120:121], v[118:119], v[130:131]
	s_nop 0
	v_pk_fma_f32 v[102:103], v[102:103], v[116:117], v[118:119]
	global_load_dwordx4 v[116:119], v[164:165], off
	s_waitcnt vmcnt(0)
	v_fma_f32 v96, -v229, v116, v96
	v_fma_f32 v97, -v229, v117, v97
	v_fma_f32 v96, v230, v96, v112
	v_fma_f32 v97, v230, v97, v113
	v_mul_f32_e32 v96, 0xbfb8aa3b, v96
	v_mul_f32_e32 v97, 0xbfb8aa3b, v97
	v_exp_f32_e32 v96, v96
	v_exp_f32_e32 v97, v97
	v_lshlrev_b32_e32 v116, 16, v122
	v_and_b32_e32 v117, 0xffff0000, v122
	v_add_f32_e32 v96, 1.0, v96
	v_add_f32_e32 v97, 1.0, v97
	v_rcp_f32_e32 v96, v96
	v_rcp_f32_e32 v97, v97
	v_pk_add_f32 v[116:117], v[116:117], v[228:229] op_sel:[0,1] neg_lo:[0,1] neg_hi:[0,1]
	v_lshlrev_b32_e32 v112, 16, v126
	v_pk_mul_f32 v[116:117], v[116:117], v[230:231] op_sel_hi:[1,0]
	v_and_b32_e32 v113, 0xffff0000, v126
	v_pk_fma_f32 v[104:105], v[116:117], v[104:105], v[108:109]
	v_lshlrev_b32_e32 v108, 16, v123
	v_pk_fma_f32 v[104:105], v[96:97], v[112:113], v[104:105]
	v_fma_f32 v96, -v229, v118, v98
	v_fma_f32 v97, -v229, v119, v99
	v_fma_f32 v96, v230, v96, v114
	v_fmac_f32_e32 v115, v230, v97
	v_mul_f32_e32 v96, 0xbfb8aa3b, v96
	v_mul_f32_e32 v97, 0xbfb8aa3b, v115
	v_exp_f32_e32 v96, v96
	v_exp_f32_e32 v97, v97
	v_and_b32_e32 v109, 0xffff0000, v123
	v_pk_add_f32 v[108:109], v[108:109], v[228:229] op_sel:[0,1] neg_lo:[0,1] neg_hi:[0,1]
	v_add_f32_e32 v96, 1.0, v96
	v_add_f32_e32 v97, 1.0, v97
	v_rcp_f32_e32 v96, v96
	v_rcp_f32_e32 v97, v97
	v_pk_mul_f32 v[108:109], v[108:109], v[230:231] op_sel_hi:[1,0]
	v_lshlrev_b32_e32 v98, 16, v127
	v_and_b32_e32 v99, 0xffff0000, v127
	v_pk_fma_f32 v[106:107], v[108:109], v[106:107], v[110:111]
	s_nop 0
	v_pk_fma_f32 v[106:107], v[96:97], v[98:99], v[106:107]
	v_cvt_pk_bf16_f32 v96, v100, v101
	v_lshlrev_b64 v[100:101], 11, v[226:227]
	v_lshl_add_u64 v[100:101], s[52:53], 0, v[100:101]
	v_cvt_pk_bf16_f32 v97, v102, v103
	v_cvt_pk_bf16_f32 v98, v104, v105
	v_cvt_pk_bf16_f32 v99, v106, v107
	v_lshl_add_u64 v[100:101], v[100:101], 0, v[166:167]
	global_store_dwordx4 v[100:101], v[96:99], off offset:256
	s_nop 1
	v_lshlrev_b64 v[96:97], 7, v[176:177]
	v_lshl_add_u64 v[100:101], v[206:207], 0, v[96:97]
	global_load_dwordx4 v[96:99], v[100:101], off offset:16
	s_nop 0
	global_load_dwordx4 v[100:103], v[100:101], off
	s_waitcnt vmcnt(1)
	v_mov_b32_e32 v105, v96
	s_waitcnt vmcnt(0)
	v_mov_b32_e32 v104, v100
	v_mov_b32_e32 v106, v102
	v_mov_b32_e32 v107, v98
	v_pk_add_f32 v[104:105], v[104:105], v[106:107]
	v_add_f32_e32 v96, v101, v103
	v_add_f32_e32 v98, v97, v99
	v_mov_b32_e32 v97, v104
	v_mov_b32_e32 v99, v105
	v_pk_add_f32 v[96:97], v[96:97], v[98:99]
	s_waitcnt lgkmcnt(0)
	v_mov_b32_e32 v99, v97
	v_mov_b32_e32 v98, v96
	s_nop 1
	v_permlane16_swap_b32_e32 v99, v97
	v_permlane16_swap_b32_e32 v98, v96
	s_nop 0
	v_pk_add_f32 v[96:97], v[96:97], v[98:99]
	s_waitcnt lgkmcnt(0)
	v_mov_b32_e32 v99, v97
	v_mov_b32_e32 v98, v96
	s_nop 1
	v_permlane32_swap_b32_e32 v99, v97
	v_permlane32_swap_b32_e32 v98, v96
	s_nop 0
	v_pk_add_f32 v[96:97], v[96:97], v[98:99]
	s_nop 0
	v_pk_mul_f32 v[178:179], v[96:97], s[28:29] op_sel_hi:[1,0]
	s_nop 0
	v_fma_f32 v96, -v179, v179, v178
	v_max_f32_e32 v96, 0, v96
	v_add_f32_e32 v96, 0x3727c5ac, v96
	v_cmp_gt_f32_e32 vcc, s91, v96
	v_mul_f32_e32 v97, 0x4b800000, v96
	s_nop 0
	v_cndmask_b32_e32 v96, v96, v97, vcc
	v_rsq_f32_e32 v96, v96
	s_nop 0
	v_mul_f32_e32 v97, 0x45800000, v96
	v_cndmask_b32_e32 v180, v96, v97, vcc
	v_lshlrev_b64 v[96:97], 10, v[176:177]
	v_lshl_add_u64 v[96:97], v[96:97], 0, v[222:223]
	v_lshlrev_b64 v[182:183], 1, v[96:97]
	v_lshl_add_u64 v[96:97], s[48:49], 0, v[182:183]
	global_load_dwordx4 v[124:127], v[96:97], off
	v_lshl_add_u64 v[96:97], s[44:45], 0, v[182:183]
	global_load_dwordx4 v[120:123], v[96:97], off
	v_or_b32_e32 v96, 0x100, v182
	v_mov_b32_e32 v97, v183
	v_lshl_add_u64 v[98:99], s[48:49], 0, v[96:97]
	v_lshl_add_u64 v[96:97], s[44:45], 0, v[96:97]
	global_load_dwordx4 v[112:115], v[96:97], off
	v_lshlrev_b64 v[96:97], 7, v[168:169]
	v_lshl_add_u64 v[100:101], v[206:207], 0, v[96:97]
	global_load_dwordx4 v[116:119], v[98:99], off
	s_nop 0
	global_load_dwordx4 v[96:99], v[100:101], off offset:16
	s_nop 0
	global_load_dwordx4 v[100:103], v[100:101], off
	s_waitcnt vmcnt(1)
; DI void row_stats(const f32x2v* st, size_t row, int fq, float& mu, float& rstd) {
;     const f32x4 a = *(const f32x4*)(st + row * 16 + 4 * fq), b = *(const f32x4*)(st + row * 16 + 4 * fq + 2);
;     float s1 = (a[0] + a[2]) + (b[0] + b[2]), s2 = (a[1] + a[3]) + (b[1] + b[3]);
;     s1 += __shfl_xor(s1, 16); s1 += __shfl_xor(s1, 32); s2 += __shfl_xor(s2, 16); s2 += __shfl_xor(s2, 32);
;     mu = s1 * (1.0f / 1024.0f); const float var = fmaxf(s2 * (1.0f / 1024.0f) - mu * mu, 0.f); rstd = rsqrtf(var + LN_EPS);
	v_mov_b32_e32 v105, v96
	s_waitcnt vmcnt(0)
	v_mov_b32_e32 v104, v100
	v_mov_b32_e32 v106, v102
	v_mov_b32_e32 v107, v98
	v_pk_add_f32 v[104:105], v[104:105], v[106:107]
	v_add_f32_e32 v96, v101, v103
	v_add_f32_e32 v98, v97, v99
	v_mov_b32_e32 v97, v104
	v_mov_b32_e32 v99, v105
	v_pk_add_f32 v[96:97], v[96:97], v[98:99]
	s_waitcnt lgkmcnt(0)
	v_mov_b32_e32 v99, v97
	v_mov_b32_e32 v98, v96
	s_nop 1
	v_permlane16_swap_b32_e32 v99, v97
	v_permlane16_swap_b32_e32 v98, v96
	s_nop 0
	v_pk_add_f32 v[96:97], v[96:97], v[98:99]
	s_waitcnt lgkmcnt(0)
	v_mov_b32_e32 v99, v97
	v_mov_b32_e32 v98, v96
	s_nop 1
	v_permlane32_swap_b32_e32 v99, v97
	v_permlane32_swap_b32_e32 v98, v96
	s_nop 0
	v_pk_add_f32 v[96:97], v[96:97], v[98:99]
	s_nop 0
	v_pk_mul_f32 v[170:171], v[96:97], s[28:29] op_sel_hi:[1,0]
	s_nop 0
	v_fma_f32 v96, -v171, v171, v170
	v_max_f32_e32 v96, 0, v96
	v_add_f32_e32 v96, 0x3727c5ac, v96
	v_cmp_gt_f32_e32 vcc, s91, v96
	v_mul_f32_e32 v97, 0x4b800000, v96
	s_nop 0
	v_cndmask_b32_e32 v96, v96, v97, vcc
	v_rsq_f32_e32 v96, v96
	s_nop 0
	v_mul_f32_e32 v97, 0x45800000, v96
	v_cndmask_b32_e32 v172, v96, v97, vcc
	v_lshlrev_b64 v[96:97], 10, v[168:169]
	v_lshl_add_u64 v[96:97], v[96:97], 0, v[222:223]
	v_lshlrev_b64 v[174:175], 1, v[96:97]
	v_lshl_add_u64 v[96:97], s[48:49], 0, v[174:175]
	global_load_dwordx4 v[108:111], v[96:97], off
	v_lshl_add_u64 v[96:97], s[44:45], 0, v[174:175]
	global_load_dwordx4 v[104:107], v[96:97], off
	v_or_b32_e32 v96, 0x100, v174
	v_mov_b32_e32 v97, v175
	v_lshl_add_u64 v[98:99], s[48:49], 0, v[96:97]
	v_lshl_add_u64 v[96:97], s[44:45], 0, v[96:97]
	global_load_dwordx4 v[100:103], v[98:99], off
	s_nop 0
	global_load_dwordx4 v[96:99], v[96:97], off
	s_nop 0
	global_load_dwordx4 v[128:131], v[214:215], off offset:16
	global_load_dwordx4 v[140:143], v[214:215], off
	global_load_dwordx4 v[132:135], v[216:217], off offset:16
	global_load_dwordx4 v[144:147], v[216:217], off
	global_load_dwordx4 v[136:139], v[218:219], off offset:16
	global_load_dwordx4 v[152:155], v[218:219], off
	global_load_dwordx4 v[148:151], v[220:221], off offset:16
	global_load_dwordx4 v[156:159], v[220:221], off
	s_waitcnt vmcnt(3)
	v_fma_f32 v88, -v179, v136, v88
	s_waitcnt vmcnt(2)
	v_fma_f32 v94, -v179, v154, v94
	v_fma_f32 v95, -v179, v155, v95
	s_waitcnt vmcnt(0)
	v_fma_f32 v94, v180, v94, v158
	v_fmac_f32_e32 v159, v180, v95
	v_mul_f32_e32 v94, 0xbfb8aa3b, v94
	v_mul_f32_e32 v95, 0xbfb8aa3b, v159
	v_exp_f32_e32 v94, v94
	v_exp_f32_e32 v95, v95
	v_fma_f32 v89, -v179, v137, v89
	v_fma_f32 v88, v180, v88, v148
	v_fma_f32 v89, v180, v89, v149
	v_mul_f32_e32 v88, 0xbfb8aa3b, v88
	v_mul_f32_e32 v89, 0xbfb8aa3b, v89
	v_fma_f32 v92, -v179, v152, v92
	v_fma_f32 v93, -v179, v153, v93
	v_add_f32_e32 v94, 1.0, v94
	v_add_f32_e32 v95, 1.0, v95
	v_exp_f32_e32 v88, v88
	v_exp_f32_e32 v89, v89
	v_fma_f32 v92, v180, v92, v156
	v_fma_f32 v93, v180, v93, v157
	v_lshlrev_b32_e32 v156, 16, v120
	v_and_b32_e32 v157, 0xffff0000, v120
	v_rcp_f32_e32 v94, v94
	v_rcp_f32_e32 v95, v95
	v_lshlrev_b32_e32 v120, 16, v121
	v_and_b32_e32 v121, 0xffff0000, v121
	v_pk_add_f32 v[120:121], v[120:121], v[178:179] op_sel:[0,1] neg_lo:[0,1] neg_hi:[0,1]
	v_lshlrev_b32_e32 v152, 16, v124
	v_pk_mul_f32 v[120:121], v[120:121], v[180:181] op_sel_hi:[1,0]
	v_and_b32_e32 v153, 0xffff0000, v124
	v_lshlrev_b32_e32 v124, 16, v125
	v_and_b32_e32 v125, 0xffff0000, v125
	v_pk_fma_f32 v[120:121], v[120:121], v[142:143], v[146:147]
	v_add_f32_e32 v88, 1.0, v88
	v_add_f32_e32 v89, 1.0, v89
	v_pk_fma_f32 v[94:95], v[94:95], v[124:125], v[120:121]
	v_rcp_f32_e32 v88, v88
	v_rcp_f32_e32 v89, v89
	v_lshlrev_b32_e32 v124, 16, v122
	v_and_b32_e32 v125, 0xffff0000, v122
	v_pk_add_f32 v[124:125], v[124:125], v[178:179] op_sel:[0,1] neg_lo:[0,1] neg_hi:[0,1]
	v_lshlrev_b32_e32 v120, 16, v126
	v_pk_mul_f32 v[124:125], v[124:125], v[180:181] op_sel_hi:[1,0]
	v_and_b32_e32 v121, 0xffff0000, v126
	v_pk_fma_f32 v[124:125], v[124:125], v[128:129], v[132:133]
	v_mul_f32_e32 v92, 0xbfb8aa3b, v92
	v_pk_fma_f32 v[120:121], v[88:89], v[120:121], v[124:125]
	v_fma_f32 v88, -v179, v138, v90
	v_fma_f32 v89, -v179, v139, v91
	v_fma_f32 v88, v180, v88, v150
	v_fmac_f32_e32 v151, v180, v89
	v_mul_f32_e32 v93, 0xbfb8aa3b, v93
	v_mul_f32_e32 v88, 0xbfb8aa3b, v88
	v_mul_f32_e32 v89, 0xbfb8aa3b, v151
	v_exp_f32_e32 v92, v92
	v_exp_f32_e32 v93, v93
	v_exp_f32_e32 v88, v88
	v_exp_f32_e32 v89, v89
	v_add_f32_e32 v92, 1.0, v92
	v_add_f32_e32 v93, 1.0, v93
	v_add_f32_e32 v88, 1.0, v88
	v_add_f32_e32 v89, 1.0, v89
	v_rcp_f32_e32 v92, v92
	v_rcp_f32_e32 v93, v93
	v_rcp_f32_e32 v88, v88
	v_rcp_f32_e32 v89, v89
	v_lshlrev_b32_e32 v122, 16, v123
	v_and_b32_e32 v123, 0xffff0000, v123
	v_pk_add_f32 v[156:157], v[156:157], v[178:179] op_sel:[0,1] neg_lo:[0,1] neg_hi:[0,1]
	v_pk_add_f32 v[122:123], v[122:123], v[178:179] op_sel:[0,1] neg_lo:[0,1] neg_hi:[0,1]
	v_pk_mul_f32 v[156:157], v[156:157], v[180:181] op_sel_hi:[1,0]
	v_pk_mul_f32 v[122:123], v[122:123], v[180:181] op_sel_hi:[1,0]
	v_pk_fma_f32 v[140:141], v[156:157], v[140:141], v[144:145]
	v_lshlrev_b32_e32 v90, 16, v127
	v_and_b32_e32 v91, 0xffff0000, v127
	v_pk_fma_f32 v[122:123], v[122:123], v[130:131], v[134:135]
	v_pk_fma_f32 v[92:93], v[92:93], v[152:153], v[140:141]
	v_pk_fma_f32 v[122:123], v[88:89], v[90:91], v[122:123]
	v_cvt_pk_bf16_f32 v88, v92, v93
	v_cvt_pk_bf16_f32 v89, v94, v95
	v_cvt_pk_bf16_f32 v90, v120, v121
	v_cvt_pk_bf16_f32 v91, v122, v123
	v_lshl_add_u64 v[92:93], s[52:53], 0, v[182:183]
	global_store_dwordx4 v[92:93], v[88:91], off
	global_load_dwordx4 v[88:91], v[214:215], off offset:528
	s_nop 0
	global_load_dwordx4 v[124:127], v[214:215], off offset:512
	global_load_dwordx4 v[92:95], v[216:217], off offset:528
	global_load_dwordx4 v[128:131], v[216:217], off offset:512
	global_load_dwordx4 v[132:135], v[160:161], off
	global_load_dwordx4 v[120:123], v[162:163], off offset:16
	global_load_dwordx4 v[136:139], v[162:163], off
	s_waitcnt vmcnt(2)
	v_fma_f32 v84, -v179, v132, v84
	v_fma_f32 v85, -v179, v133, v85
	s_waitcnt vmcnt(0)
	v_fma_f32 v84, v180, v84, v136
	v_fma_f32 v85, v180, v85, v137
	v_mul_f32_e32 v84, 0xbfb8aa3b, v84
	v_mul_f32_e32 v85, 0xbfb8aa3b, v85
	v_exp_f32_e32 v84, v84
	v_exp_f32_e32 v85, v85
	v_lshlrev_b32_e32 v136, 16, v112
	v_and_b32_e32 v137, 0xffff0000, v112
	v_add_f32_e32 v84, 1.0, v84
	v_add_f32_e32 v85, 1.0, v85
	v_rcp_f32_e32 v84, v84
	v_rcp_f32_e32 v85, v85
	v_pk_add_f32 v[136:137], v[136:137], v[178:179] op_sel:[0,1] neg_lo:[0,1] neg_hi:[0,1]
	v_lshlrev_b32_e32 v112, 16, v113
	v_and_b32_e32 v113, 0xffff0000, v113
	v_pk_mul_f32 v[136:137], v[136:137], v[180:181] op_sel_hi:[1,0]
	v_pk_add_f32 v[112:113], v[112:113], v[178:179] op_sel:[0,1] neg_lo:[0,1] neg_hi:[0,1]
	v_lshlrev_b32_e32 v132, 16, v116
	v_and_b32_e32 v133, 0xffff0000, v116
	v_pk_fma_f32 v[124:125], v[136:137], v[124:125], v[128:129]
	v_pk_mul_f32 v[112:113], v[112:113], v[180:181] op_sel_hi:[1,0]
	v_pk_fma_f32 v[84:85], v[84:85], v[132:133], v[124:125]
	v_pk_fma_f32 v[112:113], v[112:113], v[126:127], v[130:131]
	global_load_dwordx4 v[124:127], v[164:165], off
	v_fma_f32 v86, -v179, v134, v86
	v_fma_f32 v87, -v179, v135, v87
	v_fma_f32 v86, v180, v86, v138
	v_fmac_f32_e32 v139, v180, v87
	v_mul_f32_e32 v86, 0xbfb8aa3b, v86
	v_mul_f32_e32 v87, 0xbfb8aa3b, v139
	v_exp_f32_e32 v86, v86
	v_exp_f32_e32 v87, v87
	v_lshlrev_b32_e32 v116, 16, v117
	v_and_b32_e32 v117, 0xffff0000, v117
	v_add_f32_e32 v86, 1.0, v86
	v_add_f32_e32 v87, 1.0, v87
	v_rcp_f32_e32 v86, v86
	v_rcp_f32_e32 v87, v87
	v_lshl_add_u64 v[136:137], v[224:225], 0, s[22:23]
	v_lshl_add_u64 v[128:129], v[224:225], 0, s[34:35]
	s_mov_b64 s[34:35], 0xa0
	v_pk_fma_f32 v[86:87], v[86:87], v[116:117], v[112:113]
	v_lshlrev_b32_e32 v116, 16, v114
	v_and_b32_e32 v117, 0xffff0000, v114
	v_pk_add_f32 v[116:117], v[116:117], v[178:179] op_sel:[0,1] neg_lo:[0,1] neg_hi:[0,1]
	v_lshlrev_b32_e32 v112, 16, v118
	v_pk_mul_f32 v[116:117], v[116:117], v[180:181] op_sel_hi:[1,0]
	v_and_b32_e32 v113, 0xffff0000, v118
	v_pk_fma_f32 v[88:89], v[116:117], v[88:89], v[92:93]
	v_lshlrev_b32_e32 v92, 16, v115
	v_and_b32_e32 v93, 0xffff0000, v115
	v_pk_add_f32 v[92:93], v[92:93], v[178:179] op_sel:[0,1] neg_lo:[0,1] neg_hi:[0,1]
	s_waitcnt vmcnt(0)
	v_fma_f32 v80, -v179, v124, v80
	v_fma_f32 v81, -v179, v125, v81
	v_fma_f32 v80, v180, v80, v120
	v_fma_f32 v81, v180, v81, v121
	v_mul_f32_e32 v80, 0xbfb8aa3b, v80
	v_mul_f32_e32 v81, 0xbfb8aa3b, v81
	v_exp_f32_e32 v80, v80
	v_exp_f32_e32 v81, v81
	v_pk_mul_f32 v[92:93], v[92:93], v[180:181] op_sel_hi:[1,0]
	v_add_f32_e32 v80, 1.0, v80
	v_add_f32_e32 v81, 1.0, v81
	v_rcp_f32_e32 v80, v80
	v_rcp_f32_e32 v81, v81
	v_pk_fma_f32 v[90:91], v[92:93], v[90:91], v[94:95]
	v_pk_fma_f32 v[88:89], v[80:81], v[112:113], v[88:89]
	v_fma_f32 v80, -v179, v126, v82
	v_fma_f32 v81, -v179, v127, v83
	v_fma_f32 v80, v180, v80, v122
	v_fmac_f32_e32 v123, v180, v81
	v_mul_f32_e32 v80, 0xbfb8aa3b, v80
	v_mul_f32_e32 v81, 0xbfb8aa3b, v123
	v_exp_f32_e32 v80, v80
	v_exp_f32_e32 v81, v81
	v_lshlrev_b32_e32 v82, 16, v119
	v_and_b32_e32 v83, 0xffff0000, v119
	v_add_f32_e32 v80, 1.0, v80
	v_add_f32_e32 v81, 1.0, v81
	v_rcp_f32_e32 v80, v80
	v_rcp_f32_e32 v81, v81
	s_nop 0
	v_pk_fma_f32 v[90:91], v[80:81], v[82:83], v[90:91]
	v_cvt_pk_bf16_f32 v80, v84, v85
	v_lshlrev_b64 v[84:85], 11, v[176:177]
	v_lshl_add_u64 v[84:85], s[52:53], 0, v[84:85]
	v_cvt_pk_bf16_f32 v81, v86, v87
	v_cvt_pk_bf16_f32 v82, v88, v89
	v_cvt_pk_bf16_f32 v83, v90, v91
	v_lshl_add_u64 v[84:85], v[84:85], 0, v[166:167]
	global_store_dwordx4 v[84:85], v[80:83], off offset:256
	global_load_dwordx4 v[80:83], v[214:215], off offset:16
	s_nop 0
	global_load_dwordx4 v[112:115], v[214:215], off
	global_load_dwordx4 v[84:87], v[216:217], off offset:16
	global_load_dwordx4 v[116:119], v[216:217], off
	global_load_dwordx4 v[88:91], v[218:219], off offset:16
	global_load_dwordx4 v[120:123], v[218:219], off
	global_load_dwordx4 v[92:95], v[220:221], off offset:16
	global_load_dwordx4 v[124:127], v[220:221], off
	s_waitcnt vmcnt(3)
	v_fma_f32 v72, -v171, v88, v72
	v_fma_f32 v73, -v171, v89, v73
	s_waitcnt vmcnt(1)
	v_fma_f32 v72, v172, v72, v92
	v_fma_f32 v73, v172, v73, v93
	v_mul_f32_e32 v72, 0xbfb8aa3b, v72
	v_mul_f32_e32 v73, 0xbfb8aa3b, v73
	v_exp_f32_e32 v72, v72
	v_exp_f32_e32 v73, v73
	v_lshlrev_b32_e32 v92, 16, v106
	v_and_b32_e32 v93, 0xffff0000, v106
	v_add_f32_e32 v72, 1.0, v72
	v_add_f32_e32 v73, 1.0, v73
	v_rcp_f32_e32 v72, v72
	v_rcp_f32_e32 v73, v73
	v_pk_add_f32 v[92:93], v[92:93], v[170:171] op_sel:[0,1] neg_lo:[0,1] neg_hi:[0,1]
	v_lshlrev_b32_e32 v88, 16, v110
	v_pk_mul_f32 v[92:93], v[92:93], v[172:173] op_sel_hi:[1,0]
	v_and_b32_e32 v89, 0xffff0000, v110
	v_pk_fma_f32 v[80:81], v[92:93], v[80:81], v[84:85]
	v_fma_f32 v76, -v171, v120, v76
	v_fma_f32 v77, -v171, v121, v77
	v_fma_f32 v78, -v171, v122, v78
	v_fma_f32 v79, -v171, v123, v79
	v_pk_fma_f32 v[80:81], v[72:73], v[88:89], v[80:81]
	v_fma_f32 v72, -v171, v90, v74
	v_fma_f32 v73, -v171, v91, v75
	s_waitcnt vmcnt(0)
	v_fma_f32 v76, v172, v76, v124
	v_fma_f32 v77, v172, v77, v125
	v_fma_f32 v78, v172, v78, v126
	v_fmac_f32_e32 v127, v172, v79
	v_fma_f32 v72, v172, v72, v94
	v_fmac_f32_e32 v95, v172, v73
	v_mul_f32_e32 v76, 0xbfb8aa3b, v76
	v_mul_f32_e32 v77, 0xbfb8aa3b, v77
	v_mul_f32_e32 v78, 0xbfb8aa3b, v78
	v_mul_f32_e32 v79, 0xbfb8aa3b, v127
	v_mul_f32_e32 v72, 0xbfb8aa3b, v72
	v_mul_f32_e32 v73, 0xbfb8aa3b, v95
	v_exp_f32_e32 v76, v76
	v_exp_f32_e32 v77, v77
	v_exp_f32_e32 v78, v78
	v_exp_f32_e32 v79, v79
	v_exp_f32_e32 v72, v72
	v_exp_f32_e32 v73, v73
	v_add_f32_e32 v76, 1.0, v76
	v_add_f32_e32 v77, 1.0, v77
	v_add_f32_e32 v78, 1.0, v78
	v_add_f32_e32 v79, 1.0, v79
	v_add_f32_e32 v72, 1.0, v72
	v_add_f32_e32 v73, 1.0, v73
	v_rcp_f32_e32 v76, v76
	v_rcp_f32_e32 v77, v77
	v_lshlrev_b32_e32 v124, 16, v104
	v_and_b32_e32 v125, 0xffff0000, v104
	v_rcp_f32_e32 v78, v78
	v_rcp_f32_e32 v79, v79
	v_lshlrev_b32_e32 v104, 16, v105
	v_and_b32_e32 v105, 0xffff0000, v105
	v_rcp_f32_e32 v72, v72
	v_rcp_f32_e32 v73, v73
	v_lshlrev_b32_e32 v84, 16, v107
	v_and_b32_e32 v85, 0xffff0000, v107
	v_pk_add_f32 v[124:125], v[124:125], v[170:171] op_sel:[0,1] neg_lo:[0,1] neg_hi:[0,1]
	v_pk_add_f32 v[104:105], v[104:105], v[170:171] op_sel:[0,1] neg_lo:[0,1] neg_hi:[0,1]
	v_pk_add_f32 v[84:85], v[84:85], v[170:171] op_sel:[0,1] neg_lo:[0,1] neg_hi:[0,1]
	v_pk_mul_f32 v[124:125], v[124:125], v[172:173] op_sel_hi:[1,0]
	v_pk_mul_f32 v[104:105], v[104:105], v[172:173] op_sel_hi:[1,0]
	v_pk_mul_f32 v[84:85], v[84:85], v[172:173] op_sel_hi:[1,0]
	v_lshlrev_b32_e32 v120, 16, v108
	v_and_b32_e32 v121, 0xffff0000, v108
	v_pk_fma_f32 v[112:113], v[124:125], v[112:113], v[116:117]
	v_lshlrev_b32_e32 v108, 16, v109
	v_and_b32_e32 v109, 0xffff0000, v109
	v_pk_fma_f32 v[104:105], v[104:105], v[114:115], v[118:119]
	v_lshlrev_b32_e32 v74, 16, v111
	v_and_b32_e32 v75, 0xffff0000, v111
	v_pk_fma_f32 v[82:83], v[84:85], v[82:83], v[86:87]
	v_pk_fma_f32 v[76:77], v[76:77], v[120:121], v[112:113]
	v_pk_fma_f32 v[78:79], v[78:79], v[108:109], v[104:105]
	v_pk_fma_f32 v[82:83], v[72:73], v[74:75], v[82:83]
	v_cvt_pk_bf16_f32 v72, v76, v77
	v_cvt_pk_bf16_f32 v73, v78, v79
	v_cvt_pk_bf16_f32 v74, v80, v81
	v_cvt_pk_bf16_f32 v75, v82, v83
	v_lshl_add_u64 v[76:77], s[52:53], 0, v[174:175]
	global_store_dwordx4 v[76:77], v[72:75], off
	global_load_dwordx4 v[72:75], v[214:215], off offset:528
	s_nop 0
	global_load_dwordx4 v[84:87], v[214:215], off offset:512
	global_load_dwordx4 v[76:79], v[216:217], off offset:528
	global_load_dwordx4 v[88:91], v[216:217], off offset:512
	global_load_dwordx4 v[92:95], v[160:161], off
	global_load_dwordx4 v[80:83], v[162:163], off offset:16
	global_load_dwordx4 v[104:107], v[162:163], off
	s_waitcnt vmcnt(2)
	v_fma_f32 v68, -v171, v92, v68
	v_fma_f32 v69, -v171, v93, v69
	s_waitcnt vmcnt(0)
	v_fma_f32 v68, v172, v68, v104
	v_fma_f32 v69, v172, v69, v105
	v_fma_f32 v70, -v171, v94, v70
	v_fma_f32 v71, -v171, v95, v71
	v_mul_f32_e32 v68, 0xbfb8aa3b, v68
	v_mul_f32_e32 v69, 0xbfb8aa3b, v69
	v_fma_f32 v70, v172, v70, v106
	v_fmac_f32_e32 v107, v172, v71
	v_exp_f32_e32 v68, v68
	v_exp_f32_e32 v69, v69
	v_mul_f32_e32 v70, 0xbfb8aa3b, v70
	v_mul_f32_e32 v71, 0xbfb8aa3b, v107
	v_exp_f32_e32 v70, v70
	v_exp_f32_e32 v71, v71
	v_lshlrev_b32_e32 v104, 16, v96
	v_and_b32_e32 v105, 0xffff0000, v96
	v_add_f32_e32 v68, 1.0, v68
	v_add_f32_e32 v69, 1.0, v69
	v_pk_add_f32 v[104:105], v[104:105], v[170:171] op_sel:[0,1] neg_lo:[0,1] neg_hi:[0,1]
	v_rcp_f32_e32 v68, v68
	v_rcp_f32_e32 v69, v69
	v_pk_mul_f32 v[104:105], v[104:105], v[172:173] op_sel_hi:[1,0]
	v_add_f32_e32 v70, 1.0, v70
	v_add_f32_e32 v71, 1.0, v71
	v_pk_fma_f32 v[84:85], v[104:105], v[84:85], v[88:89]
	v_rcp_f32_e32 v70, v70
	v_rcp_f32_e32 v71, v71
	v_lshlrev_b32_e32 v88, 16, v97
	v_and_b32_e32 v89, 0xffff0000, v97
	v_pk_add_f32 v[88:89], v[88:89], v[170:171] op_sel:[0,1] neg_lo:[0,1] neg_hi:[0,1]
	v_lshlrev_b32_e32 v92, 16, v100
	v_and_b32_e32 v93, 0xffff0000, v100
	v_pk_mul_f32 v[88:89], v[88:89], v[172:173] op_sel_hi:[1,0]
	v_pk_fma_f32 v[68:69], v[68:69], v[92:93], v[84:85]
	v_lshlrev_b32_e32 v84, 16, v101
	v_and_b32_e32 v85, 0xffff0000, v101
	v_pk_fma_f32 v[86:87], v[88:89], v[86:87], v[90:91]
	s_nop 0
	v_pk_fma_f32 v[70:71], v[70:71], v[84:85], v[86:87]
	global_load_dwordx4 v[84:87], v[164:165], off
	s_waitcnt vmcnt(0)
	v_fma_f32 v64, -v171, v84, v64
	v_fma_f32 v65, -v171, v85, v65
	v_fma_f32 v64, v172, v64, v80
	v_fma_f32 v65, v172, v65, v81
	v_mul_f32_e32 v64, 0xbfb8aa3b, v64
	v_mul_f32_e32 v65, 0xbfb8aa3b, v65
	v_exp_f32_e32 v64, v64
	v_exp_f32_e32 v65, v65
	v_lshlrev_b32_e32 v84, 16, v98
	v_and_b32_e32 v85, 0xffff0000, v98
	v_add_f32_e32 v64, 1.0, v64
	v_add_f32_e32 v65, 1.0, v65
	v_rcp_f32_e32 v64, v64
	v_rcp_f32_e32 v65, v65
	v_pk_add_f32 v[84:85], v[84:85], v[170:171] op_sel:[0,1] neg_lo:[0,1] neg_hi:[0,1]
	v_lshlrev_b32_e32 v80, 16, v102
	v_pk_mul_f32 v[84:85], v[84:85], v[172:173] op_sel_hi:[1,0]
	v_and_b32_e32 v81, 0xffff0000, v102
	v_pk_fma_f32 v[72:73], v[84:85], v[72:73], v[76:77]
	v_lshlrev_b32_e32 v76, 16, v99
	v_pk_fma_f32 v[72:73], v[64:65], v[80:81], v[72:73]
	v_fma_f32 v64, -v171, v86, v66
	v_fma_f32 v65, -v171, v87, v67
	v_fma_f32 v64, v172, v64, v82
	v_fmac_f32_e32 v83, v172, v65
	v_mul_f32_e32 v64, 0xbfb8aa3b, v64
	v_mul_f32_e32 v65, 0xbfb8aa3b, v83
	v_exp_f32_e32 v64, v64
	v_exp_f32_e32 v65, v65
	v_and_b32_e32 v77, 0xffff0000, v99
	v_pk_add_f32 v[76:77], v[76:77], v[170:171] op_sel:[0,1] neg_lo:[0,1] neg_hi:[0,1]
	v_add_f32_e32 v64, 1.0, v64
	v_add_f32_e32 v65, 1.0, v65
	v_rcp_f32_e32 v64, v64
	v_rcp_f32_e32 v65, v65
	v_pk_mul_f32 v[76:77], v[76:77], v[172:173] op_sel_hi:[1,0]
	v_lshlrev_b32_e32 v66, 16, v103
	v_and_b32_e32 v67, 0xffff0000, v103
	v_pk_fma_f32 v[74:75], v[76:77], v[74:75], v[78:79]
	s_nop 0
	v_pk_fma_f32 v[74:75], v[64:65], v[66:67], v[74:75]
	v_cvt_pk_bf16_f32 v64, v68, v69
	v_lshlrev_b64 v[68:69], 11, v[168:169]
	v_lshl_add_u64 v[68:69], s[52:53], 0, v[68:69]
	v_cvt_pk_bf16_f32 v65, v70, v71
	v_cvt_pk_bf16_f32 v66, v72, v73
	v_cvt_pk_bf16_f32 v67, v74, v75
	v_lshl_add_u64 v[68:69], v[68:69], 0, v[166:167]
	global_store_dwordx4 v[68:69], v[64:67], off offset:256
	s_nop 1
	v_lshlrev_b64 v[64:65], 7, v[136:137]
	v_lshl_add_u64 v[68:69], v[206:207], 0, v[64:65]
	global_load_dwordx4 v[64:67], v[68:69], off offset:16
	s_nop 0
	global_load_dwordx4 v[68:71], v[68:69], off
	s_waitcnt vmcnt(1)
; DI void row_stats(const f32x2v* st, size_t row, int fq, float& mu, float& rstd) {
;     const f32x4 a = *(const f32x4*)(st + row * 16 + 4 * fq), b = *(const f32x4*)(st + row * 16 + 4 * fq + 2);
;     float s1 = (a[0] + a[2]) + (b[0] + b[2]), s2 = (a[1] + a[3]) + (b[1] + b[3]);
;     s1 += __shfl_xor(s1, 16); s1 += __shfl_xor(s1, 32); s2 += __shfl_xor(s2, 16); s2 += __shfl_xor(s2, 32);
;     mu = s1 * (1.0f / 1024.0f); const float var = fmaxf(s2 * (1.0f / 1024.0f) - mu * mu, 0.f); rstd = rsqrtf(var + LN_EPS);
; }
	v_mov_b32_e32 v73, v64
	s_waitcnt vmcnt(0)
	v_mov_b32_e32 v72, v68
	v_mov_b32_e32 v74, v70
	v_mov_b32_e32 v75, v66
	v_pk_add_f32 v[72:73], v[72:73], v[74:75]
	v_add_f32_e32 v64, v69, v71
	v_add_f32_e32 v66, v65, v67
	v_mov_b32_e32 v65, v72
	v_mov_b32_e32 v67, v73
	v_pk_add_f32 v[64:65], v[64:65], v[66:67]
	s_waitcnt lgkmcnt(0)
	v_mov_b32_e32 v67, v65
	v_mov_b32_e32 v66, v64
	s_nop 1
	v_permlane16_swap_b32_e32 v67, v65
	v_permlane16_swap_b32_e32 v66, v64
	s_nop 0
	v_pk_add_f32 v[64:65], v[64:65], v[66:67]
	s_waitcnt lgkmcnt(0)
	v_mov_b32_e32 v67, v65
	v_mov_b32_e32 v66, v64
	s_nop 1
	v_permlane32_swap_b32_e32 v67, v65
	v_permlane32_swap_b32_e32 v66, v64
	s_nop 0
	v_pk_add_f32 v[64:65], v[64:65], v[66:67]
	s_nop 0
	v_pk_mul_f32 v[138:139], v[64:65], s[28:29] op_sel_hi:[1,0]
	s_nop 0
	v_fma_f32 v64, -v139, v139, v138
	v_max_f32_e32 v64, 0, v64
	v_add_f32_e32 v64, 0x3727c5ac, v64
	v_cmp_gt_f32_e32 vcc, s91, v64
	v_mul_f32_e32 v65, 0x4b800000, v64
	s_nop 0
	v_cndmask_b32_e32 v64, v64, v65, vcc
	v_rsq_f32_e32 v64, v64
	s_nop 0
	v_mul_f32_e32 v65, 0x45800000, v64
	v_cndmask_b32_e32 v140, v64, v65, vcc
	v_lshlrev_b64 v[64:65], 10, v[136:137]
	v_lshl_add_u64 v[64:65], v[64:65], 0, v[222:223]
	v_lshlrev_b64 v[142:143], 1, v[64:65]
	v_lshl_add_u64 v[64:65], s[48:49], 0, v[142:143]
	global_load_dwordx4 v[92:95], v[64:65], off
	v_lshl_add_u64 v[64:65], s[44:45], 0, v[142:143]
	global_load_dwordx4 v[88:91], v[64:65], off
	v_or_b32_e32 v64, 0x100, v142
	v_mov_b32_e32 v65, v143
	v_lshl_add_u64 v[66:67], s[48:49], 0, v[64:65]
	v_lshl_add_u64 v[64:65], s[44:45], 0, v[64:65]
	global_load_dwordx4 v[80:83], v[64:65], off
	v_lshlrev_b64 v[64:65], 7, v[128:129]
	v_lshl_add_u64 v[68:69], v[206:207], 0, v[64:65]
	global_load_dwordx4 v[84:87], v[66:67], off
	s_nop 0
	global_load_dwordx4 v[64:67], v[68:69], off offset:16
	s_nop 0
	global_load_dwordx4 v[68:71], v[68:69], off
	s_waitcnt vmcnt(1)
	v_mov_b32_e32 v73, v64
	s_waitcnt vmcnt(0)
	v_mov_b32_e32 v72, v68
	v_mov_b32_e32 v74, v70
	v_mov_b32_e32 v75, v66
	v_pk_add_f32 v[72:73], v[72:73], v[74:75]
	v_add_f32_e32 v64, v69, v71
	v_add_f32_e32 v66, v65, v67
	v_mov_b32_e32 v65, v72
	v_mov_b32_e32 v67, v73
	v_pk_add_f32 v[64:65], v[64:65], v[66:67]
	s_waitcnt lgkmcnt(0)
	v_mov_b32_e32 v67, v65
	v_mov_b32_e32 v66, v64
	s_nop 1
	v_permlane16_swap_b32_e32 v67, v65
	v_permlane16_swap_b32_e32 v66, v64
	s_nop 0
	v_pk_add_f32 v[64:65], v[64:65], v[66:67]
	s_waitcnt lgkmcnt(0)
	v_mov_b32_e32 v67, v65
	v_mov_b32_e32 v66, v64
	s_nop 1
	v_permlane32_swap_b32_e32 v67, v65
	v_permlane32_swap_b32_e32 v66, v64
	s_nop 0
	v_pk_add_f32 v[64:65], v[64:65], v[66:67]
	s_nop 0
	v_pk_mul_f32 v[130:131], v[64:65], s[28:29] op_sel_hi:[1,0]
	s_nop 0
	v_fma_f32 v64, -v131, v131, v130
	v_max_f32_e32 v64, 0, v64
	v_add_f32_e32 v64, 0x3727c5ac, v64
	v_cmp_gt_f32_e32 vcc, s91, v64
	v_mul_f32_e32 v65, 0x4b800000, v64
	s_nop 0
	v_cndmask_b32_e32 v64, v64, v65, vcc
	v_rsq_f32_e32 v64, v64
	s_nop 0
	v_mul_f32_e32 v65, 0x45800000, v64
	v_cndmask_b32_e32 v132, v64, v65, vcc
	v_lshlrev_b64 v[64:65], 10, v[128:129]
	v_lshl_add_u64 v[64:65], v[64:65], 0, v[222:223]
	v_lshlrev_b64 v[134:135], 1, v[64:65]
	v_lshl_add_u64 v[64:65], s[48:49], 0, v[134:135]
	global_load_dwordx4 v[76:79], v[64:65], off
	v_lshl_add_u64 v[64:65], s[44:45], 0, v[134:135]
	global_load_dwordx4 v[72:75], v[64:65], off
	v_or_b32_e32 v64, 0x100, v134
	v_mov_b32_e32 v65, v135
	v_lshl_add_u64 v[66:67], s[48:49], 0, v[64:65]
	v_lshl_add_u64 v[64:65], s[44:45], 0, v[64:65]
	global_load_dwordx4 v[68:71], v[66:67], off
	s_nop 0
	global_load_dwordx4 v[64:67], v[64:65], off
	s_nop 0
	global_load_dwordx4 v[96:99], v[214:215], off offset:16
	global_load_dwordx4 v[108:111], v[214:215], off
	global_load_dwordx4 v[100:103], v[216:217], off offset:16
	global_load_dwordx4 v[112:115], v[216:217], off
	global_load_dwordx4 v[104:107], v[218:219], off offset:16
	global_load_dwordx4 v[120:123], v[218:219], off
	global_load_dwordx4 v[116:119], v[220:221], off offset:16
	global_load_dwordx4 v[124:127], v[220:221], off
	s_waitcnt vmcnt(3)
	v_fma_f32 v56, -v139, v104, v56
	s_waitcnt vmcnt(2)
	v_fma_f32 v62, -v139, v122, v62
	v_fma_f32 v63, -v139, v123, v63
	s_waitcnt vmcnt(0)
	v_fma_f32 v62, v140, v62, v126
	v_fmac_f32_e32 v127, v140, v63
	v_mul_f32_e32 v62, 0xbfb8aa3b, v62
	v_mul_f32_e32 v63, 0xbfb8aa3b, v127
	v_exp_f32_e32 v62, v62
	v_exp_f32_e32 v63, v63
	v_fma_f32 v57, -v139, v105, v57
	v_fma_f32 v56, v140, v56, v116
	v_fma_f32 v57, v140, v57, v117
	v_mul_f32_e32 v56, 0xbfb8aa3b, v56
	v_mul_f32_e32 v57, 0xbfb8aa3b, v57
	v_fma_f32 v60, -v139, v120, v60
	v_fma_f32 v61, -v139, v121, v61
	v_add_f32_e32 v62, 1.0, v62
	v_add_f32_e32 v63, 1.0, v63
	v_exp_f32_e32 v56, v56
	v_exp_f32_e32 v57, v57
	v_fma_f32 v60, v140, v60, v124
	v_fma_f32 v61, v140, v61, v125
	v_lshlrev_b32_e32 v124, 16, v88
	v_and_b32_e32 v125, 0xffff0000, v88
	v_rcp_f32_e32 v62, v62
	v_rcp_f32_e32 v63, v63
	v_lshlrev_b32_e32 v88, 16, v89
	v_and_b32_e32 v89, 0xffff0000, v89
	v_pk_add_f32 v[88:89], v[88:89], v[138:139] op_sel:[0,1] neg_lo:[0,1] neg_hi:[0,1]
	v_lshlrev_b32_e32 v120, 16, v92
	v_pk_mul_f32 v[88:89], v[88:89], v[140:141] op_sel_hi:[1,0]
	v_and_b32_e32 v121, 0xffff0000, v92
	v_lshlrev_b32_e32 v92, 16, v93
	v_and_b32_e32 v93, 0xffff0000, v93
	v_pk_fma_f32 v[88:89], v[88:89], v[110:111], v[114:115]
	v_add_f32_e32 v56, 1.0, v56
	v_add_f32_e32 v57, 1.0, v57
	v_pk_fma_f32 v[62:63], v[62:63], v[92:93], v[88:89]
	v_rcp_f32_e32 v56, v56
	v_rcp_f32_e32 v57, v57
	v_lshlrev_b32_e32 v92, 16, v90
	v_and_b32_e32 v93, 0xffff0000, v90
	v_pk_add_f32 v[92:93], v[92:93], v[138:139] op_sel:[0,1] neg_lo:[0,1] neg_hi:[0,1]
	v_lshlrev_b32_e32 v88, 16, v94
	v_pk_mul_f32 v[92:93], v[92:93], v[140:141] op_sel_hi:[1,0]
	v_and_b32_e32 v89, 0xffff0000, v94
	v_pk_fma_f32 v[92:93], v[92:93], v[96:97], v[100:101]
	v_mul_f32_e32 v60, 0xbfb8aa3b, v60
	v_pk_fma_f32 v[88:89], v[56:57], v[88:89], v[92:93]
	v_fma_f32 v56, -v139, v106, v58
	v_fma_f32 v57, -v139, v107, v59
	v_fma_f32 v56, v140, v56, v118
	v_fmac_f32_e32 v119, v140, v57
	v_mul_f32_e32 v61, 0xbfb8aa3b, v61
	v_mul_f32_e32 v56, 0xbfb8aa3b, v56
	v_mul_f32_e32 v57, 0xbfb8aa3b, v119
	v_exp_f32_e32 v60, v60
	v_exp_f32_e32 v61, v61
	v_exp_f32_e32 v56, v56
	v_exp_f32_e32 v57, v57
	v_add_f32_e32 v60, 1.0, v60
	v_add_f32_e32 v61, 1.0, v61
	v_add_f32_e32 v56, 1.0, v56
	v_add_f32_e32 v57, 1.0, v57
	v_rcp_f32_e32 v60, v60
	v_rcp_f32_e32 v61, v61
	v_rcp_f32_e32 v56, v56
	v_rcp_f32_e32 v57, v57
	v_lshlrev_b32_e32 v90, 16, v91
	v_and_b32_e32 v91, 0xffff0000, v91
	v_pk_add_f32 v[124:125], v[124:125], v[138:139] op_sel:[0,1] neg_lo:[0,1] neg_hi:[0,1]
	v_pk_add_f32 v[90:91], v[90:91], v[138:139] op_sel:[0,1] neg_lo:[0,1] neg_hi:[0,1]
	v_pk_mul_f32 v[124:125], v[124:125], v[140:141] op_sel_hi:[1,0]
	v_pk_mul_f32 v[90:91], v[90:91], v[140:141] op_sel_hi:[1,0]
	v_pk_fma_f32 v[108:109], v[124:125], v[108:109], v[112:113]
	v_lshlrev_b32_e32 v58, 16, v95
	v_and_b32_e32 v59, 0xffff0000, v95
	v_pk_fma_f32 v[90:91], v[90:91], v[98:99], v[102:103]
	v_pk_fma_f32 v[60:61], v[60:61], v[120:121], v[108:109]
	v_pk_fma_f32 v[90:91], v[56:57], v[58:59], v[90:91]
	v_cvt_pk_bf16_f32 v56, v60, v61
	v_cvt_pk_bf16_f32 v57, v62, v63
	v_cvt_pk_bf16_f32 v58, v88, v89
	v_cvt_pk_bf16_f32 v59, v90, v91
	v_lshl_add_u64 v[60:61], s[52:53], 0, v[142:143]
	global_store_dwordx4 v[60:61], v[56:59], off
	global_load_dwordx4 v[56:59], v[214:215], off offset:528
	s_nop 0
	global_load_dwordx4 v[92:95], v[214:215], off offset:512
	global_load_dwordx4 v[60:63], v[216:217], off offset:528
	global_load_dwordx4 v[96:99], v[216:217], off offset:512
	global_load_dwordx4 v[100:103], v[160:161], off
	global_load_dwordx4 v[88:91], v[162:163], off offset:16
	global_load_dwordx4 v[104:107], v[162:163], off
	s_waitcnt vmcnt(2)
	v_fma_f32 v52, -v139, v100, v52
	v_fma_f32 v53, -v139, v101, v53
	s_waitcnt vmcnt(0)
	v_fma_f32 v52, v140, v52, v104
	v_fma_f32 v53, v140, v53, v105
	v_mul_f32_e32 v52, 0xbfb8aa3b, v52
	v_mul_f32_e32 v53, 0xbfb8aa3b, v53
	v_exp_f32_e32 v52, v52
	v_exp_f32_e32 v53, v53
	v_lshlrev_b32_e32 v104, 16, v80
	v_and_b32_e32 v105, 0xffff0000, v80
	v_add_f32_e32 v52, 1.0, v52
	v_add_f32_e32 v53, 1.0, v53
	v_rcp_f32_e32 v52, v52
	v_rcp_f32_e32 v53, v53
	v_pk_add_f32 v[104:105], v[104:105], v[138:139] op_sel:[0,1] neg_lo:[0,1] neg_hi:[0,1]
	v_lshlrev_b32_e32 v80, 16, v81
	v_and_b32_e32 v81, 0xffff0000, v81
	v_pk_mul_f32 v[104:105], v[104:105], v[140:141] op_sel_hi:[1,0]
	v_pk_add_f32 v[80:81], v[80:81], v[138:139] op_sel:[0,1] neg_lo:[0,1] neg_hi:[0,1]
	v_lshlrev_b32_e32 v100, 16, v84
	v_and_b32_e32 v101, 0xffff0000, v84
	v_pk_fma_f32 v[92:93], v[104:105], v[92:93], v[96:97]
	v_pk_mul_f32 v[80:81], v[80:81], v[140:141] op_sel_hi:[1,0]
	v_pk_fma_f32 v[52:53], v[52:53], v[100:101], v[92:93]
	v_pk_fma_f32 v[80:81], v[80:81], v[94:95], v[98:99]
	global_load_dwordx4 v[92:95], v[164:165], off
	v_fma_f32 v54, -v139, v102, v54
	v_fma_f32 v55, -v139, v103, v55
	v_fma_f32 v54, v140, v54, v106
	v_fmac_f32_e32 v107, v140, v55
	v_mul_f32_e32 v54, 0xbfb8aa3b, v54
	v_mul_f32_e32 v55, 0xbfb8aa3b, v107
	v_exp_f32_e32 v54, v54
	v_exp_f32_e32 v55, v55
	v_lshlrev_b32_e32 v84, 16, v85
	v_and_b32_e32 v85, 0xffff0000, v85
	v_add_f32_e32 v54, 1.0, v54
	v_add_f32_e32 v55, 1.0, v55
	v_rcp_f32_e32 v54, v54
	v_rcp_f32_e32 v55, v55
	v_lshl_add_u64 v[104:105], v[224:225], 0, s[34:35]
	s_mov_b64 s[34:35], 0xb0
	v_lshl_add_u64 v[96:97], v[224:225], 0, s[34:35]
	v_pk_fma_f32 v[54:55], v[54:55], v[84:85], v[80:81]
	v_lshlrev_b32_e32 v84, 16, v82
	v_and_b32_e32 v85, 0xffff0000, v82
	v_pk_add_f32 v[84:85], v[84:85], v[138:139] op_sel:[0,1] neg_lo:[0,1] neg_hi:[0,1]
	v_lshlrev_b32_e32 v80, 16, v86
	v_pk_mul_f32 v[84:85], v[84:85], v[140:141] op_sel_hi:[1,0]
	v_and_b32_e32 v81, 0xffff0000, v86
	v_pk_fma_f32 v[56:57], v[84:85], v[56:57], v[60:61]
	v_lshlrev_b32_e32 v60, 16, v83
	v_and_b32_e32 v61, 0xffff0000, v83
	v_pk_add_f32 v[60:61], v[60:61], v[138:139] op_sel:[0,1] neg_lo:[0,1] neg_hi:[0,1]
	s_mov_b64 s[34:35], -1
	v_pk_mul_f32 v[60:61], v[60:61], v[140:141] op_sel_hi:[1,0]
	s_waitcnt vmcnt(0)
	v_fma_f32 v48, -v139, v92, v48
	v_fma_f32 v49, -v139, v93, v49
	v_fma_f32 v48, v140, v48, v88
	v_fma_f32 v49, v140, v49, v89
	v_mul_f32_e32 v48, 0xbfb8aa3b, v48
	v_mul_f32_e32 v49, 0xbfb8aa3b, v49
	v_exp_f32_e32 v48, v48
	v_exp_f32_e32 v49, v49
	v_pk_fma_f32 v[58:59], v[60:61], v[58:59], v[62:63]
	v_add_f32_e32 v48, 1.0, v48
	v_add_f32_e32 v49, 1.0, v49
	v_rcp_f32_e32 v48, v48
	v_rcp_f32_e32 v49, v49
	s_nop 0
	v_pk_fma_f32 v[56:57], v[48:49], v[80:81], v[56:57]
	v_fma_f32 v48, -v139, v94, v50
	v_fma_f32 v49, -v139, v95, v51
	v_fma_f32 v48, v140, v48, v90
	v_fmac_f32_e32 v91, v140, v49
	v_mul_f32_e32 v48, 0xbfb8aa3b, v48
	v_mul_f32_e32 v49, 0xbfb8aa3b, v91
	v_exp_f32_e32 v48, v48
	v_exp_f32_e32 v49, v49
	v_lshlrev_b32_e32 v50, 16, v87
	v_and_b32_e32 v51, 0xffff0000, v87
	v_add_f32_e32 v48, 1.0, v48
	v_add_f32_e32 v49, 1.0, v49
	v_rcp_f32_e32 v48, v48
	v_rcp_f32_e32 v49, v49
	s_nop 0
	v_pk_fma_f32 v[58:59], v[48:49], v[50:51], v[58:59]
	v_cvt_pk_bf16_f32 v48, v52, v53
	v_lshlrev_b64 v[52:53], 11, v[136:137]
	v_lshl_add_u64 v[52:53], s[52:53], 0, v[52:53]
	v_cvt_pk_bf16_f32 v49, v54, v55
	v_cvt_pk_bf16_f32 v50, v56, v57
	v_cvt_pk_bf16_f32 v51, v58, v59
	v_lshl_add_u64 v[52:53], v[52:53], 0, v[166:167]
	global_store_dwordx4 v[52:53], v[48:51], off offset:256
	global_load_dwordx4 v[48:51], v[214:215], off offset:16
	s_nop 0
	global_load_dwordx4 v[80:83], v[214:215], off
	global_load_dwordx4 v[52:55], v[216:217], off offset:16
	global_load_dwordx4 v[84:87], v[216:217], off
	global_load_dwordx4 v[56:59], v[218:219], off offset:16
	global_load_dwordx4 v[88:91], v[218:219], off
	global_load_dwordx4 v[60:63], v[220:221], off offset:16
	global_load_dwordx4 v[92:95], v[220:221], off
	s_waitcnt vmcnt(3)
	v_fma_f32 v40, -v131, v56, v40
	v_fma_f32 v41, -v131, v57, v41
	s_waitcnt vmcnt(1)
	v_fma_f32 v40, v132, v40, v60
	v_fma_f32 v41, v132, v41, v61
	v_mul_f32_e32 v40, 0xbfb8aa3b, v40
	v_mul_f32_e32 v41, 0xbfb8aa3b, v41
	v_exp_f32_e32 v40, v40
	v_exp_f32_e32 v41, v41
	v_lshlrev_b32_e32 v60, 16, v74
	v_and_b32_e32 v61, 0xffff0000, v74
	v_add_f32_e32 v40, 1.0, v40
	v_add_f32_e32 v41, 1.0, v41
	v_rcp_f32_e32 v40, v40
	v_rcp_f32_e32 v41, v41
	v_pk_add_f32 v[60:61], v[60:61], v[130:131] op_sel:[0,1] neg_lo:[0,1] neg_hi:[0,1]
	v_lshlrev_b32_e32 v56, 16, v78
	v_pk_mul_f32 v[60:61], v[60:61], v[132:133] op_sel_hi:[1,0]
	v_and_b32_e32 v57, 0xffff0000, v78
	v_pk_fma_f32 v[48:49], v[60:61], v[48:49], v[52:53]
	v_fma_f32 v44, -v131, v88, v44
	v_fma_f32 v45, -v131, v89, v45
	v_fma_f32 v46, -v131, v90, v46
	v_fma_f32 v47, -v131, v91, v47
	v_pk_fma_f32 v[48:49], v[40:41], v[56:57], v[48:49]
	v_fma_f32 v40, -v131, v58, v42
	v_fma_f32 v41, -v131, v59, v43
	s_waitcnt vmcnt(0)
	v_fma_f32 v44, v132, v44, v92
	v_fma_f32 v45, v132, v45, v93
	v_fma_f32 v46, v132, v46, v94
	v_fmac_f32_e32 v95, v132, v47
	v_fma_f32 v40, v132, v40, v62
	v_fmac_f32_e32 v63, v132, v41
	v_mul_f32_e32 v44, 0xbfb8aa3b, v44
	v_mul_f32_e32 v45, 0xbfb8aa3b, v45
	v_mul_f32_e32 v46, 0xbfb8aa3b, v46
	v_mul_f32_e32 v47, 0xbfb8aa3b, v95
	v_mul_f32_e32 v40, 0xbfb8aa3b, v40
	v_mul_f32_e32 v41, 0xbfb8aa3b, v63
	v_exp_f32_e32 v44, v44
	v_exp_f32_e32 v45, v45
	v_exp_f32_e32 v46, v46
	v_exp_f32_e32 v47, v47
	v_exp_f32_e32 v40, v40
	v_exp_f32_e32 v41, v41
	v_add_f32_e32 v44, 1.0, v44
	v_add_f32_e32 v45, 1.0, v45
	v_add_f32_e32 v46, 1.0, v46
	v_add_f32_e32 v47, 1.0, v47
	v_add_f32_e32 v40, 1.0, v40
	v_add_f32_e32 v41, 1.0, v41
	v_rcp_f32_e32 v44, v44
	v_rcp_f32_e32 v45, v45
	v_lshlrev_b32_e32 v92, 16, v72
	v_and_b32_e32 v93, 0xffff0000, v72
	v_rcp_f32_e32 v46, v46
	v_rcp_f32_e32 v47, v47
	v_lshlrev_b32_e32 v72, 16, v73
	v_and_b32_e32 v73, 0xffff0000, v73
	v_rcp_f32_e32 v40, v40
	v_rcp_f32_e32 v41, v41
	v_lshlrev_b32_e32 v52, 16, v75
	v_and_b32_e32 v53, 0xffff0000, v75
	v_pk_add_f32 v[92:93], v[92:93], v[130:131] op_sel:[0,1] neg_lo:[0,1] neg_hi:[0,1]
	v_pk_add_f32 v[72:73], v[72:73], v[130:131] op_sel:[0,1] neg_lo:[0,1] neg_hi:[0,1]
	v_pk_add_f32 v[52:53], v[52:53], v[130:131] op_sel:[0,1] neg_lo:[0,1] neg_hi:[0,1]
	v_pk_mul_f32 v[92:93], v[92:93], v[132:133] op_sel_hi:[1,0]
	v_pk_mul_f32 v[72:73], v[72:73], v[132:133] op_sel_hi:[1,0]
	v_pk_mul_f32 v[52:53], v[52:53], v[132:133] op_sel_hi:[1,0]
	v_lshlrev_b32_e32 v88, 16, v76
	v_and_b32_e32 v89, 0xffff0000, v76
	v_pk_fma_f32 v[80:81], v[92:93], v[80:81], v[84:85]
	v_lshlrev_b32_e32 v76, 16, v77
	v_and_b32_e32 v77, 0xffff0000, v77
	v_pk_fma_f32 v[72:73], v[72:73], v[82:83], v[86:87]
	v_lshlrev_b32_e32 v42, 16, v79
	v_and_b32_e32 v43, 0xffff0000, v79
	v_pk_fma_f32 v[50:51], v[52:53], v[50:51], v[54:55]
	v_pk_fma_f32 v[44:45], v[44:45], v[88:89], v[80:81]
	v_pk_fma_f32 v[46:47], v[46:47], v[76:77], v[72:73]
	v_pk_fma_f32 v[50:51], v[40:41], v[42:43], v[50:51]
	v_cvt_pk_bf16_f32 v40, v44, v45
	v_cvt_pk_bf16_f32 v41, v46, v47
	v_cvt_pk_bf16_f32 v42, v48, v49
	v_cvt_pk_bf16_f32 v43, v50, v51
	v_lshl_add_u64 v[44:45], s[52:53], 0, v[134:135]
	global_store_dwordx4 v[44:45], v[40:43], off
	global_load_dwordx4 v[40:43], v[214:215], off offset:528
	s_nop 0
	global_load_dwordx4 v[52:55], v[214:215], off offset:512
	global_load_dwordx4 v[44:47], v[216:217], off offset:528
	global_load_dwordx4 v[56:59], v[216:217], off offset:512
	global_load_dwordx4 v[60:63], v[160:161], off
	global_load_dwordx4 v[48:51], v[162:163], off offset:16
	global_load_dwordx4 v[72:75], v[162:163], off
	s_waitcnt vmcnt(2)
	v_fma_f32 v36, -v131, v60, v36
	v_fma_f32 v37, -v131, v61, v37
	s_waitcnt vmcnt(0)
	v_fma_f32 v36, v132, v36, v72
	v_fma_f32 v37, v132, v37, v73
	v_fma_f32 v38, -v131, v62, v38
	v_fma_f32 v39, -v131, v63, v39
	v_mul_f32_e32 v36, 0xbfb8aa3b, v36
	v_mul_f32_e32 v37, 0xbfb8aa3b, v37
	v_fma_f32 v38, v132, v38, v74
	v_fmac_f32_e32 v75, v132, v39
	v_exp_f32_e32 v36, v36
	v_exp_f32_e32 v37, v37
	v_mul_f32_e32 v38, 0xbfb8aa3b, v38
	v_mul_f32_e32 v39, 0xbfb8aa3b, v75
	v_exp_f32_e32 v38, v38
	v_exp_f32_e32 v39, v39
	v_lshlrev_b32_e32 v72, 16, v64
	v_and_b32_e32 v73, 0xffff0000, v64
	v_add_f32_e32 v36, 1.0, v36
	v_add_f32_e32 v37, 1.0, v37
	v_pk_add_f32 v[72:73], v[72:73], v[130:131] op_sel:[0,1] neg_lo:[0,1] neg_hi:[0,1]
	v_rcp_f32_e32 v36, v36
	v_rcp_f32_e32 v37, v37
	v_pk_mul_f32 v[72:73], v[72:73], v[132:133] op_sel_hi:[1,0]
	v_add_f32_e32 v38, 1.0, v38
	v_add_f32_e32 v39, 1.0, v39
	v_pk_fma_f32 v[52:53], v[72:73], v[52:53], v[56:57]
	v_rcp_f32_e32 v38, v38
	v_rcp_f32_e32 v39, v39
	v_lshlrev_b32_e32 v56, 16, v65
	v_and_b32_e32 v57, 0xffff0000, v65
	v_pk_add_f32 v[56:57], v[56:57], v[130:131] op_sel:[0,1] neg_lo:[0,1] neg_hi:[0,1]
	v_lshlrev_b32_e32 v60, 16, v68
	v_and_b32_e32 v61, 0xffff0000, v68
	v_pk_mul_f32 v[56:57], v[56:57], v[132:133] op_sel_hi:[1,0]
	v_pk_fma_f32 v[36:37], v[36:37], v[60:61], v[52:53]
	v_lshlrev_b32_e32 v52, 16, v69
	v_and_b32_e32 v53, 0xffff0000, v69
	v_pk_fma_f32 v[54:55], v[56:57], v[54:55], v[58:59]
	s_nop 0
	v_pk_fma_f32 v[38:39], v[38:39], v[52:53], v[54:55]
	global_load_dwordx4 v[52:55], v[164:165], off
	s_waitcnt vmcnt(0)
; DI void row_stats(const f32x2v* st, size_t row, int fq, float& mu, float& rstd) {
;     const f32x4 a = *(const f32x4*)(st + row * 16 + 4 * fq), b = *(const f32x4*)(st + row * 16 + 4 * fq + 2);
;     float s1 = (a[0] + a[2]) + (b[0] + b[2]), s2 = (a[1] + a[3]) + (b[1] + b[3]);
;     s1 += __shfl_xor(s1, 16); s1 += __shfl_xor(s1, 32); s2 += __shfl_xor(s2, 16); s2 += __shfl_xor(s2, 32);
;     mu = s1 * (1.0f / 1024.0f); const float var = fmaxf(s2 * (1.0f / 1024.0f) - mu * mu, 0.f); rstd = rsqrtf(var + LN_EPS);
; }
	v_fma_f32 v32, -v131, v52, v32
	v_fma_f32 v33, -v131, v53, v33
	v_fma_f32 v32, v132, v32, v48
	v_fma_f32 v33, v132, v33, v49
	v_mul_f32_e32 v32, 0xbfb8aa3b, v32
	v_mul_f32_e32 v33, 0xbfb8aa3b, v33
	v_exp_f32_e32 v32, v32
	v_exp_f32_e32 v33, v33
	v_lshlrev_b32_e32 v52, 16, v66
	v_and_b32_e32 v53, 0xffff0000, v66
	v_add_f32_e32 v32, 1.0, v32
	v_add_f32_e32 v33, 1.0, v33
	v_rcp_f32_e32 v32, v32
	v_rcp_f32_e32 v33, v33
	v_pk_add_f32 v[52:53], v[52:53], v[130:131] op_sel:[0,1] neg_lo:[0,1] neg_hi:[0,1]
	v_lshlrev_b32_e32 v48, 16, v70
	v_pk_mul_f32 v[52:53], v[52:53], v[132:133] op_sel_hi:[1,0]
	v_and_b32_e32 v49, 0xffff0000, v70
	v_pk_fma_f32 v[40:41], v[52:53], v[40:41], v[44:45]
	v_lshlrev_b32_e32 v44, 16, v67
	v_pk_fma_f32 v[40:41], v[32:33], v[48:49], v[40:41]
	v_fma_f32 v32, -v131, v54, v34
	v_fma_f32 v33, -v131, v55, v35
	v_fma_f32 v32, v132, v32, v50
	v_fmac_f32_e32 v51, v132, v33
	v_mul_f32_e32 v32, 0xbfb8aa3b, v32
	v_mul_f32_e32 v33, 0xbfb8aa3b, v51
	v_exp_f32_e32 v32, v32
	v_exp_f32_e32 v33, v33
	v_and_b32_e32 v45, 0xffff0000, v67
	v_pk_add_f32 v[44:45], v[44:45], v[130:131] op_sel:[0,1] neg_lo:[0,1] neg_hi:[0,1]
	v_add_f32_e32 v32, 1.0, v32
	v_add_f32_e32 v33, 1.0, v33
	v_rcp_f32_e32 v32, v32
	v_rcp_f32_e32 v33, v33
	v_pk_mul_f32 v[44:45], v[44:45], v[132:133] op_sel_hi:[1,0]
	v_lshlrev_b32_e32 v34, 16, v71
	v_and_b32_e32 v35, 0xffff0000, v71
	v_pk_fma_f32 v[42:43], v[44:45], v[42:43], v[46:47]
	s_nop 0
	v_pk_fma_f32 v[42:43], v[32:33], v[34:35], v[42:43]
	v_cvt_pk_bf16_f32 v32, v36, v37
	v_lshlrev_b64 v[36:37], 11, v[128:129]
	v_lshl_add_u64 v[36:37], s[52:53], 0, v[36:37]
	v_cvt_pk_bf16_f32 v33, v38, v39
	v_cvt_pk_bf16_f32 v34, v40, v41
	v_cvt_pk_bf16_f32 v35, v42, v43
	v_lshl_add_u64 v[36:37], v[36:37], 0, v[166:167]
	global_store_dwordx4 v[36:37], v[32:35], off offset:256
	s_nop 1
	v_lshlrev_b64 v[32:33], 7, v[104:105]
	v_lshl_add_u64 v[36:37], v[206:207], 0, v[32:33]
	global_load_dwordx4 v[32:35], v[36:37], off offset:16
	s_nop 0
	global_load_dwordx4 v[36:39], v[36:37], off
	s_waitcnt vmcnt(1)
	v_mov_b32_e32 v41, v32
	s_waitcnt vmcnt(0)
	v_mov_b32_e32 v40, v36
	v_mov_b32_e32 v42, v38
	v_mov_b32_e32 v43, v34
	v_pk_add_f32 v[40:41], v[40:41], v[42:43]
	v_add_f32_e32 v32, v37, v39
	v_add_f32_e32 v34, v33, v35
	v_mov_b32_e32 v33, v40
	v_mov_b32_e32 v35, v41
	v_pk_add_f32 v[32:33], v[32:33], v[34:35]
	s_waitcnt lgkmcnt(0)
	v_mov_b32_e32 v35, v33
	v_mov_b32_e32 v34, v32
	s_nop 1
	v_permlane16_swap_b32_e32 v35, v33
	v_permlane16_swap_b32_e32 v34, v32
	s_nop 0
	v_pk_add_f32 v[32:33], v[32:33], v[34:35]
	s_waitcnt lgkmcnt(0)
	v_mov_b32_e32 v35, v33
	v_mov_b32_e32 v34, v32
	s_nop 1
	v_permlane32_swap_b32_e32 v35, v33
	v_permlane32_swap_b32_e32 v34, v32
	s_nop 0
	v_pk_add_f32 v[32:33], v[32:33], v[34:35]
	s_nop 0
	v_pk_mul_f32 v[106:107], v[32:33], s[28:29] op_sel_hi:[1,0]
	s_nop 0
	v_fma_f32 v32, -v107, v107, v106
	v_max_f32_e32 v32, 0, v32
	v_add_f32_e32 v32, 0x3727c5ac, v32
	v_cmp_gt_f32_e32 vcc, s91, v32
	v_mul_f32_e32 v33, 0x4b800000, v32
	s_nop 0
	v_cndmask_b32_e32 v32, v32, v33, vcc
	v_rsq_f32_e32 v32, v32
	s_nop 0
	v_mul_f32_e32 v33, 0x45800000, v32
	v_cndmask_b32_e32 v108, v32, v33, vcc
	v_lshlrev_b64 v[32:33], 10, v[104:105]
	v_lshl_add_u64 v[32:33], v[32:33], 0, v[222:223]
	v_lshlrev_b64 v[110:111], 1, v[32:33]
	v_lshl_add_u64 v[32:33], s[48:49], 0, v[110:111]
	global_load_dwordx4 v[60:63], v[32:33], off
	v_lshl_add_u64 v[32:33], s[44:45], 0, v[110:111]
	global_load_dwordx4 v[56:59], v[32:33], off
	v_or_b32_e32 v32, 0x100, v110
	v_mov_b32_e32 v33, v111
	v_lshl_add_u64 v[34:35], s[48:49], 0, v[32:33]
	v_lshl_add_u64 v[32:33], s[44:45], 0, v[32:33]
	global_load_dwordx4 v[48:51], v[32:33], off
	v_lshlrev_b64 v[32:33], 7, v[96:97]
	v_lshl_add_u64 v[36:37], v[206:207], 0, v[32:33]
	global_load_dwordx4 v[52:55], v[34:35], off
	s_nop 0
	global_load_dwordx4 v[32:35], v[36:37], off offset:16
	s_nop 0
	global_load_dwordx4 v[36:39], v[36:37], off
	s_waitcnt vmcnt(1)
	v_mov_b32_e32 v41, v32
	s_waitcnt vmcnt(0)
	v_mov_b32_e32 v40, v36
	v_mov_b32_e32 v42, v38
	v_mov_b32_e32 v43, v34
	v_pk_add_f32 v[40:41], v[40:41], v[42:43]
	v_add_f32_e32 v32, v37, v39
	v_add_f32_e32 v34, v33, v35
	v_mov_b32_e32 v33, v40
	v_mov_b32_e32 v35, v41
	v_pk_add_f32 v[32:33], v[32:33], v[34:35]
	s_waitcnt lgkmcnt(0)
	v_mov_b32_e32 v35, v33
	v_mov_b32_e32 v34, v32
	s_nop 1
	v_permlane16_swap_b32_e32 v35, v33
	v_permlane16_swap_b32_e32 v34, v32
	s_nop 0
	v_pk_add_f32 v[32:33], v[32:33], v[34:35]
	s_waitcnt lgkmcnt(0)
	v_mov_b32_e32 v35, v33
	v_mov_b32_e32 v34, v32
	s_nop 1
	v_permlane32_swap_b32_e32 v35, v33
	v_permlane32_swap_b32_e32 v34, v32
	s_nop 0
	v_pk_add_f32 v[32:33], v[32:33], v[34:35]
	s_nop 0
	v_pk_mul_f32 v[98:99], v[32:33], s[28:29] op_sel_hi:[1,0]
	s_nop 0
	v_fma_f32 v32, -v99, v99, v98
	v_max_f32_e32 v32, 0, v32
	v_add_f32_e32 v32, 0x3727c5ac, v32
	v_cmp_gt_f32_e32 vcc, s91, v32
	v_mul_f32_e32 v33, 0x4b800000, v32
	s_nop 0
	v_cndmask_b32_e32 v32, v32, v33, vcc
	v_rsq_f32_e32 v32, v32
	s_nop 0
	v_mul_f32_e32 v33, 0x45800000, v32
	v_cndmask_b32_e32 v100, v32, v33, vcc
	v_lshlrev_b64 v[32:33], 10, v[96:97]
	v_lshl_add_u64 v[32:33], v[32:33], 0, v[222:223]
	v_lshlrev_b64 v[102:103], 1, v[32:33]
	v_lshl_add_u64 v[32:33], s[48:49], 0, v[102:103]
	global_load_dwordx4 v[44:47], v[32:33], off
	v_lshl_add_u64 v[32:33], s[44:45], 0, v[102:103]
	global_load_dwordx4 v[40:43], v[32:33], off
	v_or_b32_e32 v32, 0x100, v102
	v_mov_b32_e32 v33, v103
	v_lshl_add_u64 v[34:35], s[48:49], 0, v[32:33]
	v_lshl_add_u64 v[32:33], s[44:45], 0, v[32:33]
	global_load_dwordx4 v[36:39], v[34:35], off
	s_nop 0
	global_load_dwordx4 v[32:35], v[32:33], off
	s_nop 0
	global_load_dwordx4 v[64:67], v[214:215], off offset:16
	global_load_dwordx4 v[76:79], v[214:215], off
	global_load_dwordx4 v[68:71], v[216:217], off offset:16
	global_load_dwordx4 v[80:83], v[216:217], off
	global_load_dwordx4 v[72:75], v[218:219], off offset:16
	global_load_dwordx4 v[88:91], v[218:219], off
	global_load_dwordx4 v[84:87], v[220:221], off offset:16
	global_load_dwordx4 v[92:95], v[220:221], off
	s_and_b64 vcc, exec, s[4:5]
	s_waitcnt vmcnt(3)
	v_fma_f32 v24, -v107, v72, v24
	s_waitcnt vmcnt(2)
	v_fma_f32 v30, -v107, v90, v30
	v_fma_f32 v31, -v107, v91, v31
	s_waitcnt vmcnt(0)
	v_fma_f32 v30, v108, v30, v94
	v_fmac_f32_e32 v95, v108, v31
	v_mul_f32_e32 v30, 0xbfb8aa3b, v30
	v_mul_f32_e32 v31, 0xbfb8aa3b, v95
	v_exp_f32_e32 v30, v30
	v_exp_f32_e32 v31, v31
	v_fma_f32 v25, -v107, v73, v25
	v_fma_f32 v24, v108, v24, v84
	v_fma_f32 v25, v108, v25, v85
	v_mul_f32_e32 v24, 0xbfb8aa3b, v24
	v_mul_f32_e32 v25, 0xbfb8aa3b, v25
	v_fma_f32 v28, -v107, v88, v28
	v_fma_f32 v29, -v107, v89, v29
	v_add_f32_e32 v30, 1.0, v30
	v_add_f32_e32 v31, 1.0, v31
	v_exp_f32_e32 v24, v24
	v_exp_f32_e32 v25, v25
	v_fma_f32 v28, v108, v28, v92
	v_fma_f32 v29, v108, v29, v93
	v_lshlrev_b32_e32 v92, 16, v56
	v_and_b32_e32 v93, 0xffff0000, v56
	v_rcp_f32_e32 v30, v30
	v_rcp_f32_e32 v31, v31
	v_lshlrev_b32_e32 v56, 16, v57
	v_and_b32_e32 v57, 0xffff0000, v57
	v_pk_add_f32 v[56:57], v[56:57], v[106:107] op_sel:[0,1] neg_lo:[0,1] neg_hi:[0,1]
	v_lshlrev_b32_e32 v88, 16, v60
	v_pk_mul_f32 v[56:57], v[56:57], v[108:109] op_sel_hi:[1,0]
	v_and_b32_e32 v89, 0xffff0000, v60
	v_lshlrev_b32_e32 v60, 16, v61
	v_and_b32_e32 v61, 0xffff0000, v61
	v_pk_fma_f32 v[56:57], v[56:57], v[78:79], v[82:83]
	v_add_f32_e32 v24, 1.0, v24
	v_add_f32_e32 v25, 1.0, v25
	v_pk_fma_f32 v[30:31], v[30:31], v[60:61], v[56:57]
	v_rcp_f32_e32 v24, v24
	v_rcp_f32_e32 v25, v25
	v_lshlrev_b32_e32 v60, 16, v58
	v_and_b32_e32 v61, 0xffff0000, v58
	v_pk_add_f32 v[60:61], v[60:61], v[106:107] op_sel:[0,1] neg_lo:[0,1] neg_hi:[0,1]
	v_lshlrev_b32_e32 v56, 16, v62
	v_pk_mul_f32 v[60:61], v[60:61], v[108:109] op_sel_hi:[1,0]
	v_and_b32_e32 v57, 0xffff0000, v62
	v_pk_fma_f32 v[60:61], v[60:61], v[64:65], v[68:69]
	v_mul_f32_e32 v28, 0xbfb8aa3b, v28
	v_pk_fma_f32 v[56:57], v[24:25], v[56:57], v[60:61]
	v_fma_f32 v24, -v107, v74, v26
	v_fma_f32 v25, -v107, v75, v27
	v_fma_f32 v24, v108, v24, v86
	v_fmac_f32_e32 v87, v108, v25
	v_mul_f32_e32 v29, 0xbfb8aa3b, v29
	v_mul_f32_e32 v24, 0xbfb8aa3b, v24
	v_mul_f32_e32 v25, 0xbfb8aa3b, v87
	v_exp_f32_e32 v28, v28
	v_exp_f32_e32 v29, v29
	v_exp_f32_e32 v24, v24
	v_exp_f32_e32 v25, v25
	v_add_f32_e32 v28, 1.0, v28
	v_add_f32_e32 v29, 1.0, v29
	v_add_f32_e32 v24, 1.0, v24
	v_add_f32_e32 v25, 1.0, v25
	v_rcp_f32_e32 v28, v28
	v_rcp_f32_e32 v29, v29
	v_rcp_f32_e32 v24, v24
	v_rcp_f32_e32 v25, v25
	v_lshlrev_b32_e32 v58, 16, v59
	v_and_b32_e32 v59, 0xffff0000, v59
	v_pk_add_f32 v[92:93], v[92:93], v[106:107] op_sel:[0,1] neg_lo:[0,1] neg_hi:[0,1]
	v_pk_add_f32 v[58:59], v[58:59], v[106:107] op_sel:[0,1] neg_lo:[0,1] neg_hi:[0,1]
	v_pk_mul_f32 v[92:93], v[92:93], v[108:109] op_sel_hi:[1,0]
	v_pk_mul_f32 v[58:59], v[58:59], v[108:109] op_sel_hi:[1,0]
	v_pk_fma_f32 v[76:77], v[92:93], v[76:77], v[80:81]
	v_lshlrev_b32_e32 v26, 16, v63
	v_and_b32_e32 v27, 0xffff0000, v63
	v_pk_fma_f32 v[58:59], v[58:59], v[66:67], v[70:71]
	v_pk_fma_f32 v[28:29], v[28:29], v[88:89], v[76:77]
	v_pk_fma_f32 v[58:59], v[24:25], v[26:27], v[58:59]
	v_cvt_pk_bf16_f32 v24, v28, v29
	v_cvt_pk_bf16_f32 v25, v30, v31
	v_cvt_pk_bf16_f32 v26, v56, v57
	v_cvt_pk_bf16_f32 v27, v58, v59
	v_lshl_add_u64 v[28:29], s[52:53], 0, v[110:111]
	global_store_dwordx4 v[28:29], v[24:27], off
	global_load_dwordx4 v[24:27], v[214:215], off offset:528
	s_nop 0
	global_load_dwordx4 v[60:63], v[214:215], off offset:512
	global_load_dwordx4 v[28:31], v[216:217], off offset:528
	global_load_dwordx4 v[64:67], v[216:217], off offset:512
	global_load_dwordx4 v[68:71], v[160:161], off
	global_load_dwordx4 v[56:59], v[162:163], off offset:16
	global_load_dwordx4 v[72:75], v[162:163], off
	s_waitcnt vmcnt(2)
	v_fma_f32 v20, -v107, v68, v20
	v_fma_f32 v21, -v107, v69, v21
	s_waitcnt vmcnt(0)
	v_fma_f32 v20, v108, v20, v72
	v_fma_f32 v21, v108, v21, v73
	v_mul_f32_e32 v20, 0xbfb8aa3b, v20
	v_mul_f32_e32 v21, 0xbfb8aa3b, v21
	v_exp_f32_e32 v20, v20
	v_exp_f32_e32 v21, v21
	v_lshlrev_b32_e32 v72, 16, v48
	v_and_b32_e32 v73, 0xffff0000, v48
	v_add_f32_e32 v20, 1.0, v20
	v_add_f32_e32 v21, 1.0, v21
	v_rcp_f32_e32 v20, v20
	v_rcp_f32_e32 v21, v21
	v_pk_add_f32 v[72:73], v[72:73], v[106:107] op_sel:[0,1] neg_lo:[0,1] neg_hi:[0,1]
	v_lshlrev_b32_e32 v48, 16, v49
	v_and_b32_e32 v49, 0xffff0000, v49
	v_pk_mul_f32 v[72:73], v[72:73], v[108:109] op_sel_hi:[1,0]
	v_pk_add_f32 v[48:49], v[48:49], v[106:107] op_sel:[0,1] neg_lo:[0,1] neg_hi:[0,1]
	v_lshlrev_b32_e32 v68, 16, v52
	v_and_b32_e32 v69, 0xffff0000, v52
	v_pk_fma_f32 v[60:61], v[72:73], v[60:61], v[64:65]
	v_pk_mul_f32 v[48:49], v[48:49], v[108:109] op_sel_hi:[1,0]
	v_pk_fma_f32 v[20:21], v[20:21], v[68:69], v[60:61]
	v_pk_fma_f32 v[48:49], v[48:49], v[62:63], v[66:67]
	global_load_dwordx4 v[60:63], v[164:165], off
	v_fma_f32 v22, -v107, v70, v22
	v_fma_f32 v23, -v107, v71, v23
	v_fma_f32 v22, v108, v22, v74
	v_fmac_f32_e32 v75, v108, v23
	v_mul_f32_e32 v22, 0xbfb8aa3b, v22
	v_mul_f32_e32 v23, 0xbfb8aa3b, v75
	v_exp_f32_e32 v22, v22
	v_exp_f32_e32 v23, v23
	v_lshlrev_b32_e32 v52, 16, v53
	v_and_b32_e32 v53, 0xffff0000, v53
	v_add_f32_e32 v22, 1.0, v22
	v_add_f32_e32 v23, 1.0, v23
	v_rcp_f32_e32 v22, v22
	v_rcp_f32_e32 v23, v23
	s_waitcnt vmcnt(0)
	v_fma_f32 v16, -v107, v60, v16
	v_fma_f32 v17, -v107, v61, v17
	v_fma_f32 v16, v108, v16, v56
	v_fma_f32 v17, v108, v17, v57
	v_mul_f32_e32 v16, 0xbfb8aa3b, v16
	v_mul_f32_e32 v17, 0xbfb8aa3b, v17
	v_exp_f32_e32 v16, v16
	v_exp_f32_e32 v17, v17
	v_pk_fma_f32 v[22:23], v[22:23], v[52:53], v[48:49]
	v_lshlrev_b32_e32 v52, 16, v50
	v_add_f32_e32 v16, 1.0, v16
	v_add_f32_e32 v17, 1.0, v17
	v_rcp_f32_e32 v16, v16
	v_rcp_f32_e32 v17, v17
	v_and_b32_e32 v53, 0xffff0000, v50
	v_pk_add_f32 v[52:53], v[52:53], v[106:107] op_sel:[0,1] neg_lo:[0,1] neg_hi:[0,1]
	v_lshlrev_b32_e32 v48, 16, v54
	v_pk_mul_f32 v[52:53], v[52:53], v[108:109] op_sel_hi:[1,0]
	v_and_b32_e32 v49, 0xffff0000, v54
	v_pk_fma_f32 v[24:25], v[52:53], v[24:25], v[28:29]
	v_lshlrev_b32_e32 v28, 16, v51
	v_pk_fma_f32 v[24:25], v[16:17], v[48:49], v[24:25]
	v_fma_f32 v16, -v107, v62, v18
	v_fma_f32 v17, -v107, v63, v19
	v_fma_f32 v16, v108, v16, v58
	v_fmac_f32_e32 v59, v108, v17
	v_mul_f32_e32 v16, 0xbfb8aa3b, v16
	v_mul_f32_e32 v17, 0xbfb8aa3b, v59
	v_exp_f32_e32 v16, v16
	v_exp_f32_e32 v17, v17
	v_and_b32_e32 v29, 0xffff0000, v51
	v_pk_add_f32 v[28:29], v[28:29], v[106:107] op_sel:[0,1] neg_lo:[0,1] neg_hi:[0,1]
	v_add_f32_e32 v16, 1.0, v16
	v_add_f32_e32 v17, 1.0, v17
	v_rcp_f32_e32 v16, v16
	v_rcp_f32_e32 v17, v17
	v_pk_mul_f32 v[28:29], v[28:29], v[108:109] op_sel_hi:[1,0]
	v_lshlrev_b32_e32 v18, 16, v55
	v_and_b32_e32 v19, 0xffff0000, v55
	v_pk_fma_f32 v[26:27], v[28:29], v[26:27], v[30:31]
	s_nop 0
	v_pk_fma_f32 v[26:27], v[16:17], v[18:19], v[26:27]
	v_cvt_pk_bf16_f32 v16, v20, v21
	v_lshlrev_b64 v[20:21], 11, v[104:105]
	v_lshl_add_u64 v[20:21], s[52:53], 0, v[20:21]
	v_cvt_pk_bf16_f32 v17, v22, v23
	v_cvt_pk_bf16_f32 v18, v24, v25
	v_cvt_pk_bf16_f32 v19, v26, v27
	v_lshl_add_u64 v[20:21], v[20:21], 0, v[166:167]
	global_store_dwordx4 v[20:21], v[16:19], off offset:256
	global_load_dwordx4 v[16:19], v[214:215], off offset:16
	s_nop 0
	global_load_dwordx4 v[48:51], v[214:215], off
	global_load_dwordx4 v[20:23], v[216:217], off offset:16
	global_load_dwordx4 v[52:55], v[216:217], off
	global_load_dwordx4 v[24:27], v[218:219], off offset:16
	global_load_dwordx4 v[56:59], v[218:219], off
	global_load_dwordx4 v[28:31], v[220:221], off offset:16
	global_load_dwordx4 v[60:63], v[220:221], off
	s_waitcnt vmcnt(3)
	v_fma_f32 v8, -v99, v24, v8
	v_fma_f32 v9, -v99, v25, v9
	s_waitcnt vmcnt(1)
	v_fma_f32 v8, v100, v8, v28
	v_fma_f32 v9, v100, v9, v29
	v_mul_f32_e32 v8, 0xbfb8aa3b, v8
	v_mul_f32_e32 v9, 0xbfb8aa3b, v9
	v_exp_f32_e32 v8, v8
	v_exp_f32_e32 v9, v9
	v_lshlrev_b32_e32 v28, 16, v42
	v_and_b32_e32 v29, 0xffff0000, v42
	v_add_f32_e32 v8, 1.0, v8
	v_add_f32_e32 v9, 1.0, v9
	v_rcp_f32_e32 v8, v8
	v_rcp_f32_e32 v9, v9
	v_pk_add_f32 v[28:29], v[28:29], v[98:99] op_sel:[0,1] neg_lo:[0,1] neg_hi:[0,1]
	v_lshlrev_b32_e32 v24, 16, v46
	v_pk_mul_f32 v[28:29], v[28:29], v[100:101] op_sel_hi:[1,0]
	v_and_b32_e32 v25, 0xffff0000, v46
	v_pk_fma_f32 v[16:17], v[28:29], v[16:17], v[20:21]
	v_fma_f32 v12, -v99, v56, v12
	v_fma_f32 v13, -v99, v57, v13
	v_fma_f32 v14, -v99, v58, v14
	v_fma_f32 v15, -v99, v59, v15
	v_pk_fma_f32 v[16:17], v[8:9], v[24:25], v[16:17]
	v_fma_f32 v8, -v99, v26, v10
	v_fma_f32 v9, -v99, v27, v11
	s_waitcnt vmcnt(0)
	v_fma_f32 v12, v100, v12, v60
	v_fma_f32 v13, v100, v13, v61
	v_fma_f32 v14, v100, v14, v62
	v_fmac_f32_e32 v63, v100, v15
	v_fma_f32 v8, v100, v8, v30
	v_fmac_f32_e32 v31, v100, v9
	v_mul_f32_e32 v12, 0xbfb8aa3b, v12
	v_mul_f32_e32 v13, 0xbfb8aa3b, v13
	v_mul_f32_e32 v14, 0xbfb8aa3b, v14
	v_mul_f32_e32 v15, 0xbfb8aa3b, v63
	v_mul_f32_e32 v8, 0xbfb8aa3b, v8
	v_mul_f32_e32 v9, 0xbfb8aa3b, v31
	v_exp_f32_e32 v12, v12
	v_exp_f32_e32 v13, v13
	v_exp_f32_e32 v14, v14
	v_exp_f32_e32 v15, v15
	v_exp_f32_e32 v8, v8
	v_exp_f32_e32 v9, v9
	v_add_f32_e32 v12, 1.0, v12
	v_add_f32_e32 v13, 1.0, v13
	v_add_f32_e32 v14, 1.0, v14
	v_add_f32_e32 v15, 1.0, v15
	v_add_f32_e32 v8, 1.0, v8
	v_add_f32_e32 v9, 1.0, v9
	v_rcp_f32_e32 v12, v12
	v_rcp_f32_e32 v13, v13
	v_lshlrev_b32_e32 v60, 16, v40
	v_and_b32_e32 v61, 0xffff0000, v40
	v_rcp_f32_e32 v14, v14
	v_rcp_f32_e32 v15, v15
	v_lshlrev_b32_e32 v40, 16, v41
	v_and_b32_e32 v41, 0xffff0000, v41
	v_rcp_f32_e32 v8, v8
	v_rcp_f32_e32 v9, v9
	v_lshlrev_b32_e32 v20, 16, v43
	v_and_b32_e32 v21, 0xffff0000, v43
	v_pk_add_f32 v[60:61], v[60:61], v[98:99] op_sel:[0,1] neg_lo:[0,1] neg_hi:[0,1]
	v_pk_add_f32 v[40:41], v[40:41], v[98:99] op_sel:[0,1] neg_lo:[0,1] neg_hi:[0,1]
	v_pk_add_f32 v[20:21], v[20:21], v[98:99] op_sel:[0,1] neg_lo:[0,1] neg_hi:[0,1]
	v_pk_mul_f32 v[60:61], v[60:61], v[100:101] op_sel_hi:[1,0]
	v_pk_mul_f32 v[40:41], v[40:41], v[100:101] op_sel_hi:[1,0]
	v_pk_mul_f32 v[20:21], v[20:21], v[100:101] op_sel_hi:[1,0]
	v_lshlrev_b32_e32 v56, 16, v44
	v_and_b32_e32 v57, 0xffff0000, v44
	v_pk_fma_f32 v[48:49], v[60:61], v[48:49], v[52:53]
	v_lshlrev_b32_e32 v44, 16, v45
	v_and_b32_e32 v45, 0xffff0000, v45
	v_pk_fma_f32 v[40:41], v[40:41], v[50:51], v[54:55]
	v_lshlrev_b32_e32 v10, 16, v47
	v_and_b32_e32 v11, 0xffff0000, v47
	v_pk_fma_f32 v[18:19], v[20:21], v[18:19], v[22:23]
	v_pk_fma_f32 v[12:13], v[12:13], v[56:57], v[48:49]
	v_pk_fma_f32 v[14:15], v[14:15], v[44:45], v[40:41]
	v_pk_fma_f32 v[18:19], v[8:9], v[10:11], v[18:19]
	v_cvt_pk_bf16_f32 v8, v12, v13
	v_cvt_pk_bf16_f32 v9, v14, v15
	v_cvt_pk_bf16_f32 v10, v16, v17
	v_cvt_pk_bf16_f32 v11, v18, v19
	v_lshl_add_u64 v[12:13], s[52:53], 0, v[102:103]
	global_store_dwordx4 v[12:13], v[8:11], off
	global_load_dwordx4 v[8:11], v[214:215], off offset:528
	s_nop 0
	global_load_dwordx4 v[20:23], v[214:215], off offset:512
	global_load_dwordx4 v[12:15], v[216:217], off offset:528
	global_load_dwordx4 v[24:27], v[216:217], off offset:512
	global_load_dwordx4 v[28:31], v[160:161], off
	global_load_dwordx4 v[16:19], v[162:163], off offset:16
	global_load_dwordx4 v[40:43], v[162:163], off
	s_waitcnt vmcnt(2)
; #define PG8_BAR __builtin_amdgcn_s_barrier()
; template <class Epi, class Sched, bool ALIGN_EPI = false, bool SP2 = false>
; __device__ __forceinline__ void gemm_phase(PG8_LAS unsigned char* lds, const Gemm g, const Sched& S, const Epi& E) {
;     ...
;         if constexpr (ALIGN_EPI) { if (wr == 0) PG8_BAR; }
;         if constexpr (!Epi::AFTER_DRAIN) { E(acc, cur, wr, wc, fr, fq); S.done(cur); }
;         if (!has_next) break;
; #pragma unroll
;         for (int a = 0; a < 2; ++a)
; #pragma unroll
;             for (int b = 0; b < 2; ++b)
; #pragma unroll
;                 for (int m = 0; m < 4; ++m)
; #pragma unroll
;                     for (int n = 0; n < 2; ++n) acc[a][b][m][n] = (f32x4){0.f, 0.f, 0.f, 0.f};
;         cur = nxt; cA = nA; cB = nB; ++ui;
;         if constexpr (ALIGN_EPI) { if (wr == 1) PG8_BAR; }
	v_fma_f32 v4, -v99, v28, v4
	v_fma_f32 v5, -v99, v29, v5
	s_waitcnt vmcnt(0)
	v_fma_f32 v4, v100, v4, v40
	v_fma_f32 v5, v100, v5, v41
	v_fma_f32 v6, -v99, v30, v6
	v_fma_f32 v7, -v99, v31, v7
	v_mul_f32_e32 v4, 0xbfb8aa3b, v4
	v_mul_f32_e32 v5, 0xbfb8aa3b, v5
	v_fma_f32 v6, v100, v6, v42
	v_fmac_f32_e32 v43, v100, v7
	v_exp_f32_e32 v4, v4
	v_exp_f32_e32 v5, v5
	v_mul_f32_e32 v6, 0xbfb8aa3b, v6
	v_mul_f32_e32 v7, 0xbfb8aa3b, v43
	v_exp_f32_e32 v6, v6
	v_exp_f32_e32 v7, v7
	v_lshlrev_b32_e32 v40, 16, v32
	v_and_b32_e32 v41, 0xffff0000, v32
	v_add_f32_e32 v4, 1.0, v4
	v_add_f32_e32 v5, 1.0, v5
	v_pk_add_f32 v[40:41], v[40:41], v[98:99] op_sel:[0,1] neg_lo:[0,1] neg_hi:[0,1]
	v_rcp_f32_e32 v4, v4
	v_rcp_f32_e32 v5, v5
	v_pk_mul_f32 v[40:41], v[40:41], v[100:101] op_sel_hi:[1,0]
	v_add_f32_e32 v6, 1.0, v6
	v_add_f32_e32 v7, 1.0, v7
	v_pk_fma_f32 v[20:21], v[40:41], v[20:21], v[24:25]
	v_rcp_f32_e32 v6, v6
	v_rcp_f32_e32 v7, v7
	v_lshlrev_b32_e32 v24, 16, v33
	v_and_b32_e32 v25, 0xffff0000, v33
	v_pk_add_f32 v[24:25], v[24:25], v[98:99] op_sel:[0,1] neg_lo:[0,1] neg_hi:[0,1]
	v_lshlrev_b32_e32 v28, 16, v36
	v_and_b32_e32 v29, 0xffff0000, v36
	v_pk_mul_f32 v[24:25], v[24:25], v[100:101] op_sel_hi:[1,0]
	v_pk_fma_f32 v[4:5], v[4:5], v[28:29], v[20:21]
	v_lshlrev_b32_e32 v20, 16, v37
	v_and_b32_e32 v21, 0xffff0000, v37
	v_pk_fma_f32 v[22:23], v[24:25], v[22:23], v[26:27]
	s_nop 0
	v_pk_fma_f32 v[6:7], v[6:7], v[20:21], v[22:23]
	global_load_dwordx4 v[20:23], v[164:165], off
	s_waitcnt vmcnt(0)
	v_fma_f32 v0, -v99, v20, v0
	v_fma_f32 v1, -v99, v21, v1
	v_fma_f32 v0, v100, v0, v16
	v_fma_f32 v1, v100, v1, v17
	v_mul_f32_e32 v0, 0xbfb8aa3b, v0
	v_mul_f32_e32 v1, 0xbfb8aa3b, v1
	v_exp_f32_e32 v0, v0
	v_exp_f32_e32 v1, v1
	v_lshlrev_b32_e32 v20, 16, v34
	v_and_b32_e32 v21, 0xffff0000, v34
	v_add_f32_e32 v0, 1.0, v0
	v_add_f32_e32 v1, 1.0, v1
	v_rcp_f32_e32 v0, v0
	v_rcp_f32_e32 v1, v1
	v_pk_add_f32 v[20:21], v[20:21], v[98:99] op_sel:[0,1] neg_lo:[0,1] neg_hi:[0,1]
	v_lshlrev_b32_e32 v16, 16, v38
	v_pk_mul_f32 v[20:21], v[20:21], v[100:101] op_sel_hi:[1,0]
	v_and_b32_e32 v17, 0xffff0000, v38
	v_pk_fma_f32 v[8:9], v[20:21], v[8:9], v[12:13]
	v_lshlrev_b32_e32 v12, 16, v35
	v_pk_fma_f32 v[8:9], v[0:1], v[16:17], v[8:9]
	v_fma_f32 v0, -v99, v22, v2
	v_fma_f32 v1, -v99, v23, v3
	v_fma_f32 v0, v100, v0, v18
	v_fmac_f32_e32 v19, v100, v1
	v_mul_f32_e32 v0, 0xbfb8aa3b, v0
	v_mul_f32_e32 v1, 0xbfb8aa3b, v19
	v_exp_f32_e32 v0, v0
	v_exp_f32_e32 v1, v1
	v_and_b32_e32 v13, 0xffff0000, v35
	v_pk_add_f32 v[12:13], v[12:13], v[98:99] op_sel:[0,1] neg_lo:[0,1] neg_hi:[0,1]
	v_add_f32_e32 v0, 1.0, v0
	v_add_f32_e32 v1, 1.0, v1
	v_rcp_f32_e32 v0, v0
	v_rcp_f32_e32 v1, v1
	v_pk_mul_f32 v[12:13], v[12:13], v[100:101] op_sel_hi:[1,0]
	v_lshlrev_b32_e32 v2, 16, v39
	v_and_b32_e32 v3, 0xffff0000, v39
	v_pk_fma_f32 v[10:11], v[12:13], v[10:11], v[14:15]
	s_nop 0
	v_pk_fma_f32 v[10:11], v[0:1], v[2:3], v[10:11]
	v_cvt_pk_bf16_f32 v0, v4, v5
	v_lshlrev_b64 v[4:5], 11, v[96:97]
	v_lshl_add_u64 v[4:5], s[52:53], 0, v[4:5]
	v_cvt_pk_bf16_f32 v1, v6, v7
	v_cvt_pk_bf16_f32 v2, v8, v9
	v_cvt_pk_bf16_f32 v3, v10, v11
	v_lshl_add_u64 v[4:5], v[4:5], 0, v[166:167]
	global_store_dwordx4 v[4:5], v[0:3], off offset:256
	s_cbranch_vccnz .LBB0_1841
	s_andn2_b64 vcc, exec, s[14:15]
	s_cbranch_vccnz .LBB0_1840
	s_barrier
	s_branch .LBB0_1840

; DI void row_stats(const f32x2v* st, size_t row, int fq, float& mu, float& rstd) {
;     const f32x4 a = *(const f32x4*)(st + row * 16 + 4 * fq), b = *(const f32x4*)(st + row * 16 + 4 * fq + 2);
;     float s1 = (a[0] + a[2]) + (b[0] + b[2]), s2 = (a[1] + a[3]) + (b[1] + b[3]);
;     s1 += __shfl_xor(s1, 16); s1 += __shfl_xor(s1, 32); s2 += __shfl_xor(s2, 16); s2 += __shfl_xor(s2, 32);
;     mu = s1 * (1.0f / 1024.0f); const float var = fmaxf(s2 * (1.0f / 1024.0f) - mu * mu, 0.f); rstd = rsqrtf(var + LN_EPS);
; }
.LBB0_2356:
	v_and_b32_e32 v161, 64, v209
	v_xor_b32_e32 v160, 16, v209
	v_add_u32_e32 v161, 64, v161
	v_cmp_lt_i32_e32 vcc, v160, v161
	s_ashr_i32 s31, s30, 31
	s_lshl_b64 s[30:31], s[30:31], 8
	v_cndmask_b32_e32 v160, v209, v160, vcc
	v_lshl_or_b32 v76, s91, 8, v193
	v_lshlrev_b32_e32 v217, 2, v160
	v_xor_b32_e32 v160, 32, v209
	v_lshl_add_u64 v[204:205], s[30:31], 0, v[176:177]
	v_ashrrev_i32_e32 v77, 31, v76
	v_cmp_lt_i32_e32 vcc, v160, v161
	v_lshlrev_b64 v[76:77], 2, v[76:77]
	v_lshlrev_b64 v[162:163], 7, v[204:205]
	v_cndmask_b32_e32 v160, v209, v160, vcc
	v_lshl_add_u64 v[80:81], s[16:17], 0, v[76:77]
	v_lshl_add_u64 v[104:105], s[18:19], 0, v[76:77]
	v_lshlrev_b32_e32 v213, 2, v160
	v_lshl_add_u64 v[160:161], v[178:179], 0, v[162:163]
	global_load_dwordx4 v[88:91], v[80:81], off offset:16
	global_load_dwordx4 v[112:115], v[80:81], off
	global_load_dwordx4 v[92:95], v[104:105], off offset:16
	global_load_dwordx4 v[116:119], v[104:105], off
	global_load_dwordx4 v[76:79], v[80:81], off offset:528
	global_load_dwordx4 v[100:103], v[80:81], off offset:512
	s_nop 0
	global_load_dwordx4 v[80:83], v[104:105], off offset:528
	s_nop 0
	global_load_dwordx4 v[104:107], v[104:105], off offset:512
	s_nop 0
	global_load_dwordx4 v[164:167], v[160:161], off offset:16
	global_load_dwordx4 v[218:221], v[160:161], off
	s_mov_b64 s[30:31], 0x4000
	s_waitcnt vmcnt(0)
	v_mov_b32_e32 v187, v164
	v_mov_b32_e32 v186, v218
	v_mov_b32_e32 v190, v220
	v_mov_b32_e32 v191, v166
	v_pk_add_f32 v[186:187], v[186:187], v[190:191]
	v_add_f32_e32 v164, v219, v221
	v_add_f32_e32 v166, v165, v167
	v_mov_b32_e32 v165, v186
	v_mov_b32_e32 v167, v187
	v_pk_add_f32 v[164:165], v[164:165], v[166:167]
	s_waitcnt lgkmcnt(0)
	v_mov_b32_e32 v167, v165
	v_mov_b32_e32 v166, v164
	s_nop 1
	v_permlane16_swap_b32_e32 v167, v165
	v_permlane16_swap_b32_e32 v166, v164
	s_nop 0
	v_pk_add_f32 v[164:165], v[164:165], v[166:167]
	s_waitcnt lgkmcnt(0)
	v_mov_b32_e32 v167, v165
	v_mov_b32_e32 v166, v164
	s_nop 1
	v_permlane32_swap_b32_e32 v167, v165
	v_permlane32_swap_b32_e32 v166, v164
	s_nop 0
	v_pk_add_f32 v[164:165], v[164:165], v[166:167]
	s_nop 0
	v_pk_mul_f32 v[214:215], v[164:165], s[26:27] op_sel_hi:[1,0]
	s_nop 0
	v_fma_f32 v164, -v215, v215, v214
	v_max_f32_e32 v164, 0, v164
	v_add_f32_e32 v164, 0x3727c5ac, v164
	v_cmp_gt_f32_e32 vcc, s87, v164
	v_mul_f32_e32 v165, 0x4b800000, v164
	v_pk_fma_f32 v[156:157], v[112:113], v[214:215], v[156:157] op_sel:[0,1,0] neg_lo:[1,0,0] neg_hi:[1,0,0]
	v_cndmask_b32_e32 v164, v164, v165, vcc
	v_rsq_f32_e32 v164, v164
	v_pk_fma_f32 v[152:153], v[100:101], v[214:215], v[152:153] op_sel:[0,1,0] neg_lo:[1,0,0] neg_hi:[1,0,0]
	v_pk_fma_f32 v[154:155], v[102:103], v[214:215], v[154:155] op_sel:[0,1,0] neg_lo:[1,0,0] neg_hi:[1,0,0]
	v_pk_fma_f32 v[148:149], v[88:89], v[214:215], v[148:149] op_sel:[0,1,0] neg_lo:[1,0,0] neg_hi:[1,0,0]
	v_mul_f32_e32 v165, 0x45800000, v164
	v_cndmask_b32_e32 v216, v164, v165, vcc
	v_or_b32_e32 v164, 0x800, v162
	v_mov_b32_e32 v165, v163
	v_lshl_add_u64 v[186:187], v[178:179], 0, v[164:165]
	global_load_dwordx4 v[164:167], v[186:187], off offset:16
	global_load_dwordx4 v[218:221], v[186:187], off
	v_pk_fma_f32 v[156:157], v[156:157], v[216:217], v[116:117] op_sel_hi:[1,0,1]
	v_pk_fma_f32 v[152:153], v[152:153], v[216:217], v[104:105] op_sel_hi:[1,0,1]
	v_pk_fma_f32 v[154:155], v[154:155], v[216:217], v[106:107] op_sel_hi:[1,0,1]
	v_pk_fma_f32 v[148:149], v[148:149], v[216:217], v[92:93] op_sel_hi:[1,0,1]
	v_pk_fma_f32 v[144:145], v[76:77], v[214:215], v[144:145] op_sel:[0,1,0] neg_lo:[1,0,0] neg_hi:[1,0,0]
	v_pk_fma_f32 v[146:147], v[78:79], v[214:215], v[146:147] op_sel:[0,1,0] neg_lo:[1,0,0] neg_hi:[1,0,0]
	v_pk_fma_f32 v[144:145], v[144:145], v[216:217], v[80:81] op_sel_hi:[1,0,1]
	v_pk_fma_f32 v[146:147], v[146:147], v[216:217], v[82:83] op_sel_hi:[1,0,1]
	s_waitcnt vmcnt(1)
	v_mov_b32_e32 v187, v164
	s_waitcnt vmcnt(0)
	v_mov_b32_e32 v186, v218
	v_mov_b32_e32 v190, v220
	v_mov_b32_e32 v191, v166
	v_pk_add_f32 v[186:187], v[186:187], v[190:191]
	v_add_f32_e32 v164, v219, v221
	v_add_f32_e32 v166, v165, v167
	v_mov_b32_e32 v165, v186
	v_mov_b32_e32 v167, v187
	v_pk_add_f32 v[164:165], v[164:165], v[166:167]
	s_waitcnt lgkmcnt(0)
	v_mov_b32_e32 v167, v165
	v_mov_b32_e32 v166, v164
	s_nop 1
	v_permlane16_swap_b32_e32 v167, v165
	v_permlane16_swap_b32_e32 v166, v164
	s_nop 0
	v_pk_add_f32 v[164:165], v[164:165], v[166:167]
	s_waitcnt lgkmcnt(0)
	v_mov_b32_e32 v167, v165
	v_mov_b32_e32 v166, v164
	s_nop 1
	v_permlane32_swap_b32_e32 v167, v165
	v_permlane32_swap_b32_e32 v166, v164
	s_nop 0
	v_pk_add_f32 v[164:165], v[164:165], v[166:167]
	s_nop 0
	v_pk_mul_f32 v[210:211], v[164:165], s[26:27] op_sel_hi:[1,0]
	s_nop 0
	v_fma_f32 v164, -v211, v211, v210
	v_max_f32_e32 v164, 0, v164
	v_add_f32_e32 v164, 0x3727c5ac, v164
	v_cmp_gt_f32_e32 vcc, s87, v164
	v_mul_f32_e32 v165, 0x4b800000, v164
	v_pk_fma_f32 v[140:141], v[112:113], v[210:211], v[140:141] op_sel:[0,1,0] neg_lo:[1,0,0] neg_hi:[1,0,0]
	v_cndmask_b32_e32 v164, v164, v165, vcc
	v_rsq_f32_e32 v164, v164
	v_pk_fma_f32 v[136:137], v[100:101], v[210:211], v[136:137] op_sel:[0,1,0] neg_lo:[1,0,0] neg_hi:[1,0,0]
	v_pk_fma_f32 v[138:139], v[102:103], v[210:211], v[138:139] op_sel:[0,1,0] neg_lo:[1,0,0] neg_hi:[1,0,0]
	v_pk_fma_f32 v[132:133], v[88:89], v[210:211], v[132:133] op_sel:[0,1,0] neg_lo:[1,0,0] neg_hi:[1,0,0]
	v_mul_f32_e32 v165, 0x45800000, v164
	v_cndmask_b32_e32 v212, v164, v165, vcc
	v_or_b32_e32 v164, 0x1000, v162
	v_mov_b32_e32 v165, v163
	v_lshl_add_u64 v[186:187], v[178:179], 0, v[164:165]
	global_load_dwordx4 v[164:167], v[186:187], off offset:16
	global_load_dwordx4 v[218:221], v[186:187], off
	v_or_b32_e32 v162, 0x1800, v162
	v_pk_fma_f32 v[140:141], v[140:141], v[212:213], v[116:117] op_sel_hi:[1,0,1]
	v_pk_fma_f32 v[136:137], v[136:137], v[212:213], v[104:105] op_sel_hi:[1,0,1]
	v_pk_fma_f32 v[138:139], v[138:139], v[212:213], v[106:107] op_sel_hi:[1,0,1]
	v_pk_fma_f32 v[132:133], v[132:133], v[212:213], v[92:93] op_sel_hi:[1,0,1]
	v_pk_fma_f32 v[128:129], v[76:77], v[210:211], v[128:129] op_sel:[0,1,0] neg_lo:[1,0,0] neg_hi:[1,0,0]
	v_pk_fma_f32 v[130:131], v[78:79], v[210:211], v[130:131] op_sel:[0,1,0] neg_lo:[1,0,0] neg_hi:[1,0,0]
	v_pk_fma_f32 v[128:129], v[128:129], v[212:213], v[80:81] op_sel_hi:[1,0,1]
	v_pk_fma_f32 v[130:131], v[130:131], v[212:213], v[82:83] op_sel_hi:[1,0,1]
	s_waitcnt vmcnt(1)
; DI void row_stats(const f32x2v* st, size_t row, int fq, float& mu, float& rstd) {
;     const f32x4 a = *(const f32x4*)(st + row * 16 + 4 * fq), b = *(const f32x4*)(st + row * 16 + 4 * fq + 2);
;     float s1 = (a[0] + a[2]) + (b[0] + b[2]), s2 = (a[1] + a[3]) + (b[1] + b[3]);
;     s1 += __shfl_xor(s1, 16); s1 += __shfl_xor(s1, 32); s2 += __shfl_xor(s2, 16); s2 += __shfl_xor(s2, 32);
;     mu = s1 * (1.0f / 1024.0f); const float var = fmaxf(s2 * (1.0f / 1024.0f) - mu * mu, 0.f); rstd = rsqrtf(var + LN_EPS);
; }
	v_mov_b32_e32 v187, v164
	s_waitcnt vmcnt(0)
	v_mov_b32_e32 v186, v218
	v_mov_b32_e32 v190, v220
	v_mov_b32_e32 v191, v166
	v_pk_add_f32 v[186:187], v[186:187], v[190:191]
	v_add_f32_e32 v164, v219, v221
	v_add_f32_e32 v166, v165, v167
	v_mov_b32_e32 v165, v186
	v_mov_b32_e32 v167, v187
	v_pk_add_f32 v[164:165], v[164:165], v[166:167]
	v_lshl_add_u64 v[190:191], v[160:161], 0, s[30:31]
	s_movk_i32 s30, 0x4000
	s_waitcnt lgkmcnt(0)
	v_mov_b32_e32 v167, v165
	v_mov_b32_e32 v166, v164
	s_nop 1
	v_permlane16_swap_b32_e32 v167, v165
	v_permlane16_swap_b32_e32 v166, v164
	s_nop 0
	v_pk_add_f32 v[164:165], v[164:165], v[166:167]
	s_waitcnt lgkmcnt(0)
	v_mov_b32_e32 v167, v165
	v_mov_b32_e32 v166, v164
	s_nop 1
	v_permlane32_swap_b32_e32 v167, v165
	v_permlane32_swap_b32_e32 v166, v164
	s_nop 0
	v_pk_add_f32 v[164:165], v[164:165], v[166:167]
	s_nop 0
	v_pk_mul_f32 v[200:201], v[164:165], s[26:27] op_sel_hi:[1,0]
	v_lshl_add_u64 v[166:167], v[178:179], 0, v[162:163]
	v_fma_f32 v164, -v201, v201, v200
	v_max_f32_e32 v164, 0, v164
	v_add_f32_e32 v164, 0x3727c5ac, v164
	v_cmp_gt_f32_e32 vcc, s87, v164
	v_mul_f32_e32 v165, 0x4b800000, v164
	v_pk_fma_f32 v[124:125], v[112:113], v[200:201], v[124:125] op_sel:[0,1,0] neg_lo:[1,0,0] neg_hi:[1,0,0]
	v_cndmask_b32_e32 v164, v164, v165, vcc
	v_rsq_f32_e32 v164, v164
	v_pk_fma_f32 v[120:121], v[100:101], v[200:201], v[120:121] op_sel:[0,1,0] neg_lo:[1,0,0] neg_hi:[1,0,0]
	v_pk_fma_f32 v[122:123], v[102:103], v[200:201], v[122:123] op_sel:[0,1,0] neg_lo:[1,0,0] neg_hi:[1,0,0]
	v_pk_fma_f32 v[108:109], v[88:89], v[200:201], v[108:109] op_sel:[0,1,0] neg_lo:[1,0,0] neg_hi:[1,0,0]
	v_mul_f32_e32 v165, 0x45800000, v164
	v_cndmask_b32_e32 v202, v164, v165, vcc
	global_load_dwordx4 v[162:165], v[166:167], off offset:16
	global_load_dwordx4 v[218:221], v[166:167], off
	v_pk_fma_f32 v[124:125], v[124:125], v[202:203], v[116:117] op_sel_hi:[1,0,1]
	v_pk_fma_f32 v[120:121], v[120:121], v[202:203], v[104:105] op_sel_hi:[1,0,1]
	v_pk_fma_f32 v[122:123], v[122:123], v[202:203], v[106:107] op_sel_hi:[1,0,1]
	v_pk_fma_f32 v[108:109], v[108:109], v[202:203], v[92:93] op_sel_hi:[1,0,1]
	v_pk_fma_f32 v[96:97], v[76:77], v[200:201], v[96:97] op_sel:[0,1,0] neg_lo:[1,0,0] neg_hi:[1,0,0]
	v_pk_fma_f32 v[98:99], v[78:79], v[200:201], v[98:99] op_sel:[0,1,0] neg_lo:[1,0,0] neg_hi:[1,0,0]
	v_pk_fma_f32 v[96:97], v[96:97], v[202:203], v[80:81] op_sel_hi:[1,0,1]
	v_pk_fma_f32 v[98:99], v[98:99], v[202:203], v[82:83] op_sel_hi:[1,0,1]
	s_waitcnt vmcnt(1)
	v_mov_b32_e32 v167, v162
	s_waitcnt vmcnt(0)
	v_mov_b32_e32 v166, v218
	v_mov_b32_e32 v186, v220
	v_mov_b32_e32 v187, v164
	v_pk_add_f32 v[166:167], v[166:167], v[186:187]
	v_add_f32_e32 v162, v219, v221
	v_add_f32_e32 v164, v163, v165
	v_mov_b32_e32 v163, v166
	v_mov_b32_e32 v165, v167
	v_pk_add_f32 v[162:163], v[162:163], v[164:165]
	s_waitcnt lgkmcnt(0)
	v_mov_b32_e32 v165, v163
	v_mov_b32_e32 v164, v162
	s_nop 1
	v_permlane16_swap_b32_e32 v165, v163
	v_permlane16_swap_b32_e32 v164, v162
	s_nop 0
	v_pk_add_f32 v[162:163], v[162:163], v[164:165]
	s_waitcnt lgkmcnt(0)
	v_mov_b32_e32 v165, v163
	v_mov_b32_e32 v164, v162
	s_nop 1
	v_permlane32_swap_b32_e32 v165, v163
	v_permlane32_swap_b32_e32 v164, v162
	s_nop 0
	v_pk_add_f32 v[162:163], v[162:163], v[164:165]
	s_nop 0
	v_pk_mul_f32 v[186:187], v[162:163], s[26:27] op_sel_hi:[1,0]
	s_nop 0
	v_fma_f32 v162, -v187, v187, v186
	v_max_f32_e32 v162, 0, v162
	v_add_f32_e32 v162, 0x3727c5ac, v162
	v_cmp_gt_f32_e32 vcc, s87, v162
	v_mul_f32_e32 v163, 0x4b800000, v162
	v_pk_fma_f32 v[84:85], v[112:113], v[186:187], v[84:85] op_sel:[0,1,0] neg_lo:[1,0,0] neg_hi:[1,0,0]
	v_cndmask_b32_e32 v162, v162, v163, vcc
	v_rsq_f32_e32 v162, v162
	v_pk_fma_f32 v[72:73], v[100:101], v[186:187], v[72:73] op_sel:[0,1,0] neg_lo:[1,0,0] neg_hi:[1,0,0]
	v_pk_fma_f32 v[74:75], v[102:103], v[186:187], v[74:75] op_sel:[0,1,0] neg_lo:[1,0,0] neg_hi:[1,0,0]
	v_pk_fma_f32 v[68:69], v[88:89], v[186:187], v[68:69] op_sel:[0,1,0] neg_lo:[1,0,0] neg_hi:[1,0,0]
	v_mul_f32_e32 v163, 0x45800000, v162
	v_cndmask_b32_e32 v188, v162, v163, vcc
	v_add_co_u32_e32 v206, vcc, s30, v160
	s_movk_i32 s30, 0x5000
	s_nop 0
	v_addc_co_u32_e32 v207, vcc, 0, v161, vcc
	v_add_co_u32_e32 v162, vcc, s30, v160
	s_mov_b64 s[30:31], 0x4800
	s_nop 0
	v_addc_co_u32_e32 v163, vcc, 0, v161, vcc
	global_load_dwordx4 v[164:167], v[162:163], off offset:-4096
	global_load_dwordx4 v[218:221], v[190:191], off offset:16
	v_pk_fma_f32 v[84:85], v[84:85], v[188:189], v[116:117] op_sel_hi:[1,0,1]
	v_pk_fma_f32 v[72:73], v[72:73], v[188:189], v[104:105] op_sel_hi:[1,0,1]
	v_pk_fma_f32 v[74:75], v[74:75], v[188:189], v[106:107] op_sel_hi:[1,0,1]
	v_pk_fma_f32 v[68:69], v[68:69], v[188:189], v[92:93] op_sel_hi:[1,0,1]
	v_pk_fma_f32 v[64:65], v[76:77], v[186:187], v[64:65] op_sel:[0,1,0] neg_lo:[1,0,0] neg_hi:[1,0,0]
	v_pk_fma_f32 v[66:67], v[78:79], v[186:187], v[66:67] op_sel:[0,1,0] neg_lo:[1,0,0] neg_hi:[1,0,0]
	v_pk_fma_f32 v[64:65], v[64:65], v[188:189], v[80:81] op_sel_hi:[1,0,1]
	v_pk_fma_f32 v[66:67], v[66:67], v[188:189], v[82:83] op_sel_hi:[1,0,1]
	s_waitcnt vmcnt(1)
	v_mov_b32_e32 v190, v164
	s_waitcnt vmcnt(0)
	v_mov_b32_e32 v191, v218
	v_mov_b32_e32 v196, v166
	v_mov_b32_e32 v197, v220
	v_pk_add_f32 v[190:191], v[190:191], v[196:197]
	v_add_f32_e32 v164, v165, v167
	v_add_f32_e32 v166, v219, v221
	v_mov_b32_e32 v165, v190
	v_mov_b32_e32 v167, v191
	v_pk_add_f32 v[164:165], v[164:165], v[166:167]
	v_lshl_add_u64 v[190:191], v[160:161], 0, s[30:31]
	s_mov_b64 s[30:31], 0x5000
	s_waitcnt lgkmcnt(0)
; DI void row_stats(const f32x2v* st, size_t row, int fq, float& mu, float& rstd) {
;     const f32x4 a = *(const f32x4*)(st + row * 16 + 4 * fq), b = *(const f32x4*)(st + row * 16 + 4 * fq + 2);
;     float s1 = (a[0] + a[2]) + (b[0] + b[2]), s2 = (a[1] + a[3]) + (b[1] + b[3]);
;     s1 += __shfl_xor(s1, 16); s1 += __shfl_xor(s1, 32); s2 += __shfl_xor(s2, 16); s2 += __shfl_xor(s2, 32);
;     mu = s1 * (1.0f / 1024.0f); const float var = fmaxf(s2 * (1.0f / 1024.0f) - mu * mu, 0.f); rstd = rsqrtf(var + LN_EPS);
; }
	v_mov_b32_e32 v167, v165
	v_mov_b32_e32 v166, v164
	s_nop 1
	v_permlane16_swap_b32_e32 v167, v165
	v_permlane16_swap_b32_e32 v166, v164
	s_nop 0
	v_pk_add_f32 v[164:165], v[164:165], v[166:167]
	s_waitcnt lgkmcnt(0)
	v_mov_b32_e32 v167, v165
	v_mov_b32_e32 v166, v164
	s_nop 1
	v_permlane32_swap_b32_e32 v167, v165
	v_permlane32_swap_b32_e32 v166, v164
	s_nop 0
	v_pk_add_f32 v[164:165], v[164:165], v[166:167]
	s_nop 0
	v_pk_mul_f32 v[196:197], v[164:165], s[26:27] op_sel_hi:[1,0]
	s_nop 0
	v_fma_f32 v164, -v197, v197, v196
	v_max_f32_e32 v164, 0, v164
	v_add_f32_e32 v164, 0x3727c5ac, v164
	v_cmp_gt_f32_e32 vcc, s87, v164
	v_mul_f32_e32 v165, 0x4b800000, v164
	v_pk_fma_f32 v[60:61], v[112:113], v[196:197], v[60:61] op_sel:[0,1,0] neg_lo:[1,0,0] neg_hi:[1,0,0]
	v_cndmask_b32_e32 v164, v164, v165, vcc
	v_rsq_f32_e32 v164, v164
	v_pk_fma_f32 v[56:57], v[100:101], v[196:197], v[56:57] op_sel:[0,1,0] neg_lo:[1,0,0] neg_hi:[1,0,0]
	v_pk_fma_f32 v[58:59], v[102:103], v[196:197], v[58:59] op_sel:[0,1,0] neg_lo:[1,0,0] neg_hi:[1,0,0]
	v_pk_fma_f32 v[52:53], v[88:89], v[196:197], v[52:53] op_sel:[0,1,0] neg_lo:[1,0,0] neg_hi:[1,0,0]
	v_mul_f32_e32 v165, 0x45800000, v164
	v_cndmask_b32_e32 v198, v164, v165, vcc
	global_load_dwordx4 v[164:167], v[206:207], off offset:2048
	global_load_dwordx4 v[218:221], v[190:191], off offset:16
	v_pk_fma_f32 v[60:61], v[60:61], v[198:199], v[116:117] op_sel_hi:[1,0,1]
	v_pk_fma_f32 v[56:57], v[56:57], v[198:199], v[104:105] op_sel_hi:[1,0,1]
	v_pk_fma_f32 v[58:59], v[58:59], v[198:199], v[106:107] op_sel_hi:[1,0,1]
	v_pk_fma_f32 v[52:53], v[52:53], v[198:199], v[92:93] op_sel_hi:[1,0,1]
	v_pk_fma_f32 v[48:49], v[76:77], v[196:197], v[48:49] op_sel:[0,1,0] neg_lo:[1,0,0] neg_hi:[1,0,0]
	v_pk_fma_f32 v[50:51], v[78:79], v[196:197], v[50:51] op_sel:[0,1,0] neg_lo:[1,0,0] neg_hi:[1,0,0]
	v_pk_fma_f32 v[48:49], v[48:49], v[198:199], v[80:81] op_sel_hi:[1,0,1]
	v_pk_fma_f32 v[50:51], v[50:51], v[198:199], v[82:83] op_sel_hi:[1,0,1]
	s_waitcnt vmcnt(1)
	v_mov_b32_e32 v190, v164
	s_waitcnt vmcnt(0)
	v_mov_b32_e32 v191, v218
	v_mov_b32_e32 v206, v166
	v_mov_b32_e32 v207, v220
	v_pk_add_f32 v[190:191], v[190:191], v[206:207]
	v_add_f32_e32 v164, v165, v167
	v_add_f32_e32 v166, v219, v221
	v_mov_b32_e32 v165, v190
	v_mov_b32_e32 v167, v191
	v_pk_add_f32 v[164:165], v[164:165], v[166:167]
	v_lshl_add_u64 v[206:207], v[160:161], 0, s[30:31]
	s_mov_b64 s[30:31], 0x5800
	s_waitcnt lgkmcnt(0)
	v_mov_b32_e32 v167, v165
	v_mov_b32_e32 v166, v164
	s_nop 1
	v_permlane16_swap_b32_e32 v167, v165
	v_permlane16_swap_b32_e32 v166, v164
	s_nop 0
	v_pk_add_f32 v[164:165], v[164:165], v[166:167]
	s_waitcnt lgkmcnt(0)
	v_mov_b32_e32 v167, v165
	v_mov_b32_e32 v166, v164
	s_nop 1
	v_permlane32_swap_b32_e32 v167, v165
	v_permlane32_swap_b32_e32 v166, v164
	s_nop 0
	v_pk_add_f32 v[164:165], v[164:165], v[166:167]
	s_nop 0
	v_pk_mul_f32 v[190:191], v[164:165], s[26:27] op_sel_hi:[1,0]
	s_nop 0
	v_fma_f32 v164, -v191, v191, v190
	v_max_f32_e32 v164, 0, v164
	v_add_f32_e32 v164, 0x3727c5ac, v164
	v_cmp_gt_f32_e32 vcc, s87, v164
	v_mul_f32_e32 v165, 0x4b800000, v164
	v_pk_fma_f32 v[44:45], v[112:113], v[190:191], v[44:45] op_sel:[0,1,0] neg_lo:[1,0,0] neg_hi:[1,0,0]
	v_cndmask_b32_e32 v164, v164, v165, vcc
	v_rsq_f32_e32 v164, v164
	v_pk_fma_f32 v[40:41], v[100:101], v[190:191], v[40:41] op_sel:[0,1,0] neg_lo:[1,0,0] neg_hi:[1,0,0]
	v_pk_fma_f32 v[42:43], v[102:103], v[190:191], v[42:43] op_sel:[0,1,0] neg_lo:[1,0,0] neg_hi:[1,0,0]
	v_pk_fma_f32 v[36:37], v[88:89], v[190:191], v[36:37] op_sel:[0,1,0] neg_lo:[1,0,0] neg_hi:[1,0,0]
	v_mul_f32_e32 v165, 0x45800000, v164
	v_cndmask_b32_e32 v194, v164, v165, vcc
	global_load_dwordx4 v[164:167], v[162:163], off
	global_load_dwordx4 v[218:221], v[206:207], off offset:16
	v_pk_fma_f32 v[44:45], v[44:45], v[194:195], v[116:117] op_sel_hi:[1,0,1]
	v_pk_fma_f32 v[40:41], v[40:41], v[194:195], v[104:105] op_sel_hi:[1,0,1]
	v_pk_fma_f32 v[42:43], v[42:43], v[194:195], v[106:107] op_sel_hi:[1,0,1]
	v_pk_fma_f32 v[36:37], v[36:37], v[194:195], v[92:93] op_sel_hi:[1,0,1]
	v_pk_fma_f32 v[32:33], v[76:77], v[190:191], v[32:33] op_sel:[0,1,0] neg_lo:[1,0,0] neg_hi:[1,0,0]
	v_pk_fma_f32 v[34:35], v[78:79], v[190:191], v[34:35] op_sel:[0,1,0] neg_lo:[1,0,0] neg_hi:[1,0,0]
	v_pk_fma_f32 v[32:33], v[32:33], v[194:195], v[80:81] op_sel_hi:[1,0,1]
	v_pk_fma_f32 v[34:35], v[34:35], v[194:195], v[82:83] op_sel_hi:[1,0,1]
	s_waitcnt vmcnt(1)
	v_mov_b32_e32 v206, v164
	s_waitcnt vmcnt(0)
	v_mov_b32_e32 v207, v218
	v_mov_b32_e32 v222, v166
	v_mov_b32_e32 v223, v220
	v_pk_add_f32 v[206:207], v[206:207], v[222:223]
	v_add_f32_e32 v164, v165, v167
	v_add_f32_e32 v166, v219, v221
	v_mov_b32_e32 v165, v206
	v_mov_b32_e32 v167, v207
	v_pk_add_f32 v[164:165], v[164:165], v[166:167]
	s_waitcnt lgkmcnt(0)
	v_mov_b32_e32 v167, v165
	v_mov_b32_e32 v166, v164
	s_nop 1
	v_permlane16_swap_b32_e32 v167, v165
	v_permlane16_swap_b32_e32 v166, v164
	s_nop 0
	v_pk_add_f32 v[164:165], v[164:165], v[166:167]
	s_waitcnt lgkmcnt(0)
; DI void row_stats(const f32x2v* st, size_t row, int fq, float& mu, float& rstd) {
;     const f32x4 a = *(const f32x4*)(st + row * 16 + 4 * fq), b = *(const f32x4*)(st + row * 16 + 4 * fq + 2);
;     float s1 = (a[0] + a[2]) + (b[0] + b[2]), s2 = (a[1] + a[3]) + (b[1] + b[3]);
;     s1 += __shfl_xor(s1, 16); s1 += __shfl_xor(s1, 32); s2 += __shfl_xor(s2, 16); s2 += __shfl_xor(s2, 32);
;     mu = s1 * (1.0f / 1024.0f); const float var = fmaxf(s2 * (1.0f / 1024.0f) - mu * mu, 0.f); rstd = rsqrtf(var + LN_EPS);
; }
	v_mov_b32_e32 v167, v165
	v_mov_b32_e32 v166, v164
	s_nop 1
	v_permlane32_swap_b32_e32 v167, v165
	v_permlane32_swap_b32_e32 v166, v164
	s_nop 0
	v_pk_add_f32 v[164:165], v[164:165], v[166:167]
	s_nop 0
	v_pk_mul_f32 v[206:207], v[164:165], s[26:27] op_sel_hi:[1,0]
	s_nop 0
	v_fma_f32 v164, -v207, v207, v206
	v_max_f32_e32 v164, 0, v164
	v_add_f32_e32 v164, 0x3727c5ac, v164
	v_cmp_gt_f32_e32 vcc, s87, v164
	v_mul_f32_e32 v165, 0x4b800000, v164
	v_pk_fma_f32 v[28:29], v[112:113], v[206:207], v[28:29] op_sel:[0,1,0] neg_lo:[1,0,0] neg_hi:[1,0,0]
	v_cndmask_b32_e32 v164, v164, v165, vcc
	v_rsq_f32_e32 v164, v164
	v_pk_fma_f32 v[24:25], v[100:101], v[206:207], v[24:25] op_sel:[0,1,0] neg_lo:[1,0,0] neg_hi:[1,0,0]
	v_pk_fma_f32 v[26:27], v[102:103], v[206:207], v[26:27] op_sel:[0,1,0] neg_lo:[1,0,0] neg_hi:[1,0,0]
	v_pk_fma_f32 v[20:21], v[88:89], v[206:207], v[20:21] op_sel:[0,1,0] neg_lo:[1,0,0] neg_hi:[1,0,0]
	v_mul_f32_e32 v165, 0x45800000, v164
	v_cndmask_b32_e32 v208, v164, v165, vcc
	v_lshl_add_u64 v[164:165], v[160:161], 0, s[30:31]
	global_load_dwordx4 v[160:163], v[162:163], off offset:2048
	s_nop 0
	global_load_dwordx4 v[164:167], v[164:165], off offset:16
	v_pk_fma_f32 v[28:29], v[28:29], v[208:209], v[116:117] op_sel_hi:[1,0,1]
	v_pk_fma_f32 v[24:25], v[24:25], v[208:209], v[104:105] op_sel_hi:[1,0,1]
	v_pk_fma_f32 v[26:27], v[26:27], v[208:209], v[106:107] op_sel_hi:[1,0,1]
	v_pk_fma_f32 v[20:21], v[20:21], v[208:209], v[92:93] op_sel_hi:[1,0,1]
	v_pk_fma_f32 v[16:17], v[76:77], v[206:207], v[16:17] op_sel:[0,1,0] neg_lo:[1,0,0] neg_hi:[1,0,0]
	v_pk_fma_f32 v[18:19], v[78:79], v[206:207], v[18:19] op_sel:[0,1,0] neg_lo:[1,0,0] neg_hi:[1,0,0]
	v_pk_fma_f32 v[16:17], v[16:17], v[208:209], v[80:81] op_sel_hi:[1,0,1]
	v_pk_fma_f32 v[18:19], v[18:19], v[208:209], v[82:83] op_sel_hi:[1,0,1]
	s_waitcnt vmcnt(1)
	v_mov_b32_e32 v218, v160
	s_waitcnt vmcnt(0)
	v_mov_b32_e32 v219, v164
	v_mov_b32_e32 v220, v162
	v_mov_b32_e32 v221, v166
	v_pk_add_f32 v[218:219], v[218:219], v[220:221]
	v_add_f32_e32 v160, v161, v163
	v_add_f32_e32 v162, v165, v167
	v_mov_b32_e32 v161, v218
	v_mov_b32_e32 v163, v219
	v_pk_add_f32 v[160:161], v[160:161], v[162:163]
	v_lshl_or_b32 v164, s91, 7, v193
	v_ashrrev_i32_e32 v165, 31, v164
	s_waitcnt lgkmcnt(0)
	v_mov_b32_e32 v163, v161
	v_mov_b32_e32 v162, v160
	s_nop 1
	v_permlane16_swap_b32_e32 v163, v161
	v_permlane16_swap_b32_e32 v162, v160
	s_nop 0
	v_pk_add_f32 v[160:161], v[160:161], v[162:163]
	s_waitcnt lgkmcnt(0)
	v_mov_b32_e32 v163, v161
	v_mov_b32_e32 v162, v160
	s_nop 1
	v_permlane32_swap_b32_e32 v163, v161
	v_permlane32_swap_b32_e32 v162, v160
	s_nop 0
	v_pk_add_f32 v[160:161], v[160:161], v[162:163]
	s_nop 0
	v_pk_mul_f32 v[160:161], v[160:161], s[26:27] op_sel_hi:[1,0]
	s_nop 0
	v_fma_f32 v162, -v161, v161, v160
	v_max_f32_e32 v162, 0, v162
	v_add_f32_e32 v162, 0x3727c5ac, v162
	v_cmp_gt_f32_e32 vcc, s87, v162
	v_mul_f32_e32 v163, 0x4b800000, v162
	v_pk_fma_f32 v[12:13], v[112:113], v[160:161], v[12:13] op_sel:[0,1,0] neg_lo:[1,0,0] neg_hi:[1,0,0]
	v_cndmask_b32_e32 v162, v162, v163, vcc
	v_rsq_f32_e32 v162, v162
	v_pk_fma_f32 v[8:9], v[100:101], v[160:161], v[8:9] op_sel:[0,1,0] neg_lo:[1,0,0] neg_hi:[1,0,0]
	v_pk_fma_f32 v[10:11], v[102:103], v[160:161], v[10:11] op_sel:[0,1,0] neg_lo:[1,0,0] neg_hi:[1,0,0]
	v_pk_fma_f32 v[4:5], v[88:89], v[160:161], v[4:5] op_sel:[0,1,0] neg_lo:[1,0,0] neg_hi:[1,0,0]
	v_mul_f32_e32 v163, 0x45800000, v162
	v_cndmask_b32_e32 v162, v162, v163, vcc
	v_mul_f32_e32 v163, 0xbfb8aa3b, v156
	v_exp_f32_e32 v163, v163
	v_pk_fma_f32 v[0:1], v[76:77], v[160:161], v[0:1] op_sel:[0,1,0] neg_lo:[1,0,0] neg_hi:[1,0,0]
	v_pk_fma_f32 v[2:3], v[78:79], v[160:161], v[2:3] op_sel:[0,1,0] neg_lo:[1,0,0] neg_hi:[1,0,0]
	v_add_f32_e32 v163, 1.0, v163
	v_rcp_f32_e32 v166, v163
	v_mul_f32_e32 v163, 0xbfb8aa3b, v157
	v_exp_f32_e32 v163, v163
	s_nop 0
	v_add_f32_e32 v163, 1.0, v163
	v_rcp_f32_e32 v167, v163
	v_pk_fma_f32 v[12:13], v[12:13], v[162:163], v[116:117] op_sel_hi:[1,0,1]
	v_pk_fma_f32 v[8:9], v[8:9], v[162:163], v[104:105] op_sel_hi:[1,0,1]
	v_pk_fma_f32 v[10:11], v[10:11], v[162:163], v[106:107] op_sel_hi:[1,0,1]
	v_pk_mul_f32 v[156:157], v[156:157], v[166:167]
	v_pk_fma_f32 v[4:5], v[4:5], v[162:163], v[92:93] op_sel_hi:[1,0,1]
	v_pk_mul_f32 v[152:153], v[152:153], v[156:157]
	v_pk_fma_f32 v[156:157], v[114:115], v[214:215], v[158:159] op_sel:[0,1,0] neg_lo:[1,0,0] neg_hi:[1,0,0]
	v_pk_fma_f32 v[0:1], v[0:1], v[162:163], v[80:81] op_sel_hi:[1,0,1]
	v_pk_fma_f32 v[156:157], v[156:157], v[216:217], v[118:119] op_sel_hi:[1,0,1]
	v_pk_fma_f32 v[2:3], v[2:3], v[162:163], v[82:83] op_sel_hi:[1,0,1]
	v_mul_f32_e32 v158, 0xbfb8aa3b, v156
	v_mul_f32_e32 v159, 0xbfb8aa3b, v157
	v_exp_f32_e32 v158, v158
	v_exp_f32_e32 v159, v159
	v_add_f32_e32 v158, 1.0, v158
	v_add_f32_e32 v159, 1.0, v159
	v_rcp_f32_e32 v158, v158
	v_rcp_f32_e32 v159, v159
	s_nop 0
	v_pk_mul_f32 v[156:157], v[156:157], v[158:159]
	s_nop 0
	v_pk_mul_f32 v[154:155], v[154:155], v[156:157]
	v_mul_f32_e32 v156, 0xbfb8aa3b, v148
	v_mul_f32_e32 v157, 0xbfb8aa3b, v149
	v_exp_f32_e32 v156, v156
	v_exp_f32_e32 v157, v157
	v_add_f32_e32 v156, 1.0, v156
	v_add_f32_e32 v157, 1.0, v157
	v_rcp_f32_e32 v156, v156
	v_rcp_f32_e32 v157, v157
	s_nop 0
	v_pk_mul_f32 v[148:149], v[148:149], v[156:157]
	s_nop 0
	v_pk_mul_f32 v[144:145], v[144:145], v[148:149]
	v_pk_fma_f32 v[148:149], v[90:91], v[214:215], v[150:151] op_sel:[0,1,0] neg_lo:[1,0,0] neg_hi:[1,0,0]
	s_nop 0
	v_pk_fma_f32 v[148:149], v[148:149], v[216:217], v[94:95] op_sel_hi:[1,0,1]
	s_nop 0
	v_mul_f32_e32 v150, 0xbfb8aa3b, v148
	v_mul_f32_e32 v151, 0xbfb8aa3b, v149
	v_exp_f32_e32 v150, v150
	v_exp_f32_e32 v151, v151
	v_add_f32_e32 v150, 1.0, v150
	v_add_f32_e32 v151, 1.0, v151
	v_rcp_f32_e32 v150, v150
	v_rcp_f32_e32 v151, v151
	s_nop 0
	v_pk_mul_f32 v[148:149], v[148:149], v[150:151]
	s_nop 0
	v_pk_mul_f32 v[150:151], v[146:147], v[148:149]
	v_cvt_pk_bf16_f32 v148, v144, v145
	v_mov_b64_e32 v[144:145], s[52:53]
	v_mad_u64_u32 v[144:145], s[30:31], v204, s88, v[144:145]
	v_cvt_pk_bf16_f32 v149, v150, v151
	v_mov_b32_e32 v150, v145
	v_mad_u64_u32 v[150:151], s[30:31], v205, s88, v[150:151]
	v_mov_b32_e32 v145, v150
	v_cvt_pk_bf16_f32 v146, v152, v153
	v_cvt_pk_bf16_f32 v147, v154, v155
	v_lshl_add_u64 v[144:145], v[164:165], 1, v[144:145]
	global_store_dwordx4 v[144:145], v[146:149], off
	s_mov_b32 s30, 0x16000
	s_nop 0
	v_mul_f32_e32 v146, 0xbfb8aa3b, v140
	v_mul_f32_e32 v147, 0xbfb8aa3b, v141
	v_exp_f32_e32 v146, v146
	v_exp_f32_e32 v147, v147
	v_add_f32_e32 v146, 1.0, v146
	v_add_f32_e32 v147, 1.0, v147
	v_rcp_f32_e32 v146, v146
	v_rcp_f32_e32 v147, v147
	s_nop 0
	v_pk_mul_f32 v[140:141], v[140:141], v[146:147]
	s_nop 0
	v_pk_mul_f32 v[136:137], v[136:137], v[140:141]
	v_pk_fma_f32 v[140:141], v[114:115], v[210:211], v[142:143] op_sel:[0,1,0] neg_lo:[1,0,0] neg_hi:[1,0,0]
	s_nop 0
	v_pk_fma_f32 v[140:141], v[140:141], v[212:213], v[118:119] op_sel_hi:[1,0,1]
	s_nop 0
	v_mul_f32_e32 v142, 0xbfb8aa3b, v140
	v_mul_f32_e32 v143, 0xbfb8aa3b, v141
	v_exp_f32_e32 v142, v142
	v_exp_f32_e32 v143, v143
	v_add_f32_e32 v142, 1.0, v142
	v_add_f32_e32 v143, 1.0, v143
	v_rcp_f32_e32 v142, v142
	v_rcp_f32_e32 v143, v143
	s_nop 0
	v_pk_mul_f32 v[140:141], v[140:141], v[142:143]
	s_nop 0
	v_pk_mul_f32 v[138:139], v[138:139], v[140:141]
	v_mul_f32_e32 v140, 0xbfb8aa3b, v132
	v_mul_f32_e32 v141, 0xbfb8aa3b, v133
	v_exp_f32_e32 v140, v140
	v_exp_f32_e32 v141, v141
	v_add_f32_e32 v140, 1.0, v140
	v_add_f32_e32 v141, 1.0, v141
	v_rcp_f32_e32 v140, v140
	v_rcp_f32_e32 v141, v141
	s_nop 0
	v_pk_mul_f32 v[132:133], v[132:133], v[140:141]
	s_nop 0
	v_pk_mul_f32 v[132:133], v[128:129], v[132:133]
	v_pk_fma_f32 v[128:129], v[90:91], v[210:211], v[134:135] op_sel:[0,1,0] neg_lo:[1,0,0] neg_hi:[1,0,0]
	s_nop 0
	v_pk_fma_f32 v[128:129], v[128:129], v[212:213], v[94:95] op_sel_hi:[1,0,1]
	s_nop 0
	v_mul_f32_e32 v134, 0xbfb8aa3b, v128
	v_mul_f32_e32 v135, 0xbfb8aa3b, v129
	v_exp_f32_e32 v134, v134
	v_exp_f32_e32 v135, v135
	v_add_f32_e32 v134, 1.0, v134
	v_add_f32_e32 v135, 1.0, v135
	v_rcp_f32_e32 v134, v134
	v_rcp_f32_e32 v135, v135
	s_nop 0
	v_pk_mul_f32 v[128:129], v[128:129], v[134:135]
	s_nop 0
	v_pk_mul_f32 v[134:135], v[130:131], v[128:129]
	v_cvt_pk_bf16_f32 v130, v132, v133
	v_add_co_u32_e32 v132, vcc, s30, v144
	v_cvt_pk_bf16_f32 v128, v136, v137
	v_cvt_pk_bf16_f32 v129, v138, v139
	v_cvt_pk_bf16_f32 v131, v134, v135
	v_addc_co_u32_e32 v133, vcc, 0, v145, vcc
	global_store_dwordx4 v[132:133], v[128:131], off
	s_mov_b32 s30, 0x2c000
	s_nop 0
	v_mul_f32_e32 v128, 0xbfb8aa3b, v124
	v_mul_f32_e32 v129, 0xbfb8aa3b, v125
	v_exp_f32_e32 v128, v128
	v_exp_f32_e32 v129, v129
	v_add_f32_e32 v128, 1.0, v128
	v_add_f32_e32 v129, 1.0, v129
	v_rcp_f32_e32 v128, v128
	v_rcp_f32_e32 v129, v129
	s_nop 0
	v_pk_mul_f32 v[124:125], v[124:125], v[128:129]
	s_nop 0
	v_pk_mul_f32 v[120:121], v[120:121], v[124:125]
	v_pk_fma_f32 v[124:125], v[114:115], v[200:201], v[126:127] op_sel:[0,1,0] neg_lo:[1,0,0] neg_hi:[1,0,0]
	s_nop 0
	v_pk_fma_f32 v[124:125], v[124:125], v[202:203], v[118:119] op_sel_hi:[1,0,1]
	s_nop 0
	v_mul_f32_e32 v126, 0xbfb8aa3b, v124
	v_mul_f32_e32 v127, 0xbfb8aa3b, v125
	v_exp_f32_e32 v126, v126
	v_exp_f32_e32 v127, v127
	v_add_f32_e32 v126, 1.0, v126
	v_add_f32_e32 v127, 1.0, v127
	v_rcp_f32_e32 v126, v126
	v_rcp_f32_e32 v127, v127
	s_nop 0
	v_pk_mul_f32 v[124:125], v[124:125], v[126:127]
	s_nop 0
	v_pk_mul_f32 v[122:123], v[122:123], v[124:125]
	v_mul_f32_e32 v124, 0xbfb8aa3b, v108
	v_mul_f32_e32 v125, 0xbfb8aa3b, v109
	v_exp_f32_e32 v124, v124
	v_exp_f32_e32 v125, v125
	v_add_f32_e32 v124, 1.0, v124
	v_add_f32_e32 v125, 1.0, v125
	v_rcp_f32_e32 v124, v124
	v_rcp_f32_e32 v125, v125
	s_nop 0
	v_pk_mul_f32 v[108:109], v[108:109], v[124:125]
	s_nop 0
	v_pk_mul_f32 v[108:109], v[96:97], v[108:109]
	v_pk_fma_f32 v[96:97], v[90:91], v[200:201], v[110:111] op_sel:[0,1,0] neg_lo:[1,0,0] neg_hi:[1,0,0]
	s_nop 0
	v_pk_fma_f32 v[96:97], v[96:97], v[202:203], v[94:95] op_sel_hi:[1,0,1]
	s_nop 0
	v_mul_f32_e32 v110, 0xbfb8aa3b, v96
	v_mul_f32_e32 v111, 0xbfb8aa3b, v97
	v_exp_f32_e32 v110, v110
	v_exp_f32_e32 v111, v111
	v_add_f32_e32 v110, 1.0, v110
	v_add_f32_e32 v111, 1.0, v111
	v_rcp_f32_e32 v110, v110
	v_rcp_f32_e32 v111, v111
	s_nop 0
	v_pk_mul_f32 v[96:97], v[96:97], v[110:111]
	s_nop 0
	v_pk_mul_f32 v[110:111], v[98:99], v[96:97]
	v_cvt_pk_bf16_f32 v98, v108, v109
	v_add_co_u32_e32 v108, vcc, s30, v144
	v_cvt_pk_bf16_f32 v96, v120, v121
	v_cvt_pk_bf16_f32 v97, v122, v123
	v_cvt_pk_bf16_f32 v99, v110, v111
	v_addc_co_u32_e32 v109, vcc, 0, v145, vcc
	global_store_dwordx4 v[108:109], v[96:99], off
	s_mov_b32 s30, 0x42000
	s_nop 0
	v_mul_f32_e32 v96, 0xbfb8aa3b, v84
	v_mul_f32_e32 v97, 0xbfb8aa3b, v85
	v_exp_f32_e32 v96, v96
	v_exp_f32_e32 v97, v97
	v_add_f32_e32 v96, 1.0, v96
	v_add_f32_e32 v97, 1.0, v97
	v_rcp_f32_e32 v96, v96
	v_rcp_f32_e32 v97, v97
	s_nop 0
	v_pk_mul_f32 v[84:85], v[84:85], v[96:97]
	s_nop 0
	v_pk_mul_f32 v[72:73], v[72:73], v[84:85]
	v_pk_fma_f32 v[84:85], v[114:115], v[186:187], v[86:87] op_sel:[0,1,0] neg_lo:[1,0,0] neg_hi:[1,0,0]
	s_nop 0
	v_pk_fma_f32 v[84:85], v[84:85], v[188:189], v[118:119] op_sel_hi:[1,0,1]
	s_nop 0
	v_mul_f32_e32 v86, 0xbfb8aa3b, v84
	v_mul_f32_e32 v87, 0xbfb8aa3b, v85
	v_exp_f32_e32 v86, v86
	v_exp_f32_e32 v87, v87
	v_add_f32_e32 v86, 1.0, v86
	v_add_f32_e32 v87, 1.0, v87
	v_rcp_f32_e32 v86, v86
	v_rcp_f32_e32 v87, v87
	s_nop 0
	v_pk_mul_f32 v[84:85], v[84:85], v[86:87]
	s_nop 0
	v_pk_mul_f32 v[74:75], v[74:75], v[84:85]
	v_mul_f32_e32 v84, 0xbfb8aa3b, v68
	v_mul_f32_e32 v85, 0xbfb8aa3b, v69
	v_exp_f32_e32 v84, v84
	v_exp_f32_e32 v85, v85
	v_add_f32_e32 v84, 1.0, v84
	v_add_f32_e32 v85, 1.0, v85
	v_rcp_f32_e32 v84, v84
	v_rcp_f32_e32 v85, v85
	s_nop 0
	v_pk_mul_f32 v[68:69], v[68:69], v[84:85]
	s_nop 0
	v_pk_mul_f32 v[68:69], v[64:65], v[68:69]
	v_pk_fma_f32 v[64:65], v[90:91], v[186:187], v[70:71] op_sel:[0,1,0] neg_lo:[1,0,0] neg_hi:[1,0,0]
	s_nop 0
	v_pk_fma_f32 v[64:65], v[64:65], v[188:189], v[94:95] op_sel_hi:[1,0,1]
	s_nop 0
	v_mul_f32_e32 v70, 0xbfb8aa3b, v64
	v_mul_f32_e32 v71, 0xbfb8aa3b, v65
	v_exp_f32_e32 v70, v70
	v_exp_f32_e32 v71, v71
	v_add_f32_e32 v70, 1.0, v70
	v_add_f32_e32 v71, 1.0, v71
	v_rcp_f32_e32 v70, v70
	v_rcp_f32_e32 v71, v71
	s_nop 0
	v_pk_mul_f32 v[64:65], v[64:65], v[70:71]
	s_nop 0
	v_pk_mul_f32 v[70:71], v[66:67], v[64:65]
	v_cvt_pk_bf16_f32 v66, v68, v69
	v_add_co_u32_e32 v68, vcc, s30, v144
	v_cvt_pk_bf16_f32 v64, v72, v73
	v_cvt_pk_bf16_f32 v65, v74, v75
	v_cvt_pk_bf16_f32 v67, v70, v71
	v_addc_co_u32_e32 v69, vcc, 0, v145, vcc
	global_store_dwordx4 v[68:69], v[64:67], off
	s_mov_b32 s30, 0xb0000
	s_nop 0
	v_mul_f32_e32 v64, 0xbfb8aa3b, v60
	v_mul_f32_e32 v65, 0xbfb8aa3b, v61
	v_exp_f32_e32 v64, v64
	v_exp_f32_e32 v65, v65
	v_add_f32_e32 v64, 1.0, v64
	v_add_f32_e32 v65, 1.0, v65
	v_rcp_f32_e32 v64, v64
	v_rcp_f32_e32 v65, v65
	s_nop 0
	v_pk_mul_f32 v[60:61], v[60:61], v[64:65]
	s_nop 0
	v_pk_mul_f32 v[56:57], v[56:57], v[60:61]
	v_pk_fma_f32 v[60:61], v[114:115], v[196:197], v[62:63] op_sel:[0,1,0] neg_lo:[1,0,0] neg_hi:[1,0,0]
	s_nop 0
	v_pk_fma_f32 v[60:61], v[60:61], v[198:199], v[118:119] op_sel_hi:[1,0,1]
	s_nop 0
	v_mul_f32_e32 v62, 0xbfb8aa3b, v60
	v_mul_f32_e32 v63, 0xbfb8aa3b, v61
	v_exp_f32_e32 v62, v62
	v_exp_f32_e32 v63, v63
	v_add_f32_e32 v62, 1.0, v62
	v_add_f32_e32 v63, 1.0, v63
	v_rcp_f32_e32 v62, v62
	v_rcp_f32_e32 v63, v63
	s_nop 0
	v_pk_mul_f32 v[60:61], v[60:61], v[62:63]
	s_nop 0
	v_pk_mul_f32 v[58:59], v[58:59], v[60:61]
	v_mul_f32_e32 v60, 0xbfb8aa3b, v52
	v_mul_f32_e32 v61, 0xbfb8aa3b, v53
	v_exp_f32_e32 v60, v60
	v_exp_f32_e32 v61, v61
	v_add_f32_e32 v60, 1.0, v60
	v_add_f32_e32 v61, 1.0, v61
	v_rcp_f32_e32 v60, v60
	v_rcp_f32_e32 v61, v61
	s_nop 0
	v_pk_mul_f32 v[52:53], v[52:53], v[60:61]
	s_nop 0
	v_pk_mul_f32 v[52:53], v[48:49], v[52:53]
	v_pk_fma_f32 v[48:49], v[90:91], v[196:197], v[54:55] op_sel:[0,1,0] neg_lo:[1,0,0] neg_hi:[1,0,0]
	s_nop 0
	v_pk_fma_f32 v[48:49], v[48:49], v[198:199], v[94:95] op_sel_hi:[1,0,1]
	s_nop 0
	v_mul_f32_e32 v54, 0xbfb8aa3b, v48
	v_mul_f32_e32 v55, 0xbfb8aa3b, v49
	v_exp_f32_e32 v54, v54
	v_exp_f32_e32 v55, v55
	v_add_f32_e32 v54, 1.0, v54
	v_add_f32_e32 v55, 1.0, v55
	v_rcp_f32_e32 v54, v54
	v_rcp_f32_e32 v55, v55
	s_nop 0
	v_pk_mul_f32 v[48:49], v[48:49], v[54:55]
	s_nop 0
	v_pk_mul_f32 v[54:55], v[50:51], v[48:49]
	v_cvt_pk_bf16_f32 v50, v52, v53
	v_add_co_u32_e32 v52, vcc, s30, v144
	v_cvt_pk_bf16_f32 v48, v56, v57
	v_cvt_pk_bf16_f32 v49, v58, v59
	v_cvt_pk_bf16_f32 v51, v54, v55
	v_addc_co_u32_e32 v53, vcc, 0, v145, vcc
	global_store_dwordx4 v[52:53], v[48:51], off
	s_mov_b32 s30, 0xc6000
	s_nop 0
	v_mul_f32_e32 v48, 0xbfb8aa3b, v44
	v_mul_f32_e32 v49, 0xbfb8aa3b, v45
	v_exp_f32_e32 v48, v48
	v_exp_f32_e32 v49, v49
	v_add_f32_e32 v48, 1.0, v48
	v_add_f32_e32 v49, 1.0, v49
	v_rcp_f32_e32 v48, v48
	v_rcp_f32_e32 v49, v49
	s_nop 0
	v_pk_mul_f32 v[44:45], v[44:45], v[48:49]
	s_nop 0
	v_pk_mul_f32 v[40:41], v[40:41], v[44:45]
	v_pk_fma_f32 v[44:45], v[114:115], v[190:191], v[46:47] op_sel:[0,1,0] neg_lo:[1,0,0] neg_hi:[1,0,0]
	s_nop 0
	v_pk_fma_f32 v[44:45], v[44:45], v[194:195], v[118:119] op_sel_hi:[1,0,1]
	s_nop 0
	v_mul_f32_e32 v46, 0xbfb8aa3b, v44
	v_mul_f32_e32 v47, 0xbfb8aa3b, v45
	v_exp_f32_e32 v46, v46
	v_exp_f32_e32 v47, v47
	v_add_f32_e32 v46, 1.0, v46
	v_add_f32_e32 v47, 1.0, v47
	v_rcp_f32_e32 v46, v46
	v_rcp_f32_e32 v47, v47
	s_nop 0
	v_pk_mul_f32 v[44:45], v[44:45], v[46:47]
	s_nop 0
	v_pk_mul_f32 v[42:43], v[42:43], v[44:45]
	v_mul_f32_e32 v44, 0xbfb8aa3b, v36
	v_mul_f32_e32 v45, 0xbfb8aa3b, v37
	v_exp_f32_e32 v44, v44
	v_exp_f32_e32 v45, v45
	v_add_f32_e32 v44, 1.0, v44
	v_add_f32_e32 v45, 1.0, v45
	v_rcp_f32_e32 v44, v44
	v_rcp_f32_e32 v45, v45
	s_nop 0
	v_pk_mul_f32 v[36:37], v[36:37], v[44:45]
	s_nop 0
	v_pk_mul_f32 v[36:37], v[32:33], v[36:37]
	v_pk_fma_f32 v[32:33], v[90:91], v[190:191], v[38:39] op_sel:[0,1,0] neg_lo:[1,0,0] neg_hi:[1,0,0]
	s_nop 0
; #define PG8_BAR __builtin_amdgcn_s_barrier()
; template <class Epi, class Sched, bool ALIGN_EPI = false, bool SP2 = false>
; __device__ __forceinline__ void gemm_phase(PG8_LAS unsigned char* lds, const Gemm g, const Sched& S, const Epi& E) {
;     ...
;         if constexpr (ALIGN_EPI) { if (wr == 0) PG8_BAR; }
;         if constexpr (!Epi::AFTER_DRAIN) { E(acc, cur, wr, wc, fr, fq); S.done(cur); }
;         if (!has_next) break;
; #pragma unroll
;         for (int a = 0; a < 2; ++a)
; #pragma unroll
;             for (int b = 0; b < 2; ++b)
; #pragma unroll
;                 for (int m = 0; m < 4; ++m)
; #pragma unroll
;                     for (int n = 0; n < 2; ++n) acc[a][b][m][n] = (f32x4){0.f, 0.f, 0.f, 0.f};
;         cur = nxt; cA = nA; cB = nB; ++ui;
;         if constexpr (ALIGN_EPI) { if (wr == 1) PG8_BAR; }
	v_pk_fma_f32 v[32:33], v[32:33], v[194:195], v[94:95] op_sel_hi:[1,0,1]
	s_nop 0
	v_mul_f32_e32 v38, 0xbfb8aa3b, v32
	v_mul_f32_e32 v39, 0xbfb8aa3b, v33
	v_exp_f32_e32 v38, v38
	v_exp_f32_e32 v39, v39
	v_add_f32_e32 v38, 1.0, v38
	v_add_f32_e32 v39, 1.0, v39
	v_rcp_f32_e32 v38, v38
	v_rcp_f32_e32 v39, v39
	s_nop 0
	v_pk_mul_f32 v[32:33], v[32:33], v[38:39]
	s_nop 0
	v_pk_mul_f32 v[38:39], v[34:35], v[32:33]
	v_cvt_pk_bf16_f32 v34, v36, v37
	v_add_co_u32_e32 v36, vcc, s30, v144
	v_cvt_pk_bf16_f32 v32, v40, v41
	v_cvt_pk_bf16_f32 v33, v42, v43
	v_cvt_pk_bf16_f32 v35, v38, v39
	v_addc_co_u32_e32 v37, vcc, 0, v145, vcc
	global_store_dwordx4 v[36:37], v[32:35], off
	s_mov_b32 s30, 0xdc000
	s_nop 0
	v_mul_f32_e32 v32, 0xbfb8aa3b, v28
	v_mul_f32_e32 v33, 0xbfb8aa3b, v29
	v_exp_f32_e32 v32, v32
	v_exp_f32_e32 v33, v33
	v_add_f32_e32 v32, 1.0, v32
	v_add_f32_e32 v33, 1.0, v33
	v_rcp_f32_e32 v32, v32
	v_rcp_f32_e32 v33, v33
	s_nop 0
	v_pk_mul_f32 v[28:29], v[28:29], v[32:33]
	s_nop 0
	v_pk_mul_f32 v[24:25], v[24:25], v[28:29]
	v_pk_fma_f32 v[28:29], v[114:115], v[206:207], v[30:31] op_sel:[0,1,0] neg_lo:[1,0,0] neg_hi:[1,0,0]
	s_nop 0
	v_pk_fma_f32 v[28:29], v[28:29], v[208:209], v[118:119] op_sel_hi:[1,0,1]
	s_nop 0
	v_mul_f32_e32 v30, 0xbfb8aa3b, v28
	v_mul_f32_e32 v31, 0xbfb8aa3b, v29
	v_exp_f32_e32 v30, v30
	v_exp_f32_e32 v31, v31
	v_add_f32_e32 v30, 1.0, v30
	v_add_f32_e32 v31, 1.0, v31
	v_rcp_f32_e32 v30, v30
	v_rcp_f32_e32 v31, v31
	s_nop 0
	v_pk_mul_f32 v[28:29], v[28:29], v[30:31]
	s_nop 0
	v_pk_mul_f32 v[26:27], v[26:27], v[28:29]
	v_mul_f32_e32 v28, 0xbfb8aa3b, v20
	v_mul_f32_e32 v29, 0xbfb8aa3b, v21
	v_exp_f32_e32 v28, v28
	v_exp_f32_e32 v29, v29
	v_add_f32_e32 v28, 1.0, v28
	v_add_f32_e32 v29, 1.0, v29
	v_rcp_f32_e32 v28, v28
	v_rcp_f32_e32 v29, v29
	s_nop 0
	v_pk_mul_f32 v[20:21], v[20:21], v[28:29]
	s_nop 0
	v_pk_mul_f32 v[20:21], v[16:17], v[20:21]
	v_pk_fma_f32 v[16:17], v[90:91], v[206:207], v[22:23] op_sel:[0,1,0] neg_lo:[1,0,0] neg_hi:[1,0,0]
	s_nop 0
	v_pk_fma_f32 v[16:17], v[16:17], v[208:209], v[94:95] op_sel_hi:[1,0,1]
	s_nop 0
	v_mul_f32_e32 v22, 0xbfb8aa3b, v16
	v_mul_f32_e32 v23, 0xbfb8aa3b, v17
	v_exp_f32_e32 v22, v22
	v_exp_f32_e32 v23, v23
	v_add_f32_e32 v22, 1.0, v22
	v_add_f32_e32 v23, 1.0, v23
	v_rcp_f32_e32 v22, v22
	v_rcp_f32_e32 v23, v23
	s_nop 0
	v_pk_mul_f32 v[16:17], v[16:17], v[22:23]
	s_nop 0
	v_pk_mul_f32 v[22:23], v[18:19], v[16:17]
	v_cvt_pk_bf16_f32 v18, v20, v21
	v_add_co_u32_e32 v20, vcc, s30, v144
	v_cvt_pk_bf16_f32 v16, v24, v25
	v_cvt_pk_bf16_f32 v17, v26, v27
	v_cvt_pk_bf16_f32 v19, v22, v23
	v_addc_co_u32_e32 v21, vcc, 0, v145, vcc
	global_store_dwordx4 v[20:21], v[16:19], off
	s_mov_b64 s[30:31], -1
	s_nop 0
	v_mul_f32_e32 v16, 0xbfb8aa3b, v12
	v_mul_f32_e32 v17, 0xbfb8aa3b, v13
	v_exp_f32_e32 v16, v16
	v_exp_f32_e32 v17, v17
	v_add_f32_e32 v16, 1.0, v16
	v_add_f32_e32 v17, 1.0, v17
	v_rcp_f32_e32 v16, v16
	v_rcp_f32_e32 v17, v17
	s_nop 0
	v_pk_mul_f32 v[12:13], v[12:13], v[16:17]
	s_nop 0
	v_pk_mul_f32 v[8:9], v[8:9], v[12:13]
	v_pk_fma_f32 v[12:13], v[114:115], v[160:161], v[14:15] op_sel:[0,1,0] neg_lo:[1,0,0] neg_hi:[1,0,0]
	s_nop 0
	v_pk_fma_f32 v[12:13], v[12:13], v[162:163], v[118:119] op_sel_hi:[1,0,1]
	s_nop 0
	v_mul_f32_e32 v14, 0xbfb8aa3b, v12
	v_mul_f32_e32 v15, 0xbfb8aa3b, v13
	v_exp_f32_e32 v14, v14
	v_exp_f32_e32 v15, v15
	v_add_f32_e32 v14, 1.0, v14
	v_add_f32_e32 v15, 1.0, v15
	v_rcp_f32_e32 v14, v14
	v_rcp_f32_e32 v15, v15
	s_nop 0
	v_pk_mul_f32 v[12:13], v[12:13], v[14:15]
	s_nop 0
	v_pk_mul_f32 v[10:11], v[10:11], v[12:13]
	v_mul_f32_e32 v12, 0xbfb8aa3b, v4
	v_mul_f32_e32 v13, 0xbfb8aa3b, v5
	v_exp_f32_e32 v12, v12
	v_exp_f32_e32 v13, v13
	v_add_f32_e32 v12, 1.0, v12
	v_add_f32_e32 v13, 1.0, v13
	v_rcp_f32_e32 v12, v12
	v_rcp_f32_e32 v13, v13
	s_nop 0
	v_pk_mul_f32 v[4:5], v[4:5], v[12:13]
	s_nop 0
	v_pk_mul_f32 v[4:5], v[0:1], v[4:5]
	v_pk_fma_f32 v[0:1], v[90:91], v[160:161], v[6:7] op_sel:[0,1,0] neg_lo:[1,0,0] neg_hi:[1,0,0]
	s_nop 0
	v_pk_fma_f32 v[0:1], v[0:1], v[162:163], v[94:95] op_sel_hi:[1,0,1]
	s_nop 0
	v_mul_f32_e32 v6, 0xbfb8aa3b, v0
	v_mul_f32_e32 v7, 0xbfb8aa3b, v1
	v_exp_f32_e32 v6, v6
	v_exp_f32_e32 v7, v7
	v_add_f32_e32 v6, 1.0, v6
	v_add_f32_e32 v7, 1.0, v7
	v_rcp_f32_e32 v6, v6
	v_rcp_f32_e32 v7, v7
	s_nop 0
	v_pk_mul_f32 v[0:1], v[0:1], v[6:7]
	s_nop 0
	v_pk_mul_f32 v[6:7], v[2:3], v[0:1]
	v_cvt_pk_bf16_f32 v2, v4, v5
	v_add_co_u32_e32 v4, vcc, 0xf2000, v144
	v_cvt_pk_bf16_f32 v0, v8, v9
	s_nop 0
	v_addc_co_u32_e32 v5, vcc, 0, v145, vcc
	v_cvt_pk_bf16_f32 v1, v10, v11
	v_cvt_pk_bf16_f32 v3, v6, v7
	s_and_b64 vcc, exec, s[4:5]
	global_store_dwordx4 v[4:5], v[0:3], off
	s_cbranch_vccnz .LBB0_2340
	s_andn2_b64 vcc, exec, s[14:15]
	s_cbranch_vccnz .LBB0_2339
	s_barrier
	s_branch .LBB0_2339

; DI void row_stats(const f32x2v* st, size_t row, int fq, float& mu, float& rstd) {
;     const f32x4 a = *(const f32x4*)(st + row * 16 + 4 * fq), b = *(const f32x4*)(st + row * 16 + 4 * fq + 2);
;     float s1 = (a[0] + a[2]) + (b[0] + b[2]), s2 = (a[1] + a[3]) + (b[1] + b[3]);
;     s1 += __shfl_xor(s1, 16); s1 += __shfl_xor(s1, 32); s2 += __shfl_xor(s2, 16); s2 += __shfl_xor(s2, 32);
;     mu = s1 * (1.0f / 1024.0f); const float var = fmaxf(s2 * (1.0f / 1024.0f) - mu * mu, 0.f); rstd = rsqrtf(var + LN_EPS);
; }
.LBB0_2471:
	v_and_b32_e32 v117, 64, v246
	v_xor_b32_e32 v116, 16, v246
	v_add_u32_e32 v117, 64, v117
	s_ashr_i32 s67, s66, 31
	v_cmp_lt_i32_e32 vcc, v116, v117
	s_lshl_b64 s[50:51], s[66:67], 8
	v_lshl_add_u64 v[184:185], s[50:51], 0, v[166:167]
	v_cndmask_b32_e32 v116, v246, v116, vcc
	v_lshlrev_b32_e32 v248, 2, v116
	v_xor_b32_e32 v116, 32, v246
	v_cmp_lt_i32_e32 vcc, v116, v117
	v_lshlrev_b64 v[208:209], 7, v[184:185]
	v_lshl_add_u64 v[124:125], v[168:169], 0, v[208:209]
	v_cndmask_b32_e32 v116, v246, v116, vcc
	v_lshlrev_b32_e32 v247, 2, v116
	global_load_dwordx4 v[116:119], v[124:125], off offset:16
	s_nop 0
	global_load_dwordx4 v[124:127], v[124:125], off
	v_lshl_or_b32 v176, s16, 8, v242
	v_ashrrev_i32_e32 v177, 31, v176
	v_lshlrev_b64 v[232:233], 1, v[176:177]
	v_or_b32_e32 v128, 16, v184
	v_mov_b32_e32 v129, v185
	v_lshl_add_u64 v[182:183], s[44:45], 0, v[232:233]
	v_lshlrev_b64 v[234:235], 11, v[184:185]
	v_lshlrev_b64 v[204:205], 7, v[128:129]
	v_lshlrev_b64 v[206:207], 11, v[128:129]
	v_or_b32_e32 v128, 32, v184
	v_lshlrev_b64 v[196:197], 7, v[128:129]
	v_or_b32_e32 v188, 48, v184
	v_mov_b32_e32 v189, v185
	v_lshlrev_b64 v[198:199], 11, v[128:129]
	v_lshlrev_b64 v[186:187], 7, v[188:189]
	v_lshlrev_b64 v[188:189], 11, v[188:189]
	s_lshl_b32 s50, s16, 2
	s_ashr_i32 s51, s50, 31
	s_waitcnt vmcnt(0)
	v_pk_add_f32 v[116:117], v[116:117], v[118:119]
	v_pk_add_f32 v[124:125], v[124:125], v[126:127]
	s_nop 0
	v_pk_add_f32 v[116:117], v[124:125], v[116:117]
	v_lshl_add_u64 v[124:125], v[168:169], 0, v[204:205]
	s_waitcnt lgkmcnt(0)
	v_mov_b32_e32 v118, v116
	v_mov_b32_e32 v119, v117
	s_nop 1
	v_permlane16_swap_b32_e32 v118, v116
	v_permlane16_swap_b32_e32 v119, v117
	s_nop 0
	v_pk_add_f32 v[116:117], v[116:117], v[118:119]
	s_waitcnt lgkmcnt(0)
	v_mov_b32_e32 v118, v116
	v_mov_b32_e32 v119, v117
	s_nop 1
	v_permlane32_swap_b32_e32 v118, v116
	v_permlane32_swap_b32_e32 v119, v117
	s_nop 0
	v_pk_add_f32 v[116:117], v[116:117], v[118:119]
	s_nop 0
	v_pk_mul_f32 v[216:217], v[116:117], s[30:31] op_sel_hi:[1,0]
	s_nop 0
	v_fma_f32 v116, -v216, v216, v217
	v_max_f32_e32 v116, 0, v116
	v_add_f32_e32 v116, 0x3727c5ac, v116
	v_cmp_gt_f32_e32 vcc, s92, v116
	v_mul_f32_e32 v117, 0x4b800000, v116
	s_nop 0
	v_cndmask_b32_e32 v116, v116, v117, vcc
	v_rsq_f32_e32 v116, v116
	s_nop 0
	v_mul_f32_e32 v117, 0x45800000, v116
	v_cndmask_b32_e32 v214, v116, v117, vcc
	v_lshl_add_u64 v[116:117], v[182:183], 0, v[234:235]
	global_load_dwordx4 v[178:181], v[116:117], off
	global_load_dwordx4 v[152:155], v[116:117], off offset:256
	s_nop 0
	global_load_dwordx4 v[116:119], v[124:125], off offset:16
	s_nop 0
	global_load_dwordx4 v[124:127], v[124:125], off
	s_waitcnt vmcnt(3)
	v_lshlrev_b32_e32 v215, 16, v179
	s_waitcnt vmcnt(1)
	v_pk_add_f32 v[116:117], v[116:117], v[118:119]
	s_waitcnt vmcnt(0)
	v_pk_add_f32 v[124:125], v[124:125], v[126:127]
	v_and_b32_e32 v217, 0xffff0000, v179
	v_pk_add_f32 v[116:117], v[124:125], v[116:117]
	ds_bpermute_b32 v118, v248, v116
	ds_bpermute_b32 v119, v248, v117
	v_lshl_add_u64 v[124:125], v[168:169], 0, v[196:197]
	v_lshlrev_b32_e32 v165, 16, v178
	v_and_b32_e32 v178, 0xffff0000, v178
	v_lshlrev_b32_e32 v249, 16, v180
	s_waitcnt lgkmcnt(0)
	v_pk_add_f32 v[210:211], v[116:117], v[118:119]
	v_lshl_add_u64 v[116:117], v[182:183], 0, v[206:207]
	global_load_dwordx4 v[148:151], v[116:117], off
	global_load_dwordx4 v[144:147], v[116:117], off offset:256
	s_nop 0
	global_load_dwordx4 v[116:119], v[124:125], off offset:16
	s_nop 0
	global_load_dwordx4 v[124:127], v[124:125], off
	v_and_b32_e32 v250, 0xffff0000, v180
	v_lshlrev_b32_e32 v251, 16, v181
	v_and_b32_e32 v252, 0xffff0000, v181
	v_sub_f32_e32 v181, v217, v216
	v_sub_f32_e32 v180, v215, v216
	v_sub_f32_e32 v179, v178, v216
	v_sub_f32_e32 v178, v165, v216
	v_pk_mul_f32 v[226:227], v[180:181], v[214:215] op_sel_hi:[1,0]
	v_lshlrev_b64 v[180:181], 2, v[176:177]
	v_pk_mul_f32 v[240:241], v[178:179], v[214:215] op_sel_hi:[1,0]
	v_lshl_add_u64 v[178:179], s[20:21], 0, v[180:181]
	v_lshl_add_u64 v[180:181], s[22:23], 0, v[180:181]
	v_lshlrev_b32_e32 v165, 16, v154
	ds_bpermute_b32 v212, v247, v210
	ds_bpermute_b32 v213, v247, v211
	s_waitcnt vmcnt(1)
	v_pk_add_f32 v[116:117], v[116:117], v[118:119]
	s_waitcnt vmcnt(0)
	v_pk_add_f32 v[124:125], v[124:125], v[126:127]
	s_nop 0
	v_pk_add_f32 v[116:117], v[124:125], v[116:117]
	ds_bpermute_b32 v118, v248, v116
	ds_bpermute_b32 v119, v248, v117
	v_lshl_add_u64 v[124:125], v[168:169], 0, v[186:187]
	s_waitcnt lgkmcnt(0)
	v_pk_add_f32 v[200:201], v[116:117], v[118:119]
	v_lshl_add_u64 v[116:117], v[182:183], 0, v[198:199]
	global_load_dwordx4 v[132:135], v[116:117], off
	global_load_dwordx4 v[128:131], v[116:117], off offset:256
	s_nop 0
	global_load_dwordx4 v[116:119], v[124:125], off offset:16
	s_nop 0
	global_load_dwordx4 v[124:127], v[124:125], off
	ds_bpermute_b32 v202, v247, v200
	ds_bpermute_b32 v203, v247, v201
	s_waitcnt vmcnt(1)
	v_pk_add_f32 v[116:117], v[116:117], v[118:119]
	s_waitcnt vmcnt(0)
	v_pk_add_f32 v[124:125], v[124:125], v[126:127]
	s_nop 0
	v_pk_add_f32 v[116:117], v[124:125], v[116:117]
	ds_bpermute_b32 v118, v248, v116
	ds_bpermute_b32 v119, v248, v117
	s_waitcnt lgkmcnt(0)
	v_pk_add_f32 v[190:191], v[116:117], v[118:119]
	v_lshl_add_u64 v[116:117], v[182:183], 0, v[188:189]
	global_load_dwordx4 v[124:127], v[116:117], off
	s_nop 0
	global_load_dwordx4 v[116:119], v[116:117], off offset:256
	s_nop 0
	global_load_dwordx4 v[228:231], v[178:179], off offset:16
	global_load_dwordx4 v[218:221], v[178:179], off
	global_load_dwordx4 v[236:239], v[180:181], off offset:16
	global_load_dwordx4 v[222:225], v[180:181], off
	ds_bpermute_b32 v194, v247, v190
	ds_bpermute_b32 v195, v247, v191
	s_waitcnt vmcnt(0)
	v_pk_fma_f32 v[220:221], v[226:227], v[220:221], v[224:225]
	s_nop 0
	v_pk_fma_f32 v[142:143], v[220:221], s[34:35], v[142:143] op_sel_hi:[1,0,1]
	v_pk_fma_f32 v[218:219], v[240:241], v[218:219], v[222:223]
	v_mul_f32_e32 v215, v142, v142
	v_sub_f32_e32 v223, v250, v216
	v_sub_f32_e32 v222, v249, v216
	v_sub_f32_e32 v241, v252, v216
	v_sub_f32_e32 v240, v251, v216
	v_pk_mul_f32 v[240:241], v[240:241], v[214:215] op_sel_hi:[1,0]
	v_pk_mul_f32 v[222:223], v[222:223], v[214:215] op_sel_hi:[1,0]
	v_pk_fma_f32 v[140:141], v[218:219], s[34:35], v[140:141] op_sel_hi:[1,0,1]
	v_pk_fma_f32 v[222:223], v[222:223], v[228:229], v[236:237]
	v_pk_fma_f32 v[228:229], v[240:241], v[230:231], v[238:239]
	v_pk_fma_f32 v[230:231], v[222:223], s[34:35], v[136:137] op_sel_hi:[1,0,1]
	v_pk_fma_f32 v[228:229], v[228:229], s[34:35], v[138:139] op_sel_hi:[1,0,1]
	v_add_f32_e32 v218, v140, v141
	v_mul_f32_e32 v136, v228, v228
	v_mul_f32_e32 v225, v140, v140
	v_mul_f32_e32 v227, v141, v141
	v_pk_fma_f32 v[222:223], v[228:229], v[228:229], v[136:137] op_sel_hi:[1,1,0]
	v_cvt_pk_bf16_f32 v136, v140, v141
	v_lshl_add_u64 v[140:141], s[44:45], 0, v[234:235]
	v_cvt_pk_bf16_f32 v137, v142, v143
	v_cvt_pk_bf16_f32 v138, v230, v231
	v_cvt_pk_bf16_f32 v139, v228, v229
	v_lshl_add_u64 v[232:233], v[140:141], 0, v[232:233]
	global_store_dwordx4 v[232:233], v[136:139], off
	v_lshlrev_b32_e32 v140, 16, v153
	v_and_b32_e32 v141, 0xffff0000, v153
	v_lshlrev_b32_e32 v137, 16, v152
	v_and_b32_e32 v138, 0xffff0000, v152
	v_or_b32_e32 v136, 0x80, v176
	v_sub_f32_e32 v139, v138, v216
	v_sub_f32_e32 v138, v137, v216
	v_sub_f32_e32 v141, v141, v216
	v_sub_f32_e32 v140, v140, v216
	v_ashrrev_i32_e32 v137, 31, v136
	v_pk_mul_f32 v[234:235], v[140:141], v[214:215] op_sel_hi:[1,0]
	v_lshlrev_b64 v[140:141], 2, v[136:137]
	v_and_b32_e32 v224, 0xffff0000, v154
	v_lshlrev_b32_e32 v222, 16, v155
	v_and_b32_e32 v226, 0xffff0000, v155
	v_lshl_add_u64 v[152:153], s[20:21], 0, v[140:141]
	v_lshl_add_u64 v[154:155], s[22:23], 0, v[140:141]
	v_add_f32_e32 v220, v142, v143
	v_mul_f32_e32 v217, v143, v143
	v_pk_mul_f32 v[236:237], v[138:139], v[214:215] op_sel_hi:[1,0]
	global_load_dwordx4 v[136:139], v[152:153], off offset:16
	global_load_dwordx4 v[238:241], v[152:153], off
	global_load_dwordx4 v[140:143], v[154:155], off offset:16
	global_load_dwordx4 v[250:253], v[154:155], off
	v_mul_f32_e32 v219, v230, v230
	v_mul_f32_e32 v221, v231, v231
	s_waitcnt vmcnt(0)
	v_pk_fma_f32 v[236:237], v[236:237], v[238:239], v[250:251]
	v_pk_fma_f32 v[234:235], v[234:235], v[240:241], v[252:253]
	v_sub_f32_e32 v251, v224, v216
	v_sub_f32_e32 v250, v165, v216
	v_sub_f32_e32 v253, v226, v216
	v_sub_f32_e32 v252, v222, v216
	v_pk_mul_f32 v[252:253], v[252:253], v[214:215] op_sel_hi:[1,0]
	v_pk_mul_f32 v[250:251], v[250:251], v[214:215] op_sel_hi:[1,0]
	v_pk_fma_f32 v[138:139], v[252:253], v[138:139], v[142:143]
	v_pk_fma_f32 v[136:137], v[250:251], v[136:137], v[140:141]
	v_pk_fma_f32 v[122:123], v[234:235], s[34:35], v[122:123] op_sel_hi:[1,0,1]
	v_pk_fma_f32 v[238:239], v[236:237], s[34:35], v[120:121] op_sel_hi:[1,0,1]
	v_pk_fma_f32 v[138:139], v[138:139], s[34:35], v[114:115] op_sel_hi:[1,0,1]
	v_pk_fma_f32 v[136:137], v[136:137], s[34:35], v[112:113] op_sel_hi:[1,0,1]
	v_cvt_pk_bf16_f32 v112, v238, v239
	v_cvt_pk_bf16_f32 v113, v122, v123
	v_cvt_pk_bf16_f32 v114, v136, v137
	v_cvt_pk_bf16_f32 v115, v138, v139
	v_mov_b32_e32 v224, v230
	v_mov_b32_e32 v226, v231
	v_mov_b32_e32 v214, v228
	v_mov_b32_e32 v216, v229
	global_store_dwordx4 v[232:233], v[112:115], off offset:256
	v_mov_b32_e32 v165, v223
	v_mul_f32_e32 v237, v238, v238
	v_pk_add_f32 v[112:113], v[224:225], v[226:227]
	v_pk_add_f32 v[114:115], v[214:215], v[216:217]
	v_mul_f32_e32 v241, v239, v239
	v_pk_add_f32 v[112:113], v[112:113], v[114:115]
	v_pk_add_f32 v[114:115], v[218:219], v[220:221]
	v_mul_f32_e32 v121, v122, v122
	v_mul_f32_e32 v235, v123, v123
	v_pk_add_f32 v[114:115], v[114:115], v[164:165]
	v_mov_b32_e32 v236, v238
	v_mov_b32_e32 v240, v239
	v_mov_b32_e32 v120, v122
	v_mov_b32_e32 v234, v123
	v_pk_add_f32 v[112:113], v[112:113], v[114:115]
	v_pk_add_f32 v[114:115], v[236:237], v[240:241]
	v_pk_add_f32 v[120:121], v[120:121], v[234:235]
	v_mul_f32_e32 v141, v136, v136
	v_mul_f32_e32 v143, v137, v137
	v_mul_f32_e32 v251, v138, v138
	v_mul_f32_e32 v253, v139, v139
	v_pk_add_f32 v[114:115], v[114:115], v[120:121]
	v_mov_b32_e32 v140, v136
	v_mov_b32_e32 v142, v137
	v_mov_b32_e32 v250, v138
	v_mov_b32_e32 v252, v139
	v_pk_add_f32 v[112:113], v[112:113], v[114:115]
	v_pk_add_f32 v[114:115], v[140:141], v[142:143]
	v_pk_add_f32 v[120:121], v[250:251], v[252:253]
	s_nop 0
	v_pk_add_f32 v[114:115], v[114:115], v[120:121]
	s_nop 0
	v_pk_add_f32 v[112:113], v[112:113], v[114:115]
	s_waitcnt lgkmcnt(0)
	v_mov_b32_e32 v114, v112
	v_mov_b32_e32 v115, v113
	s_nop 1
	v_permlane16_swap_b32_e32 v114, v112
	v_permlane16_swap_b32_e32 v115, v113
	s_nop 0
	v_pk_add_f32 v[112:113], v[112:113], v[114:115]
	ds_bpermute_b32 v114, v247, v112
	ds_bpermute_b32 v115, v247, v113
	s_and_saveexec_b64 s[60:61], s[4:5]
	s_cbranch_execz .LBB0_2473
	v_lshl_add_u64 v[120:121], s[76:77], 0, v[208:209]
	v_lshl_add_u64 v[120:121], s[50:51], 3, v[120:121]
	s_lshl_b32 s16, s81, 3
	v_lshl_add_u64 v[120:121], v[120:121], 0, s[16:17]
	s_waitcnt lgkmcnt(0)
	v_pk_add_f32 v[112:113], v[112:113], v[114:115]
	global_store_dwordx2 v[120:121], v[112:113], off
; DI void row_stats(const f32x2v* st, size_t row, int fq, float& mu, float& rstd) {
;     ...
;     mu = s1 * (1.0f / 1024.0f); const float var = fmaxf(s2 * (1.0f / 1024.0f) - mu * mu, 0.f); rstd = rsqrtf(var + LN_EPS);
.LBB0_2473:
	s_or_b64 exec, exec, s[60:61]
	s_waitcnt lgkmcnt(0)
	global_load_dwordx4 v[112:115], v[180:181], off
	global_load_dwordx4 v[120:123], v[178:179], off
	global_load_dwordx4 v[136:139], v[178:179], off offset:16
	global_load_dwordx4 v[140:143], v[180:181], off offset:16
	v_pk_add_f32 v[208:209], v[210:211], v[212:213]
	v_lshlrev_b32_e32 v213, 16, v150
	v_and_b32_e32 v214, 0xffff0000, v150
	v_lshlrev_b32_e32 v215, 16, v151
	v_and_b32_e32 v216, 0xffff0000, v151
	v_pk_mul_f32 v[150:151], v[208:209], s[30:31] op_sel_hi:[1,0]
	v_lshlrev_b32_e32 v165, 16, v148
	v_fma_f32 v151, -v150, v150, v151
	v_max_f32_e32 v151, 0, v151
	v_add_f32_e32 v151, 0x3727c5ac, v151
	v_and_b32_e32 v210, 0xffff0000, v148
	v_lshlrev_b32_e32 v211, 16, v149
	v_and_b32_e32 v212, 0xffff0000, v149
	v_lshl_add_u64 v[148:149], s[44:45], 0, v[206:207]
	v_sub_f32_e32 v206, v165, v150
	v_mul_f32_e32 v165, 0x4b800000, v151
	v_cmp_gt_f32_e32 vcc, s92, v151
	v_sub_f32_e32 v207, v210, v150
	v_sub_f32_e32 v209, v212, v150
	v_cndmask_b32_e32 v151, v151, v165, vcc
	v_rsq_f32_e32 v151, v151
	v_sub_f32_e32 v208, v211, v150
	v_sub_f32_e32 v211, v214, v150
	v_sub_f32_e32 v210, v213, v150
	v_mul_f32_e32 v165, 0x45800000, v151
	v_sub_f32_e32 v213, v216, v150
	v_sub_f32_e32 v212, v215, v150
	v_cndmask_b32_e32 v214, v151, v165, vcc
	v_pk_mul_f32 v[208:209], v[208:209], v[214:215] op_sel_hi:[1,0]
	v_pk_mul_f32 v[206:207], v[206:207], v[214:215] op_sel_hi:[1,0]
	v_pk_mul_f32 v[212:213], v[212:213], v[214:215] op_sel_hi:[1,0]
	v_pk_mul_f32 v[210:211], v[210:211], v[214:215] op_sel_hi:[1,0]
	v_lshl_add_u64 v[148:149], v[176:177], 1, v[148:149]
	v_lshlrev_b32_e32 v151, 16, v144
	v_and_b32_e32 v144, 0xffff0000, v144
	v_lshlrev_b32_e32 v165, 16, v145
	s_waitcnt vmcnt(2)
	v_pk_fma_f32 v[112:113], v[206:207], v[120:121], v[112:113]
	v_pk_fma_f32 v[114:115], v[208:209], v[122:123], v[114:115]
	s_waitcnt vmcnt(0)
	v_pk_fma_f32 v[120:121], v[210:211], v[136:137], v[140:141]
	v_pk_fma_f32 v[122:123], v[212:213], v[138:139], v[142:143]
	v_pk_fma_f32 v[136:137], v[114:115], s[34:35], v[110:111] op_sel_hi:[1,0,1]
	v_pk_fma_f32 v[138:139], v[112:113], s[34:35], v[108:109] op_sel_hi:[1,0,1]
	v_pk_fma_f32 v[140:141], v[122:123], s[34:35], v[106:107] op_sel_hi:[1,0,1]
	v_pk_fma_f32 v[142:143], v[120:121], s[34:35], v[104:105] op_sel_hi:[1,0,1]
	v_cvt_pk_bf16_f32 v104, v138, v139
	v_cvt_pk_bf16_f32 v105, v136, v137
	v_cvt_pk_bf16_f32 v106, v142, v143
	v_cvt_pk_bf16_f32 v107, v140, v141
	global_store_dwordx4 v[148:149], v[104:107], off
	global_load_dwordx4 v[104:107], v[154:155], off
	s_nop 0
	global_load_dwordx4 v[108:111], v[152:153], off
	global_load_dwordx4 v[112:115], v[152:153], off offset:16
	global_load_dwordx4 v[120:123], v[154:155], off offset:16
	v_and_b32_e32 v206, 0xffff0000, v145
	v_lshlrev_b32_e32 v208, 16, v146
	v_and_b32_e32 v207, 0xffff0000, v146
	v_lshlrev_b32_e32 v209, 16, v147
	v_and_b32_e32 v210, 0xffff0000, v147
	v_sub_f32_e32 v145, v144, v150
	v_sub_f32_e32 v144, v151, v150
	v_sub_f32_e32 v147, v206, v150
	v_sub_f32_e32 v146, v165, v150
	v_sub_f32_e32 v207, v207, v150
	v_sub_f32_e32 v206, v208, v150
	v_sub_f32_e32 v151, v210, v150
	v_sub_f32_e32 v150, v209, v150
	v_pk_mul_f32 v[146:147], v[146:147], v[214:215] op_sel_hi:[1,0]
	v_pk_mul_f32 v[144:145], v[144:145], v[214:215] op_sel_hi:[1,0]
	v_pk_mul_f32 v[150:151], v[150:151], v[214:215] op_sel_hi:[1,0]
	v_pk_mul_f32 v[206:207], v[206:207], v[214:215] op_sel_hi:[1,0]
	v_mul_f32_e32 v216, v140, v140
	v_add_f32_e32 v208, v138, v139
	v_add_f32_e32 v210, v136, v137
	v_mul_f32_e32 v213, v138, v138
	v_mul_f32_e32 v139, v139, v139
	v_mul_f32_e32 v215, v136, v136
	v_mul_f32_e32 v137, v137, v137
	v_mul_f32_e32 v209, v142, v142
	v_mul_f32_e32 v211, v143, v143
	v_mov_b32_e32 v212, v142
	v_mov_b32_e32 v138, v143
	v_mov_b32_e32 v214, v140
	v_mov_b32_e32 v136, v141
	v_pk_fma_f32 v[140:141], v[140:141], v[140:141], v[216:217] op_sel_hi:[1,1,0]
	v_pk_add_f32 v[138:139], v[212:213], v[138:139]
	v_pk_add_f32 v[136:137], v[214:215], v[136:137]
	v_pk_add_f32 v[142:143], v[208:209], v[210:211]
	v_mov_b32_e32 v165, v141
	v_pk_add_f32 v[136:137], v[138:139], v[136:137]
	v_pk_add_f32 v[138:139], v[142:143], v[164:165]
	s_waitcnt vmcnt(2)
	v_pk_fma_f32 v[104:105], v[144:145], v[108:109], v[104:105]
	v_pk_fma_f32 v[106:107], v[146:147], v[110:111], v[106:107]
	s_waitcnt vmcnt(0)
	v_pk_fma_f32 v[108:109], v[206:207], v[112:113], v[120:121]
	v_pk_fma_f32 v[110:111], v[150:151], v[114:115], v[122:123]
	v_pk_fma_f32 v[102:103], v[106:107], s[34:35], v[102:103] op_sel_hi:[1,0,1]
	v_pk_fma_f32 v[100:101], v[104:105], s[34:35], v[100:101] op_sel_hi:[1,0,1]
	v_pk_fma_f32 v[104:105], v[110:111], s[34:35], v[98:99] op_sel_hi:[1,0,1]
	v_pk_fma_f32 v[106:107], v[108:109], s[34:35], v[96:97] op_sel_hi:[1,0,1]
	v_mul_f32_e32 v97, v100, v100
	v_mul_f32_e32 v99, v101, v101
	v_mul_f32_e32 v109, v102, v102
	v_mul_f32_e32 v111, v103, v103
	v_mov_b32_e32 v96, v100
	v_mov_b32_e32 v98, v101
	v_mov_b32_e32 v108, v102
	v_mov_b32_e32 v110, v103
	v_mul_f32_e32 v113, v106, v106
	v_mul_f32_e32 v115, v107, v107
	v_mul_f32_e32 v121, v104, v104
	v_mul_f32_e32 v123, v105, v105
	v_mov_b32_e32 v112, v106
	v_mov_b32_e32 v114, v107
	v_mov_b32_e32 v120, v104
	v_mov_b32_e32 v122, v105
	v_pk_add_f32 v[96:97], v[96:97], v[98:99]
	v_pk_add_f32 v[98:99], v[108:109], v[110:111]
	v_pk_add_f32 v[136:137], v[136:137], v[138:139]
	v_pk_add_f32 v[108:109], v[112:113], v[114:115]
	v_pk_add_f32 v[110:111], v[120:121], v[122:123]
	v_pk_add_f32 v[96:97], v[96:97], v[98:99]
	v_pk_add_f32 v[98:99], v[108:109], v[110:111]
	v_pk_add_f32 v[96:97], v[136:137], v[96:97]
	v_cvt_pk_bf16_f32 v100, v100, v101
	v_pk_add_f32 v[96:97], v[96:97], v[98:99]
	v_cvt_pk_bf16_f32 v101, v102, v103
	v_cvt_pk_bf16_f32 v102, v106, v107
	v_cvt_pk_bf16_f32 v103, v104, v105
	global_store_dwordx4 v[148:149], v[100:103], off offset:256
	s_waitcnt lgkmcnt(0)
	v_mov_b32_e32 v98, v96
	v_mov_b32_e32 v99, v97
	s_nop 1
	v_permlane16_swap_b32_e32 v98, v96
	v_permlane16_swap_b32_e32 v99, v97
	s_nop 0
	v_pk_add_f32 v[96:97], v[96:97], v[98:99]
	ds_bpermute_b32 v98, v247, v96
	ds_bpermute_b32 v99, v247, v97
	s_and_saveexec_b64 s[60:61], s[4:5]
	s_cbranch_execz .LBB0_2475
	v_lshl_add_u64 v[100:101], s[76:77], 0, v[204:205]
	v_lshl_add_u64 v[100:101], s[50:51], 3, v[100:101]
	s_lshl_b32 s16, s81, 3
	v_lshl_add_u64 v[100:101], v[100:101], 0, s[16:17]
	s_waitcnt lgkmcnt(0)
	v_pk_add_f32 v[96:97], v[96:97], v[98:99]
	global_store_dwordx2 v[100:101], v[96:97], off
; DI void row_stats(const f32x2v* st, size_t row, int fq, float& mu, float& rstd) {
;     ...
;     mu = s1 * (1.0f / 1024.0f); const float var = fmaxf(s2 * (1.0f / 1024.0f) - mu * mu, 0.f); rstd = rsqrtf(var + LN_EPS);
.LBB0_2475:
	s_or_b64 exec, exec, s[60:61]
	s_waitcnt lgkmcnt(0)
	global_load_dwordx4 v[96:99], v[180:181], off
	global_load_dwordx4 v[100:103], v[178:179], off
	global_load_dwordx4 v[104:107], v[178:179], off offset:16
	global_load_dwordx4 v[108:111], v[180:181], off offset:16
	v_pk_add_f32 v[112:113], v[200:201], v[202:203]
	v_lshlrev_b32_e32 v120, 16, v132
	v_pk_mul_f32 v[112:113], v[112:113], s[30:31] op_sel_hi:[1,0]
	v_and_b32_e32 v121, 0xffff0000, v132
	v_fma_f32 v113, -v112, v112, v113
	v_max_f32_e32 v113, 0, v113
	v_add_f32_e32 v113, 0x3727c5ac, v113
	v_mul_f32_e32 v136, 0x4b800000, v113
	v_cmp_gt_f32_e32 vcc, s92, v113
	v_lshlrev_b32_e32 v122, 16, v133
	v_and_b32_e32 v123, 0xffff0000, v133
	v_cndmask_b32_e32 v113, v113, v136, vcc
	v_rsq_f32_e32 v113, v113
	v_lshlrev_b32_e32 v132, 16, v134
	v_and_b32_e32 v133, 0xffff0000, v134
	v_lshlrev_b32_e32 v134, 16, v135
	v_and_b32_e32 v135, 0xffff0000, v135
	v_mul_f32_e32 v136, 0x45800000, v113
	v_sub_f32_e32 v121, v121, v112
	v_sub_f32_e32 v120, v120, v112
	v_sub_f32_e32 v123, v123, v112
	v_sub_f32_e32 v122, v122, v112
	v_sub_f32_e32 v133, v133, v112
	v_sub_f32_e32 v132, v132, v112
	v_sub_f32_e32 v135, v135, v112
	v_sub_f32_e32 v134, v134, v112
	v_cndmask_b32_e32 v136, v113, v136, vcc
	v_pk_mul_f32 v[122:123], v[122:123], v[136:137] op_sel_hi:[1,0]
	v_pk_mul_f32 v[120:121], v[120:121], v[136:137] op_sel_hi:[1,0]
	v_pk_mul_f32 v[134:135], v[134:135], v[136:137] op_sel_hi:[1,0]
	v_pk_mul_f32 v[132:133], v[132:133], v[136:137] op_sel_hi:[1,0]
	v_lshl_add_u64 v[114:115], s[44:45], 0, v[198:199]
	v_lshl_add_u64 v[114:115], v[176:177], 1, v[114:115]
	v_lshlrev_b32_e32 v113, 16, v128
	s_waitcnt vmcnt(2)
	v_pk_fma_f32 v[96:97], v[120:121], v[100:101], v[96:97]
	v_pk_fma_f32 v[98:99], v[122:123], v[102:103], v[98:99]
	s_waitcnt vmcnt(0)
	v_pk_fma_f32 v[100:101], v[132:133], v[104:105], v[108:109]
	v_pk_fma_f32 v[102:103], v[134:135], v[106:107], v[110:111]
	v_pk_fma_f32 v[104:105], v[98:99], s[34:35], v[94:95] op_sel_hi:[1,0,1]
	v_pk_fma_f32 v[106:107], v[96:97], s[34:35], v[92:93] op_sel_hi:[1,0,1]
	v_pk_fma_f32 v[108:109], v[102:103], s[34:35], v[90:91] op_sel_hi:[1,0,1]
	v_pk_fma_f32 v[110:111], v[100:101], s[34:35], v[88:89] op_sel_hi:[1,0,1]
	v_cvt_pk_bf16_f32 v88, v106, v107
	v_cvt_pk_bf16_f32 v89, v104, v105
	v_cvt_pk_bf16_f32 v90, v110, v111
	v_cvt_pk_bf16_f32 v91, v108, v109
	global_store_dwordx4 v[114:115], v[88:91], off
	global_load_dwordx4 v[88:91], v[154:155], off
	s_nop 0
	global_load_dwordx4 v[92:95], v[152:153], off
	global_load_dwordx4 v[96:99], v[152:153], off offset:16
	global_load_dwordx4 v[100:103], v[154:155], off offset:16
	v_and_b32_e32 v120, 0xffff0000, v128
	v_lshlrev_b32_e32 v122, 16, v129
	v_and_b32_e32 v123, 0xffff0000, v129
	v_lshlrev_b32_e32 v128, 16, v130
	v_and_b32_e32 v129, 0xffff0000, v130
	v_lshlrev_b32_e32 v130, 16, v131
	v_and_b32_e32 v131, 0xffff0000, v131
	v_sub_f32_e32 v121, v120, v112
	v_sub_f32_e32 v120, v113, v112
	v_sub_f32_e32 v123, v123, v112
	v_sub_f32_e32 v122, v122, v112
	v_sub_f32_e32 v129, v129, v112
	v_sub_f32_e32 v128, v128, v112
	v_sub_f32_e32 v113, v131, v112
	v_sub_f32_e32 v112, v130, v112
	v_pk_mul_f32 v[122:123], v[122:123], v[136:137] op_sel_hi:[1,0]
	v_pk_mul_f32 v[120:121], v[120:121], v[136:137] op_sel_hi:[1,0]
	v_pk_mul_f32 v[112:113], v[112:113], v[136:137] op_sel_hi:[1,0]
	v_pk_mul_f32 v[128:129], v[128:129], v[136:137] op_sel_hi:[1,0]
	v_mul_f32_e32 v138, v108, v108
	v_add_f32_e32 v130, v106, v107
	v_add_f32_e32 v132, v104, v105
	v_mul_f32_e32 v135, v106, v106
	v_mul_f32_e32 v107, v107, v107
	v_mul_f32_e32 v137, v104, v104
	v_mul_f32_e32 v105, v105, v105
	v_mul_f32_e32 v131, v110, v110
	v_mul_f32_e32 v133, v111, v111
	v_mov_b32_e32 v134, v110
	v_mov_b32_e32 v106, v111
	v_mov_b32_e32 v136, v108
	v_mov_b32_e32 v104, v109
	v_pk_fma_f32 v[108:109], v[108:109], v[108:109], v[138:139] op_sel_hi:[1,1,0]
	v_pk_add_f32 v[106:107], v[134:135], v[106:107]
	v_pk_add_f32 v[104:105], v[136:137], v[104:105]
	v_pk_add_f32 v[110:111], v[130:131], v[132:133]
	v_mov_b32_e32 v165, v109
	v_pk_add_f32 v[104:105], v[106:107], v[104:105]
	v_pk_add_f32 v[106:107], v[110:111], v[164:165]
	s_waitcnt vmcnt(2)
	v_pk_fma_f32 v[88:89], v[120:121], v[92:93], v[88:89]
	v_pk_fma_f32 v[90:91], v[122:123], v[94:95], v[90:91]
	s_waitcnt vmcnt(0)
	v_pk_fma_f32 v[92:93], v[128:129], v[96:97], v[100:101]
	v_pk_fma_f32 v[94:95], v[112:113], v[98:99], v[102:103]
	v_pk_fma_f32 v[86:87], v[90:91], s[34:35], v[86:87] op_sel_hi:[1,0,1]
	v_pk_fma_f32 v[84:85], v[88:89], s[34:35], v[84:85] op_sel_hi:[1,0,1]
	v_pk_fma_f32 v[88:89], v[94:95], s[34:35], v[82:83] op_sel_hi:[1,0,1]
	v_pk_fma_f32 v[90:91], v[92:93], s[34:35], v[80:81] op_sel_hi:[1,0,1]
	v_mul_f32_e32 v81, v84, v84
	v_mul_f32_e32 v83, v85, v85
	v_mul_f32_e32 v93, v86, v86
	v_mul_f32_e32 v95, v87, v87
	v_mov_b32_e32 v80, v84
	v_mov_b32_e32 v82, v85
	v_mov_b32_e32 v92, v86
	v_mov_b32_e32 v94, v87
	v_mul_f32_e32 v97, v90, v90
	v_mul_f32_e32 v99, v91, v91
	v_mul_f32_e32 v101, v88, v88
	v_mul_f32_e32 v103, v89, v89
	v_mov_b32_e32 v96, v90
	v_mov_b32_e32 v98, v91
	v_mov_b32_e32 v100, v88
	v_mov_b32_e32 v102, v89
	v_pk_add_f32 v[80:81], v[80:81], v[82:83]
	v_pk_add_f32 v[82:83], v[92:93], v[94:95]
	v_pk_add_f32 v[104:105], v[104:105], v[106:107]
	v_pk_add_f32 v[92:93], v[96:97], v[98:99]
	v_pk_add_f32 v[94:95], v[100:101], v[102:103]
	v_pk_add_f32 v[80:81], v[80:81], v[82:83]
	v_pk_add_f32 v[82:83], v[92:93], v[94:95]
	v_pk_add_f32 v[80:81], v[104:105], v[80:81]
	v_cvt_pk_bf16_f32 v84, v84, v85
	v_pk_add_f32 v[80:81], v[80:81], v[82:83]
	v_cvt_pk_bf16_f32 v85, v86, v87
	v_cvt_pk_bf16_f32 v86, v90, v91
	v_cvt_pk_bf16_f32 v87, v88, v89
	global_store_dwordx4 v[114:115], v[84:87], off offset:256
	s_waitcnt lgkmcnt(0)
	v_mov_b32_e32 v82, v80
	v_mov_b32_e32 v83, v81
	s_nop 1
	v_permlane16_swap_b32_e32 v82, v80
	v_permlane16_swap_b32_e32 v83, v81
	s_nop 0
	v_pk_add_f32 v[80:81], v[80:81], v[82:83]
	ds_bpermute_b32 v82, v247, v80
	ds_bpermute_b32 v83, v247, v81
	s_and_saveexec_b64 s[60:61], s[4:5]
	s_cbranch_execz .LBB0_2477
	v_lshl_add_u64 v[84:85], s[76:77], 0, v[196:197]
	v_lshl_add_u64 v[84:85], s[50:51], 3, v[84:85]
	s_lshl_b32 s16, s81, 3
	v_lshl_add_u64 v[84:85], v[84:85], 0, s[16:17]
	s_waitcnt lgkmcnt(0)
	v_pk_add_f32 v[80:81], v[80:81], v[82:83]
	global_store_dwordx2 v[84:85], v[80:81], off
; DI void row_stats(const f32x2v* st, size_t row, int fq, float& mu, float& rstd) {
;     ...
;     mu = s1 * (1.0f / 1024.0f); const float var = fmaxf(s2 * (1.0f / 1024.0f) - mu * mu, 0.f); rstd = rsqrtf(var + LN_EPS);
.LBB0_2477:
	s_or_b64 exec, exec, s[60:61]
	s_waitcnt lgkmcnt(0)
	global_load_dwordx4 v[80:83], v[180:181], off
	global_load_dwordx4 v[84:87], v[178:179], off
	global_load_dwordx4 v[88:91], v[178:179], off offset:16
	global_load_dwordx4 v[92:95], v[180:181], off offset:16
	v_pk_add_f32 v[96:97], v[190:191], v[194:195]
	v_lshlrev_b32_e32 v100, 16, v124
	v_pk_mul_f32 v[96:97], v[96:97], s[30:31] op_sel_hi:[1,0]
	v_and_b32_e32 v101, 0xffff0000, v124
	v_fma_f32 v97, -v96, v96, v97
	v_max_f32_e32 v97, 0, v97
	v_add_f32_e32 v97, 0x3727c5ac, v97
	v_mul_f32_e32 v108, 0x4b800000, v97
	v_cmp_gt_f32_e32 vcc, s92, v97
	v_lshlrev_b32_e32 v102, 16, v125
	v_and_b32_e32 v103, 0xffff0000, v125
	v_cndmask_b32_e32 v97, v97, v108, vcc
	v_rsq_f32_e32 v97, v97
	v_lshlrev_b32_e32 v104, 16, v126
	v_and_b32_e32 v105, 0xffff0000, v126
	v_lshlrev_b32_e32 v106, 16, v127
	v_and_b32_e32 v107, 0xffff0000, v127
	v_mul_f32_e32 v108, 0x45800000, v97
	v_sub_f32_e32 v101, v101, v96
	v_sub_f32_e32 v100, v100, v96
	v_sub_f32_e32 v103, v103, v96
	v_sub_f32_e32 v102, v102, v96
	v_sub_f32_e32 v105, v105, v96
	v_sub_f32_e32 v104, v104, v96
	v_sub_f32_e32 v107, v107, v96
	v_sub_f32_e32 v106, v106, v96
	v_cndmask_b32_e32 v108, v97, v108, vcc
	v_pk_mul_f32 v[102:103], v[102:103], v[108:109] op_sel_hi:[1,0]
	v_pk_mul_f32 v[100:101], v[100:101], v[108:109] op_sel_hi:[1,0]
	v_pk_mul_f32 v[106:107], v[106:107], v[108:109] op_sel_hi:[1,0]
	v_pk_mul_f32 v[104:105], v[104:105], v[108:109] op_sel_hi:[1,0]
	v_lshl_add_u64 v[98:99], s[44:45], 0, v[188:189]
	v_lshl_add_u64 v[98:99], v[176:177], 1, v[98:99]
	v_lshlrev_b32_e32 v97, 16, v116
	s_waitcnt vmcnt(2)
	v_pk_fma_f32 v[80:81], v[100:101], v[84:85], v[80:81]
	v_pk_fma_f32 v[82:83], v[102:103], v[86:87], v[82:83]
	s_waitcnt vmcnt(0)
	v_pk_fma_f32 v[84:85], v[104:105], v[88:89], v[92:93]
	v_pk_fma_f32 v[86:87], v[106:107], v[90:91], v[94:95]
	v_pk_fma_f32 v[88:89], v[82:83], s[34:35], v[78:79] op_sel_hi:[1,0,1]
	v_pk_fma_f32 v[90:91], v[80:81], s[34:35], v[76:77] op_sel_hi:[1,0,1]
	v_pk_fma_f32 v[92:93], v[86:87], s[34:35], v[74:75] op_sel_hi:[1,0,1]
	v_pk_fma_f32 v[94:95], v[84:85], s[34:35], v[72:73] op_sel_hi:[1,0,1]
	v_cvt_pk_bf16_f32 v72, v90, v91
	v_cvt_pk_bf16_f32 v73, v88, v89
	v_cvt_pk_bf16_f32 v74, v94, v95
	v_cvt_pk_bf16_f32 v75, v92, v93
	global_store_dwordx4 v[98:99], v[72:75], off
	global_load_dwordx4 v[72:75], v[154:155], off
	s_nop 0
	global_load_dwordx4 v[76:79], v[152:153], off
	global_load_dwordx4 v[80:83], v[152:153], off offset:16
	global_load_dwordx4 v[84:87], v[154:155], off offset:16
	v_and_b32_e32 v100, 0xffff0000, v116
	v_lshlrev_b32_e32 v102, 16, v117
	v_and_b32_e32 v103, 0xffff0000, v117
	v_lshlrev_b32_e32 v104, 16, v118
	v_and_b32_e32 v105, 0xffff0000, v118
	v_lshlrev_b32_e32 v106, 16, v119
	v_and_b32_e32 v107, 0xffff0000, v119
	v_sub_f32_e32 v101, v100, v96
	v_sub_f32_e32 v100, v97, v96
	v_sub_f32_e32 v103, v103, v96
	v_sub_f32_e32 v102, v102, v96
	v_sub_f32_e32 v105, v105, v96
	v_sub_f32_e32 v104, v104, v96
	v_sub_f32_e32 v97, v107, v96
	v_sub_f32_e32 v96, v106, v96
	v_pk_mul_f32 v[102:103], v[102:103], v[108:109] op_sel_hi:[1,0]
	v_pk_mul_f32 v[100:101], v[100:101], v[108:109] op_sel_hi:[1,0]
	v_pk_mul_f32 v[96:97], v[96:97], v[108:109] op_sel_hi:[1,0]
	v_pk_mul_f32 v[104:105], v[104:105], v[108:109] op_sel_hi:[1,0]
	v_mul_f32_e32 v114, v92, v92
	v_add_f32_e32 v106, v90, v91
	v_add_f32_e32 v108, v88, v89
	v_mul_f32_e32 v111, v90, v90
	v_mul_f32_e32 v91, v91, v91
	v_mul_f32_e32 v113, v88, v88
	v_mul_f32_e32 v89, v89, v89
	v_mul_f32_e32 v107, v94, v94
	v_mul_f32_e32 v109, v95, v95
	v_mov_b32_e32 v110, v94
	v_mov_b32_e32 v90, v95
	v_mov_b32_e32 v112, v92
	v_mov_b32_e32 v88, v93
	v_pk_fma_f32 v[92:93], v[92:93], v[92:93], v[114:115] op_sel_hi:[1,1,0]
	v_pk_add_f32 v[90:91], v[110:111], v[90:91]
	v_pk_add_f32 v[88:89], v[112:113], v[88:89]
	v_pk_add_f32 v[94:95], v[106:107], v[108:109]
	v_mov_b32_e32 v165, v93
	v_pk_add_f32 v[88:89], v[90:91], v[88:89]
	v_pk_add_f32 v[90:91], v[94:95], v[164:165]
	s_waitcnt vmcnt(2)
	v_pk_fma_f32 v[72:73], v[100:101], v[76:77], v[72:73]
	v_pk_fma_f32 v[74:75], v[102:103], v[78:79], v[74:75]
	s_waitcnt vmcnt(0)
	v_pk_fma_f32 v[76:77], v[104:105], v[80:81], v[84:85]
	v_pk_fma_f32 v[78:79], v[96:97], v[82:83], v[86:87]
	v_pk_fma_f32 v[70:71], v[74:75], s[34:35], v[70:71] op_sel_hi:[1,0,1]
	v_pk_fma_f32 v[68:69], v[72:73], s[34:35], v[68:69] op_sel_hi:[1,0,1]
	v_pk_fma_f32 v[72:73], v[78:79], s[34:35], v[66:67] op_sel_hi:[1,0,1]
	v_pk_fma_f32 v[74:75], v[76:77], s[34:35], v[64:65] op_sel_hi:[1,0,1]
	v_mul_f32_e32 v65, v68, v68
	v_mul_f32_e32 v67, v69, v69
	v_mul_f32_e32 v77, v70, v70
	v_mul_f32_e32 v79, v71, v71
	v_mov_b32_e32 v64, v68
	v_mov_b32_e32 v66, v69
	v_mov_b32_e32 v76, v70
	v_mov_b32_e32 v78, v71
	v_mul_f32_e32 v81, v74, v74
	v_mul_f32_e32 v83, v75, v75
	v_mul_f32_e32 v85, v72, v72
	v_mul_f32_e32 v87, v73, v73
	v_mov_b32_e32 v80, v74
	v_mov_b32_e32 v82, v75
	v_mov_b32_e32 v84, v72
	v_mov_b32_e32 v86, v73
	v_pk_add_f32 v[64:65], v[64:65], v[66:67]
	v_pk_add_f32 v[66:67], v[76:77], v[78:79]
	v_pk_add_f32 v[88:89], v[88:89], v[90:91]
	v_pk_add_f32 v[76:77], v[80:81], v[82:83]
	v_pk_add_f32 v[78:79], v[84:85], v[86:87]
	v_pk_add_f32 v[64:65], v[64:65], v[66:67]
	v_pk_add_f32 v[66:67], v[76:77], v[78:79]
	v_pk_add_f32 v[64:65], v[88:89], v[64:65]
	v_cvt_pk_bf16_f32 v68, v68, v69
	v_pk_add_f32 v[64:65], v[64:65], v[66:67]
	v_cvt_pk_bf16_f32 v69, v70, v71
	v_cvt_pk_bf16_f32 v70, v74, v75
	v_cvt_pk_bf16_f32 v71, v72, v73
	global_store_dwordx4 v[98:99], v[68:71], off offset:256
	s_waitcnt lgkmcnt(0)
	v_mov_b32_e32 v66, v64
	v_mov_b32_e32 v67, v65
	s_nop 1
	v_permlane16_swap_b32_e32 v66, v64
	v_permlane16_swap_b32_e32 v67, v65
	s_nop 0
	v_pk_add_f32 v[64:65], v[64:65], v[66:67]
	ds_bpermute_b32 v66, v247, v64
	ds_bpermute_b32 v67, v247, v65
	s_and_saveexec_b64 s[60:61], s[4:5]
	s_cbranch_execz .LBB0_2479
	v_lshl_add_u64 v[68:69], s[76:77], 0, v[186:187]
	v_lshl_add_u64 v[68:69], s[50:51], 3, v[68:69]
	s_lshl_b32 s16, s81, 3
	v_lshl_add_u64 v[68:69], v[68:69], 0, s[16:17]
	s_waitcnt lgkmcnt(0)
	v_pk_add_f32 v[64:65], v[64:65], v[66:67]
	global_store_dwordx2 v[68:69], v[64:65], off
; DI void row_stats(const f32x2v* st, size_t row, int fq, float& mu, float& rstd) {
;     const f32x4 a = *(const f32x4*)(st + row * 16 + 4 * fq), b = *(const f32x4*)(st + row * 16 + 4 * fq + 2);
;     float s1 = (a[0] + a[2]) + (b[0] + b[2]), s2 = (a[1] + a[3]) + (b[1] + b[3]);
;     s1 += __shfl_xor(s1, 16); s1 += __shfl_xor(s1, 32); s2 += __shfl_xor(s2, 16); s2 += __shfl_xor(s2, 32);
;     mu = s1 * (1.0f / 1024.0f); const float var = fmaxf(s2 * (1.0f / 1024.0f) - mu * mu, 0.f); rstd = rsqrtf(var + LN_EPS);
; }
.LBB0_2479:
	s_or_b64 exec, exec, s[60:61]
	v_lshl_add_u64 v[72:73], v[184:185], 0, s[24:25]
	v_lshlrev_b64 v[96:97], 7, v[72:73]
	v_lshl_add_u64 v[68:69], v[168:169], 0, v[96:97]
	s_waitcnt lgkmcnt(0)
	global_load_dwordx4 v[64:67], v[68:69], off
	s_nop 0
	global_load_dwordx4 v[68:71], v[68:69], off offset:16
	v_lshlrev_b64 v[94:95], 11, v[72:73]
	v_lshl_add_u64 v[98:99], v[182:183], 0, v[94:95]
	global_load_dwordx4 v[72:75], v[98:99], off
	global_load_dwordx4 v[76:79], v[180:181], off
	global_load_dwordx4 v[84:87], v[178:179], off
	global_load_dwordx4 v[90:93], v[178:179], off offset:16
	global_load_dwordx4 v[102:105], v[180:181], off offset:16
	v_lshl_add_u64 v[150:151], v[184:185], 0, s[36:37]
	v_lshl_add_u64 v[186:187], v[184:185], 0, s[38:39]
	v_lshl_add_u64 v[184:185], v[184:185], 0, s[40:41]
	v_lshlrev_b64 v[88:89], 7, v[150:151]
	v_lshlrev_b64 v[82:83], 7, v[186:187]
	v_lshlrev_b64 v[80:81], 7, v[184:185]
	v_lshl_add_u64 v[100:101], v[168:169], 0, v[88:89]
	v_lshl_add_u64 v[118:119], v[168:169], 0, v[82:83]
	global_load_dwordx4 v[106:109], v[100:101], off offset:16
	global_load_dwordx4 v[110:113], v[100:101], off
	global_load_dwordx4 v[114:117], v[118:119], off offset:16
	s_nop 0
	global_load_dwordx4 v[118:121], v[118:119], off
	v_lshl_add_u64 v[100:101], v[168:169], 0, v[80:81]
	v_lshl_add_u64 v[94:95], s[44:45], 0, v[94:95]
	global_load_dwordx4 v[122:125], v[100:101], off
	global_load_dwordx4 v[126:129], v[100:101], off offset:16
	global_load_dwordx4 v[130:133], v[98:99], off offset:256
	v_lshl_add_u64 v[100:101], v[176:177], 1, v[94:95]
	v_lshlrev_b64 v[98:99], 11, v[150:151]
	s_waitcnt vmcnt(13)
	v_pk_add_f32 v[64:65], v[64:65], v[66:67]
	s_waitcnt vmcnt(12)
	v_pk_add_f32 v[66:67], v[68:69], v[70:71]
	s_waitcnt vmcnt(11)
	v_lshlrev_b32_e32 v68, 16, v72
	v_pk_add_f32 v[64:65], v[64:65], v[66:67]
	v_lshlrev_b32_e32 v70, 16, v73
	v_and_b32_e32 v69, 0xffff0000, v72
	v_and_b32_e32 v71, 0xffff0000, v73
	v_and_b32_e32 v73, 0xffff0000, v74
	s_waitcnt lgkmcnt(0)
	v_mov_b32_e32 v66, v64
	v_mov_b32_e32 v67, v65
	s_nop 1
	v_permlane16_swap_b32_e32 v66, v64
	v_permlane16_swap_b32_e32 v67, v65
	s_nop 0
	v_pk_add_f32 v[64:65], v[64:65], v[66:67]
	v_lshlrev_b32_e32 v72, 16, v74
	v_lshlrev_b32_e32 v74, 16, v75
	v_and_b32_e32 v75, 0xffff0000, v75
	s_waitcnt lgkmcnt(0)
	v_mov_b32_e32 v66, v64
	v_mov_b32_e32 v67, v65
	s_nop 1
	v_permlane32_swap_b32_e32 v66, v64
	v_permlane32_swap_b32_e32 v67, v65
	s_nop 0
	v_pk_add_f32 v[64:65], v[64:65], v[66:67]
	s_nop 0
	v_pk_mul_f32 v[188:189], v[64:65], s[30:31] op_sel_hi:[1,0]
	s_nop 0
	v_fma_f32 v94, -v188, v188, v189
	v_sub_f32_e32 v64, v68, v188
	v_max_f32_e32 v68, 0, v94
	v_add_f32_e32 v68, 0x3727c5ac, v68
	v_sub_f32_e32 v66, v70, v188
	v_mul_f32_e32 v70, 0x4b800000, v68
	v_cmp_gt_f32_e32 vcc, s92, v68
	v_sub_f32_e32 v65, v69, v188
	v_sub_f32_e32 v69, v73, v188
	v_cndmask_b32_e32 v68, v68, v70, vcc
	v_rsq_f32_e32 v73, v68
	v_sub_f32_e32 v68, v72, v188
	v_sub_f32_e32 v67, v71, v188
	v_sub_f32_e32 v71, v75, v188
	v_mul_f32_e32 v72, 0x45800000, v73
	v_sub_f32_e32 v70, v74, v188
	v_cndmask_b32_e32 v190, v73, v72, vcc
	v_pk_mul_f32 v[66:67], v[66:67], v[190:191] op_sel_hi:[1,0]
	v_pk_mul_f32 v[64:65], v[64:65], v[190:191] op_sel_hi:[1,0]
	v_pk_mul_f32 v[70:71], v[70:71], v[190:191] op_sel_hi:[1,0]
	v_pk_mul_f32 v[68:69], v[68:69], v[190:191] op_sel_hi:[1,0]
	s_waitcnt vmcnt(9)
	v_pk_fma_f32 v[64:65], v[64:65], v[84:85], v[76:77]
	v_pk_fma_f32 v[66:67], v[66:67], v[86:87], v[78:79]
	s_waitcnt vmcnt(7)
	v_pk_fma_f32 v[68:69], v[68:69], v[90:91], v[102:103]
	v_pk_fma_f32 v[70:71], v[70:71], v[92:93], v[104:105]
	v_pk_fma_f32 v[194:195], v[66:67], s[34:35], v[62:63] op_sel_hi:[1,0,1]
	v_pk_fma_f32 v[196:197], v[64:65], s[34:35], v[60:61] op_sel_hi:[1,0,1]
	v_pk_fma_f32 v[198:199], v[70:71], s[34:35], v[58:59] op_sel_hi:[1,0,1]
	v_pk_fma_f32 v[200:201], v[68:69], s[34:35], v[56:57] op_sel_hi:[1,0,1]
	v_cvt_pk_bf16_f32 v56, v196, v197
	v_cvt_pk_bf16_f32 v57, v194, v195
	v_cvt_pk_bf16_f32 v58, v200, v201
	v_cvt_pk_bf16_f32 v59, v198, v199
	global_store_dwordx4 v[100:101], v[56:59], off
	global_load_dwordx4 v[134:137], v[154:155], off
	global_load_dwordx4 v[138:141], v[152:153], off
	global_load_dwordx4 v[142:145], v[152:153], off offset:16
	global_load_dwordx4 v[146:149], v[154:155], off offset:16
	v_lshlrev_b64 v[90:91], 11, v[186:187]
	v_lshlrev_b64 v[84:85], 11, v[184:185]
	v_lshl_add_u64 v[56:57], v[182:183], 0, v[98:99]
	v_lshl_add_u64 v[58:59], v[182:183], 0, v[90:91]
	v_lshl_add_u64 v[86:87], v[182:183], 0, v[84:85]
	global_load_dwordx4 v[76:79], v[56:57], off
	global_load_dwordx4 v[72:75], v[56:57], off offset:256
	global_load_dwordx4 v[68:71], v[58:59], off
	global_load_dwordx4 v[64:67], v[58:59], off offset:256
	global_load_dwordx4 v[60:63], v[86:87], off
	s_nop 0
	global_load_dwordx4 v[56:59], v[86:87], off offset:256
	s_waitcnt vmcnt(16)
	v_pk_add_f32 v[86:87], v[110:111], v[112:113]
	v_pk_add_f32 v[92:93], v[106:107], v[108:109]
	s_waitcnt vmcnt(14)
	v_pk_add_f32 v[94:95], v[118:119], v[120:121]
	v_pk_add_f32 v[102:103], v[114:115], v[116:117]
	s_waitcnt vmcnt(13)
	v_pk_add_f32 v[104:105], v[122:123], v[124:125]
	s_waitcnt vmcnt(12)
	v_pk_add_f32 v[106:107], v[126:127], v[128:129]
	v_pk_add_f32 v[86:87], v[86:87], v[92:93]
	v_pk_add_f32 v[92:93], v[94:95], v[102:103]
	v_pk_add_f32 v[94:95], v[104:105], v[106:107]
	ds_bpermute_b32 v102, v248, v86
	ds_bpermute_b32 v103, v248, v87
	ds_bpermute_b32 v106, v248, v94
	ds_bpermute_b32 v107, v248, v95
	s_waitcnt vmcnt(11)
; DI void row_stats(const f32x2v* st, size_t row, int fq, float& mu, float& rstd) {
;     const f32x4 a = *(const f32x4*)(st + row * 16 + 4 * fq), b = *(const f32x4*)(st + row * 16 + 4 * fq + 2);
;     float s1 = (a[0] + a[2]) + (b[0] + b[2]), s2 = (a[1] + a[3]) + (b[1] + b[3]);
;     s1 += __shfl_xor(s1, 16); s1 += __shfl_xor(s1, 32); s2 += __shfl_xor(s2, 16); s2 += __shfl_xor(s2, 32);
	v_lshlrev_b32_e32 v108, 16, v130
	v_and_b32_e32 v109, 0xffff0000, v130
	v_lshlrev_b32_e32 v110, 16, v131
	v_and_b32_e32 v111, 0xffff0000, v131
	v_lshlrev_b32_e32 v112, 16, v132
	v_and_b32_e32 v113, 0xffff0000, v132
	v_lshlrev_b32_e32 v114, 16, v133
	v_and_b32_e32 v115, 0xffff0000, v133
	s_waitcnt lgkmcnt(2)
	v_pk_add_f32 v[102:103], v[86:87], v[102:103]
	s_waitcnt lgkmcnt(0)
	v_pk_add_f32 v[86:87], v[94:95], v[106:107]
	v_sub_f32_e32 v107, v109, v188
	v_sub_f32_e32 v106, v108, v188
	v_sub_f32_e32 v109, v111, v188
	v_sub_f32_e32 v108, v110, v188
	v_sub_f32_e32 v111, v113, v188
	v_sub_f32_e32 v110, v112, v188
	v_sub_f32_e32 v113, v115, v188
	v_sub_f32_e32 v112, v114, v188
	v_pk_mul_f32 v[108:109], v[108:109], v[190:191] op_sel_hi:[1,0]
	v_pk_mul_f32 v[106:107], v[106:107], v[190:191] op_sel_hi:[1,0]
	v_mul_f32_e32 v126, v198, v198
	v_pk_mul_f32 v[112:113], v[112:113], v[190:191] op_sel_hi:[1,0]
	v_pk_mul_f32 v[110:111], v[110:111], v[190:191] op_sel_hi:[1,0]
	v_add_f32_e32 v114, v196, v197
	v_add_f32_e32 v116, v194, v195
	v_mul_f32_e32 v119, v196, v196
	v_mul_f32_e32 v121, v197, v197
	v_mul_f32_e32 v123, v194, v194
	v_mul_f32_e32 v125, v195, v195
	v_mul_f32_e32 v115, v200, v200
	v_mul_f32_e32 v117, v201, v201
	v_mov_b32_e32 v118, v200
	v_mov_b32_e32 v120, v201
	v_mov_b32_e32 v122, v198
	v_mov_b32_e32 v124, v199
	v_pk_fma_f32 v[126:127], v[198:199], v[198:199], v[126:127] op_sel_hi:[1,1,0]
	v_pk_add_f32 v[118:119], v[118:119], v[120:121]
	v_pk_add_f32 v[120:121], v[122:123], v[124:125]
	v_pk_add_f32 v[114:115], v[114:115], v[116:117]
	v_mov_b32_e32 v165, v127
	v_pk_add_f32 v[116:117], v[118:119], v[120:121]
	v_pk_add_f32 v[114:115], v[114:115], v[164:165]
	v_pk_add_f32 v[114:115], v[116:117], v[114:115]
	s_waitcnt lgkmcnt(0)
	v_mov_b32_e32 v104, v92
	v_mov_b32_e32 v105, v93
	s_nop 1
	v_permlane16_swap_b32_e32 v104, v92
	v_permlane16_swap_b32_e32 v105, v93
	s_nop 0
	v_pk_add_f32 v[92:93], v[92:93], v[104:105]
	ds_bpermute_b32 v104, v247, v102
	ds_bpermute_b32 v105, v247, v103
	ds_bpermute_b32 v94, v247, v92
	ds_bpermute_b32 v95, v247, v93
	s_waitcnt vmcnt(8)
	v_pk_fma_f32 v[106:107], v[106:107], v[138:139], v[134:135]
	v_pk_fma_f32 v[108:109], v[108:109], v[140:141], v[136:137]
	s_waitcnt vmcnt(6)
	v_pk_fma_f32 v[110:111], v[110:111], v[142:143], v[146:147]
	v_pk_fma_f32 v[112:113], v[112:113], v[144:145], v[148:149]
	v_pk_fma_f32 v[54:55], v[108:109], s[34:35], v[54:55] op_sel_hi:[1,0,1]
	v_pk_fma_f32 v[52:53], v[106:107], s[34:35], v[52:53] op_sel_hi:[1,0,1]
	v_pk_fma_f32 v[112:113], v[112:113], s[34:35], v[50:51] op_sel_hi:[1,0,1]
	v_pk_fma_f32 v[108:109], v[110:111], s[34:35], v[48:49] op_sel_hi:[1,0,1]
	v_mul_f32_e32 v49, v52, v52
	v_mul_f32_e32 v51, v53, v53
	v_mul_f32_e32 v107, v54, v54
	v_mul_f32_e32 v111, v55, v55
	v_mov_b32_e32 v48, v52
	v_mov_b32_e32 v50, v53
	v_mov_b32_e32 v106, v54
	v_mov_b32_e32 v110, v55
	v_mul_f32_e32 v117, v108, v108
	v_mul_f32_e32 v119, v109, v109
	v_mul_f32_e32 v121, v112, v112
	v_mul_f32_e32 v123, v113, v113
	v_mov_b32_e32 v116, v108
	v_mov_b32_e32 v118, v109
	v_mov_b32_e32 v120, v112
	v_mov_b32_e32 v122, v113
	v_pk_add_f32 v[48:49], v[48:49], v[50:51]
	v_pk_add_f32 v[50:51], v[106:107], v[110:111]
	v_pk_add_f32 v[106:107], v[116:117], v[118:119]
	v_pk_add_f32 v[110:111], v[120:121], v[122:123]
	v_pk_add_f32 v[48:49], v[48:49], v[50:51]
	v_pk_add_f32 v[50:51], v[106:107], v[110:111]
	v_pk_add_f32 v[48:49], v[114:115], v[48:49]
	v_cvt_pk_bf16_f32 v106, v52, v53
	v_pk_add_f32 v[50:51], v[48:49], v[50:51]
	ds_bpermute_b32 v48, v247, v86
	ds_bpermute_b32 v49, v247, v87
	v_cvt_pk_bf16_f32 v107, v54, v55
	v_cvt_pk_bf16_f32 v108, v108, v109
	s_waitcnt lgkmcnt(2)
	v_mov_b32_e32 v110, v50
	v_mov_b32_e32 v111, v51
	s_nop 1
	v_permlane16_swap_b32_e32 v110, v50
	v_permlane16_swap_b32_e32 v111, v51
	s_nop 0
	v_pk_add_f32 v[50:51], v[50:51], v[110:111]
	ds_bpermute_b32 v52, v247, v50
	ds_bpermute_b32 v53, v247, v51
	v_cvt_pk_bf16_f32 v109, v112, v113
	global_store_dwordx4 v[100:101], v[106:109], off offset:256
	s_and_saveexec_b64 s[60:61], s[4:5]
	s_cbranch_execz .LBB0_2481
	v_lshl_add_u64 v[54:55], s[76:77], 0, v[96:97]
	v_lshl_add_u64 v[54:55], s[50:51], 3, v[54:55]
	s_lshl_b32 s16, s81, 3
	v_lshl_add_u64 v[54:55], v[54:55], 0, s[16:17]
	s_waitcnt lgkmcnt(0)
	v_pk_add_f32 v[50:51], v[50:51], v[52:53]
	global_store_dwordx2 v[54:55], v[50:51], off
; DI void row_stats(const f32x2v* st, size_t row, int fq, float& mu, float& rstd) {
;     ...
;     mu = s1 * (1.0f / 1024.0f); const float var = fmaxf(s2 * (1.0f / 1024.0f) - mu * mu, 0.f); rstd = rsqrtf(var + LN_EPS);
.LBB0_2481:
	s_or_b64 exec, exec, s[60:61]
	s_waitcnt lgkmcnt(0)
	global_load_dwordx4 v[50:53], v[180:181], off
	global_load_dwordx4 v[106:109], v[178:179], off
	global_load_dwordx4 v[110:113], v[178:179], off offset:16
	global_load_dwordx4 v[114:117], v[180:181], off offset:16
	v_pk_add_f32 v[54:55], v[102:103], v[104:105]
	s_waitcnt vmcnt(10)
	v_lshlrev_b32_e32 v100, 16, v76
	v_pk_mul_f32 v[54:55], v[54:55], s[30:31] op_sel_hi:[1,0]
	v_and_b32_e32 v101, 0xffff0000, v76
	v_fma_f32 v55, -v54, v54, v55
	v_max_f32_e32 v55, 0, v55
	v_add_f32_e32 v55, 0x3727c5ac, v55
	v_lshlrev_b32_e32 v102, 16, v77
	v_and_b32_e32 v103, 0xffff0000, v77
	v_lshl_add_u64 v[76:77], s[44:45], 0, v[98:99]
	v_mul_f32_e32 v98, 0x4b800000, v55
	v_cmp_gt_f32_e32 vcc, s92, v55
	v_lshlrev_b32_e32 v104, 16, v78
	v_and_b32_e32 v105, 0xffff0000, v78
	v_cndmask_b32_e32 v55, v55, v98, vcc
	v_rsq_f32_e32 v55, v55
	v_lshlrev_b32_e32 v118, 16, v79
	v_and_b32_e32 v119, 0xffff0000, v79
	v_sub_f32_e32 v78, v102, v54
	v_mul_f32_e32 v102, 0x45800000, v55
	v_lshl_add_u64 v[96:97], v[176:177], 1, v[76:77]
	v_sub_f32_e32 v77, v101, v54
	v_sub_f32_e32 v76, v100, v54
	v_sub_f32_e32 v79, v103, v54
	v_sub_f32_e32 v99, v105, v54
	v_sub_f32_e32 v98, v104, v54
	v_sub_f32_e32 v101, v119, v54
	v_sub_f32_e32 v100, v118, v54
	v_cndmask_b32_e32 v102, v55, v102, vcc
	v_pk_mul_f32 v[78:79], v[78:79], v[102:103] op_sel_hi:[1,0]
	v_pk_mul_f32 v[76:77], v[76:77], v[102:103] op_sel_hi:[1,0]
	v_pk_mul_f32 v[100:101], v[100:101], v[102:103] op_sel_hi:[1,0]
	v_pk_mul_f32 v[98:99], v[98:99], v[102:103] op_sel_hi:[1,0]
	s_waitcnt vmcnt(9)
	v_lshlrev_b32_e32 v55, 16, v72
	v_and_b32_e32 v72, 0xffff0000, v72
	v_lshlrev_b32_e32 v103, 16, v73
	s_waitcnt vmcnt(2)
	v_pk_fma_f32 v[50:51], v[76:77], v[106:107], v[50:51]
	v_pk_fma_f32 v[52:53], v[78:79], v[108:109], v[52:53]
	s_waitcnt vmcnt(0)
	v_pk_fma_f32 v[76:77], v[98:99], v[110:111], v[114:115]
	v_pk_fma_f32 v[78:79], v[100:101], v[112:113], v[116:117]
	v_pk_fma_f32 v[98:99], v[52:53], s[34:35], v[46:47] op_sel_hi:[1,0,1]
	v_pk_fma_f32 v[100:101], v[50:51], s[34:35], v[44:45] op_sel_hi:[1,0,1]
	v_pk_fma_f32 v[104:105], v[78:79], s[34:35], v[42:43] op_sel_hi:[1,0,1]
	v_pk_fma_f32 v[106:107], v[76:77], s[34:35], v[40:41] op_sel_hi:[1,0,1]
	v_cvt_pk_bf16_f32 v40, v100, v101
	v_cvt_pk_bf16_f32 v41, v98, v99
	v_cvt_pk_bf16_f32 v42, v106, v107
	v_cvt_pk_bf16_f32 v43, v104, v105
	global_store_dwordx4 v[96:97], v[40:43], off
	global_load_dwordx4 v[40:43], v[154:155], off
	s_nop 0
	global_load_dwordx4 v[44:47], v[152:153], off
	global_load_dwordx4 v[50:53], v[152:153], off offset:16
	global_load_dwordx4 v[76:79], v[154:155], off offset:16
	v_and_b32_e32 v108, 0xffff0000, v73
	v_lshlrev_b32_e32 v110, 16, v74
	v_and_b32_e32 v109, 0xffff0000, v74
	v_lshlrev_b32_e32 v111, 16, v75
	v_and_b32_e32 v112, 0xffff0000, v75
	v_sub_f32_e32 v73, v72, v54
	v_sub_f32_e32 v72, v55, v54
	v_sub_f32_e32 v75, v108, v54
	v_sub_f32_e32 v74, v103, v54
	v_sub_f32_e32 v109, v109, v54
	v_sub_f32_e32 v108, v110, v54
	v_sub_f32_e32 v55, v112, v54
	v_sub_f32_e32 v54, v111, v54
	v_pk_mul_f32 v[74:75], v[74:75], v[102:103] op_sel_hi:[1,0]
	v_pk_mul_f32 v[72:73], v[72:73], v[102:103] op_sel_hi:[1,0]
	v_pk_mul_f32 v[54:55], v[54:55], v[102:103] op_sel_hi:[1,0]
	v_pk_mul_f32 v[102:103], v[108:109], v[102:103] op_sel_hi:[1,0]
	v_mul_f32_e32 v116, v104, v104
	v_add_f32_e32 v108, v100, v101
	v_add_f32_e32 v110, v98, v99
	v_mul_f32_e32 v113, v100, v100
	v_mul_f32_e32 v101, v101, v101
	v_mul_f32_e32 v115, v98, v98
	v_mul_f32_e32 v99, v99, v99
	v_mul_f32_e32 v109, v106, v106
	v_mul_f32_e32 v111, v107, v107
	v_mov_b32_e32 v112, v106
	v_mov_b32_e32 v100, v107
	v_mov_b32_e32 v114, v104
	v_mov_b32_e32 v98, v105
	v_pk_fma_f32 v[104:105], v[104:105], v[104:105], v[116:117] op_sel_hi:[1,1,0]
	v_pk_add_f32 v[100:101], v[112:113], v[100:101]
	v_pk_add_f32 v[98:99], v[114:115], v[98:99]
	v_pk_add_f32 v[106:107], v[108:109], v[110:111]
	v_mov_b32_e32 v165, v105
	v_pk_add_f32 v[98:99], v[100:101], v[98:99]
	v_pk_add_f32 v[100:101], v[106:107], v[164:165]
	s_waitcnt vmcnt(2)
	v_pk_fma_f32 v[40:41], v[72:73], v[44:45], v[40:41]
	v_pk_fma_f32 v[42:43], v[74:75], v[46:47], v[42:43]
	s_waitcnt vmcnt(0)
	v_pk_fma_f32 v[44:45], v[102:103], v[50:51], v[76:77]
	v_pk_fma_f32 v[46:47], v[54:55], v[52:53], v[78:79]
	v_pk_fma_f32 v[38:39], v[42:43], s[34:35], v[38:39] op_sel_hi:[1,0,1]
	v_pk_fma_f32 v[36:37], v[40:41], s[34:35], v[36:37] op_sel_hi:[1,0,1]
	v_pk_fma_f32 v[40:41], v[46:47], s[34:35], v[34:35] op_sel_hi:[1,0,1]
	v_pk_fma_f32 v[42:43], v[44:45], s[34:35], v[32:33] op_sel_hi:[1,0,1]
	v_mul_f32_e32 v33, v36, v36
	v_mul_f32_e32 v35, v37, v37
	v_mul_f32_e32 v45, v38, v38
	v_mul_f32_e32 v47, v39, v39
	v_mov_b32_e32 v32, v36
	v_mov_b32_e32 v34, v37
	v_mov_b32_e32 v44, v38
	v_mov_b32_e32 v46, v39
	v_mul_f32_e32 v51, v42, v42
	v_mul_f32_e32 v53, v43, v43
	v_mul_f32_e32 v55, v40, v40
	v_mul_f32_e32 v73, v41, v41
	v_mov_b32_e32 v50, v42
	v_mov_b32_e32 v52, v43
	v_mov_b32_e32 v54, v40
	v_mov_b32_e32 v72, v41
	v_pk_add_f32 v[32:33], v[32:33], v[34:35]
	v_pk_add_f32 v[34:35], v[44:45], v[46:47]
	v_pk_add_f32 v[98:99], v[98:99], v[100:101]
	v_pk_add_f32 v[44:45], v[50:51], v[52:53]
	v_pk_add_f32 v[46:47], v[54:55], v[72:73]
	v_pk_add_f32 v[32:33], v[32:33], v[34:35]
	v_pk_add_f32 v[34:35], v[44:45], v[46:47]
	v_pk_add_f32 v[32:33], v[98:99], v[32:33]
	v_cvt_pk_bf16_f32 v36, v36, v37
	v_pk_add_f32 v[32:33], v[32:33], v[34:35]
	v_cvt_pk_bf16_f32 v37, v38, v39
	v_cvt_pk_bf16_f32 v38, v42, v43
	v_cvt_pk_bf16_f32 v39, v40, v41
	global_store_dwordx4 v[96:97], v[36:39], off offset:256
	s_waitcnt lgkmcnt(0)
	v_mov_b32_e32 v34, v32
	v_mov_b32_e32 v35, v33
	s_nop 1
	v_permlane16_swap_b32_e32 v34, v32
	v_permlane16_swap_b32_e32 v35, v33
	s_nop 0
	v_pk_add_f32 v[32:33], v[32:33], v[34:35]
	ds_bpermute_b32 v34, v247, v32
	ds_bpermute_b32 v35, v247, v33
	s_and_saveexec_b64 s[60:61], s[4:5]
	s_cbranch_execz .LBB0_2483
	v_lshl_add_u64 v[36:37], s[76:77], 0, v[88:89]
	v_lshl_add_u64 v[36:37], s[50:51], 3, v[36:37]
	s_lshl_b32 s16, s81, 3
	v_lshl_add_u64 v[36:37], v[36:37], 0, s[16:17]
	s_waitcnt lgkmcnt(0)
	v_pk_add_f32 v[32:33], v[32:33], v[34:35]
	global_store_dwordx2 v[36:37], v[32:33], off
; DI void row_stats(const f32x2v* st, size_t row, int fq, float& mu, float& rstd) {
;     ...
;     mu = s1 * (1.0f / 1024.0f); const float var = fmaxf(s2 * (1.0f / 1024.0f) - mu * mu, 0.f); rstd = rsqrtf(var + LN_EPS);
.LBB0_2483:
	s_or_b64 exec, exec, s[60:61]
	s_waitcnt lgkmcnt(0)
	global_load_dwordx4 v[32:35], v[180:181], off
	global_load_dwordx4 v[36:39], v[178:179], off
	global_load_dwordx4 v[40:43], v[178:179], off offset:16
	global_load_dwordx4 v[44:47], v[180:181], off offset:16
	v_pk_add_f32 v[50:51], v[92:93], v[94:95]
	v_lshlrev_b32_e32 v72, 16, v70
	v_pk_mul_f32 v[50:51], v[50:51], s[30:31] op_sel_hi:[1,0]
	v_and_b32_e32 v70, 0xffff0000, v70
	v_fma_f32 v51, -v50, v50, v51
	v_max_f32_e32 v51, 0, v51
	v_add_f32_e32 v51, 0x3727c5ac, v51
	v_lshlrev_b32_e32 v74, 16, v71
	v_and_b32_e32 v73, 0xffff0000, v71
	v_sub_f32_e32 v71, v70, v50
	v_mul_f32_e32 v70, 0x4b800000, v51
	v_cmp_gt_f32_e32 vcc, s92, v51
	v_lshlrev_b32_e32 v54, 16, v68
	v_and_b32_e32 v55, 0xffff0000, v68
	v_cndmask_b32_e32 v51, v51, v70, vcc
	v_rsq_f32_e32 v51, v51
	v_lshlrev_b32_e32 v68, 16, v69
	v_and_b32_e32 v69, 0xffff0000, v69
	v_sub_f32_e32 v70, v72, v50
	v_sub_f32_e32 v72, v74, v50
	v_mul_f32_e32 v74, 0x45800000, v51
	v_sub_f32_e32 v55, v55, v50
	v_sub_f32_e32 v54, v54, v50
	v_sub_f32_e32 v69, v69, v50
	v_sub_f32_e32 v68, v68, v50
	v_sub_f32_e32 v73, v73, v50
	v_cndmask_b32_e32 v74, v51, v74, vcc
	v_pk_mul_f32 v[68:69], v[68:69], v[74:75] op_sel_hi:[1,0]
	v_pk_mul_f32 v[54:55], v[54:55], v[74:75] op_sel_hi:[1,0]
	v_pk_mul_f32 v[72:73], v[72:73], v[74:75] op_sel_hi:[1,0]
	v_pk_mul_f32 v[70:71], v[70:71], v[74:75] op_sel_hi:[1,0]
	v_lshl_add_u64 v[52:53], s[44:45], 0, v[90:91]
	v_lshl_add_u64 v[52:53], v[176:177], 1, v[52:53]
	v_lshlrev_b32_e32 v51, 16, v64
	s_waitcnt vmcnt(2)
	v_pk_fma_f32 v[32:33], v[54:55], v[36:37], v[32:33]
	v_pk_fma_f32 v[34:35], v[68:69], v[38:39], v[34:35]
	s_waitcnt vmcnt(0)
	v_pk_fma_f32 v[36:37], v[70:71], v[40:41], v[44:45]
	v_pk_fma_f32 v[38:39], v[72:73], v[42:43], v[46:47]
	v_pk_fma_f32 v[40:41], v[34:35], s[34:35], v[30:31] op_sel_hi:[1,0,1]
	v_pk_fma_f32 v[42:43], v[32:33], s[34:35], v[28:29] op_sel_hi:[1,0,1]
	v_pk_fma_f32 v[44:45], v[38:39], s[34:35], v[26:27] op_sel_hi:[1,0,1]
	v_pk_fma_f32 v[46:47], v[36:37], s[34:35], v[24:25] op_sel_hi:[1,0,1]
	v_cvt_pk_bf16_f32 v24, v42, v43
	v_cvt_pk_bf16_f32 v25, v40, v41
	v_cvt_pk_bf16_f32 v26, v46, v47
	v_cvt_pk_bf16_f32 v27, v44, v45
	global_store_dwordx4 v[52:53], v[24:27], off
	global_load_dwordx4 v[24:27], v[154:155], off
	s_nop 0
	global_load_dwordx4 v[28:31], v[152:153], off
	global_load_dwordx4 v[32:35], v[152:153], off offset:16
	global_load_dwordx4 v[36:39], v[154:155], off offset:16
	v_and_b32_e32 v54, 0xffff0000, v64
	v_lshlrev_b32_e32 v64, 16, v65
	v_and_b32_e32 v65, 0xffff0000, v65
	v_lshlrev_b32_e32 v68, 16, v66
	v_and_b32_e32 v66, 0xffff0000, v66
	v_lshlrev_b32_e32 v69, 16, v67
	v_and_b32_e32 v70, 0xffff0000, v67
	v_sub_f32_e32 v55, v54, v50
	v_sub_f32_e32 v54, v51, v50
	v_sub_f32_e32 v65, v65, v50
	v_sub_f32_e32 v64, v64, v50
	v_sub_f32_e32 v67, v66, v50
	v_sub_f32_e32 v66, v68, v50
	v_sub_f32_e32 v51, v70, v50
	v_sub_f32_e32 v50, v69, v50
	v_pk_mul_f32 v[64:65], v[64:65], v[74:75] op_sel_hi:[1,0]
	v_pk_mul_f32 v[54:55], v[54:55], v[74:75] op_sel_hi:[1,0]
	v_pk_mul_f32 v[50:51], v[50:51], v[74:75] op_sel_hi:[1,0]
	v_pk_mul_f32 v[66:67], v[66:67], v[74:75] op_sel_hi:[1,0]
	v_mul_f32_e32 v76, v44, v44
	v_add_f32_e32 v68, v42, v43
	v_add_f32_e32 v70, v40, v41
	v_mul_f32_e32 v73, v42, v42
	v_mul_f32_e32 v43, v43, v43
	v_mul_f32_e32 v75, v40, v40
	v_mul_f32_e32 v41, v41, v41
	v_mul_f32_e32 v69, v46, v46
	v_mul_f32_e32 v71, v47, v47
	v_mov_b32_e32 v72, v46
	v_mov_b32_e32 v42, v47
	v_mov_b32_e32 v74, v44
	v_mov_b32_e32 v40, v45
	v_pk_fma_f32 v[44:45], v[44:45], v[44:45], v[76:77] op_sel_hi:[1,1,0]
	v_pk_add_f32 v[42:43], v[72:73], v[42:43]
	v_pk_add_f32 v[40:41], v[74:75], v[40:41]
	v_pk_add_f32 v[46:47], v[68:69], v[70:71]
	v_mov_b32_e32 v165, v45
	v_pk_add_f32 v[40:41], v[42:43], v[40:41]
	v_pk_add_f32 v[42:43], v[46:47], v[164:165]
	s_waitcnt vmcnt(2)
	v_pk_fma_f32 v[24:25], v[54:55], v[28:29], v[24:25]
	v_pk_fma_f32 v[26:27], v[64:65], v[30:31], v[26:27]
	s_waitcnt vmcnt(0)
	v_pk_fma_f32 v[28:29], v[66:67], v[32:33], v[36:37]
	v_pk_fma_f32 v[30:31], v[50:51], v[34:35], v[38:39]
	v_pk_fma_f32 v[22:23], v[26:27], s[34:35], v[22:23] op_sel_hi:[1,0,1]
	v_pk_fma_f32 v[20:21], v[24:25], s[34:35], v[20:21] op_sel_hi:[1,0,1]
	v_pk_fma_f32 v[24:25], v[30:31], s[34:35], v[18:19] op_sel_hi:[1,0,1]
	v_pk_fma_f32 v[26:27], v[28:29], s[34:35], v[16:17] op_sel_hi:[1,0,1]
	v_mul_f32_e32 v17, v20, v20
	v_mul_f32_e32 v19, v21, v21
	v_mul_f32_e32 v29, v22, v22
	v_mul_f32_e32 v31, v23, v23
	v_mov_b32_e32 v16, v20
	v_mov_b32_e32 v18, v21
	v_mov_b32_e32 v28, v22
	v_mov_b32_e32 v30, v23
	v_mul_f32_e32 v33, v26, v26
	v_mul_f32_e32 v35, v27, v27
	v_mul_f32_e32 v37, v24, v24
	v_mul_f32_e32 v39, v25, v25
	v_mov_b32_e32 v32, v26
	v_mov_b32_e32 v34, v27
	v_mov_b32_e32 v36, v24
	v_mov_b32_e32 v38, v25
	v_pk_add_f32 v[16:17], v[16:17], v[18:19]
	v_pk_add_f32 v[18:19], v[28:29], v[30:31]
	v_pk_add_f32 v[40:41], v[40:41], v[42:43]
	v_pk_add_f32 v[28:29], v[32:33], v[34:35]
	v_pk_add_f32 v[30:31], v[36:37], v[38:39]
	v_pk_add_f32 v[16:17], v[16:17], v[18:19]
	v_pk_add_f32 v[18:19], v[28:29], v[30:31]
	v_pk_add_f32 v[16:17], v[40:41], v[16:17]
	v_cvt_pk_bf16_f32 v20, v20, v21
	v_pk_add_f32 v[16:17], v[16:17], v[18:19]
	v_cvt_pk_bf16_f32 v21, v22, v23
	v_cvt_pk_bf16_f32 v22, v26, v27
	v_cvt_pk_bf16_f32 v23, v24, v25
	global_store_dwordx4 v[52:53], v[20:23], off offset:256
	s_waitcnt lgkmcnt(0)
	v_mov_b32_e32 v18, v16
	v_mov_b32_e32 v19, v17
	s_nop 1
	v_permlane16_swap_b32_e32 v18, v16
	v_permlane16_swap_b32_e32 v19, v17
	s_nop 0
	v_pk_add_f32 v[16:17], v[16:17], v[18:19]
	ds_bpermute_b32 v18, v247, v16
	ds_bpermute_b32 v19, v247, v17
	s_and_saveexec_b64 s[60:61], s[4:5]
	s_cbranch_execz .LBB0_2485
	v_lshl_add_u64 v[20:21], s[76:77], 0, v[82:83]
	v_lshl_add_u64 v[20:21], s[50:51], 3, v[20:21]
	s_lshl_b32 s16, s81, 3
	v_lshl_add_u64 v[20:21], v[20:21], 0, s[16:17]
	s_waitcnt lgkmcnt(0)
	v_pk_add_f32 v[16:17], v[16:17], v[18:19]
	global_store_dwordx2 v[20:21], v[16:17], off
; DI void row_stats(const f32x2v* st, size_t row, int fq, float& mu, float& rstd) {
;     ...
;     mu = s1 * (1.0f / 1024.0f); const float var = fmaxf(s2 * (1.0f / 1024.0f) - mu * mu, 0.f); rstd = rsqrtf(var + LN_EPS);
.LBB0_2485:
	s_or_b64 exec, exec, s[60:61]
	s_waitcnt lgkmcnt(0)
	global_load_dwordx4 v[16:19], v[180:181], off
	global_load_dwordx4 v[20:23], v[178:179], off
	global_load_dwordx4 v[24:27], v[178:179], off offset:16
	global_load_dwordx4 v[28:31], v[180:181], off offset:16
	v_pk_add_f32 v[32:33], v[86:87], v[48:49]
	v_lshlrev_b32_e32 v36, 16, v60
	v_pk_mul_f32 v[32:33], v[32:33], s[30:31] op_sel_hi:[1,0]
	v_and_b32_e32 v37, 0xffff0000, v60
	v_fma_f32 v33, -v32, v32, v33
	v_max_f32_e32 v33, 0, v33
	v_add_f32_e32 v33, 0x3727c5ac, v33
	v_mul_f32_e32 v44, 0x4b800000, v33
	v_cmp_gt_f32_e32 vcc, s92, v33
	v_lshlrev_b32_e32 v38, 16, v61
	v_and_b32_e32 v39, 0xffff0000, v61
	v_cndmask_b32_e32 v33, v33, v44, vcc
	v_rsq_f32_e32 v33, v33
	v_lshlrev_b32_e32 v40, 16, v62
	v_and_b32_e32 v41, 0xffff0000, v62
	v_lshlrev_b32_e32 v42, 16, v63
	v_and_b32_e32 v43, 0xffff0000, v63
	v_mul_f32_e32 v44, 0x45800000, v33
	v_sub_f32_e32 v37, v37, v32
	v_sub_f32_e32 v36, v36, v32
	v_sub_f32_e32 v39, v39, v32
	v_sub_f32_e32 v38, v38, v32
	v_sub_f32_e32 v41, v41, v32
	v_sub_f32_e32 v40, v40, v32
	v_sub_f32_e32 v43, v43, v32
	v_sub_f32_e32 v42, v42, v32
	v_cndmask_b32_e32 v44, v33, v44, vcc
	v_pk_mul_f32 v[38:39], v[38:39], v[44:45] op_sel_hi:[1,0]
	v_pk_mul_f32 v[36:37], v[36:37], v[44:45] op_sel_hi:[1,0]
	v_pk_mul_f32 v[42:43], v[42:43], v[44:45] op_sel_hi:[1,0]
	v_pk_mul_f32 v[40:41], v[40:41], v[44:45] op_sel_hi:[1,0]
	v_lshl_add_u64 v[34:35], s[44:45], 0, v[84:85]
	v_lshl_add_u64 v[34:35], v[176:177], 1, v[34:35]
	v_lshlrev_b32_e32 v33, 16, v56
	s_waitcnt vmcnt(2)
	v_pk_fma_f32 v[16:17], v[36:37], v[20:21], v[16:17]
	v_pk_fma_f32 v[18:19], v[38:39], v[22:23], v[18:19]
	s_waitcnt vmcnt(0)
	v_pk_fma_f32 v[20:21], v[40:41], v[24:25], v[28:29]
	v_pk_fma_f32 v[22:23], v[42:43], v[26:27], v[30:31]
	v_pk_fma_f32 v[24:25], v[18:19], s[34:35], v[14:15] op_sel_hi:[1,0,1]
	v_pk_fma_f32 v[26:27], v[16:17], s[34:35], v[12:13] op_sel_hi:[1,0,1]
	v_pk_fma_f32 v[28:29], v[22:23], s[34:35], v[10:11] op_sel_hi:[1,0,1]
	v_pk_fma_f32 v[30:31], v[20:21], s[34:35], v[8:9] op_sel_hi:[1,0,1]
	v_cvt_pk_bf16_f32 v8, v26, v27
	v_cvt_pk_bf16_f32 v9, v24, v25
	v_cvt_pk_bf16_f32 v10, v30, v31
	v_cvt_pk_bf16_f32 v11, v28, v29
	global_store_dwordx4 v[34:35], v[8:11], off
	global_load_dwordx4 v[8:11], v[154:155], off
	s_nop 0
	global_load_dwordx4 v[12:15], v[152:153], off
	global_load_dwordx4 v[16:19], v[152:153], off offset:16
	global_load_dwordx4 v[20:23], v[154:155], off offset:16
	v_and_b32_e32 v36, 0xffff0000, v56
	v_lshlrev_b32_e32 v38, 16, v57
	v_and_b32_e32 v39, 0xffff0000, v57
	v_lshlrev_b32_e32 v40, 16, v58
	v_and_b32_e32 v41, 0xffff0000, v58
	v_lshlrev_b32_e32 v42, 16, v59
	v_and_b32_e32 v43, 0xffff0000, v59
	v_sub_f32_e32 v37, v36, v32
	v_sub_f32_e32 v36, v33, v32
	v_sub_f32_e32 v39, v39, v32
	v_sub_f32_e32 v38, v38, v32
	v_sub_f32_e32 v41, v41, v32
	v_sub_f32_e32 v40, v40, v32
	v_sub_f32_e32 v33, v43, v32
	v_sub_f32_e32 v32, v42, v32
	v_pk_mul_f32 v[38:39], v[38:39], v[44:45] op_sel_hi:[1,0]
	v_pk_mul_f32 v[36:37], v[36:37], v[44:45] op_sel_hi:[1,0]
	v_pk_mul_f32 v[32:33], v[32:33], v[44:45] op_sel_hi:[1,0]
	v_pk_mul_f32 v[40:41], v[40:41], v[44:45] op_sel_hi:[1,0]
	v_mul_f32_e32 v50, v28, v28
	v_add_f32_e32 v42, v26, v27
	v_add_f32_e32 v44, v24, v25
	v_mul_f32_e32 v47, v26, v26
	v_mul_f32_e32 v27, v27, v27
	v_mul_f32_e32 v49, v24, v24
	v_mul_f32_e32 v25, v25, v25
	v_mul_f32_e32 v43, v30, v30
	v_mul_f32_e32 v45, v31, v31
	v_mov_b32_e32 v46, v30
	v_mov_b32_e32 v26, v31
	v_mov_b32_e32 v48, v28
	v_mov_b32_e32 v24, v29
	v_pk_fma_f32 v[28:29], v[28:29], v[28:29], v[50:51] op_sel_hi:[1,1,0]
	v_pk_add_f32 v[26:27], v[46:47], v[26:27]
	v_pk_add_f32 v[24:25], v[48:49], v[24:25]
	v_pk_add_f32 v[30:31], v[42:43], v[44:45]
	v_mov_b32_e32 v165, v29
	v_pk_add_f32 v[24:25], v[26:27], v[24:25]
	v_pk_add_f32 v[26:27], v[30:31], v[164:165]
	s_waitcnt vmcnt(2)
	v_pk_fma_f32 v[8:9], v[36:37], v[12:13], v[8:9]
	v_pk_fma_f32 v[10:11], v[38:39], v[14:15], v[10:11]
	s_waitcnt vmcnt(0)
	v_pk_fma_f32 v[12:13], v[40:41], v[16:17], v[20:21]
	v_pk_fma_f32 v[14:15], v[32:33], v[18:19], v[22:23]
	v_pk_fma_f32 v[6:7], v[10:11], s[34:35], v[6:7] op_sel_hi:[1,0,1]
	v_pk_fma_f32 v[4:5], v[8:9], s[34:35], v[4:5] op_sel_hi:[1,0,1]
	v_pk_fma_f32 v[8:9], v[14:15], s[34:35], v[2:3] op_sel_hi:[1,0,1]
	v_pk_fma_f32 v[10:11], v[12:13], s[34:35], v[0:1] op_sel_hi:[1,0,1]
	v_mul_f32_e32 v1, v4, v4
	v_mul_f32_e32 v3, v5, v5
	v_mul_f32_e32 v13, v6, v6
	v_mul_f32_e32 v15, v7, v7
	v_mov_b32_e32 v0, v4
	v_mov_b32_e32 v2, v5
	v_mov_b32_e32 v12, v6
	v_mov_b32_e32 v14, v7
	v_mul_f32_e32 v17, v10, v10
	v_mul_f32_e32 v19, v11, v11
	v_mul_f32_e32 v21, v8, v8
	v_mul_f32_e32 v23, v9, v9
	v_mov_b32_e32 v16, v10
	v_mov_b32_e32 v18, v11
	v_mov_b32_e32 v20, v8
	v_mov_b32_e32 v22, v9
	v_pk_add_f32 v[0:1], v[0:1], v[2:3]
	v_pk_add_f32 v[2:3], v[12:13], v[14:15]
	v_pk_add_f32 v[24:25], v[24:25], v[26:27]
	v_pk_add_f32 v[12:13], v[16:17], v[18:19]
	v_pk_add_f32 v[14:15], v[20:21], v[22:23]
	v_pk_add_f32 v[0:1], v[0:1], v[2:3]
	v_pk_add_f32 v[2:3], v[12:13], v[14:15]
	v_pk_add_f32 v[0:1], v[24:25], v[0:1]
	v_cvt_pk_bf16_f32 v4, v4, v5
	v_pk_add_f32 v[0:1], v[0:1], v[2:3]
	v_cvt_pk_bf16_f32 v5, v6, v7
	v_cvt_pk_bf16_f32 v6, v10, v11
	v_cvt_pk_bf16_f32 v7, v8, v9
	global_store_dwordx4 v[34:35], v[4:7], off offset:256
	s_waitcnt lgkmcnt(0)
	v_mov_b32_e32 v2, v0
	v_mov_b32_e32 v3, v1
	s_nop 1
	v_permlane16_swap_b32_e32 v2, v0
	v_permlane16_swap_b32_e32 v3, v1
	s_nop 0
	v_pk_add_f32 v[0:1], v[0:1], v[2:3]
	ds_bpermute_b32 v2, v247, v0
	ds_bpermute_b32 v3, v247, v1
	s_and_saveexec_b64 s[60:61], s[4:5]
	s_cbranch_execz .LBB0_2487
	v_lshl_add_u64 v[4:5], s[76:77], 0, v[80:81]
	v_lshl_add_u64 v[4:5], s[50:51], 3, v[4:5]
	s_lshl_b32 s16, s81, 3
	v_lshl_add_u64 v[4:5], v[4:5], 0, s[16:17]
	s_waitcnt lgkmcnt(0)
	v_pk_add_f32 v[0:1], v[0:1], v[2:3]
	global_store_dwordx2 v[4:5], v[0:1], off
